# MFMA order: the two K-halves of each accumulator issued back to back (accumulator forwarded MFMA to MFMA) instead of 8 accumulators apart
# speedup vs baseline: 1.0059x; 1.0032x over previous
.LBB0_74:
	s_ashr_i32 s27, s26, 31
	s_lshl_b64 s[28:29], s[26:27], 19
	s_add_u32 s28, s3, s28
	s_addc_u32 s29, s35, s29
	s_and_b64 s[30:31], s[4:5], exec
	s_cselect_b32 s27, s29, s49
	s_cselect_b32 s68, s28, s48
	s_ashr_i32 s23, s22, 31
	s_lshl_b64 s[30:31], s[22:23], 19
	s_add_u32 s30, s50, s30
	s_addc_u32 s31, s51, s31
	s_and_b64 s[70:71], s[4:5], exec
	s_cselect_b32 s69, s31, s47
	s_cselect_b32 s70, s30, s46
	s_lshl_b32 s23, s44, 8
	v_add_u32_e32 v0, s23, v148
	s_add_u32 s71, s46, 0x100
	v_ashrrev_i32_e32 v1, 31, v0
	s_addc_u32 s74, s47, 0
	v_lshl_add_u64 v[144:145], v[0:1], 4, s[12:13]
	s_add_u32 s44, s48, 0x40080
	s_addc_u32 s45, s49, 0
	s_mov_b32 s75, -2
	s_mov_b64 s[46:47], 0
	s_cmp_eq_u32 s59, 1
	s_cbranch_scc1 .Lfa_0
	v_add_u32_e32 v153, s64, v147
	ds_read_b128 v[160:163], v153
	ds_read_b128 v[164:167], v153 offset:1024
	ds_read_b128 v[168:171], v153 offset:2048
	ds_read_b128 v[172:175], v153 offset:3072
	v_add_u32_e32 v153, s65, v147
	ds_read_b128 v[176:179], v153
	ds_read_b128 v[180:183], v153 offset:1024
	ds_read_b128 v[186:189], v153 offset:2048
	ds_read_b128 v[190:193], v153 offset:3072
	s_add_u32 s48, s44, 0xfffc0080
	s_addc_u32 s49, s45, -1
	s_and_b64 s[46:47], s[46:47], exec
	s_cselect_b32 s49, s27, s49
	s_cselect_b32 s48, s68, s48
	s_cselect_b32 s47, s69, s74
	s_cselect_b32 s46, s70, s71
	v_lshl_add_u64 v[154:155], s[44:45], 0, v[138:139]
	s_add_i32 m0, s55, 0xc000
	ds_read_b128 v[194:197], v150
	ds_read_b128 v[198:201], v150 offset:1024
	ds_read_b128 v[202:205], v150 offset:2048
	ds_read_b128 v[206:209], v150 offset:3072
	ds_read_b128 v[210:213], v150 offset:4096
	ds_read_b128 v[214:217], v150 offset:5120
	ds_read_b128 v[218:221], v150 offset:6144
	ds_read_b128 v[222:225], v150 offset:7168
	global_load_lds_dwordx4 v[154:155], off
	v_lshl_add_u64 v[154:155], s[44:45], 0, v[136:137]
	s_add_i32 m0, s55, 0xe000
	s_nop 0
	global_load_lds_dwordx4 v[154:155], off
	s_waitcnt vmcnt(16)
	s_waitcnt lgkmcnt(0)
	s_barrier
	s_setprio 1
	s_waitcnt lgkmcnt(0)
	v_mfma_f32_16x16x32_bf16 v[124:127], v[160:163], v[194:197], 0
	v_mfma_f32_16x16x32_bf16 v[116:119], v[168:171], v[194:197], 0
	v_mfma_f32_16x16x32_bf16 v[108:111], v[160:163], v[202:205], 0
	v_mfma_f32_16x16x32_bf16 v[100:103], v[168:171], v[202:205], 0
	v_mfma_f32_16x16x32_bf16 v[92:95], v[160:163], v[210:213], 0
	v_mfma_f32_16x16x32_bf16 v[84:87], v[168:171], v[210:213], 0
	v_mfma_f32_16x16x32_bf16 v[76:79], v[160:163], v[218:221], 0
	v_mfma_f32_16x16x32_bf16 v[68:71], v[168:171], v[218:221], 0
	v_mfma_f32_16x16x32_bf16 v[124:127], v[164:167], v[198:201], v[124:127]
	v_mfma_f32_16x16x32_bf16 v[116:119], v[172:175], v[198:201], v[116:119]
	v_mfma_f32_16x16x32_bf16 v[108:111], v[164:167], v[206:209], v[108:111]
	v_mfma_f32_16x16x32_bf16 v[100:103], v[172:175], v[206:209], v[100:103]
	v_mfma_f32_16x16x32_bf16 v[92:95], v[164:167], v[214:217], v[92:95]
	v_mfma_f32_16x16x32_bf16 v[84:87], v[172:175], v[214:217], v[84:87]
	v_mfma_f32_16x16x32_bf16 v[76:79], v[164:167], v[222:225], v[76:79]
	v_mfma_f32_16x16x32_bf16 v[68:71], v[172:175], v[222:225], v[68:71]
	s_setprio 0
	s_setprio 1
	v_mfma_f32_16x16x32_bf16 v[120:123], v[176:179], v[194:197], 0
	v_mfma_f32_16x16x32_bf16 v[112:115], v[186:189], v[194:197], 0
	v_mfma_f32_16x16x32_bf16 v[104:107], v[176:179], v[202:205], 0
	v_mfma_f32_16x16x32_bf16 v[96:99], v[186:189], v[202:205], 0
	v_mfma_f32_16x16x32_bf16 v[88:91], v[176:179], v[210:213], 0
	v_mfma_f32_16x16x32_bf16 v[80:83], v[186:189], v[210:213], 0
	v_mfma_f32_16x16x32_bf16 v[72:75], v[176:179], v[218:221], 0
	v_mfma_f32_16x16x32_bf16 v[64:67], v[186:189], v[218:221], 0
	v_mfma_f32_16x16x32_bf16 v[120:123], v[180:183], v[198:201], v[120:123]
	v_mfma_f32_16x16x32_bf16 v[112:115], v[190:193], v[198:201], v[112:115]
	v_mfma_f32_16x16x32_bf16 v[104:107], v[180:183], v[206:209], v[104:107]
	v_mfma_f32_16x16x32_bf16 v[96:99], v[190:193], v[206:209], v[96:99]
	v_mfma_f32_16x16x32_bf16 v[88:91], v[180:183], v[214:217], v[88:91]
	v_mfma_f32_16x16x32_bf16 v[80:83], v[190:193], v[214:217], v[80:83]
	v_mfma_f32_16x16x32_bf16 v[72:75], v[180:183], v[222:225], v[72:75]
	v_mfma_f32_16x16x32_bf16 v[64:67], v[190:193], v[222:225], v[64:67]
	s_setprio 0
	s_barrier
	s_add_i32 s76, s64, s52
	v_lshl_add_u64 v[154:155], s[46:47], 0, v[132:133]
	s_mov_b32 m0, s76
	ds_read_b128 v[194:197], v150 offset:16384
	ds_read_b128 v[198:201], v150 offset:17408
	ds_read_b128 v[202:205], v150 offset:18432
	ds_read_b128 v[206:209], v150 offset:19456
	ds_read_b128 v[210:213], v150 offset:20480
	ds_read_b128 v[214:217], v150 offset:21504
	ds_read_b128 v[218:221], v150 offset:22528
	ds_read_b128 v[222:225], v150 offset:23552
	global_load_lds_dwordx4 v[154:155], off
	s_add_i32 m0, s76, 0x2000
	s_add_u32 s76, s46, 0x40000
	v_lshl_add_u64 v[226:227], s[46:47], 0, v[128:129]
	s_addc_u32 s77, s47, 0
	s_add_i32 s78, s65, s52
	global_load_lds_dwordx4 v[226:227], off
	v_lshl_add_u64 v[228:229], s[76:77], 0, v[132:133]
	s_mov_b32 m0, s78
	v_lshl_add_u64 v[230:231], s[48:49], 0, v[130:131]
	global_load_lds_dwordx4 v[228:229], off
	v_lshl_add_u64 v[228:229], s[76:77], 0, v[128:129]
	s_add_i32 m0, s78, 0x2000
	s_nop 0
	global_load_lds_dwordx4 v[228:229], off
	v_lshl_add_u64 v[228:229], s[48:49], 0, v[134:135]
	s_mov_b32 m0, s55
	s_nop 0
	global_load_lds_dwordx4 v[228:229], off
	s_mov_b32 m0, s56
	s_nop 0
	global_load_lds_dwordx4 v[230:231], off
	s_waitcnt vmcnt(16)
	s_waitcnt lgkmcnt(0)
	s_barrier
	s_setprio 1
	s_waitcnt lgkmcnt(0)
	v_mfma_f32_16x16x32_bf16 v[60:63], v[160:163], v[194:197], 0
	v_mfma_f32_16x16x32_bf16 v[52:55], v[168:171], v[194:197], 0
	v_mfma_f32_16x16x32_bf16 v[44:47], v[160:163], v[202:205], 0
	v_mfma_f32_16x16x32_bf16 v[36:39], v[168:171], v[202:205], 0
	v_mfma_f32_16x16x32_bf16 v[28:31], v[160:163], v[210:213], 0
	v_mfma_f32_16x16x32_bf16 v[20:23], v[168:171], v[210:213], 0
	v_mfma_f32_16x16x32_bf16 v[12:15], v[160:163], v[218:221], 0
	v_mfma_f32_16x16x32_bf16 v[4:7], v[168:171], v[218:221], 0
	v_mfma_f32_16x16x32_bf16 v[60:63], v[164:167], v[198:201], v[60:63]
	v_mfma_f32_16x16x32_bf16 v[52:55], v[172:175], v[198:201], v[52:55]
	v_mfma_f32_16x16x32_bf16 v[44:47], v[164:167], v[206:209], v[44:47]
	v_mfma_f32_16x16x32_bf16 v[36:39], v[172:175], v[206:209], v[36:39]
	v_mfma_f32_16x16x32_bf16 v[28:31], v[164:167], v[214:217], v[28:31]
	v_mfma_f32_16x16x32_bf16 v[20:23], v[172:175], v[214:217], v[20:23]
	v_mfma_f32_16x16x32_bf16 v[12:15], v[164:167], v[222:225], v[12:15]
	v_mfma_f32_16x16x32_bf16 v[4:7], v[172:175], v[222:225], v[4:7]
	s_setprio 0
	s_setprio 1
	v_mfma_f32_16x16x32_bf16 v[56:59], v[176:179], v[194:197], 0
	v_mfma_f32_16x16x32_bf16 v[48:51], v[186:189], v[194:197], 0
	v_mfma_f32_16x16x32_bf16 v[40:43], v[176:179], v[202:205], 0
	v_mfma_f32_16x16x32_bf16 v[32:35], v[186:189], v[202:205], 0
	v_mfma_f32_16x16x32_bf16 v[24:27], v[176:179], v[210:213], 0
	v_mfma_f32_16x16x32_bf16 v[16:19], v[186:189], v[210:213], 0
	v_mfma_f32_16x16x32_bf16 v[8:11], v[176:179], v[218:221], 0
	v_mfma_f32_16x16x32_bf16 v[0:3], v[186:189], v[218:221], 0
	v_mfma_f32_16x16x32_bf16 v[56:59], v[180:183], v[198:201], v[56:59]
	v_mfma_f32_16x16x32_bf16 v[48:51], v[190:193], v[198:201], v[48:51]
	v_mfma_f32_16x16x32_bf16 v[40:43], v[180:183], v[206:209], v[40:43]
	v_mfma_f32_16x16x32_bf16 v[32:35], v[190:193], v[206:209], v[32:35]
	v_mfma_f32_16x16x32_bf16 v[24:27], v[180:183], v[214:217], v[24:27]
	v_mfma_f32_16x16x32_bf16 v[16:19], v[190:193], v[214:217], v[16:19]
	v_mfma_f32_16x16x32_bf16 v[8:11], v[180:183], v[222:225], v[8:11]
	v_mfma_f32_16x16x32_bf16 v[0:3], v[190:193], v[222:225], v[0:3]
	s_setprio 0
	s_barrier
	s_add_i32 s76, 0, 0x18000
	v_add_u32_e32 v153, s76, v147
	s_add_i32 s77, 0, 0x1c000
	ds_read_b128 v[160:163], v153
	ds_read_b128 v[164:167], v153 offset:1024
	ds_read_b128 v[168:171], v153 offset:2048
	ds_read_b128 v[172:175], v153 offset:3072
	v_add_u32_e32 v153, s77, v147
	ds_read_b128 v[176:179], v153
	ds_read_b128 v[180:183], v153 offset:1024
	ds_read_b128 v[186:189], v153 offset:2048
	ds_read_b128 v[190:193], v153 offset:3072
	s_add_u32 s48, s48, 0x40000
	s_addc_u32 s49, s49, 0
	s_mov_b32 m0, s57
	v_lshl_add_u64 v[232:233], s[48:49], 0, v[134:135]
	ds_read_b128 v[194:197], v150 offset:32768
	ds_read_b128 v[198:201], v150 offset:33792
	ds_read_b128 v[202:205], v150 offset:34816
	ds_read_b128 v[206:209], v150 offset:35840
	ds_read_b128 v[210:213], v150 offset:36864
	ds_read_b128 v[214:217], v150 offset:37888
	ds_read_b128 v[218:221], v150 offset:38912
	ds_read_b128 v[222:225], v150 offset:39936
	global_load_lds_dwordx4 v[232:233], off
	v_lshl_add_u64 v[232:233], s[48:49], 0, v[130:131]
	s_mov_b32 m0, s58
	s_nop 0
	global_load_lds_dwordx4 v[232:233], off
	s_waitcnt vmcnt(8)
	s_waitcnt lgkmcnt(0)
	s_barrier
	s_setprio 1
	s_waitcnt lgkmcnt(0)
	v_mfma_f32_16x16x32_bf16 v[124:127], v[160:163], v[194:197], v[124:127]
	v_mfma_f32_16x16x32_bf16 v[124:127], v[164:167], v[198:201], v[124:127]
	v_mfma_f32_16x16x32_bf16 v[116:119], v[168:171], v[194:197], v[116:119]
	v_mfma_f32_16x16x32_bf16 v[116:119], v[172:175], v[198:201], v[116:119]
	v_mfma_f32_16x16x32_bf16 v[108:111], v[160:163], v[202:205], v[108:111]
	v_mfma_f32_16x16x32_bf16 v[108:111], v[164:167], v[206:209], v[108:111]
	v_mfma_f32_16x16x32_bf16 v[100:103], v[168:171], v[202:205], v[100:103]
	v_mfma_f32_16x16x32_bf16 v[100:103], v[172:175], v[206:209], v[100:103]
	v_mfma_f32_16x16x32_bf16 v[92:95], v[160:163], v[210:213], v[92:95]
	v_mfma_f32_16x16x32_bf16 v[92:95], v[164:167], v[214:217], v[92:95]
	v_mfma_f32_16x16x32_bf16 v[84:87], v[168:171], v[210:213], v[84:87]
	v_mfma_f32_16x16x32_bf16 v[84:87], v[172:175], v[214:217], v[84:87]
	v_mfma_f32_16x16x32_bf16 v[76:79], v[160:163], v[218:221], v[76:79]
	v_mfma_f32_16x16x32_bf16 v[76:79], v[164:167], v[222:225], v[76:79]
	v_mfma_f32_16x16x32_bf16 v[68:71], v[168:171], v[218:221], v[68:71]
	v_mfma_f32_16x16x32_bf16 v[68:71], v[172:175], v[222:225], v[68:71]
	s_setprio 0
	s_setprio 1
	v_mfma_f32_16x16x32_bf16 v[120:123], v[176:179], v[194:197], v[120:123]
	v_mfma_f32_16x16x32_bf16 v[120:123], v[180:183], v[198:201], v[120:123]
	v_mfma_f32_16x16x32_bf16 v[112:115], v[186:189], v[194:197], v[112:115]
	v_mfma_f32_16x16x32_bf16 v[112:115], v[190:193], v[198:201], v[112:115]
	v_mfma_f32_16x16x32_bf16 v[104:107], v[176:179], v[202:205], v[104:107]
	v_mfma_f32_16x16x32_bf16 v[104:107], v[180:183], v[206:209], v[104:107]
	v_mfma_f32_16x16x32_bf16 v[96:99], v[186:189], v[202:205], v[96:99]
	v_mfma_f32_16x16x32_bf16 v[96:99], v[190:193], v[206:209], v[96:99]
	v_mfma_f32_16x16x32_bf16 v[88:91], v[176:179], v[210:213], v[88:91]
	v_mfma_f32_16x16x32_bf16 v[88:91], v[180:183], v[214:217], v[88:91]
	v_mfma_f32_16x16x32_bf16 v[80:83], v[186:189], v[210:213], v[80:83]
	v_mfma_f32_16x16x32_bf16 v[80:83], v[190:193], v[214:217], v[80:83]
	v_mfma_f32_16x16x32_bf16 v[72:75], v[176:179], v[218:221], v[72:75]
	v_mfma_f32_16x16x32_bf16 v[72:75], v[180:183], v[222:225], v[72:75]
	v_mfma_f32_16x16x32_bf16 v[64:67], v[186:189], v[218:221], v[64:67]
	v_mfma_f32_16x16x32_bf16 v[64:67], v[190:193], v[222:225], v[64:67]
	s_setprio 0
	s_barrier
	s_add_i32 s48, s76, s52
	v_lshl_add_u64 v[154:155], v[154:155], 0, s[14:15]
	s_mov_b32 m0, s48
	ds_read_b128 v[194:197], v150 offset:49152
	ds_read_b128 v[198:201], v150 offset:50176
	ds_read_b128 v[202:205], v150 offset:51200
	ds_read_b128 v[206:209], v150 offset:52224
	ds_read_b128 v[210:213], v150 offset:53248
	ds_read_b128 v[214:217], v150 offset:54272
	ds_read_b128 v[218:221], v150 offset:55296
	ds_read_b128 v[222:225], v150 offset:56320
	global_load_lds_dwordx4 v[154:155], off
	s_add_i32 m0, s48, 0x2000
	s_add_u32 s46, s46, 0x40080
	v_lshl_add_u64 v[154:155], v[226:227], 0, s[14:15]
	s_addc_u32 s47, s47, 0
	s_add_i32 s48, s77, s52
	global_load_lds_dwordx4 v[154:155], off
	v_lshl_add_u64 v[154:155], s[46:47], 0, v[132:133]
	s_mov_b32 m0, s48
	s_nop 0
	global_load_lds_dwordx4 v[154:155], off
	v_lshl_add_u64 v[154:155], s[46:47], 0, v[128:129]
	s_add_i32 m0, s48, 0x2000
	s_nop 0
	global_load_lds_dwordx4 v[154:155], off
	v_lshl_add_u64 v[154:155], v[228:229], 0, s[14:15]
	s_mov_b32 m0, s60
	s_nop 0
	global_load_lds_dwordx4 v[154:155], off
	v_lshl_add_u64 v[154:155], v[230:231], 0, s[14:15]
	s_mov_b32 m0, s61
	s_nop 0
	global_load_lds_dwordx4 v[154:155], off
	s_waitcnt vmcnt(8)
	s_waitcnt lgkmcnt(0)
	s_barrier
	s_setprio 1
	s_waitcnt lgkmcnt(0)
	v_mfma_f32_16x16x32_bf16 v[60:63], v[160:163], v[194:197], v[60:63]
	v_mfma_f32_16x16x32_bf16 v[60:63], v[164:167], v[198:201], v[60:63]
	v_mfma_f32_16x16x32_bf16 v[52:55], v[168:171], v[194:197], v[52:55]
	v_mfma_f32_16x16x32_bf16 v[52:55], v[172:175], v[198:201], v[52:55]
	v_mfma_f32_16x16x32_bf16 v[44:47], v[160:163], v[202:205], v[44:47]
	v_mfma_f32_16x16x32_bf16 v[44:47], v[164:167], v[206:209], v[44:47]
	v_mfma_f32_16x16x32_bf16 v[36:39], v[168:171], v[202:205], v[36:39]
	v_mfma_f32_16x16x32_bf16 v[36:39], v[172:175], v[206:209], v[36:39]
	v_mfma_f32_16x16x32_bf16 v[28:31], v[160:163], v[210:213], v[28:31]
	v_mfma_f32_16x16x32_bf16 v[28:31], v[164:167], v[214:217], v[28:31]
	v_mfma_f32_16x16x32_bf16 v[20:23], v[168:171], v[210:213], v[20:23]
	v_mfma_f32_16x16x32_bf16 v[20:23], v[172:175], v[214:217], v[20:23]
	v_mfma_f32_16x16x32_bf16 v[12:15], v[160:163], v[218:221], v[12:15]
	v_mfma_f32_16x16x32_bf16 v[12:15], v[164:167], v[222:225], v[12:15]
	v_mfma_f32_16x16x32_bf16 v[4:7], v[168:171], v[218:221], v[4:7]
	v_mfma_f32_16x16x32_bf16 v[4:7], v[172:175], v[222:225], v[4:7]
	s_setprio 0
	s_setprio 1
	v_mfma_f32_16x16x32_bf16 v[56:59], v[176:179], v[194:197], v[56:59]
	v_mfma_f32_16x16x32_bf16 v[56:59], v[180:183], v[198:201], v[56:59]
	v_mfma_f32_16x16x32_bf16 v[48:51], v[186:189], v[194:197], v[48:51]
	v_mfma_f32_16x16x32_bf16 v[48:51], v[190:193], v[198:201], v[48:51]
	v_mfma_f32_16x16x32_bf16 v[40:43], v[176:179], v[202:205], v[40:43]
	v_mfma_f32_16x16x32_bf16 v[40:43], v[180:183], v[206:209], v[40:43]
	v_mfma_f32_16x16x32_bf16 v[32:35], v[186:189], v[202:205], v[32:35]
	v_mfma_f32_16x16x32_bf16 v[32:35], v[190:193], v[206:209], v[32:35]
	v_mfma_f32_16x16x32_bf16 v[24:27], v[176:179], v[210:213], v[24:27]
	v_mfma_f32_16x16x32_bf16 v[24:27], v[180:183], v[214:217], v[24:27]
	v_mfma_f32_16x16x32_bf16 v[16:19], v[186:189], v[210:213], v[16:19]
	v_mfma_f32_16x16x32_bf16 v[16:19], v[190:193], v[214:217], v[16:19]
	v_mfma_f32_16x16x32_bf16 v[8:11], v[176:179], v[218:221], v[8:11]
	v_mfma_f32_16x16x32_bf16 v[8:11], v[180:183], v[222:225], v[8:11]
	v_mfma_f32_16x16x32_bf16 v[0:3], v[186:189], v[218:221], v[0:3]
	v_mfma_f32_16x16x32_bf16 v[0:3], v[190:193], v[222:225], v[0:3]
	s_setprio 0
	s_barrier
	s_add_i32 s75, s75, 2
	s_add_u32 s71, s71, 0x100
	s_addc_u32 s74, s74, 0
	s_add_u32 s44, s44, 0x100
	s_addc_u32 s45, s45, 0
	s_branch .LBB0_76
.Lfa_0:
	v_add_u32_e32 v153, s64, v147
	ds_read_b128 v[160:163], v153
	ds_read_b128 v[164:167], v153 offset:1024
	ds_read_b128 v[168:171], v153 offset:2048
	ds_read_b128 v[172:175], v153 offset:3072
	v_add_u32_e32 v153, s65, v147
	ds_read_b128 v[176:179], v153
	ds_read_b128 v[180:183], v153 offset:1024
	ds_read_b128 v[186:189], v153 offset:2048
	ds_read_b128 v[190:193], v153 offset:3072
	s_add_u32 s48, s44, 0xfffc0080
	s_addc_u32 s49, s45, -1
	s_and_b64 s[46:47], s[46:47], exec
	s_cselect_b32 s49, s27, s49
	s_cselect_b32 s48, s68, s48
	s_cselect_b32 s47, s69, s74
	s_cselect_b32 s46, s70, s71
	v_lshl_add_u64 v[154:155], s[44:45], 0, v[138:139]
	s_add_i32 m0, s55, 0xc000
	ds_read_b128 v[194:197], v150
	ds_read_b128 v[198:201], v150 offset:1024
	ds_read_b128 v[202:205], v150 offset:2048
	ds_read_b128 v[206:209], v150 offset:3072
	ds_read_b128 v[210:213], v150 offset:4096
	ds_read_b128 v[214:217], v150 offset:5120
	ds_read_b128 v[218:221], v150 offset:6144
	ds_read_b128 v[222:225], v150 offset:7168
	global_load_lds_dwordx4 v[154:155], off
	v_lshl_add_u64 v[154:155], s[44:45], 0, v[136:137]
	s_add_i32 m0, s55, 0xe000
	s_nop 0
	global_load_lds_dwordx4 v[154:155], off
	s_waitcnt vmcnt(8)
	s_waitcnt lgkmcnt(0)
	s_barrier
	s_setprio 1
	s_waitcnt lgkmcnt(0)
	v_mfma_f32_16x16x32_bf16 v[124:127], v[160:163], v[194:197], 0
	v_mfma_f32_16x16x32_bf16 v[116:119], v[168:171], v[194:197], 0
	v_mfma_f32_16x16x32_bf16 v[108:111], v[160:163], v[202:205], 0
	v_mfma_f32_16x16x32_bf16 v[100:103], v[168:171], v[202:205], 0
	v_mfma_f32_16x16x32_bf16 v[92:95], v[160:163], v[210:213], 0
	v_mfma_f32_16x16x32_bf16 v[84:87], v[168:171], v[210:213], 0
	v_mfma_f32_16x16x32_bf16 v[76:79], v[160:163], v[218:221], 0
	v_mfma_f32_16x16x32_bf16 v[68:71], v[168:171], v[218:221], 0
	v_mfma_f32_16x16x32_bf16 v[124:127], v[164:167], v[198:201], v[124:127]
	v_mfma_f32_16x16x32_bf16 v[116:119], v[172:175], v[198:201], v[116:119]
	v_mfma_f32_16x16x32_bf16 v[108:111], v[164:167], v[206:209], v[108:111]
	v_mfma_f32_16x16x32_bf16 v[100:103], v[172:175], v[206:209], v[100:103]
	v_mfma_f32_16x16x32_bf16 v[92:95], v[164:167], v[214:217], v[92:95]
	v_mfma_f32_16x16x32_bf16 v[84:87], v[172:175], v[214:217], v[84:87]
	v_mfma_f32_16x16x32_bf16 v[76:79], v[164:167], v[222:225], v[76:79]
	v_mfma_f32_16x16x32_bf16 v[68:71], v[172:175], v[222:225], v[68:71]
	s_setprio 0
	s_setprio 1
	v_mfma_f32_16x16x32_bf16 v[120:123], v[176:179], v[194:197], 0
	v_mfma_f32_16x16x32_bf16 v[112:115], v[186:189], v[194:197], 0
	v_mfma_f32_16x16x32_bf16 v[104:107], v[176:179], v[202:205], 0
	v_mfma_f32_16x16x32_bf16 v[96:99], v[186:189], v[202:205], 0
	v_mfma_f32_16x16x32_bf16 v[88:91], v[176:179], v[210:213], 0
	v_mfma_f32_16x16x32_bf16 v[80:83], v[186:189], v[210:213], 0
	v_mfma_f32_16x16x32_bf16 v[72:75], v[176:179], v[218:221], 0
	v_mfma_f32_16x16x32_bf16 v[64:67], v[186:189], v[218:221], 0
	v_mfma_f32_16x16x32_bf16 v[120:123], v[180:183], v[198:201], v[120:123]
	v_mfma_f32_16x16x32_bf16 v[112:115], v[190:193], v[198:201], v[112:115]
	v_mfma_f32_16x16x32_bf16 v[104:107], v[180:183], v[206:209], v[104:107]
	v_mfma_f32_16x16x32_bf16 v[96:99], v[190:193], v[206:209], v[96:99]
	v_mfma_f32_16x16x32_bf16 v[88:91], v[180:183], v[214:217], v[88:91]
	v_mfma_f32_16x16x32_bf16 v[80:83], v[190:193], v[214:217], v[80:83]
	v_mfma_f32_16x16x32_bf16 v[72:75], v[180:183], v[222:225], v[72:75]
	v_mfma_f32_16x16x32_bf16 v[64:67], v[190:193], v[222:225], v[64:67]
	s_setprio 0
	s_barrier
	s_add_i32 s76, s64, s52
	v_lshl_add_u64 v[154:155], s[46:47], 0, v[132:133]
	s_mov_b32 m0, s76
	ds_read_b128 v[194:197], v150 offset:16384
	ds_read_b128 v[198:201], v150 offset:17408
	ds_read_b128 v[202:205], v150 offset:18432
	ds_read_b128 v[206:209], v150 offset:19456
	ds_read_b128 v[210:213], v150 offset:20480
	ds_read_b128 v[214:217], v150 offset:21504
	ds_read_b128 v[218:221], v150 offset:22528
	ds_read_b128 v[222:225], v150 offset:23552
	global_load_lds_dwordx4 v[154:155], off
	s_add_i32 m0, s76, 0x2000
	s_add_u32 s76, s46, 0x40000
	v_lshl_add_u64 v[226:227], s[46:47], 0, v[128:129]
	s_addc_u32 s77, s47, 0
	s_add_i32 s78, s65, s52
	global_load_lds_dwordx4 v[226:227], off
	v_lshl_add_u64 v[228:229], s[76:77], 0, v[132:133]
	s_mov_b32 m0, s78
	v_lshl_add_u64 v[230:231], s[48:49], 0, v[130:131]
	global_load_lds_dwordx4 v[228:229], off
	v_lshl_add_u64 v[228:229], s[76:77], 0, v[128:129]
	s_add_i32 m0, s78, 0x2000
	s_nop 0
	global_load_lds_dwordx4 v[228:229], off
	v_lshl_add_u64 v[228:229], s[48:49], 0, v[134:135]
	s_mov_b32 m0, s55
	s_nop 0
	global_load_lds_dwordx4 v[228:229], off
	s_mov_b32 m0, s56
	s_nop 0
	global_load_lds_dwordx4 v[230:231], off
	s_waitcnt vmcnt(8)
	s_waitcnt lgkmcnt(0)
	s_barrier
	s_setprio 1
	s_waitcnt lgkmcnt(0)
	v_mfma_f32_16x16x32_bf16 v[60:63], v[160:163], v[194:197], 0
	v_mfma_f32_16x16x32_bf16 v[52:55], v[168:171], v[194:197], 0
	v_mfma_f32_16x16x32_bf16 v[44:47], v[160:163], v[202:205], 0
	v_mfma_f32_16x16x32_bf16 v[36:39], v[168:171], v[202:205], 0
	v_mfma_f32_16x16x32_bf16 v[28:31], v[160:163], v[210:213], 0
	v_mfma_f32_16x16x32_bf16 v[20:23], v[168:171], v[210:213], 0
	v_mfma_f32_16x16x32_bf16 v[12:15], v[160:163], v[218:221], 0
	v_mfma_f32_16x16x32_bf16 v[4:7], v[168:171], v[218:221], 0
	v_mfma_f32_16x16x32_bf16 v[60:63], v[164:167], v[198:201], v[60:63]
	v_mfma_f32_16x16x32_bf16 v[52:55], v[172:175], v[198:201], v[52:55]
	v_mfma_f32_16x16x32_bf16 v[44:47], v[164:167], v[206:209], v[44:47]
	v_mfma_f32_16x16x32_bf16 v[36:39], v[172:175], v[206:209], v[36:39]
	v_mfma_f32_16x16x32_bf16 v[28:31], v[164:167], v[214:217], v[28:31]
	v_mfma_f32_16x16x32_bf16 v[20:23], v[172:175], v[214:217], v[20:23]
	v_mfma_f32_16x16x32_bf16 v[12:15], v[164:167], v[222:225], v[12:15]
	v_mfma_f32_16x16x32_bf16 v[4:7], v[172:175], v[222:225], v[4:7]
	s_setprio 0
	s_setprio 1
	v_mfma_f32_16x16x32_bf16 v[56:59], v[176:179], v[194:197], 0
	v_mfma_f32_16x16x32_bf16 v[48:51], v[186:189], v[194:197], 0
	v_mfma_f32_16x16x32_bf16 v[40:43], v[176:179], v[202:205], 0
	v_mfma_f32_16x16x32_bf16 v[32:35], v[186:189], v[202:205], 0
	v_mfma_f32_16x16x32_bf16 v[24:27], v[176:179], v[210:213], 0
	v_mfma_f32_16x16x32_bf16 v[16:19], v[186:189], v[210:213], 0
	v_mfma_f32_16x16x32_bf16 v[8:11], v[176:179], v[218:221], 0
	v_mfma_f32_16x16x32_bf16 v[0:3], v[186:189], v[218:221], 0
	v_mfma_f32_16x16x32_bf16 v[56:59], v[180:183], v[198:201], v[56:59]
	v_mfma_f32_16x16x32_bf16 v[48:51], v[190:193], v[198:201], v[48:51]
	v_mfma_f32_16x16x32_bf16 v[40:43], v[180:183], v[206:209], v[40:43]
	v_mfma_f32_16x16x32_bf16 v[32:35], v[190:193], v[206:209], v[32:35]
	v_mfma_f32_16x16x32_bf16 v[24:27], v[180:183], v[214:217], v[24:27]
	v_mfma_f32_16x16x32_bf16 v[16:19], v[190:193], v[214:217], v[16:19]
	v_mfma_f32_16x16x32_bf16 v[8:11], v[180:183], v[222:225], v[8:11]
	v_mfma_f32_16x16x32_bf16 v[0:3], v[190:193], v[222:225], v[0:3]
	s_setprio 0
	s_barrier
	s_add_i32 s76, 0, 0x18000
	v_add_u32_e32 v153, s76, v147
	s_add_i32 s77, 0, 0x1c000
	ds_read_b128 v[160:163], v153
	ds_read_b128 v[164:167], v153 offset:1024
	ds_read_b128 v[168:171], v153 offset:2048
	ds_read_b128 v[172:175], v153 offset:3072
	v_add_u32_e32 v153, s77, v147
	ds_read_b128 v[176:179], v153
	ds_read_b128 v[180:183], v153 offset:1024
	ds_read_b128 v[186:189], v153 offset:2048
	ds_read_b128 v[190:193], v153 offset:3072
	s_add_u32 s48, s48, 0x40000
	s_addc_u32 s49, s49, 0
	s_mov_b32 m0, s57
	v_lshl_add_u64 v[232:233], s[48:49], 0, v[134:135]
	ds_read_b128 v[194:197], v150 offset:32768
	ds_read_b128 v[198:201], v150 offset:33792
	ds_read_b128 v[202:205], v150 offset:34816
	ds_read_b128 v[206:209], v150 offset:35840
	ds_read_b128 v[210:213], v150 offset:36864
	ds_read_b128 v[214:217], v150 offset:37888
	ds_read_b128 v[218:221], v150 offset:38912
	ds_read_b128 v[222:225], v150 offset:39936
	global_load_lds_dwordx4 v[232:233], off
	v_lshl_add_u64 v[232:233], s[48:49], 0, v[130:131]
	s_mov_b32 m0, s58
	s_nop 0
	global_load_lds_dwordx4 v[232:233], off
	s_waitcnt vmcnt(8)
	s_waitcnt lgkmcnt(0)
	s_barrier
	s_setprio 1
	s_waitcnt lgkmcnt(0)
	v_mfma_f32_16x16x32_bf16 v[124:127], v[160:163], v[194:197], v[124:127]
	v_mfma_f32_16x16x32_bf16 v[124:127], v[164:167], v[198:201], v[124:127]
	v_mfma_f32_16x16x32_bf16 v[116:119], v[168:171], v[194:197], v[116:119]
	v_mfma_f32_16x16x32_bf16 v[116:119], v[172:175], v[198:201], v[116:119]
	v_mfma_f32_16x16x32_bf16 v[108:111], v[160:163], v[202:205], v[108:111]
	v_mfma_f32_16x16x32_bf16 v[108:111], v[164:167], v[206:209], v[108:111]
	v_mfma_f32_16x16x32_bf16 v[100:103], v[168:171], v[202:205], v[100:103]
	v_mfma_f32_16x16x32_bf16 v[100:103], v[172:175], v[206:209], v[100:103]
	v_mfma_f32_16x16x32_bf16 v[92:95], v[160:163], v[210:213], v[92:95]
	v_mfma_f32_16x16x32_bf16 v[92:95], v[164:167], v[214:217], v[92:95]
	v_mfma_f32_16x16x32_bf16 v[84:87], v[168:171], v[210:213], v[84:87]
	v_mfma_f32_16x16x32_bf16 v[84:87], v[172:175], v[214:217], v[84:87]
	v_mfma_f32_16x16x32_bf16 v[76:79], v[160:163], v[218:221], v[76:79]
	v_mfma_f32_16x16x32_bf16 v[76:79], v[164:167], v[222:225], v[76:79]
	v_mfma_f32_16x16x32_bf16 v[68:71], v[168:171], v[218:221], v[68:71]
	v_mfma_f32_16x16x32_bf16 v[68:71], v[172:175], v[222:225], v[68:71]
	s_setprio 0
	s_setprio 1
	v_mfma_f32_16x16x32_bf16 v[120:123], v[176:179], v[194:197], v[120:123]
	v_mfma_f32_16x16x32_bf16 v[120:123], v[180:183], v[198:201], v[120:123]
	v_mfma_f32_16x16x32_bf16 v[112:115], v[186:189], v[194:197], v[112:115]
	v_mfma_f32_16x16x32_bf16 v[112:115], v[190:193], v[198:201], v[112:115]
	v_mfma_f32_16x16x32_bf16 v[104:107], v[176:179], v[202:205], v[104:107]
	v_mfma_f32_16x16x32_bf16 v[104:107], v[180:183], v[206:209], v[104:107]
	v_mfma_f32_16x16x32_bf16 v[96:99], v[186:189], v[202:205], v[96:99]
	v_mfma_f32_16x16x32_bf16 v[96:99], v[190:193], v[206:209], v[96:99]
	v_mfma_f32_16x16x32_bf16 v[88:91], v[176:179], v[210:213], v[88:91]
	v_mfma_f32_16x16x32_bf16 v[88:91], v[180:183], v[214:217], v[88:91]
	v_mfma_f32_16x16x32_bf16 v[80:83], v[186:189], v[210:213], v[80:83]
	v_mfma_f32_16x16x32_bf16 v[80:83], v[190:193], v[214:217], v[80:83]
	v_mfma_f32_16x16x32_bf16 v[72:75], v[176:179], v[218:221], v[72:75]
	v_mfma_f32_16x16x32_bf16 v[72:75], v[180:183], v[222:225], v[72:75]
	v_mfma_f32_16x16x32_bf16 v[64:67], v[186:189], v[218:221], v[64:67]
	v_mfma_f32_16x16x32_bf16 v[64:67], v[190:193], v[222:225], v[64:67]
	s_setprio 0
	s_barrier
	s_add_i32 s48, s76, s52
	v_lshl_add_u64 v[154:155], v[154:155], 0, s[14:15]
	s_mov_b32 m0, s48
	ds_read_b128 v[194:197], v150 offset:49152
	ds_read_b128 v[198:201], v150 offset:50176
	ds_read_b128 v[202:205], v150 offset:51200
	ds_read_b128 v[206:209], v150 offset:52224
	ds_read_b128 v[210:213], v150 offset:53248
	ds_read_b128 v[214:217], v150 offset:54272
	ds_read_b128 v[218:221], v150 offset:55296
	ds_read_b128 v[222:225], v150 offset:56320
	global_load_lds_dwordx4 v[154:155], off
	s_add_i32 m0, s48, 0x2000
	s_add_u32 s46, s46, 0x40080
	v_lshl_add_u64 v[154:155], v[226:227], 0, s[14:15]
	s_addc_u32 s47, s47, 0
	s_add_i32 s48, s77, s52
	global_load_lds_dwordx4 v[154:155], off
	v_lshl_add_u64 v[154:155], s[46:47], 0, v[132:133]
	s_mov_b32 m0, s48
	s_nop 0
	global_load_lds_dwordx4 v[154:155], off
	v_lshl_add_u64 v[154:155], s[46:47], 0, v[128:129]
	s_add_i32 m0, s48, 0x2000
	s_nop 0
	global_load_lds_dwordx4 v[154:155], off
	v_lshl_add_u64 v[154:155], v[228:229], 0, s[14:15]
	s_mov_b32 m0, s60
	s_nop 0
	global_load_lds_dwordx4 v[154:155], off
	v_lshl_add_u64 v[154:155], v[230:231], 0, s[14:15]
	s_mov_b32 m0, s61
	s_nop 0
	global_load_lds_dwordx4 v[154:155], off
	s_waitcnt vmcnt(8)
	s_waitcnt lgkmcnt(0)
	s_barrier
	s_setprio 1
	s_waitcnt lgkmcnt(0)
	v_mfma_f32_16x16x32_bf16 v[60:63], v[160:163], v[194:197], v[60:63]
	v_mfma_f32_16x16x32_bf16 v[60:63], v[164:167], v[198:201], v[60:63]
	v_mfma_f32_16x16x32_bf16 v[52:55], v[168:171], v[194:197], v[52:55]
	v_mfma_f32_16x16x32_bf16 v[52:55], v[172:175], v[198:201], v[52:55]
	v_mfma_f32_16x16x32_bf16 v[44:47], v[160:163], v[202:205], v[44:47]
	v_mfma_f32_16x16x32_bf16 v[44:47], v[164:167], v[206:209], v[44:47]
	v_mfma_f32_16x16x32_bf16 v[36:39], v[168:171], v[202:205], v[36:39]
	v_mfma_f32_16x16x32_bf16 v[36:39], v[172:175], v[206:209], v[36:39]
	v_mfma_f32_16x16x32_bf16 v[28:31], v[160:163], v[210:213], v[28:31]
	v_mfma_f32_16x16x32_bf16 v[28:31], v[164:167], v[214:217], v[28:31]
	v_mfma_f32_16x16x32_bf16 v[20:23], v[168:171], v[210:213], v[20:23]
	v_mfma_f32_16x16x32_bf16 v[20:23], v[172:175], v[214:217], v[20:23]
	v_mfma_f32_16x16x32_bf16 v[12:15], v[160:163], v[218:221], v[12:15]
	v_mfma_f32_16x16x32_bf16 v[12:15], v[164:167], v[222:225], v[12:15]
	v_mfma_f32_16x16x32_bf16 v[4:7], v[168:171], v[218:221], v[4:7]
	v_mfma_f32_16x16x32_bf16 v[4:7], v[172:175], v[222:225], v[4:7]
	s_setprio 0
	s_setprio 1
	v_mfma_f32_16x16x32_bf16 v[56:59], v[176:179], v[194:197], v[56:59]
	v_mfma_f32_16x16x32_bf16 v[56:59], v[180:183], v[198:201], v[56:59]
	v_mfma_f32_16x16x32_bf16 v[48:51], v[186:189], v[194:197], v[48:51]
	v_mfma_f32_16x16x32_bf16 v[48:51], v[190:193], v[198:201], v[48:51]
	v_mfma_f32_16x16x32_bf16 v[40:43], v[176:179], v[202:205], v[40:43]
	v_mfma_f32_16x16x32_bf16 v[40:43], v[180:183], v[206:209], v[40:43]
	v_mfma_f32_16x16x32_bf16 v[32:35], v[186:189], v[202:205], v[32:35]
	v_mfma_f32_16x16x32_bf16 v[32:35], v[190:193], v[206:209], v[32:35]
	v_mfma_f32_16x16x32_bf16 v[24:27], v[176:179], v[210:213], v[24:27]
	v_mfma_f32_16x16x32_bf16 v[24:27], v[180:183], v[214:217], v[24:27]
	v_mfma_f32_16x16x32_bf16 v[16:19], v[186:189], v[210:213], v[16:19]
	v_mfma_f32_16x16x32_bf16 v[16:19], v[190:193], v[214:217], v[16:19]
	v_mfma_f32_16x16x32_bf16 v[8:11], v[176:179], v[218:221], v[8:11]
	v_mfma_f32_16x16x32_bf16 v[8:11], v[180:183], v[222:225], v[8:11]
	v_mfma_f32_16x16x32_bf16 v[0:3], v[186:189], v[218:221], v[0:3]
	v_mfma_f32_16x16x32_bf16 v[0:3], v[190:193], v[222:225], v[0:3]
	s_setprio 0
	s_barrier
	s_add_i32 s75, s75, 2
	s_add_u32 s71, s71, 0x100
	s_addc_u32 s74, s74, 0
	s_add_u32 s44, s44, 0x100
	s_addc_u32 s45, s45, 0
	s_branch .LBB0_76
.LBB0_75:
	v_add_u32_e32 v153, s64, v147
	ds_read_b128 v[160:163], v153
	ds_read_b128 v[164:167], v153 offset:1024
	ds_read_b128 v[168:171], v153 offset:2048
	ds_read_b128 v[172:175], v153 offset:3072
	v_add_u32_e32 v153, s65, v147
	ds_read_b128 v[176:179], v153
	ds_read_b128 v[180:183], v153 offset:1024
	ds_read_b128 v[186:189], v153 offset:2048
	ds_read_b128 v[190:193], v153 offset:3072
	s_add_u32 s48, s44, 0xfffc0080
	s_addc_u32 s49, s45, -1
	s_and_b64 s[46:47], s[46:47], exec
	s_cselect_b32 s49, s27, s49
	s_cselect_b32 s48, s68, s48
	s_cselect_b32 s47, s69, s74
	s_cselect_b32 s46, s70, s71
	v_lshl_add_u64 v[154:155], s[44:45], 0, v[138:139]
	s_add_i32 m0, s55, 0xc000
	ds_read_b128 v[194:197], v150
	ds_read_b128 v[198:201], v150 offset:1024
	ds_read_b128 v[202:205], v150 offset:2048
	ds_read_b128 v[206:209], v150 offset:3072
	ds_read_b128 v[210:213], v150 offset:4096
	ds_read_b128 v[214:217], v150 offset:5120
	ds_read_b128 v[218:221], v150 offset:6144
	ds_read_b128 v[222:225], v150 offset:7168
	global_load_lds_dwordx4 v[154:155], off
	v_lshl_add_u64 v[154:155], s[44:45], 0, v[136:137]
	s_add_i32 m0, s55, 0xe000
	s_nop 0
	global_load_lds_dwordx4 v[154:155], off
	s_waitcnt vmcnt(8)
	s_waitcnt lgkmcnt(0)
	s_barrier
	s_setprio 1
	s_waitcnt lgkmcnt(0)
	v_mfma_f32_16x16x32_bf16 v[124:127], v[160:163], v[194:197], v[124:127]
	v_mfma_f32_16x16x32_bf16 v[124:127], v[164:167], v[198:201], v[124:127]
	v_mfma_f32_16x16x32_bf16 v[116:119], v[168:171], v[194:197], v[116:119]
	v_mfma_f32_16x16x32_bf16 v[116:119], v[172:175], v[198:201], v[116:119]
	v_mfma_f32_16x16x32_bf16 v[108:111], v[160:163], v[202:205], v[108:111]
	v_mfma_f32_16x16x32_bf16 v[108:111], v[164:167], v[206:209], v[108:111]
	v_mfma_f32_16x16x32_bf16 v[100:103], v[168:171], v[202:205], v[100:103]
	v_mfma_f32_16x16x32_bf16 v[100:103], v[172:175], v[206:209], v[100:103]
	v_mfma_f32_16x16x32_bf16 v[92:95], v[160:163], v[210:213], v[92:95]
	v_mfma_f32_16x16x32_bf16 v[92:95], v[164:167], v[214:217], v[92:95]
	v_mfma_f32_16x16x32_bf16 v[84:87], v[168:171], v[210:213], v[84:87]
	v_mfma_f32_16x16x32_bf16 v[84:87], v[172:175], v[214:217], v[84:87]
	v_mfma_f32_16x16x32_bf16 v[76:79], v[160:163], v[218:221], v[76:79]
	v_mfma_f32_16x16x32_bf16 v[76:79], v[164:167], v[222:225], v[76:79]
	v_mfma_f32_16x16x32_bf16 v[68:71], v[168:171], v[218:221], v[68:71]
	v_mfma_f32_16x16x32_bf16 v[68:71], v[172:175], v[222:225], v[68:71]
	s_setprio 0
	s_setprio 1
	v_mfma_f32_16x16x32_bf16 v[120:123], v[176:179], v[194:197], v[120:123]
	v_mfma_f32_16x16x32_bf16 v[120:123], v[180:183], v[198:201], v[120:123]
	v_mfma_f32_16x16x32_bf16 v[112:115], v[186:189], v[194:197], v[112:115]
	v_mfma_f32_16x16x32_bf16 v[112:115], v[190:193], v[198:201], v[112:115]
	v_mfma_f32_16x16x32_bf16 v[104:107], v[176:179], v[202:205], v[104:107]
	v_mfma_f32_16x16x32_bf16 v[104:107], v[180:183], v[206:209], v[104:107]
	v_mfma_f32_16x16x32_bf16 v[96:99], v[186:189], v[202:205], v[96:99]
	v_mfma_f32_16x16x32_bf16 v[96:99], v[190:193], v[206:209], v[96:99]
	v_mfma_f32_16x16x32_bf16 v[88:91], v[176:179], v[210:213], v[88:91]
	v_mfma_f32_16x16x32_bf16 v[88:91], v[180:183], v[214:217], v[88:91]
	v_mfma_f32_16x16x32_bf16 v[80:83], v[186:189], v[210:213], v[80:83]
	v_mfma_f32_16x16x32_bf16 v[80:83], v[190:193], v[214:217], v[80:83]
	v_mfma_f32_16x16x32_bf16 v[72:75], v[176:179], v[218:221], v[72:75]
	v_mfma_f32_16x16x32_bf16 v[72:75], v[180:183], v[222:225], v[72:75]
	v_mfma_f32_16x16x32_bf16 v[64:67], v[186:189], v[218:221], v[64:67]
	v_mfma_f32_16x16x32_bf16 v[64:67], v[190:193], v[222:225], v[64:67]
	s_setprio 0
	s_barrier
	s_add_i32 s76, s64, s52
	v_lshl_add_u64 v[154:155], s[46:47], 0, v[132:133]
	s_mov_b32 m0, s76
	ds_read_b128 v[194:197], v150 offset:16384
	ds_read_b128 v[198:201], v150 offset:17408
	ds_read_b128 v[202:205], v150 offset:18432
	ds_read_b128 v[206:209], v150 offset:19456
	ds_read_b128 v[210:213], v150 offset:20480
	ds_read_b128 v[214:217], v150 offset:21504
	ds_read_b128 v[218:221], v150 offset:22528
	ds_read_b128 v[222:225], v150 offset:23552
	global_load_lds_dwordx4 v[154:155], off
	s_add_i32 m0, s76, 0x2000
	s_add_u32 s76, s46, 0x40000
	v_lshl_add_u64 v[226:227], s[46:47], 0, v[128:129]
	s_addc_u32 s77, s47, 0
	s_add_i32 s78, s65, s52
	global_load_lds_dwordx4 v[226:227], off
	v_lshl_add_u64 v[228:229], s[76:77], 0, v[132:133]
	s_mov_b32 m0, s78
	v_lshl_add_u64 v[230:231], s[48:49], 0, v[130:131]
	global_load_lds_dwordx4 v[228:229], off
	v_lshl_add_u64 v[228:229], s[76:77], 0, v[128:129]
	s_add_i32 m0, s78, 0x2000
	s_nop 0
	global_load_lds_dwordx4 v[228:229], off
	v_lshl_add_u64 v[228:229], s[48:49], 0, v[134:135]
	s_mov_b32 m0, s55
	s_nop 0
	global_load_lds_dwordx4 v[228:229], off
	s_mov_b32 m0, s56
	s_nop 0
	global_load_lds_dwordx4 v[230:231], off
	s_waitcnt vmcnt(8)
	s_waitcnt lgkmcnt(0)
	s_barrier
	s_setprio 1
	s_waitcnt lgkmcnt(0)
	v_mfma_f32_16x16x32_bf16 v[60:63], v[160:163], v[194:197], v[60:63]
	v_mfma_f32_16x16x32_bf16 v[60:63], v[164:167], v[198:201], v[60:63]
	v_mfma_f32_16x16x32_bf16 v[52:55], v[168:171], v[194:197], v[52:55]
	v_mfma_f32_16x16x32_bf16 v[52:55], v[172:175], v[198:201], v[52:55]
	v_mfma_f32_16x16x32_bf16 v[44:47], v[160:163], v[202:205], v[44:47]
	v_mfma_f32_16x16x32_bf16 v[44:47], v[164:167], v[206:209], v[44:47]
	v_mfma_f32_16x16x32_bf16 v[36:39], v[168:171], v[202:205], v[36:39]
	v_mfma_f32_16x16x32_bf16 v[36:39], v[172:175], v[206:209], v[36:39]
	v_mfma_f32_16x16x32_bf16 v[28:31], v[160:163], v[210:213], v[28:31]
	v_mfma_f32_16x16x32_bf16 v[28:31], v[164:167], v[214:217], v[28:31]
	v_mfma_f32_16x16x32_bf16 v[20:23], v[168:171], v[210:213], v[20:23]
	v_mfma_f32_16x16x32_bf16 v[20:23], v[172:175], v[214:217], v[20:23]
	v_mfma_f32_16x16x32_bf16 v[12:15], v[160:163], v[218:221], v[12:15]
	v_mfma_f32_16x16x32_bf16 v[12:15], v[164:167], v[222:225], v[12:15]
	v_mfma_f32_16x16x32_bf16 v[4:7], v[168:171], v[218:221], v[4:7]
	v_mfma_f32_16x16x32_bf16 v[4:7], v[172:175], v[222:225], v[4:7]
	s_setprio 0
	s_setprio 1
	v_mfma_f32_16x16x32_bf16 v[56:59], v[176:179], v[194:197], v[56:59]
	v_mfma_f32_16x16x32_bf16 v[56:59], v[180:183], v[198:201], v[56:59]
	v_mfma_f32_16x16x32_bf16 v[48:51], v[186:189], v[194:197], v[48:51]
	v_mfma_f32_16x16x32_bf16 v[48:51], v[190:193], v[198:201], v[48:51]
	v_mfma_f32_16x16x32_bf16 v[40:43], v[176:179], v[202:205], v[40:43]
	v_mfma_f32_16x16x32_bf16 v[40:43], v[180:183], v[206:209], v[40:43]
	v_mfma_f32_16x16x32_bf16 v[32:35], v[186:189], v[202:205], v[32:35]
	v_mfma_f32_16x16x32_bf16 v[32:35], v[190:193], v[206:209], v[32:35]
	v_mfma_f32_16x16x32_bf16 v[24:27], v[176:179], v[210:213], v[24:27]
	v_mfma_f32_16x16x32_bf16 v[24:27], v[180:183], v[214:217], v[24:27]
	v_mfma_f32_16x16x32_bf16 v[16:19], v[186:189], v[210:213], v[16:19]
	v_mfma_f32_16x16x32_bf16 v[16:19], v[190:193], v[214:217], v[16:19]
	v_mfma_f32_16x16x32_bf16 v[8:11], v[176:179], v[218:221], v[8:11]
	v_mfma_f32_16x16x32_bf16 v[8:11], v[180:183], v[222:225], v[8:11]
	v_mfma_f32_16x16x32_bf16 v[0:3], v[186:189], v[218:221], v[0:3]
	v_mfma_f32_16x16x32_bf16 v[0:3], v[190:193], v[222:225], v[0:3]
	s_setprio 0
	s_barrier
	s_add_i32 s76, 0, 0x18000
	v_add_u32_e32 v153, s76, v147
	s_add_i32 s77, 0, 0x1c000
	ds_read_b128 v[160:163], v153
	ds_read_b128 v[164:167], v153 offset:1024
	ds_read_b128 v[168:171], v153 offset:2048
	ds_read_b128 v[172:175], v153 offset:3072
	v_add_u32_e32 v153, s77, v147
	ds_read_b128 v[176:179], v153
	ds_read_b128 v[180:183], v153 offset:1024
	ds_read_b128 v[186:189], v153 offset:2048
	ds_read_b128 v[190:193], v153 offset:3072
	s_add_u32 s48, s48, 0x40000
	s_addc_u32 s49, s49, 0
	s_mov_b32 m0, s57
	v_lshl_add_u64 v[232:233], s[48:49], 0, v[134:135]
	ds_read_b128 v[194:197], v150 offset:32768
	ds_read_b128 v[198:201], v150 offset:33792
	ds_read_b128 v[202:205], v150 offset:34816
	ds_read_b128 v[206:209], v150 offset:35840
	ds_read_b128 v[210:213], v150 offset:36864
	ds_read_b128 v[214:217], v150 offset:37888
	ds_read_b128 v[218:221], v150 offset:38912
	ds_read_b128 v[222:225], v150 offset:39936
	global_load_lds_dwordx4 v[232:233], off
	v_lshl_add_u64 v[232:233], s[48:49], 0, v[130:131]
	s_mov_b32 m0, s58
	s_nop 0
	global_load_lds_dwordx4 v[232:233], off
	s_waitcnt vmcnt(8)
	s_waitcnt lgkmcnt(0)
	s_barrier
	s_setprio 1
	s_waitcnt lgkmcnt(0)
	v_mfma_f32_16x16x32_bf16 v[124:127], v[160:163], v[194:197], v[124:127]
	v_mfma_f32_16x16x32_bf16 v[124:127], v[164:167], v[198:201], v[124:127]
	v_mfma_f32_16x16x32_bf16 v[116:119], v[168:171], v[194:197], v[116:119]
	v_mfma_f32_16x16x32_bf16 v[116:119], v[172:175], v[198:201], v[116:119]
	v_mfma_f32_16x16x32_bf16 v[108:111], v[160:163], v[202:205], v[108:111]
	v_mfma_f32_16x16x32_bf16 v[108:111], v[164:167], v[206:209], v[108:111]
	v_mfma_f32_16x16x32_bf16 v[100:103], v[168:171], v[202:205], v[100:103]
	v_mfma_f32_16x16x32_bf16 v[100:103], v[172:175], v[206:209], v[100:103]
	v_mfma_f32_16x16x32_bf16 v[92:95], v[160:163], v[210:213], v[92:95]
	v_mfma_f32_16x16x32_bf16 v[92:95], v[164:167], v[214:217], v[92:95]
	v_mfma_f32_16x16x32_bf16 v[84:87], v[168:171], v[210:213], v[84:87]
	v_mfma_f32_16x16x32_bf16 v[84:87], v[172:175], v[214:217], v[84:87]
	v_mfma_f32_16x16x32_bf16 v[76:79], v[160:163], v[218:221], v[76:79]
	v_mfma_f32_16x16x32_bf16 v[76:79], v[164:167], v[222:225], v[76:79]
	v_mfma_f32_16x16x32_bf16 v[68:71], v[168:171], v[218:221], v[68:71]
	v_mfma_f32_16x16x32_bf16 v[68:71], v[172:175], v[222:225], v[68:71]
	s_setprio 0
	s_setprio 1
	v_mfma_f32_16x16x32_bf16 v[120:123], v[176:179], v[194:197], v[120:123]
	v_mfma_f32_16x16x32_bf16 v[120:123], v[180:183], v[198:201], v[120:123]
	v_mfma_f32_16x16x32_bf16 v[112:115], v[186:189], v[194:197], v[112:115]
	v_mfma_f32_16x16x32_bf16 v[112:115], v[190:193], v[198:201], v[112:115]
	v_mfma_f32_16x16x32_bf16 v[104:107], v[176:179], v[202:205], v[104:107]
	v_mfma_f32_16x16x32_bf16 v[104:107], v[180:183], v[206:209], v[104:107]
	v_mfma_f32_16x16x32_bf16 v[96:99], v[186:189], v[202:205], v[96:99]
	v_mfma_f32_16x16x32_bf16 v[96:99], v[190:193], v[206:209], v[96:99]
	v_mfma_f32_16x16x32_bf16 v[88:91], v[176:179], v[210:213], v[88:91]
	v_mfma_f32_16x16x32_bf16 v[88:91], v[180:183], v[214:217], v[88:91]
	v_mfma_f32_16x16x32_bf16 v[80:83], v[186:189], v[210:213], v[80:83]
	v_mfma_f32_16x16x32_bf16 v[80:83], v[190:193], v[214:217], v[80:83]
	v_mfma_f32_16x16x32_bf16 v[72:75], v[176:179], v[218:221], v[72:75]
	v_mfma_f32_16x16x32_bf16 v[72:75], v[180:183], v[222:225], v[72:75]
	v_mfma_f32_16x16x32_bf16 v[64:67], v[186:189], v[218:221], v[64:67]
	v_mfma_f32_16x16x32_bf16 v[64:67], v[190:193], v[222:225], v[64:67]
	s_setprio 0
	s_barrier
	s_add_i32 s48, s76, s52
	v_lshl_add_u64 v[154:155], v[154:155], 0, s[14:15]
	s_mov_b32 m0, s48
	ds_read_b128 v[194:197], v150 offset:49152
	ds_read_b128 v[198:201], v150 offset:50176
	ds_read_b128 v[202:205], v150 offset:51200
	ds_read_b128 v[206:209], v150 offset:52224
	ds_read_b128 v[210:213], v150 offset:53248
	ds_read_b128 v[214:217], v150 offset:54272
	ds_read_b128 v[218:221], v150 offset:55296
	ds_read_b128 v[222:225], v150 offset:56320
	global_load_lds_dwordx4 v[154:155], off
	s_add_i32 m0, s48, 0x2000
	s_add_u32 s46, s46, 0x40080
	v_lshl_add_u64 v[154:155], v[226:227], 0, s[14:15]
	s_addc_u32 s47, s47, 0
	s_add_i32 s48, s77, s52
	global_load_lds_dwordx4 v[154:155], off
	v_lshl_add_u64 v[154:155], s[46:47], 0, v[132:133]
	s_mov_b32 m0, s48
	s_nop 0
	global_load_lds_dwordx4 v[154:155], off
	v_lshl_add_u64 v[154:155], s[46:47], 0, v[128:129]
	s_add_i32 m0, s48, 0x2000
	s_nop 0
	global_load_lds_dwordx4 v[154:155], off
	v_lshl_add_u64 v[154:155], v[228:229], 0, s[14:15]
	s_mov_b32 m0, s60
	s_nop 0
	global_load_lds_dwordx4 v[154:155], off
	v_lshl_add_u64 v[154:155], v[230:231], 0, s[14:15]
	s_mov_b32 m0, s61
	s_nop 0
	global_load_lds_dwordx4 v[154:155], off
	s_waitcnt vmcnt(8)
	s_waitcnt lgkmcnt(0)
	s_barrier
	s_setprio 1
	s_waitcnt lgkmcnt(0)
	v_mfma_f32_16x16x32_bf16 v[60:63], v[160:163], v[194:197], v[60:63]
	v_mfma_f32_16x16x32_bf16 v[60:63], v[164:167], v[198:201], v[60:63]
	v_mfma_f32_16x16x32_bf16 v[52:55], v[168:171], v[194:197], v[52:55]
	v_mfma_f32_16x16x32_bf16 v[52:55], v[172:175], v[198:201], v[52:55]
	v_mfma_f32_16x16x32_bf16 v[44:47], v[160:163], v[202:205], v[44:47]
	v_mfma_f32_16x16x32_bf16 v[44:47], v[164:167], v[206:209], v[44:47]
	v_mfma_f32_16x16x32_bf16 v[36:39], v[168:171], v[202:205], v[36:39]
	v_mfma_f32_16x16x32_bf16 v[36:39], v[172:175], v[206:209], v[36:39]
	v_mfma_f32_16x16x32_bf16 v[28:31], v[160:163], v[210:213], v[28:31]
	v_mfma_f32_16x16x32_bf16 v[28:31], v[164:167], v[214:217], v[28:31]
	v_mfma_f32_16x16x32_bf16 v[20:23], v[168:171], v[210:213], v[20:23]
	v_mfma_f32_16x16x32_bf16 v[20:23], v[172:175], v[214:217], v[20:23]
	v_mfma_f32_16x16x32_bf16 v[12:15], v[160:163], v[218:221], v[12:15]
	v_mfma_f32_16x16x32_bf16 v[12:15], v[164:167], v[222:225], v[12:15]
	v_mfma_f32_16x16x32_bf16 v[4:7], v[168:171], v[218:221], v[4:7]
	v_mfma_f32_16x16x32_bf16 v[4:7], v[172:175], v[222:225], v[4:7]
	s_setprio 0
	s_setprio 1
	v_mfma_f32_16x16x32_bf16 v[56:59], v[176:179], v[194:197], v[56:59]
	v_mfma_f32_16x16x32_bf16 v[56:59], v[180:183], v[198:201], v[56:59]
	v_mfma_f32_16x16x32_bf16 v[48:51], v[186:189], v[194:197], v[48:51]
	v_mfma_f32_16x16x32_bf16 v[48:51], v[190:193], v[198:201], v[48:51]
	v_mfma_f32_16x16x32_bf16 v[40:43], v[176:179], v[202:205], v[40:43]
	v_mfma_f32_16x16x32_bf16 v[40:43], v[180:183], v[206:209], v[40:43]
	v_mfma_f32_16x16x32_bf16 v[32:35], v[186:189], v[202:205], v[32:35]
	v_mfma_f32_16x16x32_bf16 v[32:35], v[190:193], v[206:209], v[32:35]
	v_mfma_f32_16x16x32_bf16 v[24:27], v[176:179], v[210:213], v[24:27]
	v_mfma_f32_16x16x32_bf16 v[24:27], v[180:183], v[214:217], v[24:27]
	v_mfma_f32_16x16x32_bf16 v[16:19], v[186:189], v[210:213], v[16:19]
	v_mfma_f32_16x16x32_bf16 v[16:19], v[190:193], v[214:217], v[16:19]
	v_mfma_f32_16x16x32_bf16 v[8:11], v[176:179], v[218:221], v[8:11]
	v_mfma_f32_16x16x32_bf16 v[8:11], v[180:183], v[222:225], v[8:11]
	v_mfma_f32_16x16x32_bf16 v[0:3], v[186:189], v[218:221], v[0:3]
	v_mfma_f32_16x16x32_bf16 v[0:3], v[190:193], v[222:225], v[0:3]
	s_setprio 0
	s_barrier
	s_add_i32 s75, s75, 2
	s_add_u32 s71, s71, 0x100
	s_addc_u32 s74, s74, 0
	s_add_u32 s44, s44, 0x100
	s_addc_u32 s45, s45, 0
	s_cmp_gt_u32 s75, 13
	s_cbranch_scc1 .LBB0_78

.Llast_0:
	v_add_u32_e32 v153, s64, v147
	ds_read_b128 v[160:163], v153
	ds_read_b128 v[164:167], v153 offset:1024
	ds_read_b128 v[168:171], v153 offset:2048
	ds_read_b128 v[172:175], v153 offset:3072
	v_add_u32_e32 v153, s65, v147
	ds_read_b128 v[176:179], v153
	ds_read_b128 v[180:183], v153 offset:1024
	ds_read_b128 v[186:189], v153 offset:2048
	ds_read_b128 v[190:193], v153 offset:3072
	s_add_u32 s48, s44, 0xfffc0080
	s_addc_u32 s49, s45, -1
	s_and_b64 s[46:47], s[46:47], exec
	s_cselect_b32 s49, s27, s49
	s_cselect_b32 s48, s68, s48
	s_cselect_b32 s47, s69, s74
	s_cselect_b32 s46, s70, s71
	v_lshl_add_u64 v[154:155], s[44:45], 0, v[138:139]
	s_add_i32 m0, s55, 0xc000
	ds_read_b128 v[194:197], v150
	ds_read_b128 v[198:201], v150 offset:1024
	ds_read_b128 v[202:205], v150 offset:2048
	ds_read_b128 v[206:209], v150 offset:3072
	ds_read_b128 v[210:213], v150 offset:4096
	ds_read_b128 v[214:217], v150 offset:5120
	ds_read_b128 v[218:221], v150 offset:6144
	ds_read_b128 v[222:225], v150 offset:7168
	global_load_lds_dwordx4 v[154:155], off
	v_lshl_add_u64 v[154:155], s[44:45], 0, v[136:137]
	s_add_i32 m0, s55, 0xe000
	s_nop 0
	global_load_lds_dwordx4 v[154:155], off
	s_waitcnt vmcnt(8)
	s_waitcnt lgkmcnt(0)
	s_barrier
	s_setprio 1
	s_waitcnt lgkmcnt(0)
	v_mfma_f32_16x16x32_bf16 v[124:127], v[160:163], v[194:197], v[124:127]
	v_mfma_f32_16x16x32_bf16 v[124:127], v[164:167], v[198:201], v[124:127]
	v_mfma_f32_16x16x32_bf16 v[116:119], v[168:171], v[194:197], v[116:119]
	v_mfma_f32_16x16x32_bf16 v[116:119], v[172:175], v[198:201], v[116:119]
	v_mfma_f32_16x16x32_bf16 v[108:111], v[160:163], v[202:205], v[108:111]
	v_mfma_f32_16x16x32_bf16 v[108:111], v[164:167], v[206:209], v[108:111]
	v_mfma_f32_16x16x32_bf16 v[100:103], v[168:171], v[202:205], v[100:103]
	v_mfma_f32_16x16x32_bf16 v[100:103], v[172:175], v[206:209], v[100:103]
	v_mfma_f32_16x16x32_bf16 v[92:95], v[160:163], v[210:213], v[92:95]
	v_mfma_f32_16x16x32_bf16 v[92:95], v[164:167], v[214:217], v[92:95]
	v_mfma_f32_16x16x32_bf16 v[84:87], v[168:171], v[210:213], v[84:87]
	v_mfma_f32_16x16x32_bf16 v[84:87], v[172:175], v[214:217], v[84:87]
	v_mfma_f32_16x16x32_bf16 v[76:79], v[160:163], v[218:221], v[76:79]
	v_mfma_f32_16x16x32_bf16 v[76:79], v[164:167], v[222:225], v[76:79]
	v_mfma_f32_16x16x32_bf16 v[68:71], v[168:171], v[218:221], v[68:71]
	v_mfma_f32_16x16x32_bf16 v[68:71], v[172:175], v[222:225], v[68:71]
	s_setprio 0
	s_setprio 1
	v_mfma_f32_16x16x32_bf16 v[120:123], v[176:179], v[194:197], v[120:123]
	v_mfma_f32_16x16x32_bf16 v[120:123], v[180:183], v[198:201], v[120:123]
	v_mfma_f32_16x16x32_bf16 v[112:115], v[186:189], v[194:197], v[112:115]
	v_mfma_f32_16x16x32_bf16 v[112:115], v[190:193], v[198:201], v[112:115]
	v_mfma_f32_16x16x32_bf16 v[104:107], v[176:179], v[202:205], v[104:107]
	v_mfma_f32_16x16x32_bf16 v[104:107], v[180:183], v[206:209], v[104:107]
	v_mfma_f32_16x16x32_bf16 v[96:99], v[186:189], v[202:205], v[96:99]
	v_mfma_f32_16x16x32_bf16 v[96:99], v[190:193], v[206:209], v[96:99]
	v_mfma_f32_16x16x32_bf16 v[88:91], v[176:179], v[210:213], v[88:91]
	v_mfma_f32_16x16x32_bf16 v[88:91], v[180:183], v[214:217], v[88:91]
	v_mfma_f32_16x16x32_bf16 v[80:83], v[186:189], v[210:213], v[80:83]
	v_mfma_f32_16x16x32_bf16 v[80:83], v[190:193], v[214:217], v[80:83]
	v_mfma_f32_16x16x32_bf16 v[72:75], v[176:179], v[218:221], v[72:75]
	v_mfma_f32_16x16x32_bf16 v[72:75], v[180:183], v[222:225], v[72:75]
	v_mfma_f32_16x16x32_bf16 v[64:67], v[186:189], v[218:221], v[64:67]
	v_mfma_f32_16x16x32_bf16 v[64:67], v[190:193], v[222:225], v[64:67]
	s_setprio 0
	s_barrier
	s_add_i32 s76, s64, s52
	v_lshl_add_u64 v[154:155], s[46:47], 0, v[132:133]
	s_mov_b32 m0, s76
	ds_read_b128 v[194:197], v150 offset:16384
	ds_read_b128 v[198:201], v150 offset:17408
	ds_read_b128 v[202:205], v150 offset:18432
	ds_read_b128 v[206:209], v150 offset:19456
	ds_read_b128 v[210:213], v150 offset:20480
	ds_read_b128 v[214:217], v150 offset:21504
	ds_read_b128 v[218:221], v150 offset:22528
	ds_read_b128 v[222:225], v150 offset:23552
	global_load_lds_dwordx4 v[154:155], off
	s_add_i32 m0, s76, 0x2000
	s_add_u32 s76, s46, 0x40000
	v_lshl_add_u64 v[226:227], s[46:47], 0, v[128:129]
	s_addc_u32 s77, s47, 0
	s_add_i32 s78, s65, s52
	global_load_lds_dwordx4 v[226:227], off
	v_lshl_add_u64 v[228:229], s[76:77], 0, v[132:133]
	s_mov_b32 m0, s78
	v_lshl_add_u64 v[230:231], s[48:49], 0, v[130:131]
	global_load_lds_dwordx4 v[228:229], off
	v_lshl_add_u64 v[228:229], s[76:77], 0, v[128:129]
	s_add_i32 m0, s78, 0x2000
	s_nop 0
	global_load_lds_dwordx4 v[228:229], off
	v_lshl_add_u64 v[228:229], s[48:49], 0, v[134:135]
	s_mov_b32 m0, s55
	s_nop 0
	global_load_lds_dwordx4 v[228:229], off
	s_mov_b32 m0, s56
	s_nop 0
	global_load_lds_dwordx4 v[230:231], off
	s_waitcnt vmcnt(8)
	s_waitcnt lgkmcnt(0)
	s_barrier
	s_setprio 1
	s_waitcnt lgkmcnt(0)
	v_mfma_f32_16x16x32_bf16 v[60:63], v[160:163], v[194:197], v[60:63]
	v_mfma_f32_16x16x32_bf16 v[60:63], v[164:167], v[198:201], v[60:63]
	v_mfma_f32_16x16x32_bf16 v[52:55], v[168:171], v[194:197], v[52:55]
	v_mfma_f32_16x16x32_bf16 v[52:55], v[172:175], v[198:201], v[52:55]
	v_mfma_f32_16x16x32_bf16 v[44:47], v[160:163], v[202:205], v[44:47]
	v_mfma_f32_16x16x32_bf16 v[44:47], v[164:167], v[206:209], v[44:47]
	v_mfma_f32_16x16x32_bf16 v[36:39], v[168:171], v[202:205], v[36:39]
	v_mfma_f32_16x16x32_bf16 v[36:39], v[172:175], v[206:209], v[36:39]
	v_mfma_f32_16x16x32_bf16 v[28:31], v[160:163], v[210:213], v[28:31]
	v_mfma_f32_16x16x32_bf16 v[28:31], v[164:167], v[214:217], v[28:31]
	v_mfma_f32_16x16x32_bf16 v[20:23], v[168:171], v[210:213], v[20:23]
	v_mfma_f32_16x16x32_bf16 v[20:23], v[172:175], v[214:217], v[20:23]
	v_mfma_f32_16x16x32_bf16 v[12:15], v[160:163], v[218:221], v[12:15]
	v_mfma_f32_16x16x32_bf16 v[12:15], v[164:167], v[222:225], v[12:15]
	v_mfma_f32_16x16x32_bf16 v[4:7], v[168:171], v[218:221], v[4:7]
	v_mfma_f32_16x16x32_bf16 v[4:7], v[172:175], v[222:225], v[4:7]
	s_setprio 0
	s_setprio 1
	v_mfma_f32_16x16x32_bf16 v[56:59], v[176:179], v[194:197], v[56:59]
	v_mfma_f32_16x16x32_bf16 v[56:59], v[180:183], v[198:201], v[56:59]
	v_mfma_f32_16x16x32_bf16 v[48:51], v[186:189], v[194:197], v[48:51]
	v_mfma_f32_16x16x32_bf16 v[48:51], v[190:193], v[198:201], v[48:51]
	v_mfma_f32_16x16x32_bf16 v[40:43], v[176:179], v[202:205], v[40:43]
	v_mfma_f32_16x16x32_bf16 v[40:43], v[180:183], v[206:209], v[40:43]
	v_mfma_f32_16x16x32_bf16 v[32:35], v[186:189], v[202:205], v[32:35]
	v_mfma_f32_16x16x32_bf16 v[32:35], v[190:193], v[206:209], v[32:35]
	v_mfma_f32_16x16x32_bf16 v[24:27], v[176:179], v[210:213], v[24:27]
	v_mfma_f32_16x16x32_bf16 v[24:27], v[180:183], v[214:217], v[24:27]
	v_mfma_f32_16x16x32_bf16 v[16:19], v[186:189], v[210:213], v[16:19]
	v_mfma_f32_16x16x32_bf16 v[16:19], v[190:193], v[214:217], v[16:19]
	v_mfma_f32_16x16x32_bf16 v[8:11], v[176:179], v[218:221], v[8:11]
	v_mfma_f32_16x16x32_bf16 v[8:11], v[180:183], v[222:225], v[8:11]
	v_mfma_f32_16x16x32_bf16 v[0:3], v[186:189], v[218:221], v[0:3]
	v_mfma_f32_16x16x32_bf16 v[0:3], v[190:193], v[222:225], v[0:3]
	s_setprio 0
	s_barrier
	s_add_i32 s76, 0, 0x18000
	v_add_u32_e32 v153, s76, v147
	s_add_i32 s77, 0, 0x1c000
	ds_read_b128 v[160:163], v153
	ds_read_b128 v[164:167], v153 offset:1024
	ds_read_b128 v[168:171], v153 offset:2048
	ds_read_b128 v[172:175], v153 offset:3072
	v_add_u32_e32 v153, s77, v147
	ds_read_b128 v[176:179], v153
	ds_read_b128 v[180:183], v153 offset:1024
	ds_read_b128 v[186:189], v153 offset:2048
	ds_read_b128 v[190:193], v153 offset:3072
	s_add_u32 s48, s48, 0x40000
	s_addc_u32 s49, s49, 0
	s_mov_b32 m0, s57
	v_lshl_add_u64 v[232:233], s[48:49], 0, v[134:135]
	ds_read_b128 v[194:197], v150 offset:32768
	ds_read_b128 v[198:201], v150 offset:33792
	ds_read_b128 v[202:205], v150 offset:34816
	ds_read_b128 v[206:209], v150 offset:35840
	ds_read_b128 v[210:213], v150 offset:36864
	ds_read_b128 v[214:217], v150 offset:37888
	ds_read_b128 v[218:221], v150 offset:38912
	ds_read_b128 v[222:225], v150 offset:39936
	global_load_lds_dwordx4 v[232:233], off
	v_lshl_add_u64 v[232:233], s[48:49], 0, v[130:131]
	s_mov_b32 m0, s58
	s_nop 0
	global_load_lds_dwordx4 v[232:233], off
	s_waitcnt vmcnt(8)
	s_waitcnt lgkmcnt(0)
	s_barrier
	s_setprio 1
	s_waitcnt lgkmcnt(0)
	v_mfma_f32_16x16x32_bf16 v[124:127], v[160:163], v[194:197], v[124:127]
	v_mfma_f32_16x16x32_bf16 v[124:127], v[164:167], v[198:201], v[124:127]
	v_mfma_f32_16x16x32_bf16 v[116:119], v[168:171], v[194:197], v[116:119]
	v_mfma_f32_16x16x32_bf16 v[116:119], v[172:175], v[198:201], v[116:119]
	v_mfma_f32_16x16x32_bf16 v[108:111], v[160:163], v[202:205], v[108:111]
	v_mfma_f32_16x16x32_bf16 v[108:111], v[164:167], v[206:209], v[108:111]
	v_mfma_f32_16x16x32_bf16 v[100:103], v[168:171], v[202:205], v[100:103]
	v_mfma_f32_16x16x32_bf16 v[100:103], v[172:175], v[206:209], v[100:103]
	v_mfma_f32_16x16x32_bf16 v[92:95], v[160:163], v[210:213], v[92:95]
	v_mfma_f32_16x16x32_bf16 v[92:95], v[164:167], v[214:217], v[92:95]
	v_mfma_f32_16x16x32_bf16 v[84:87], v[168:171], v[210:213], v[84:87]
	v_mfma_f32_16x16x32_bf16 v[84:87], v[172:175], v[214:217], v[84:87]
	v_mfma_f32_16x16x32_bf16 v[76:79], v[160:163], v[218:221], v[76:79]
	v_mfma_f32_16x16x32_bf16 v[76:79], v[164:167], v[222:225], v[76:79]
	v_mfma_f32_16x16x32_bf16 v[68:71], v[168:171], v[218:221], v[68:71]
	v_mfma_f32_16x16x32_bf16 v[68:71], v[172:175], v[222:225], v[68:71]
	s_setprio 0
	s_setprio 1
	v_mfma_f32_16x16x32_bf16 v[120:123], v[176:179], v[194:197], v[120:123]
	v_mfma_f32_16x16x32_bf16 v[120:123], v[180:183], v[198:201], v[120:123]
	v_mfma_f32_16x16x32_bf16 v[112:115], v[186:189], v[194:197], v[112:115]
	v_mfma_f32_16x16x32_bf16 v[112:115], v[190:193], v[198:201], v[112:115]
	v_mfma_f32_16x16x32_bf16 v[104:107], v[176:179], v[202:205], v[104:107]
	v_mfma_f32_16x16x32_bf16 v[104:107], v[180:183], v[206:209], v[104:107]
	v_mfma_f32_16x16x32_bf16 v[96:99], v[186:189], v[202:205], v[96:99]
	v_mfma_f32_16x16x32_bf16 v[96:99], v[190:193], v[206:209], v[96:99]
	v_mfma_f32_16x16x32_bf16 v[88:91], v[176:179], v[210:213], v[88:91]
	v_mfma_f32_16x16x32_bf16 v[88:91], v[180:183], v[214:217], v[88:91]
	v_mfma_f32_16x16x32_bf16 v[80:83], v[186:189], v[210:213], v[80:83]
	v_mfma_f32_16x16x32_bf16 v[80:83], v[190:193], v[214:217], v[80:83]
	v_mfma_f32_16x16x32_bf16 v[72:75], v[176:179], v[218:221], v[72:75]
	v_mfma_f32_16x16x32_bf16 v[72:75], v[180:183], v[222:225], v[72:75]
	v_mfma_f32_16x16x32_bf16 v[64:67], v[186:189], v[218:221], v[64:67]
	v_mfma_f32_16x16x32_bf16 v[64:67], v[190:193], v[222:225], v[64:67]
	s_setprio 0
	s_barrier
	v_add_u32_e32 v234, 0x21000, v151
	ds_read_b128 v[236:239], v234
	ds_read_b128 v[240:243], v234 offset:256
	ds_read_b128 v[244:247], v234 offset:512
	ds_read_b128 v[248:251], v234 offset:768
	v_add_u32_e32 v235, s23, v146
	v_mul_u32_u24_e32 v235, 0x1600, v235
	v_lshl_or_b32 v234, s67, 7, v149
	v_lshl_add_u32 v235, v234, 1, v235
	s_add_i32 s48, s76, s52
	v_lshl_add_u64 v[154:155], v[154:155], 0, s[14:15]
	s_mov_b32 m0, s48
	ds_read_b128 v[194:197], v150 offset:49152
	ds_read_b128 v[198:201], v150 offset:50176
	ds_read_b128 v[202:205], v150 offset:51200
	ds_read_b128 v[206:209], v150 offset:52224
	ds_read_b128 v[210:213], v150 offset:53248
	ds_read_b128 v[214:217], v150 offset:54272
	ds_read_b128 v[218:221], v150 offset:55296
	ds_read_b128 v[222:225], v150 offset:56320
	global_load_lds_dwordx4 v[154:155], off
	s_add_i32 m0, s48, 0x2000
	s_add_u32 s46, s46, 0x40080
	v_lshl_add_u64 v[154:155], v[226:227], 0, s[14:15]
	s_addc_u32 s47, s47, 0
	s_add_i32 s48, s77, s52
	global_load_lds_dwordx4 v[154:155], off
	v_lshl_add_u64 v[154:155], s[46:47], 0, v[132:133]
	s_mov_b32 m0, s48
	s_nop 0
	global_load_lds_dwordx4 v[154:155], off
	v_lshl_add_u64 v[154:155], s[46:47], 0, v[128:129]
	s_add_i32 m0, s48, 0x2000
	s_nop 0
	global_load_lds_dwordx4 v[154:155], off
	v_lshl_add_u64 v[154:155], v[228:229], 0, s[14:15]
	s_mov_b32 m0, s60
	s_nop 0
	global_load_lds_dwordx4 v[154:155], off
	v_lshl_add_u64 v[154:155], v[230:231], 0, s[14:15]
	s_mov_b32 m0, s61
	s_nop 0
	global_load_lds_dwordx4 v[154:155], off
	s_waitcnt lgkmcnt(8)
	v_add_f32_e32 v236, v236, v237
	v_add_f32_e32 v238, v238, v239
	v_add_f32_e32 v240, v240, v241
	v_add_f32_e32 v242, v242, v243
	v_add_f32_e32 v244, v244, v245
	v_add_f32_e32 v246, v246, v247
	v_add_f32_e32 v248, v248, v249
	v_add_f32_e32 v250, v250, v251
	v_add_f32_e32 v236, v236, v238
	v_add_f32_e32 v240, v240, v242
	v_add_f32_e32 v244, v244, v246
	v_add_f32_e32 v248, v248, v250
	v_fmamk_f32 v236, v236, 0x3a800000, v152
	v_fmamk_f32 v240, v240, 0x3a800000, v152
	v_fmamk_f32 v244, v244, 0x3a800000, v152
	v_fmamk_f32 v248, v248, 0x3a800000, v152
	v_rsq_f32_e32 v236, v236
	v_rsq_f32_e32 v240, v240
	v_rsq_f32_e32 v244, v244
	v_rsq_f32_e32 v248, v248
	v_mul_f32_e32 v252, 0xbfb8aa3b, v236
	v_mul_f32_e32 v254, v236, v236
	v_pk_mul_f32 v[120:121], v[124:125], v[120:121]
	v_pk_mul_f32 v[122:123], v[126:127], v[122:123]
	v_pk_mul_f32 v[112:113], v[116:117], v[112:113]
	v_pk_mul_f32 v[114:115], v[118:119], v[114:115]
	v_pk_mul_f32 v[124:125], v[124:125], v[252:253] op_sel_hi:[1,0]
	v_pk_mul_f32 v[126:127], v[126:127], v[252:253] op_sel_hi:[1,0]
	v_pk_mul_f32 v[116:117], v[116:117], v[252:253] op_sel_hi:[1,0]
	v_pk_mul_f32 v[118:119], v[118:119], v[252:253] op_sel_hi:[1,0]
	v_exp_f32_e32 v124, v124
	v_exp_f32_e32 v125, v125
	v_exp_f32_e32 v126, v126
	v_exp_f32_e32 v127, v127
	v_exp_f32_e32 v116, v116
	v_exp_f32_e32 v117, v117
	v_exp_f32_e32 v118, v118
	v_exp_f32_e32 v119, v119
	v_pk_add_f32 v[124:125], v[124:125], 1.0 op_sel_hi:[1,0]
	v_pk_add_f32 v[126:127], v[126:127], 1.0 op_sel_hi:[1,0]
	v_pk_add_f32 v[116:117], v[116:117], 1.0 op_sel_hi:[1,0]
	v_pk_add_f32 v[118:119], v[118:119], 1.0 op_sel_hi:[1,0]
	v_rcp_f32_e32 v124, v124
	v_rcp_f32_e32 v125, v125
	v_rcp_f32_e32 v126, v126
	v_rcp_f32_e32 v127, v127
	v_rcp_f32_e32 v116, v116
	v_rcp_f32_e32 v117, v117
	v_rcp_f32_e32 v118, v118
	v_rcp_f32_e32 v119, v119
	v_pk_mul_f32 v[120:121], v[120:121], v[254:255] op_sel_hi:[1,0]
	v_pk_mul_f32 v[122:123], v[122:123], v[254:255] op_sel_hi:[1,0]
	v_pk_mul_f32 v[112:113], v[112:113], v[254:255] op_sel_hi:[1,0]
	v_pk_mul_f32 v[114:115], v[114:115], v[254:255] op_sel_hi:[1,0]
	v_pk_mul_f32 v[120:121], v[120:121], v[124:125]
	v_pk_mul_f32 v[122:123], v[122:123], v[126:127]
	v_pk_mul_f32 v[112:113], v[112:113], v[116:117]
	v_pk_mul_f32 v[114:115], v[114:115], v[118:119]
	v_cvt_pk_bf16_f32 v120, v120, v121
	v_cvt_pk_bf16_f32 v121, v122, v123
	v_cvt_pk_bf16_f32 v122, v112, v113
	v_cvt_pk_bf16_f32 v123, v114, v115
	global_store_dwordx4 v235, v[120:123], s[10:11]
	v_add_u32_e32 v234, 0x16000, v235
	v_mul_f32_e32 v252, 0xbfb8aa3b, v240
	v_mul_f32_e32 v254, v240, v240
	v_pk_mul_f32 v[104:105], v[108:109], v[104:105]
	v_pk_mul_f32 v[106:107], v[110:111], v[106:107]
	v_pk_mul_f32 v[96:97], v[100:101], v[96:97]
	v_pk_mul_f32 v[98:99], v[102:103], v[98:99]
	v_pk_mul_f32 v[108:109], v[108:109], v[252:253] op_sel_hi:[1,0]
	v_pk_mul_f32 v[110:111], v[110:111], v[252:253] op_sel_hi:[1,0]
	v_pk_mul_f32 v[100:101], v[100:101], v[252:253] op_sel_hi:[1,0]
	v_pk_mul_f32 v[102:103], v[102:103], v[252:253] op_sel_hi:[1,0]
	v_exp_f32_e32 v108, v108
	v_exp_f32_e32 v109, v109
	v_exp_f32_e32 v110, v110
	v_exp_f32_e32 v111, v111
	v_exp_f32_e32 v100, v100
	v_exp_f32_e32 v101, v101
	v_exp_f32_e32 v102, v102
	v_exp_f32_e32 v103, v103
	v_pk_add_f32 v[108:109], v[108:109], 1.0 op_sel_hi:[1,0]
	v_pk_add_f32 v[110:111], v[110:111], 1.0 op_sel_hi:[1,0]
	v_pk_add_f32 v[100:101], v[100:101], 1.0 op_sel_hi:[1,0]
	v_pk_add_f32 v[102:103], v[102:103], 1.0 op_sel_hi:[1,0]
	v_rcp_f32_e32 v108, v108
	v_rcp_f32_e32 v109, v109
	v_rcp_f32_e32 v110, v110
	v_rcp_f32_e32 v111, v111
	v_rcp_f32_e32 v100, v100
	v_rcp_f32_e32 v101, v101
	v_rcp_f32_e32 v102, v102
	v_rcp_f32_e32 v103, v103
	v_pk_mul_f32 v[104:105], v[104:105], v[254:255] op_sel_hi:[1,0]
	v_pk_mul_f32 v[106:107], v[106:107], v[254:255] op_sel_hi:[1,0]
	v_pk_mul_f32 v[96:97], v[96:97], v[254:255] op_sel_hi:[1,0]
	v_pk_mul_f32 v[98:99], v[98:99], v[254:255] op_sel_hi:[1,0]
	v_pk_mul_f32 v[104:105], v[104:105], v[108:109]
	v_pk_mul_f32 v[106:107], v[106:107], v[110:111]
	v_pk_mul_f32 v[96:97], v[96:97], v[100:101]
	v_pk_mul_f32 v[98:99], v[98:99], v[102:103]
	v_cvt_pk_bf16_f32 v104, v104, v105
	v_cvt_pk_bf16_f32 v105, v106, v107
	v_cvt_pk_bf16_f32 v106, v96, v97
	v_cvt_pk_bf16_f32 v107, v98, v99
	global_store_dwordx4 v234, v[104:107], s[10:11]
	v_add_u32_e32 v235, 0x16000, v234
	v_mul_f32_e32 v252, 0xbfb8aa3b, v244
	v_mul_f32_e32 v254, v244, v244
	v_pk_mul_f32 v[88:89], v[92:93], v[88:89]
	v_pk_mul_f32 v[90:91], v[94:95], v[90:91]
	v_pk_mul_f32 v[80:81], v[84:85], v[80:81]
	v_pk_mul_f32 v[82:83], v[86:87], v[82:83]
	v_pk_mul_f32 v[92:93], v[92:93], v[252:253] op_sel_hi:[1,0]
	v_pk_mul_f32 v[94:95], v[94:95], v[252:253] op_sel_hi:[1,0]
	v_pk_mul_f32 v[84:85], v[84:85], v[252:253] op_sel_hi:[1,0]
	v_pk_mul_f32 v[86:87], v[86:87], v[252:253] op_sel_hi:[1,0]
	v_exp_f32_e32 v92, v92
	v_exp_f32_e32 v93, v93
	v_exp_f32_e32 v94, v94
	v_exp_f32_e32 v95, v95
	v_exp_f32_e32 v84, v84
	v_exp_f32_e32 v85, v85
	v_exp_f32_e32 v86, v86
	v_exp_f32_e32 v87, v87
	v_pk_add_f32 v[92:93], v[92:93], 1.0 op_sel_hi:[1,0]
	v_pk_add_f32 v[94:95], v[94:95], 1.0 op_sel_hi:[1,0]
	v_pk_add_f32 v[84:85], v[84:85], 1.0 op_sel_hi:[1,0]
	v_pk_add_f32 v[86:87], v[86:87], 1.0 op_sel_hi:[1,0]
	v_rcp_f32_e32 v92, v92
	v_rcp_f32_e32 v93, v93
	v_rcp_f32_e32 v94, v94
	v_rcp_f32_e32 v95, v95
	v_rcp_f32_e32 v84, v84
	v_rcp_f32_e32 v85, v85
	v_rcp_f32_e32 v86, v86
	v_rcp_f32_e32 v87, v87
	v_pk_mul_f32 v[88:89], v[88:89], v[254:255] op_sel_hi:[1,0]
	v_pk_mul_f32 v[90:91], v[90:91], v[254:255] op_sel_hi:[1,0]
	v_pk_mul_f32 v[80:81], v[80:81], v[254:255] op_sel_hi:[1,0]
	v_pk_mul_f32 v[82:83], v[82:83], v[254:255] op_sel_hi:[1,0]
	v_pk_mul_f32 v[88:89], v[88:89], v[92:93]
	v_pk_mul_f32 v[90:91], v[90:91], v[94:95]
	v_pk_mul_f32 v[80:81], v[80:81], v[84:85]
	v_pk_mul_f32 v[82:83], v[82:83], v[86:87]
	v_cvt_pk_bf16_f32 v88, v88, v89
	v_cvt_pk_bf16_f32 v89, v90, v91
	v_cvt_pk_bf16_f32 v90, v80, v81
	v_cvt_pk_bf16_f32 v91, v82, v83
	global_store_dwordx4 v235, v[88:91], s[10:11]
	v_add_u32_e32 v234, 0x16000, v235
	v_mul_f32_e32 v252, 0xbfb8aa3b, v248
	v_mul_f32_e32 v254, v248, v248
	v_pk_mul_f32 v[72:73], v[76:77], v[72:73]
	v_pk_mul_f32 v[74:75], v[78:79], v[74:75]
	v_pk_mul_f32 v[64:65], v[68:69], v[64:65]
	v_pk_mul_f32 v[66:67], v[70:71], v[66:67]
	v_pk_mul_f32 v[76:77], v[76:77], v[252:253] op_sel_hi:[1,0]
	v_pk_mul_f32 v[78:79], v[78:79], v[252:253] op_sel_hi:[1,0]
	v_pk_mul_f32 v[68:69], v[68:69], v[252:253] op_sel_hi:[1,0]
	v_pk_mul_f32 v[70:71], v[70:71], v[252:253] op_sel_hi:[1,0]
	v_exp_f32_e32 v76, v76
	v_exp_f32_e32 v77, v77
	v_exp_f32_e32 v78, v78
	v_exp_f32_e32 v79, v79
	v_exp_f32_e32 v68, v68
	v_exp_f32_e32 v69, v69
	v_exp_f32_e32 v70, v70
	v_exp_f32_e32 v71, v71
	v_pk_add_f32 v[76:77], v[76:77], 1.0 op_sel_hi:[1,0]
	v_pk_add_f32 v[78:79], v[78:79], 1.0 op_sel_hi:[1,0]
	v_pk_add_f32 v[68:69], v[68:69], 1.0 op_sel_hi:[1,0]
	v_pk_add_f32 v[70:71], v[70:71], 1.0 op_sel_hi:[1,0]
	v_rcp_f32_e32 v76, v76
	v_rcp_f32_e32 v77, v77
	v_rcp_f32_e32 v78, v78
	v_rcp_f32_e32 v79, v79
	v_rcp_f32_e32 v68, v68
	v_rcp_f32_e32 v69, v69
	v_rcp_f32_e32 v70, v70
	v_rcp_f32_e32 v71, v71
	v_pk_mul_f32 v[72:73], v[72:73], v[254:255] op_sel_hi:[1,0]
	v_pk_mul_f32 v[74:75], v[74:75], v[254:255] op_sel_hi:[1,0]
	v_pk_mul_f32 v[64:65], v[64:65], v[254:255] op_sel_hi:[1,0]
	v_pk_mul_f32 v[66:67], v[66:67], v[254:255] op_sel_hi:[1,0]
	v_pk_mul_f32 v[72:73], v[72:73], v[76:77]
	v_pk_mul_f32 v[74:75], v[74:75], v[78:79]
	v_pk_mul_f32 v[64:65], v[64:65], v[68:69]
	v_pk_mul_f32 v[66:67], v[66:67], v[70:71]
	v_cvt_pk_bf16_f32 v72, v72, v73
	v_cvt_pk_bf16_f32 v73, v74, v75
	v_cvt_pk_bf16_f32 v74, v64, v65
	v_cvt_pk_bf16_f32 v75, v66, v67
	global_store_dwordx4 v234, v[72:75], s[10:11]
	s_waitcnt vmcnt(12)
	s_waitcnt lgkmcnt(0)
	s_barrier
	s_setprio 1
	s_waitcnt lgkmcnt(0)
	v_mfma_f32_16x16x32_bf16 v[60:63], v[160:163], v[194:197], v[60:63]
	v_mfma_f32_16x16x32_bf16 v[60:63], v[164:167], v[198:201], v[60:63]
	v_mfma_f32_16x16x32_bf16 v[52:55], v[168:171], v[194:197], v[52:55]
	v_mfma_f32_16x16x32_bf16 v[52:55], v[172:175], v[198:201], v[52:55]
	v_mfma_f32_16x16x32_bf16 v[44:47], v[160:163], v[202:205], v[44:47]
	v_mfma_f32_16x16x32_bf16 v[44:47], v[164:167], v[206:209], v[44:47]
	v_mfma_f32_16x16x32_bf16 v[36:39], v[168:171], v[202:205], v[36:39]
	v_mfma_f32_16x16x32_bf16 v[36:39], v[172:175], v[206:209], v[36:39]
	v_mfma_f32_16x16x32_bf16 v[28:31], v[160:163], v[210:213], v[28:31]
	v_mfma_f32_16x16x32_bf16 v[28:31], v[164:167], v[214:217], v[28:31]
	v_mfma_f32_16x16x32_bf16 v[20:23], v[168:171], v[210:213], v[20:23]
	v_mfma_f32_16x16x32_bf16 v[20:23], v[172:175], v[214:217], v[20:23]
	v_mfma_f32_16x16x32_bf16 v[12:15], v[160:163], v[218:221], v[12:15]
	v_mfma_f32_16x16x32_bf16 v[12:15], v[164:167], v[222:225], v[12:15]
	v_mfma_f32_16x16x32_bf16 v[4:7], v[168:171], v[218:221], v[4:7]
	v_mfma_f32_16x16x32_bf16 v[4:7], v[172:175], v[222:225], v[4:7]
	s_setprio 0
	s_setprio 1
	v_mfma_f32_16x16x32_bf16 v[56:59], v[176:179], v[194:197], v[56:59]
	v_mfma_f32_16x16x32_bf16 v[56:59], v[180:183], v[198:201], v[56:59]
	v_mfma_f32_16x16x32_bf16 v[48:51], v[186:189], v[194:197], v[48:51]
	v_mfma_f32_16x16x32_bf16 v[48:51], v[190:193], v[198:201], v[48:51]
	v_mfma_f32_16x16x32_bf16 v[40:43], v[176:179], v[202:205], v[40:43]
	v_mfma_f32_16x16x32_bf16 v[40:43], v[180:183], v[206:209], v[40:43]
	v_mfma_f32_16x16x32_bf16 v[32:35], v[186:189], v[202:205], v[32:35]
	v_mfma_f32_16x16x32_bf16 v[32:35], v[190:193], v[206:209], v[32:35]
	v_mfma_f32_16x16x32_bf16 v[24:27], v[176:179], v[210:213], v[24:27]
	v_mfma_f32_16x16x32_bf16 v[24:27], v[180:183], v[214:217], v[24:27]
	v_mfma_f32_16x16x32_bf16 v[16:19], v[186:189], v[210:213], v[16:19]
	v_mfma_f32_16x16x32_bf16 v[16:19], v[190:193], v[214:217], v[16:19]
	v_mfma_f32_16x16x32_bf16 v[8:11], v[176:179], v[218:221], v[8:11]
	v_mfma_f32_16x16x32_bf16 v[8:11], v[180:183], v[222:225], v[8:11]
	v_mfma_f32_16x16x32_bf16 v[0:3], v[186:189], v[218:221], v[0:3]
	v_mfma_f32_16x16x32_bf16 v[0:3], v[190:193], v[222:225], v[0:3]
	s_setprio 0
	s_barrier
	s_add_i32 s75, s75, 2
	s_add_u32 s71, s71, 0x100
	s_addc_u32 s74, s74, 0
	s_add_u32 s44, s44, 0x100
	s_addc_u32 s45, s45, 0

.LBB0_158:
	s_add_u32 s81, s56, 0x100
	s_addc_u32 s82, s57, 0
	s_mov_b32 s83, -2
	s_waitcnt lgkmcnt(0)
	s_cmp_eq_u32 s70, 1
	s_cbranch_scc1 .Lfa_1
	ds_read_b128 v[128:131], v189
	ds_read_b128 v[132:135], v189 offset:1024
	ds_read_b128 v[136:139], v189 offset:2048
	ds_read_b128 v[140:143], v189 offset:3072
	ds_read_b128 v[144:147], v190
	ds_read_b128 v[148:151], v190 offset:1024
	ds_read_b128 v[172:175], v190 offset:2048
	ds_read_b128 v[176:179], v190 offset:3072
	s_add_u32 s56, s54, 0x100
	s_addc_u32 s57, s55, 0
	s_cmp_eq_u32 s83, 40
	s_cselect_b32 s61, s15, s57
	s_cselect_b32 s60, s14, s56
	s_cselect_b32 s59, s53, s82
	s_cselect_b32 s58, s52, s81
	v_lshl_add_u64 v[222:223], s[54:55], 0, v[166:167]
	s_add_i32 m0, s66, 0xc000
	ds_read_b128 v[180:183], v191
	ds_read_b128 v[194:197], v191 offset:1024
	ds_read_b128 v[198:201], v191 offset:2048
	ds_read_b128 v[202:205], v191 offset:3072
	ds_read_b128 v[206:209], v191 offset:4096
	ds_read_b128 v[210:213], v191 offset:5120
	ds_read_b128 v[214:217], v191 offset:6144
	ds_read_b128 v[218:221], v191 offset:7168
	global_load_lds_dwordx4 v[222:223], off
	v_lshl_add_u64 v[222:223], s[54:55], 0, v[164:165]
	s_add_i32 m0, s66, 0xe000
	s_nop 0
	global_load_lds_dwordx4 v[222:223], off
	s_waitcnt vmcnt(24)
	s_waitcnt lgkmcnt(0)
	s_barrier
	s_setprio 1
	s_waitcnt lgkmcnt(0)
	v_mfma_f32_16x16x32_bf16 v[124:127], v[128:131], v[180:183], 0
	v_mfma_f32_16x16x32_bf16 v[120:123], v[136:139], v[180:183], 0
	v_mfma_f32_16x16x32_bf16 v[108:111], v[128:131], v[198:201], 0
	v_mfma_f32_16x16x32_bf16 v[104:107], v[136:139], v[198:201], 0
	v_mfma_f32_16x16x32_bf16 v[92:95], v[128:131], v[206:209], 0
	v_mfma_f32_16x16x32_bf16 v[88:91], v[136:139], v[206:209], 0
	v_mfma_f32_16x16x32_bf16 v[76:79], v[128:131], v[214:217], 0
	v_mfma_f32_16x16x32_bf16 v[72:75], v[136:139], v[214:217], 0
	v_mfma_f32_16x16x32_bf16 v[124:127], v[132:135], v[194:197], v[124:127]
	v_mfma_f32_16x16x32_bf16 v[120:123], v[140:143], v[194:197], v[120:123]
	v_mfma_f32_16x16x32_bf16 v[108:111], v[132:135], v[202:205], v[108:111]
	v_mfma_f32_16x16x32_bf16 v[104:107], v[140:143], v[202:205], v[104:107]
	v_mfma_f32_16x16x32_bf16 v[92:95], v[132:135], v[210:213], v[92:95]
	v_mfma_f32_16x16x32_bf16 v[88:91], v[140:143], v[210:213], v[88:91]
	v_mfma_f32_16x16x32_bf16 v[76:79], v[132:135], v[218:221], v[76:79]
	v_mfma_f32_16x16x32_bf16 v[72:75], v[140:143], v[218:221], v[72:75]
	s_setprio 0
	s_setprio 1
	v_mfma_f32_16x16x32_bf16 v[116:119], v[144:147], v[180:183], 0
	v_mfma_f32_16x16x32_bf16 v[112:115], v[172:175], v[180:183], 0
	v_mfma_f32_16x16x32_bf16 v[100:103], v[144:147], v[198:201], 0
	v_mfma_f32_16x16x32_bf16 v[96:99], v[172:175], v[198:201], 0
	v_mfma_f32_16x16x32_bf16 v[84:87], v[144:147], v[206:209], 0
	v_mfma_f32_16x16x32_bf16 v[80:83], v[172:175], v[206:209], 0
	v_mfma_f32_16x16x32_bf16 v[68:71], v[144:147], v[214:217], 0
	v_mfma_f32_16x16x32_bf16 v[64:67], v[172:175], v[214:217], 0
	v_mfma_f32_16x16x32_bf16 v[116:119], v[148:151], v[194:197], v[116:119]
	v_mfma_f32_16x16x32_bf16 v[112:115], v[176:179], v[194:197], v[112:115]
	v_mfma_f32_16x16x32_bf16 v[100:103], v[148:151], v[202:205], v[100:103]
	v_mfma_f32_16x16x32_bf16 v[96:99], v[176:179], v[202:205], v[96:99]
	v_mfma_f32_16x16x32_bf16 v[84:87], v[148:151], v[210:213], v[84:87]
	v_mfma_f32_16x16x32_bf16 v[80:83], v[176:179], v[210:213], v[80:83]
	v_mfma_f32_16x16x32_bf16 v[68:71], v[148:151], v[218:221], v[68:71]
	v_mfma_f32_16x16x32_bf16 v[64:67], v[176:179], v[218:221], v[64:67]
	s_setprio 0
	s_barrier
	s_add_i32 s54, s77, s65
	v_lshl_add_u64 v[222:223], s[58:59], 0, v[154:155]
	s_mov_b32 m0, s54
	ds_read_b128 v[180:183], v191 offset:16384
	ds_read_b128 v[194:197], v191 offset:17408
	ds_read_b128 v[198:201], v191 offset:18432
	ds_read_b128 v[202:205], v191 offset:19456
	ds_read_b128 v[206:209], v191 offset:20480
	ds_read_b128 v[210:213], v191 offset:21504
	ds_read_b128 v[214:217], v191 offset:22528
	ds_read_b128 v[218:221], v191 offset:23552
	global_load_lds_dwordx4 v[222:223], off
	s_add_i32 m0, s54, 0x2000
	s_add_u32 s54, s58, 0xb0000
	v_lshl_add_u64 v[224:225], s[58:59], 0, v[162:163]
	s_addc_u32 s55, s59, 0
	s_add_i32 s84, s78, s65
	global_load_lds_dwordx4 v[224:225], off
	v_lshl_add_u64 v[226:227], s[54:55], 0, v[154:155]
	s_mov_b32 m0, s84
	v_lshl_add_u64 v[228:229], s[60:61], 0, v[160:161]
	global_load_lds_dwordx4 v[226:227], off
	v_lshl_add_u64 v[226:227], s[54:55], 0, v[162:163]
	s_add_i32 m0, s84, 0x2000
	s_nop 0
	global_load_lds_dwordx4 v[226:227], off
	v_lshl_add_u64 v[226:227], s[60:61], 0, v[152:153]
	s_mov_b32 m0, s66
	s_nop 0
	global_load_lds_dwordx4 v[226:227], off
	s_mov_b32 m0, s67
	s_nop 0
	global_load_lds_dwordx4 v[228:229], off
	s_waitcnt vmcnt(24)
	s_waitcnt lgkmcnt(0)
	s_barrier
	s_setprio 1
	s_waitcnt lgkmcnt(0)
	v_mfma_f32_16x16x32_bf16 v[60:63], v[128:131], v[180:183], 0
	v_mfma_f32_16x16x32_bf16 v[56:59], v[136:139], v[180:183], 0
	v_mfma_f32_16x16x32_bf16 v[44:47], v[128:131], v[198:201], 0
	v_mfma_f32_16x16x32_bf16 v[40:43], v[136:139], v[198:201], 0
	v_mfma_f32_16x16x32_bf16 v[28:31], v[128:131], v[206:209], 0
	v_mfma_f32_16x16x32_bf16 v[24:27], v[136:139], v[206:209], 0
	v_mfma_f32_16x16x32_bf16 v[12:15], v[128:131], v[214:217], 0
	v_mfma_f32_16x16x32_bf16 v[8:11], v[136:139], v[214:217], 0
	v_mfma_f32_16x16x32_bf16 v[60:63], v[132:135], v[194:197], v[60:63]
	v_mfma_f32_16x16x32_bf16 v[56:59], v[140:143], v[194:197], v[56:59]
	v_mfma_f32_16x16x32_bf16 v[44:47], v[132:135], v[202:205], v[44:47]
	v_mfma_f32_16x16x32_bf16 v[40:43], v[140:143], v[202:205], v[40:43]
	v_mfma_f32_16x16x32_bf16 v[28:31], v[132:135], v[210:213], v[28:31]
	v_mfma_f32_16x16x32_bf16 v[24:27], v[140:143], v[210:213], v[24:27]
	v_mfma_f32_16x16x32_bf16 v[12:15], v[132:135], v[218:221], v[12:15]
	v_mfma_f32_16x16x32_bf16 v[8:11], v[140:143], v[218:221], v[8:11]
	s_setprio 0
	s_setprio 1
	v_mfma_f32_16x16x32_bf16 v[52:55], v[144:147], v[180:183], 0
	v_mfma_f32_16x16x32_bf16 v[48:51], v[172:175], v[180:183], 0
	v_mfma_f32_16x16x32_bf16 v[36:39], v[144:147], v[198:201], 0
	v_mfma_f32_16x16x32_bf16 v[32:35], v[172:175], v[198:201], 0
	v_mfma_f32_16x16x32_bf16 v[20:23], v[144:147], v[206:209], 0
	v_mfma_f32_16x16x32_bf16 v[16:19], v[172:175], v[206:209], 0
	v_mfma_f32_16x16x32_bf16 v[4:7], v[144:147], v[214:217], 0
	v_mfma_f32_16x16x32_bf16 v[0:3], v[172:175], v[214:217], 0
	v_mfma_f32_16x16x32_bf16 v[52:55], v[148:151], v[194:197], v[52:55]
	v_mfma_f32_16x16x32_bf16 v[48:51], v[176:179], v[194:197], v[48:51]
	v_mfma_f32_16x16x32_bf16 v[36:39], v[148:151], v[202:205], v[36:39]
	v_mfma_f32_16x16x32_bf16 v[32:35], v[176:179], v[202:205], v[32:35]
	v_mfma_f32_16x16x32_bf16 v[20:23], v[148:151], v[210:213], v[20:23]
	v_mfma_f32_16x16x32_bf16 v[16:19], v[176:179], v[210:213], v[16:19]
	v_mfma_f32_16x16x32_bf16 v[4:7], v[148:151], v[218:221], v[4:7]
	v_mfma_f32_16x16x32_bf16 v[0:3], v[176:179], v[218:221], v[0:3]
	s_setprio 0
	s_barrier
	s_add_i32 s84, 0, 0x18000
	s_add_i32 s85, 0, 0x1c000
	v_add_u32_e32 v140, s84, v186
	v_add_u32_e32 v176, s85, v186
	ds_read_b128 v[128:131], v140
	ds_read_b128 v[132:135], v140 offset:1024
	ds_read_b128 v[136:139], v140 offset:2048
	ds_read_b128 v[140:143], v140 offset:3072
	ds_read_b128 v[144:147], v176
	ds_read_b128 v[148:151], v176 offset:1024
	ds_read_b128 v[172:175], v176 offset:2048
	ds_read_b128 v[176:179], v176 offset:3072
	s_add_u32 s54, s60, 0xb0000
	s_addc_u32 s55, s61, 0
	s_mov_b32 m0, s68
	v_lshl_add_u64 v[230:231], s[54:55], 0, v[152:153]
	ds_read_b128 v[180:183], v191 offset:32768
	ds_read_b128 v[194:197], v191 offset:33792
	ds_read_b128 v[198:201], v191 offset:34816
	ds_read_b128 v[202:205], v191 offset:35840
	ds_read_b128 v[206:209], v191 offset:36864
	ds_read_b128 v[210:213], v191 offset:37888
	ds_read_b128 v[214:217], v191 offset:38912
	ds_read_b128 v[218:221], v191 offset:39936
	global_load_lds_dwordx4 v[230:231], off
	v_lshl_add_u64 v[230:231], s[54:55], 0, v[160:161]
	s_mov_b32 m0, s69
	s_nop 0
	global_load_lds_dwordx4 v[230:231], off
	s_waitcnt vmcnt(8)
	s_waitcnt lgkmcnt(0)
	s_barrier
	s_setprio 1
	s_waitcnt lgkmcnt(0)
	v_mfma_f32_16x16x32_bf16 v[124:127], v[128:131], v[180:183], v[124:127]
	v_mfma_f32_16x16x32_bf16 v[124:127], v[132:135], v[194:197], v[124:127]
	v_mfma_f32_16x16x32_bf16 v[120:123], v[136:139], v[180:183], v[120:123]
	v_mfma_f32_16x16x32_bf16 v[120:123], v[140:143], v[194:197], v[120:123]
	v_mfma_f32_16x16x32_bf16 v[108:111], v[128:131], v[198:201], v[108:111]
	v_mfma_f32_16x16x32_bf16 v[108:111], v[132:135], v[202:205], v[108:111]
	v_mfma_f32_16x16x32_bf16 v[104:107], v[136:139], v[198:201], v[104:107]
	v_mfma_f32_16x16x32_bf16 v[104:107], v[140:143], v[202:205], v[104:107]
	v_mfma_f32_16x16x32_bf16 v[92:95], v[128:131], v[206:209], v[92:95]
	v_mfma_f32_16x16x32_bf16 v[92:95], v[132:135], v[210:213], v[92:95]
	v_mfma_f32_16x16x32_bf16 v[88:91], v[136:139], v[206:209], v[88:91]
	v_mfma_f32_16x16x32_bf16 v[88:91], v[140:143], v[210:213], v[88:91]
	v_mfma_f32_16x16x32_bf16 v[76:79], v[128:131], v[214:217], v[76:79]
	v_mfma_f32_16x16x32_bf16 v[76:79], v[132:135], v[218:221], v[76:79]
	v_mfma_f32_16x16x32_bf16 v[72:75], v[136:139], v[214:217], v[72:75]
	v_mfma_f32_16x16x32_bf16 v[72:75], v[140:143], v[218:221], v[72:75]
	s_setprio 0
	s_setprio 1
	v_mfma_f32_16x16x32_bf16 v[116:119], v[144:147], v[180:183], v[116:119]
	v_mfma_f32_16x16x32_bf16 v[116:119], v[148:151], v[194:197], v[116:119]
	v_mfma_f32_16x16x32_bf16 v[112:115], v[172:175], v[180:183], v[112:115]
	v_mfma_f32_16x16x32_bf16 v[112:115], v[176:179], v[194:197], v[112:115]
	v_mfma_f32_16x16x32_bf16 v[100:103], v[144:147], v[198:201], v[100:103]
	v_mfma_f32_16x16x32_bf16 v[100:103], v[148:151], v[202:205], v[100:103]
	v_mfma_f32_16x16x32_bf16 v[96:99], v[172:175], v[198:201], v[96:99]
	v_mfma_f32_16x16x32_bf16 v[96:99], v[176:179], v[202:205], v[96:99]
	v_mfma_f32_16x16x32_bf16 v[84:87], v[144:147], v[206:209], v[84:87]
	v_mfma_f32_16x16x32_bf16 v[84:87], v[148:151], v[210:213], v[84:87]
	v_mfma_f32_16x16x32_bf16 v[80:83], v[172:175], v[206:209], v[80:83]
	v_mfma_f32_16x16x32_bf16 v[80:83], v[176:179], v[210:213], v[80:83]
	v_mfma_f32_16x16x32_bf16 v[68:71], v[144:147], v[214:217], v[68:71]
	v_mfma_f32_16x16x32_bf16 v[68:71], v[148:151], v[218:221], v[68:71]
	v_mfma_f32_16x16x32_bf16 v[64:67], v[172:175], v[214:217], v[64:67]
	v_mfma_f32_16x16x32_bf16 v[64:67], v[176:179], v[218:221], v[64:67]
	s_setprio 0
	s_barrier
	s_add_i32 s54, s84, s65
	v_lshl_add_u64 v[222:223], v[222:223], 0, s[28:29]
	s_mov_b32 m0, s54
	ds_read_b128 v[180:183], v191 offset:49152
	ds_read_b128 v[194:197], v191 offset:50176
	ds_read_b128 v[198:201], v191 offset:51200
	ds_read_b128 v[202:205], v191 offset:52224
	ds_read_b128 v[206:209], v191 offset:53248
	ds_read_b128 v[210:213], v191 offset:54272
	ds_read_b128 v[214:217], v191 offset:55296
	ds_read_b128 v[218:221], v191 offset:56320
	global_load_lds_dwordx4 v[222:223], off
	s_add_i32 m0, s54, 0x2000
	s_add_u32 s54, s58, 0xb0080
	v_lshl_add_u64 v[222:223], v[224:225], 0, s[28:29]
	s_addc_u32 s55, s59, 0
	s_add_i32 s58, s85, s65
	global_load_lds_dwordx4 v[222:223], off
	v_lshl_add_u64 v[222:223], s[54:55], 0, v[154:155]
	s_mov_b32 m0, s58
	s_nop 0
	global_load_lds_dwordx4 v[222:223], off
	v_lshl_add_u64 v[222:223], s[54:55], 0, v[162:163]
	s_add_i32 m0, s58, 0x2000
	s_nop 0
	global_load_lds_dwordx4 v[222:223], off
	v_lshl_add_u64 v[222:223], v[226:227], 0, s[28:29]
	s_mov_b32 m0, s3
	s_nop 0
	global_load_lds_dwordx4 v[222:223], off
	v_lshl_add_u64 v[222:223], v[228:229], 0, s[28:29]
	s_mov_b32 m0, s71
	s_nop 0
	global_load_lds_dwordx4 v[222:223], off
	s_waitcnt vmcnt(8)
	s_waitcnt lgkmcnt(0)
	s_barrier
	s_setprio 1
	s_waitcnt lgkmcnt(0)
	v_mfma_f32_16x16x32_bf16 v[60:63], v[128:131], v[180:183], v[60:63]
	v_mfma_f32_16x16x32_bf16 v[60:63], v[132:135], v[194:197], v[60:63]
	v_mfma_f32_16x16x32_bf16 v[56:59], v[136:139], v[180:183], v[56:59]
	v_mfma_f32_16x16x32_bf16 v[56:59], v[140:143], v[194:197], v[56:59]
	v_mfma_f32_16x16x32_bf16 v[44:47], v[128:131], v[198:201], v[44:47]
	v_mfma_f32_16x16x32_bf16 v[44:47], v[132:135], v[202:205], v[44:47]
	v_mfma_f32_16x16x32_bf16 v[40:43], v[136:139], v[198:201], v[40:43]
	v_mfma_f32_16x16x32_bf16 v[40:43], v[140:143], v[202:205], v[40:43]
	v_mfma_f32_16x16x32_bf16 v[28:31], v[128:131], v[206:209], v[28:31]
	v_mfma_f32_16x16x32_bf16 v[28:31], v[132:135], v[210:213], v[28:31]
	v_mfma_f32_16x16x32_bf16 v[24:27], v[136:139], v[206:209], v[24:27]
	v_mfma_f32_16x16x32_bf16 v[24:27], v[140:143], v[210:213], v[24:27]
	v_mfma_f32_16x16x32_bf16 v[12:15], v[128:131], v[214:217], v[12:15]
	v_mfma_f32_16x16x32_bf16 v[12:15], v[132:135], v[218:221], v[12:15]
	v_mfma_f32_16x16x32_bf16 v[8:11], v[136:139], v[214:217], v[8:11]
	v_mfma_f32_16x16x32_bf16 v[8:11], v[140:143], v[218:221], v[8:11]
	s_setprio 0
	s_setprio 1
	v_mfma_f32_16x16x32_bf16 v[52:55], v[144:147], v[180:183], v[52:55]
	v_mfma_f32_16x16x32_bf16 v[52:55], v[148:151], v[194:197], v[52:55]
	v_mfma_f32_16x16x32_bf16 v[48:51], v[172:175], v[180:183], v[48:51]
	v_mfma_f32_16x16x32_bf16 v[48:51], v[176:179], v[194:197], v[48:51]
	v_mfma_f32_16x16x32_bf16 v[36:39], v[144:147], v[198:201], v[36:39]
	v_mfma_f32_16x16x32_bf16 v[36:39], v[148:151], v[202:205], v[36:39]
	v_mfma_f32_16x16x32_bf16 v[32:35], v[172:175], v[198:201], v[32:35]
	v_mfma_f32_16x16x32_bf16 v[32:35], v[176:179], v[202:205], v[32:35]
	v_mfma_f32_16x16x32_bf16 v[20:23], v[144:147], v[206:209], v[20:23]
	v_mfma_f32_16x16x32_bf16 v[20:23], v[148:151], v[210:213], v[20:23]
	v_mfma_f32_16x16x32_bf16 v[16:19], v[172:175], v[206:209], v[16:19]
	v_mfma_f32_16x16x32_bf16 v[16:19], v[176:179], v[210:213], v[16:19]
	v_mfma_f32_16x16x32_bf16 v[4:7], v[144:147], v[214:217], v[4:7]
	v_mfma_f32_16x16x32_bf16 v[4:7], v[148:151], v[218:221], v[4:7]
	v_mfma_f32_16x16x32_bf16 v[0:3], v[172:175], v[214:217], v[0:3]
	v_mfma_f32_16x16x32_bf16 v[0:3], v[176:179], v[218:221], v[0:3]
	s_setprio 0
	s_barrier
	s_add_i32 s83, s83, 2
	s_add_u32 s81, s81, 0x100
	s_addc_u32 s82, s82, 0
	s_cmp_gt_u32 s83, 41
	s_mov_b64 s[54:55], s[56:57]
	s_branch .LBB0_159
.Lfa_1:
	ds_read_b128 v[128:131], v189
	ds_read_b128 v[132:135], v189 offset:1024
	ds_read_b128 v[136:139], v189 offset:2048
	ds_read_b128 v[140:143], v189 offset:3072
	ds_read_b128 v[144:147], v190
	ds_read_b128 v[148:151], v190 offset:1024
	ds_read_b128 v[172:175], v190 offset:2048
	ds_read_b128 v[176:179], v190 offset:3072
	s_add_u32 s56, s54, 0x100
	s_addc_u32 s57, s55, 0
	s_cmp_eq_u32 s83, 40
	s_cselect_b32 s61, s15, s57
	s_cselect_b32 s60, s14, s56
	s_cselect_b32 s59, s53, s82
	s_cselect_b32 s58, s52, s81
	v_lshl_add_u64 v[222:223], s[54:55], 0, v[166:167]
	s_add_i32 m0, s66, 0xc000
	ds_read_b128 v[180:183], v191
	ds_read_b128 v[194:197], v191 offset:1024
	ds_read_b128 v[198:201], v191 offset:2048
	ds_read_b128 v[202:205], v191 offset:3072
	ds_read_b128 v[206:209], v191 offset:4096
	ds_read_b128 v[210:213], v191 offset:5120
	ds_read_b128 v[214:217], v191 offset:6144
	ds_read_b128 v[218:221], v191 offset:7168
	global_load_lds_dwordx4 v[222:223], off
	v_lshl_add_u64 v[222:223], s[54:55], 0, v[164:165]
	s_add_i32 m0, s66, 0xe000
	s_nop 0
	global_load_lds_dwordx4 v[222:223], off
	s_waitcnt vmcnt(8)
	s_waitcnt lgkmcnt(0)
	s_barrier
	s_setprio 1
	s_waitcnt lgkmcnt(0)
	v_mfma_f32_16x16x32_bf16 v[124:127], v[128:131], v[180:183], 0
	v_mfma_f32_16x16x32_bf16 v[120:123], v[136:139], v[180:183], 0
	v_mfma_f32_16x16x32_bf16 v[108:111], v[128:131], v[198:201], 0
	v_mfma_f32_16x16x32_bf16 v[104:107], v[136:139], v[198:201], 0
	v_mfma_f32_16x16x32_bf16 v[92:95], v[128:131], v[206:209], 0
	v_mfma_f32_16x16x32_bf16 v[88:91], v[136:139], v[206:209], 0
	v_mfma_f32_16x16x32_bf16 v[76:79], v[128:131], v[214:217], 0
	v_mfma_f32_16x16x32_bf16 v[72:75], v[136:139], v[214:217], 0
	v_mfma_f32_16x16x32_bf16 v[124:127], v[132:135], v[194:197], v[124:127]
	v_mfma_f32_16x16x32_bf16 v[120:123], v[140:143], v[194:197], v[120:123]
	v_mfma_f32_16x16x32_bf16 v[108:111], v[132:135], v[202:205], v[108:111]
	v_mfma_f32_16x16x32_bf16 v[104:107], v[140:143], v[202:205], v[104:107]
	v_mfma_f32_16x16x32_bf16 v[92:95], v[132:135], v[210:213], v[92:95]
	v_mfma_f32_16x16x32_bf16 v[88:91], v[140:143], v[210:213], v[88:91]
	v_mfma_f32_16x16x32_bf16 v[76:79], v[132:135], v[218:221], v[76:79]
	v_mfma_f32_16x16x32_bf16 v[72:75], v[140:143], v[218:221], v[72:75]
	s_setprio 0
	s_setprio 1
	v_mfma_f32_16x16x32_bf16 v[116:119], v[144:147], v[180:183], 0
	v_mfma_f32_16x16x32_bf16 v[112:115], v[172:175], v[180:183], 0
	v_mfma_f32_16x16x32_bf16 v[100:103], v[144:147], v[198:201], 0
	v_mfma_f32_16x16x32_bf16 v[96:99], v[172:175], v[198:201], 0
	v_mfma_f32_16x16x32_bf16 v[84:87], v[144:147], v[206:209], 0
	v_mfma_f32_16x16x32_bf16 v[80:83], v[172:175], v[206:209], 0
	v_mfma_f32_16x16x32_bf16 v[68:71], v[144:147], v[214:217], 0
	v_mfma_f32_16x16x32_bf16 v[64:67], v[172:175], v[214:217], 0
	v_mfma_f32_16x16x32_bf16 v[116:119], v[148:151], v[194:197], v[116:119]
	v_mfma_f32_16x16x32_bf16 v[112:115], v[176:179], v[194:197], v[112:115]
	v_mfma_f32_16x16x32_bf16 v[100:103], v[148:151], v[202:205], v[100:103]
	v_mfma_f32_16x16x32_bf16 v[96:99], v[176:179], v[202:205], v[96:99]
	v_mfma_f32_16x16x32_bf16 v[84:87], v[148:151], v[210:213], v[84:87]
	v_mfma_f32_16x16x32_bf16 v[80:83], v[176:179], v[210:213], v[80:83]
	v_mfma_f32_16x16x32_bf16 v[68:71], v[148:151], v[218:221], v[68:71]
	v_mfma_f32_16x16x32_bf16 v[64:67], v[176:179], v[218:221], v[64:67]
	s_setprio 0
	s_barrier
	s_add_i32 s54, s77, s65
	v_lshl_add_u64 v[222:223], s[58:59], 0, v[154:155]
	s_mov_b32 m0, s54
	ds_read_b128 v[180:183], v191 offset:16384
	ds_read_b128 v[194:197], v191 offset:17408
	ds_read_b128 v[198:201], v191 offset:18432
	ds_read_b128 v[202:205], v191 offset:19456
	ds_read_b128 v[206:209], v191 offset:20480
	ds_read_b128 v[210:213], v191 offset:21504
	ds_read_b128 v[214:217], v191 offset:22528
	ds_read_b128 v[218:221], v191 offset:23552
	global_load_lds_dwordx4 v[222:223], off
	s_add_i32 m0, s54, 0x2000
	s_add_u32 s54, s58, 0xb0000
	v_lshl_add_u64 v[224:225], s[58:59], 0, v[162:163]
	s_addc_u32 s55, s59, 0
	s_add_i32 s84, s78, s65
	global_load_lds_dwordx4 v[224:225], off
	v_lshl_add_u64 v[226:227], s[54:55], 0, v[154:155]
	s_mov_b32 m0, s84
	v_lshl_add_u64 v[228:229], s[60:61], 0, v[160:161]
	global_load_lds_dwordx4 v[226:227], off
	v_lshl_add_u64 v[226:227], s[54:55], 0, v[162:163]
	s_add_i32 m0, s84, 0x2000
	s_nop 0
	global_load_lds_dwordx4 v[226:227], off
	v_lshl_add_u64 v[226:227], s[60:61], 0, v[152:153]
	s_mov_b32 m0, s66
	s_nop 0
	global_load_lds_dwordx4 v[226:227], off
	s_mov_b32 m0, s67
	s_nop 0
	global_load_lds_dwordx4 v[228:229], off
	s_waitcnt vmcnt(8)
	s_waitcnt lgkmcnt(0)
	s_barrier
	s_setprio 1
	s_waitcnt lgkmcnt(0)
	v_mfma_f32_16x16x32_bf16 v[60:63], v[128:131], v[180:183], 0
	v_mfma_f32_16x16x32_bf16 v[56:59], v[136:139], v[180:183], 0
	v_mfma_f32_16x16x32_bf16 v[44:47], v[128:131], v[198:201], 0
	v_mfma_f32_16x16x32_bf16 v[40:43], v[136:139], v[198:201], 0
	v_mfma_f32_16x16x32_bf16 v[28:31], v[128:131], v[206:209], 0
	v_mfma_f32_16x16x32_bf16 v[24:27], v[136:139], v[206:209], 0
	v_mfma_f32_16x16x32_bf16 v[12:15], v[128:131], v[214:217], 0
	v_mfma_f32_16x16x32_bf16 v[8:11], v[136:139], v[214:217], 0
	v_mfma_f32_16x16x32_bf16 v[60:63], v[132:135], v[194:197], v[60:63]
	v_mfma_f32_16x16x32_bf16 v[56:59], v[140:143], v[194:197], v[56:59]
	v_mfma_f32_16x16x32_bf16 v[44:47], v[132:135], v[202:205], v[44:47]
	v_mfma_f32_16x16x32_bf16 v[40:43], v[140:143], v[202:205], v[40:43]
	v_mfma_f32_16x16x32_bf16 v[28:31], v[132:135], v[210:213], v[28:31]
	v_mfma_f32_16x16x32_bf16 v[24:27], v[140:143], v[210:213], v[24:27]
	v_mfma_f32_16x16x32_bf16 v[12:15], v[132:135], v[218:221], v[12:15]
	v_mfma_f32_16x16x32_bf16 v[8:11], v[140:143], v[218:221], v[8:11]
	s_setprio 0
	s_setprio 1
	v_mfma_f32_16x16x32_bf16 v[52:55], v[144:147], v[180:183], 0
	v_mfma_f32_16x16x32_bf16 v[48:51], v[172:175], v[180:183], 0
	v_mfma_f32_16x16x32_bf16 v[36:39], v[144:147], v[198:201], 0
	v_mfma_f32_16x16x32_bf16 v[32:35], v[172:175], v[198:201], 0
	v_mfma_f32_16x16x32_bf16 v[20:23], v[144:147], v[206:209], 0
	v_mfma_f32_16x16x32_bf16 v[16:19], v[172:175], v[206:209], 0
	v_mfma_f32_16x16x32_bf16 v[4:7], v[144:147], v[214:217], 0
	v_mfma_f32_16x16x32_bf16 v[0:3], v[172:175], v[214:217], 0
	v_mfma_f32_16x16x32_bf16 v[52:55], v[148:151], v[194:197], v[52:55]
	v_mfma_f32_16x16x32_bf16 v[48:51], v[176:179], v[194:197], v[48:51]
	v_mfma_f32_16x16x32_bf16 v[36:39], v[148:151], v[202:205], v[36:39]
	v_mfma_f32_16x16x32_bf16 v[32:35], v[176:179], v[202:205], v[32:35]
	v_mfma_f32_16x16x32_bf16 v[20:23], v[148:151], v[210:213], v[20:23]
	v_mfma_f32_16x16x32_bf16 v[16:19], v[176:179], v[210:213], v[16:19]
	v_mfma_f32_16x16x32_bf16 v[4:7], v[148:151], v[218:221], v[4:7]
	v_mfma_f32_16x16x32_bf16 v[0:3], v[176:179], v[218:221], v[0:3]
	s_setprio 0
	s_barrier
	s_add_i32 s84, 0, 0x18000
	s_add_i32 s85, 0, 0x1c000
	v_add_u32_e32 v140, s84, v186
	v_add_u32_e32 v176, s85, v186
	ds_read_b128 v[128:131], v140
	ds_read_b128 v[132:135], v140 offset:1024
	ds_read_b128 v[136:139], v140 offset:2048
	ds_read_b128 v[140:143], v140 offset:3072
	ds_read_b128 v[144:147], v176
	ds_read_b128 v[148:151], v176 offset:1024
	ds_read_b128 v[172:175], v176 offset:2048
	ds_read_b128 v[176:179], v176 offset:3072
	s_add_u32 s54, s60, 0xb0000
	s_addc_u32 s55, s61, 0
	s_mov_b32 m0, s68
	v_lshl_add_u64 v[230:231], s[54:55], 0, v[152:153]
	ds_read_b128 v[180:183], v191 offset:32768
	ds_read_b128 v[194:197], v191 offset:33792
	ds_read_b128 v[198:201], v191 offset:34816
	ds_read_b128 v[202:205], v191 offset:35840
	ds_read_b128 v[206:209], v191 offset:36864
	ds_read_b128 v[210:213], v191 offset:37888
	ds_read_b128 v[214:217], v191 offset:38912
	ds_read_b128 v[218:221], v191 offset:39936
	global_load_lds_dwordx4 v[230:231], off
	v_lshl_add_u64 v[230:231], s[54:55], 0, v[160:161]
	s_mov_b32 m0, s69
	s_nop 0
	global_load_lds_dwordx4 v[230:231], off
	s_waitcnt vmcnt(8)
	s_waitcnt lgkmcnt(0)
	s_barrier
	s_setprio 1
	s_waitcnt lgkmcnt(0)
	v_mfma_f32_16x16x32_bf16 v[124:127], v[128:131], v[180:183], v[124:127]
	v_mfma_f32_16x16x32_bf16 v[124:127], v[132:135], v[194:197], v[124:127]
	v_mfma_f32_16x16x32_bf16 v[120:123], v[136:139], v[180:183], v[120:123]
	v_mfma_f32_16x16x32_bf16 v[120:123], v[140:143], v[194:197], v[120:123]
	v_mfma_f32_16x16x32_bf16 v[108:111], v[128:131], v[198:201], v[108:111]
	v_mfma_f32_16x16x32_bf16 v[108:111], v[132:135], v[202:205], v[108:111]
	v_mfma_f32_16x16x32_bf16 v[104:107], v[136:139], v[198:201], v[104:107]
	v_mfma_f32_16x16x32_bf16 v[104:107], v[140:143], v[202:205], v[104:107]
	v_mfma_f32_16x16x32_bf16 v[92:95], v[128:131], v[206:209], v[92:95]
	v_mfma_f32_16x16x32_bf16 v[92:95], v[132:135], v[210:213], v[92:95]
	v_mfma_f32_16x16x32_bf16 v[88:91], v[136:139], v[206:209], v[88:91]
	v_mfma_f32_16x16x32_bf16 v[88:91], v[140:143], v[210:213], v[88:91]
	v_mfma_f32_16x16x32_bf16 v[76:79], v[128:131], v[214:217], v[76:79]
	v_mfma_f32_16x16x32_bf16 v[76:79], v[132:135], v[218:221], v[76:79]
	v_mfma_f32_16x16x32_bf16 v[72:75], v[136:139], v[214:217], v[72:75]
	v_mfma_f32_16x16x32_bf16 v[72:75], v[140:143], v[218:221], v[72:75]
	s_setprio 0
	s_setprio 1
	v_mfma_f32_16x16x32_bf16 v[116:119], v[144:147], v[180:183], v[116:119]
	v_mfma_f32_16x16x32_bf16 v[116:119], v[148:151], v[194:197], v[116:119]
	v_mfma_f32_16x16x32_bf16 v[112:115], v[172:175], v[180:183], v[112:115]
	v_mfma_f32_16x16x32_bf16 v[112:115], v[176:179], v[194:197], v[112:115]
	v_mfma_f32_16x16x32_bf16 v[100:103], v[144:147], v[198:201], v[100:103]
	v_mfma_f32_16x16x32_bf16 v[100:103], v[148:151], v[202:205], v[100:103]
	v_mfma_f32_16x16x32_bf16 v[96:99], v[172:175], v[198:201], v[96:99]
	v_mfma_f32_16x16x32_bf16 v[96:99], v[176:179], v[202:205], v[96:99]
	v_mfma_f32_16x16x32_bf16 v[84:87], v[144:147], v[206:209], v[84:87]
	v_mfma_f32_16x16x32_bf16 v[84:87], v[148:151], v[210:213], v[84:87]
	v_mfma_f32_16x16x32_bf16 v[80:83], v[172:175], v[206:209], v[80:83]
	v_mfma_f32_16x16x32_bf16 v[80:83], v[176:179], v[210:213], v[80:83]
	v_mfma_f32_16x16x32_bf16 v[68:71], v[144:147], v[214:217], v[68:71]
	v_mfma_f32_16x16x32_bf16 v[68:71], v[148:151], v[218:221], v[68:71]
	v_mfma_f32_16x16x32_bf16 v[64:67], v[172:175], v[214:217], v[64:67]
	v_mfma_f32_16x16x32_bf16 v[64:67], v[176:179], v[218:221], v[64:67]
	s_setprio 0
	s_barrier
	s_add_i32 s54, s84, s65
	v_lshl_add_u64 v[222:223], v[222:223], 0, s[28:29]
	s_mov_b32 m0, s54
	ds_read_b128 v[180:183], v191 offset:49152
	ds_read_b128 v[194:197], v191 offset:50176
	ds_read_b128 v[198:201], v191 offset:51200
	ds_read_b128 v[202:205], v191 offset:52224
	ds_read_b128 v[206:209], v191 offset:53248
	ds_read_b128 v[210:213], v191 offset:54272
	ds_read_b128 v[214:217], v191 offset:55296
	ds_read_b128 v[218:221], v191 offset:56320
	global_load_lds_dwordx4 v[222:223], off
	s_add_i32 m0, s54, 0x2000
	s_add_u32 s54, s58, 0xb0080
	v_lshl_add_u64 v[222:223], v[224:225], 0, s[28:29]
	s_addc_u32 s55, s59, 0
	s_add_i32 s58, s85, s65
	global_load_lds_dwordx4 v[222:223], off
	v_lshl_add_u64 v[222:223], s[54:55], 0, v[154:155]
	s_mov_b32 m0, s58
	s_nop 0
	global_load_lds_dwordx4 v[222:223], off
	v_lshl_add_u64 v[222:223], s[54:55], 0, v[162:163]
	s_add_i32 m0, s58, 0x2000
	s_nop 0
	global_load_lds_dwordx4 v[222:223], off
	v_lshl_add_u64 v[222:223], v[226:227], 0, s[28:29]
	s_mov_b32 m0, s3
	s_nop 0
	global_load_lds_dwordx4 v[222:223], off
	v_lshl_add_u64 v[222:223], v[228:229], 0, s[28:29]
	s_mov_b32 m0, s71
	s_nop 0
	global_load_lds_dwordx4 v[222:223], off
	s_waitcnt vmcnt(8)
	s_waitcnt lgkmcnt(0)
	s_barrier
	s_setprio 1
	s_waitcnt lgkmcnt(0)
	v_mfma_f32_16x16x32_bf16 v[60:63], v[128:131], v[180:183], v[60:63]
	v_mfma_f32_16x16x32_bf16 v[60:63], v[132:135], v[194:197], v[60:63]
	v_mfma_f32_16x16x32_bf16 v[56:59], v[136:139], v[180:183], v[56:59]
	v_mfma_f32_16x16x32_bf16 v[56:59], v[140:143], v[194:197], v[56:59]
	v_mfma_f32_16x16x32_bf16 v[44:47], v[128:131], v[198:201], v[44:47]
	v_mfma_f32_16x16x32_bf16 v[44:47], v[132:135], v[202:205], v[44:47]
	v_mfma_f32_16x16x32_bf16 v[40:43], v[136:139], v[198:201], v[40:43]
	v_mfma_f32_16x16x32_bf16 v[40:43], v[140:143], v[202:205], v[40:43]
	v_mfma_f32_16x16x32_bf16 v[28:31], v[128:131], v[206:209], v[28:31]
	v_mfma_f32_16x16x32_bf16 v[28:31], v[132:135], v[210:213], v[28:31]
	v_mfma_f32_16x16x32_bf16 v[24:27], v[136:139], v[206:209], v[24:27]
	v_mfma_f32_16x16x32_bf16 v[24:27], v[140:143], v[210:213], v[24:27]
	v_mfma_f32_16x16x32_bf16 v[12:15], v[128:131], v[214:217], v[12:15]
	v_mfma_f32_16x16x32_bf16 v[12:15], v[132:135], v[218:221], v[12:15]
	v_mfma_f32_16x16x32_bf16 v[8:11], v[136:139], v[214:217], v[8:11]
	v_mfma_f32_16x16x32_bf16 v[8:11], v[140:143], v[218:221], v[8:11]
	s_setprio 0
	s_setprio 1
	v_mfma_f32_16x16x32_bf16 v[52:55], v[144:147], v[180:183], v[52:55]
	v_mfma_f32_16x16x32_bf16 v[52:55], v[148:151], v[194:197], v[52:55]
	v_mfma_f32_16x16x32_bf16 v[48:51], v[172:175], v[180:183], v[48:51]
	v_mfma_f32_16x16x32_bf16 v[48:51], v[176:179], v[194:197], v[48:51]
	v_mfma_f32_16x16x32_bf16 v[36:39], v[144:147], v[198:201], v[36:39]
	v_mfma_f32_16x16x32_bf16 v[36:39], v[148:151], v[202:205], v[36:39]
	v_mfma_f32_16x16x32_bf16 v[32:35], v[172:175], v[198:201], v[32:35]
	v_mfma_f32_16x16x32_bf16 v[32:35], v[176:179], v[202:205], v[32:35]
	v_mfma_f32_16x16x32_bf16 v[20:23], v[144:147], v[206:209], v[20:23]
	v_mfma_f32_16x16x32_bf16 v[20:23], v[148:151], v[210:213], v[20:23]
	v_mfma_f32_16x16x32_bf16 v[16:19], v[172:175], v[206:209], v[16:19]
	v_mfma_f32_16x16x32_bf16 v[16:19], v[176:179], v[210:213], v[16:19]
	v_mfma_f32_16x16x32_bf16 v[4:7], v[144:147], v[214:217], v[4:7]
	v_mfma_f32_16x16x32_bf16 v[4:7], v[148:151], v[218:221], v[4:7]
	v_mfma_f32_16x16x32_bf16 v[0:3], v[172:175], v[214:217], v[0:3]
	v_mfma_f32_16x16x32_bf16 v[0:3], v[176:179], v[218:221], v[0:3]
	s_setprio 0
	s_barrier
	s_add_i32 s83, s83, 2
	s_add_u32 s81, s81, 0x100
	s_addc_u32 s82, s82, 0
	s_cmp_gt_u32 s83, 41
	s_mov_b64 s[54:55], s[56:57]
.LBB0_159:
	ds_read_b128 v[128:131], v189
	ds_read_b128 v[132:135], v189 offset:1024
	ds_read_b128 v[136:139], v189 offset:2048
	ds_read_b128 v[140:143], v189 offset:3072
	ds_read_b128 v[144:147], v190
	ds_read_b128 v[148:151], v190 offset:1024
	ds_read_b128 v[172:175], v190 offset:2048
	ds_read_b128 v[176:179], v190 offset:3072
	s_add_u32 s56, s54, 0x100
	s_addc_u32 s57, s55, 0
	s_cmp_eq_u32 s83, 40
	s_cselect_b32 s61, s15, s57
	s_cselect_b32 s60, s14, s56
	s_cselect_b32 s59, s53, s82
	s_cselect_b32 s58, s52, s81
	v_lshl_add_u64 v[222:223], s[54:55], 0, v[166:167]
	s_add_i32 m0, s66, 0xc000
	ds_read_b128 v[180:183], v191
	ds_read_b128 v[194:197], v191 offset:1024
	ds_read_b128 v[198:201], v191 offset:2048
	ds_read_b128 v[202:205], v191 offset:3072
	ds_read_b128 v[206:209], v191 offset:4096
	ds_read_b128 v[210:213], v191 offset:5120
	ds_read_b128 v[214:217], v191 offset:6144
	ds_read_b128 v[218:221], v191 offset:7168
	global_load_lds_dwordx4 v[222:223], off
	v_lshl_add_u64 v[222:223], s[54:55], 0, v[164:165]
	s_add_i32 m0, s66, 0xe000
	s_nop 0
	global_load_lds_dwordx4 v[222:223], off
	s_waitcnt vmcnt(8)
	s_waitcnt lgkmcnt(0)
	s_barrier
	s_setprio 1
	s_waitcnt lgkmcnt(0)
	v_mfma_f32_16x16x32_bf16 v[124:127], v[128:131], v[180:183], v[124:127]
	v_mfma_f32_16x16x32_bf16 v[124:127], v[132:135], v[194:197], v[124:127]
	v_mfma_f32_16x16x32_bf16 v[120:123], v[136:139], v[180:183], v[120:123]
	v_mfma_f32_16x16x32_bf16 v[120:123], v[140:143], v[194:197], v[120:123]
	v_mfma_f32_16x16x32_bf16 v[108:111], v[128:131], v[198:201], v[108:111]
	v_mfma_f32_16x16x32_bf16 v[108:111], v[132:135], v[202:205], v[108:111]
	v_mfma_f32_16x16x32_bf16 v[104:107], v[136:139], v[198:201], v[104:107]
	v_mfma_f32_16x16x32_bf16 v[104:107], v[140:143], v[202:205], v[104:107]
	v_mfma_f32_16x16x32_bf16 v[92:95], v[128:131], v[206:209], v[92:95]
	v_mfma_f32_16x16x32_bf16 v[92:95], v[132:135], v[210:213], v[92:95]
	v_mfma_f32_16x16x32_bf16 v[88:91], v[136:139], v[206:209], v[88:91]
	v_mfma_f32_16x16x32_bf16 v[88:91], v[140:143], v[210:213], v[88:91]
	v_mfma_f32_16x16x32_bf16 v[76:79], v[128:131], v[214:217], v[76:79]
	v_mfma_f32_16x16x32_bf16 v[76:79], v[132:135], v[218:221], v[76:79]
	v_mfma_f32_16x16x32_bf16 v[72:75], v[136:139], v[214:217], v[72:75]
	v_mfma_f32_16x16x32_bf16 v[72:75], v[140:143], v[218:221], v[72:75]
	s_setprio 0
	s_setprio 1
	v_mfma_f32_16x16x32_bf16 v[116:119], v[144:147], v[180:183], v[116:119]
	v_mfma_f32_16x16x32_bf16 v[116:119], v[148:151], v[194:197], v[116:119]
	v_mfma_f32_16x16x32_bf16 v[112:115], v[172:175], v[180:183], v[112:115]
	v_mfma_f32_16x16x32_bf16 v[112:115], v[176:179], v[194:197], v[112:115]
	v_mfma_f32_16x16x32_bf16 v[100:103], v[144:147], v[198:201], v[100:103]
	v_mfma_f32_16x16x32_bf16 v[100:103], v[148:151], v[202:205], v[100:103]
	v_mfma_f32_16x16x32_bf16 v[96:99], v[172:175], v[198:201], v[96:99]
	v_mfma_f32_16x16x32_bf16 v[96:99], v[176:179], v[202:205], v[96:99]
	v_mfma_f32_16x16x32_bf16 v[84:87], v[144:147], v[206:209], v[84:87]
	v_mfma_f32_16x16x32_bf16 v[84:87], v[148:151], v[210:213], v[84:87]
	v_mfma_f32_16x16x32_bf16 v[80:83], v[172:175], v[206:209], v[80:83]
	v_mfma_f32_16x16x32_bf16 v[80:83], v[176:179], v[210:213], v[80:83]
	v_mfma_f32_16x16x32_bf16 v[68:71], v[144:147], v[214:217], v[68:71]
	v_mfma_f32_16x16x32_bf16 v[68:71], v[148:151], v[218:221], v[68:71]
	v_mfma_f32_16x16x32_bf16 v[64:67], v[172:175], v[214:217], v[64:67]
	v_mfma_f32_16x16x32_bf16 v[64:67], v[176:179], v[218:221], v[64:67]
	s_setprio 0
	s_barrier
	s_add_i32 s54, s77, s65
	v_lshl_add_u64 v[222:223], s[58:59], 0, v[154:155]
	s_mov_b32 m0, s54
	ds_read_b128 v[180:183], v191 offset:16384
	ds_read_b128 v[194:197], v191 offset:17408
	ds_read_b128 v[198:201], v191 offset:18432
	ds_read_b128 v[202:205], v191 offset:19456
	ds_read_b128 v[206:209], v191 offset:20480
	ds_read_b128 v[210:213], v191 offset:21504
	ds_read_b128 v[214:217], v191 offset:22528
	ds_read_b128 v[218:221], v191 offset:23552
	global_load_lds_dwordx4 v[222:223], off
	s_add_i32 m0, s54, 0x2000
	s_add_u32 s54, s58, 0xb0000
	v_lshl_add_u64 v[224:225], s[58:59], 0, v[162:163]
	s_addc_u32 s55, s59, 0
	s_add_i32 s84, s78, s65
	global_load_lds_dwordx4 v[224:225], off
	v_lshl_add_u64 v[226:227], s[54:55], 0, v[154:155]
	s_mov_b32 m0, s84
	v_lshl_add_u64 v[228:229], s[60:61], 0, v[160:161]
	global_load_lds_dwordx4 v[226:227], off
	v_lshl_add_u64 v[226:227], s[54:55], 0, v[162:163]
	s_add_i32 m0, s84, 0x2000
	s_nop 0
	global_load_lds_dwordx4 v[226:227], off
	v_lshl_add_u64 v[226:227], s[60:61], 0, v[152:153]
	s_mov_b32 m0, s66
	s_nop 0
	global_load_lds_dwordx4 v[226:227], off
	s_mov_b32 m0, s67
	s_nop 0
	global_load_lds_dwordx4 v[228:229], off
	s_waitcnt vmcnt(8)
	s_waitcnt lgkmcnt(0)
	s_barrier
	s_setprio 1
	s_waitcnt lgkmcnt(0)
	v_mfma_f32_16x16x32_bf16 v[60:63], v[128:131], v[180:183], v[60:63]
	v_mfma_f32_16x16x32_bf16 v[60:63], v[132:135], v[194:197], v[60:63]
	v_mfma_f32_16x16x32_bf16 v[56:59], v[136:139], v[180:183], v[56:59]
	v_mfma_f32_16x16x32_bf16 v[56:59], v[140:143], v[194:197], v[56:59]
	v_mfma_f32_16x16x32_bf16 v[44:47], v[128:131], v[198:201], v[44:47]
	v_mfma_f32_16x16x32_bf16 v[44:47], v[132:135], v[202:205], v[44:47]
	v_mfma_f32_16x16x32_bf16 v[40:43], v[136:139], v[198:201], v[40:43]
	v_mfma_f32_16x16x32_bf16 v[40:43], v[140:143], v[202:205], v[40:43]
	v_mfma_f32_16x16x32_bf16 v[28:31], v[128:131], v[206:209], v[28:31]
	v_mfma_f32_16x16x32_bf16 v[28:31], v[132:135], v[210:213], v[28:31]
	v_mfma_f32_16x16x32_bf16 v[24:27], v[136:139], v[206:209], v[24:27]
	v_mfma_f32_16x16x32_bf16 v[24:27], v[140:143], v[210:213], v[24:27]
	v_mfma_f32_16x16x32_bf16 v[12:15], v[128:131], v[214:217], v[12:15]
	v_mfma_f32_16x16x32_bf16 v[12:15], v[132:135], v[218:221], v[12:15]
	v_mfma_f32_16x16x32_bf16 v[8:11], v[136:139], v[214:217], v[8:11]
	v_mfma_f32_16x16x32_bf16 v[8:11], v[140:143], v[218:221], v[8:11]
	s_setprio 0
	s_setprio 1
	v_mfma_f32_16x16x32_bf16 v[52:55], v[144:147], v[180:183], v[52:55]
	v_mfma_f32_16x16x32_bf16 v[52:55], v[148:151], v[194:197], v[52:55]
	v_mfma_f32_16x16x32_bf16 v[48:51], v[172:175], v[180:183], v[48:51]
	v_mfma_f32_16x16x32_bf16 v[48:51], v[176:179], v[194:197], v[48:51]
	v_mfma_f32_16x16x32_bf16 v[36:39], v[144:147], v[198:201], v[36:39]
	v_mfma_f32_16x16x32_bf16 v[36:39], v[148:151], v[202:205], v[36:39]
	v_mfma_f32_16x16x32_bf16 v[32:35], v[172:175], v[198:201], v[32:35]
	v_mfma_f32_16x16x32_bf16 v[32:35], v[176:179], v[202:205], v[32:35]
	v_mfma_f32_16x16x32_bf16 v[20:23], v[144:147], v[206:209], v[20:23]
	v_mfma_f32_16x16x32_bf16 v[20:23], v[148:151], v[210:213], v[20:23]
	v_mfma_f32_16x16x32_bf16 v[16:19], v[172:175], v[206:209], v[16:19]
	v_mfma_f32_16x16x32_bf16 v[16:19], v[176:179], v[210:213], v[16:19]
	v_mfma_f32_16x16x32_bf16 v[4:7], v[144:147], v[214:217], v[4:7]
	v_mfma_f32_16x16x32_bf16 v[4:7], v[148:151], v[218:221], v[4:7]
	v_mfma_f32_16x16x32_bf16 v[0:3], v[172:175], v[214:217], v[0:3]
	v_mfma_f32_16x16x32_bf16 v[0:3], v[176:179], v[218:221], v[0:3]
	s_setprio 0
	s_barrier
	s_add_i32 s84, 0, 0x18000
	s_add_i32 s85, 0, 0x1c000
	v_add_u32_e32 v140, s84, v186
	v_add_u32_e32 v176, s85, v186
	ds_read_b128 v[128:131], v140
	ds_read_b128 v[132:135], v140 offset:1024
	ds_read_b128 v[136:139], v140 offset:2048
	ds_read_b128 v[140:143], v140 offset:3072
	ds_read_b128 v[144:147], v176
	ds_read_b128 v[148:151], v176 offset:1024
	ds_read_b128 v[172:175], v176 offset:2048
	ds_read_b128 v[176:179], v176 offset:3072
	s_add_u32 s54, s60, 0xb0000
	s_addc_u32 s55, s61, 0
	s_mov_b32 m0, s68
	v_lshl_add_u64 v[230:231], s[54:55], 0, v[152:153]
	ds_read_b128 v[180:183], v191 offset:32768
	ds_read_b128 v[194:197], v191 offset:33792
	ds_read_b128 v[198:201], v191 offset:34816
	ds_read_b128 v[202:205], v191 offset:35840
	ds_read_b128 v[206:209], v191 offset:36864
	ds_read_b128 v[210:213], v191 offset:37888
	ds_read_b128 v[214:217], v191 offset:38912
	ds_read_b128 v[218:221], v191 offset:39936
	global_load_lds_dwordx4 v[230:231], off
	v_lshl_add_u64 v[230:231], s[54:55], 0, v[160:161]
	s_mov_b32 m0, s69
	s_nop 0
	global_load_lds_dwordx4 v[230:231], off
	s_waitcnt vmcnt(8)
	s_waitcnt lgkmcnt(0)
	s_barrier
	s_setprio 1
	s_waitcnt lgkmcnt(0)
	v_mfma_f32_16x16x32_bf16 v[124:127], v[128:131], v[180:183], v[124:127]
	v_mfma_f32_16x16x32_bf16 v[124:127], v[132:135], v[194:197], v[124:127]
	v_mfma_f32_16x16x32_bf16 v[120:123], v[136:139], v[180:183], v[120:123]
	v_mfma_f32_16x16x32_bf16 v[120:123], v[140:143], v[194:197], v[120:123]
	v_mfma_f32_16x16x32_bf16 v[108:111], v[128:131], v[198:201], v[108:111]
	v_mfma_f32_16x16x32_bf16 v[108:111], v[132:135], v[202:205], v[108:111]
	v_mfma_f32_16x16x32_bf16 v[104:107], v[136:139], v[198:201], v[104:107]
	v_mfma_f32_16x16x32_bf16 v[104:107], v[140:143], v[202:205], v[104:107]
	v_mfma_f32_16x16x32_bf16 v[92:95], v[128:131], v[206:209], v[92:95]
	v_mfma_f32_16x16x32_bf16 v[92:95], v[132:135], v[210:213], v[92:95]
	v_mfma_f32_16x16x32_bf16 v[88:91], v[136:139], v[206:209], v[88:91]
	v_mfma_f32_16x16x32_bf16 v[88:91], v[140:143], v[210:213], v[88:91]
	v_mfma_f32_16x16x32_bf16 v[76:79], v[128:131], v[214:217], v[76:79]
	v_mfma_f32_16x16x32_bf16 v[76:79], v[132:135], v[218:221], v[76:79]
	v_mfma_f32_16x16x32_bf16 v[72:75], v[136:139], v[214:217], v[72:75]
	v_mfma_f32_16x16x32_bf16 v[72:75], v[140:143], v[218:221], v[72:75]
	s_setprio 0
	s_setprio 1
	v_mfma_f32_16x16x32_bf16 v[116:119], v[144:147], v[180:183], v[116:119]
	v_mfma_f32_16x16x32_bf16 v[116:119], v[148:151], v[194:197], v[116:119]
	v_mfma_f32_16x16x32_bf16 v[112:115], v[172:175], v[180:183], v[112:115]
	v_mfma_f32_16x16x32_bf16 v[112:115], v[176:179], v[194:197], v[112:115]
	v_mfma_f32_16x16x32_bf16 v[100:103], v[144:147], v[198:201], v[100:103]
	v_mfma_f32_16x16x32_bf16 v[100:103], v[148:151], v[202:205], v[100:103]
	v_mfma_f32_16x16x32_bf16 v[96:99], v[172:175], v[198:201], v[96:99]
	v_mfma_f32_16x16x32_bf16 v[96:99], v[176:179], v[202:205], v[96:99]
	v_mfma_f32_16x16x32_bf16 v[84:87], v[144:147], v[206:209], v[84:87]
	v_mfma_f32_16x16x32_bf16 v[84:87], v[148:151], v[210:213], v[84:87]
	v_mfma_f32_16x16x32_bf16 v[80:83], v[172:175], v[206:209], v[80:83]
	v_mfma_f32_16x16x32_bf16 v[80:83], v[176:179], v[210:213], v[80:83]
	v_mfma_f32_16x16x32_bf16 v[68:71], v[144:147], v[214:217], v[68:71]
	v_mfma_f32_16x16x32_bf16 v[68:71], v[148:151], v[218:221], v[68:71]
	v_mfma_f32_16x16x32_bf16 v[64:67], v[172:175], v[214:217], v[64:67]
	v_mfma_f32_16x16x32_bf16 v[64:67], v[176:179], v[218:221], v[64:67]
	s_setprio 0
	s_barrier
	s_add_i32 s54, s84, s65
	v_lshl_add_u64 v[222:223], v[222:223], 0, s[28:29]
	s_mov_b32 m0, s54
	ds_read_b128 v[180:183], v191 offset:49152
	ds_read_b128 v[194:197], v191 offset:50176
	ds_read_b128 v[198:201], v191 offset:51200
	ds_read_b128 v[202:205], v191 offset:52224
	ds_read_b128 v[206:209], v191 offset:53248
	ds_read_b128 v[210:213], v191 offset:54272
	ds_read_b128 v[214:217], v191 offset:55296
	ds_read_b128 v[218:221], v191 offset:56320
	global_load_lds_dwordx4 v[222:223], off
	s_add_i32 m0, s54, 0x2000
	s_add_u32 s54, s58, 0xb0080
	v_lshl_add_u64 v[222:223], v[224:225], 0, s[28:29]
	s_addc_u32 s55, s59, 0
	s_add_i32 s58, s85, s65
	global_load_lds_dwordx4 v[222:223], off
	v_lshl_add_u64 v[222:223], s[54:55], 0, v[154:155]
	s_mov_b32 m0, s58
	s_nop 0
	global_load_lds_dwordx4 v[222:223], off
	v_lshl_add_u64 v[222:223], s[54:55], 0, v[162:163]
	s_add_i32 m0, s58, 0x2000
	s_nop 0
	global_load_lds_dwordx4 v[222:223], off
	v_lshl_add_u64 v[222:223], v[226:227], 0, s[28:29]
	s_mov_b32 m0, s3
	s_nop 0
	global_load_lds_dwordx4 v[222:223], off
	v_lshl_add_u64 v[222:223], v[228:229], 0, s[28:29]
	s_mov_b32 m0, s71
	s_nop 0
	global_load_lds_dwordx4 v[222:223], off
	s_waitcnt vmcnt(8)
	s_waitcnt lgkmcnt(0)
	s_barrier
	s_setprio 1
	s_waitcnt lgkmcnt(0)
	v_mfma_f32_16x16x32_bf16 v[60:63], v[128:131], v[180:183], v[60:63]
	v_mfma_f32_16x16x32_bf16 v[60:63], v[132:135], v[194:197], v[60:63]
	v_mfma_f32_16x16x32_bf16 v[56:59], v[136:139], v[180:183], v[56:59]
	v_mfma_f32_16x16x32_bf16 v[56:59], v[140:143], v[194:197], v[56:59]
	v_mfma_f32_16x16x32_bf16 v[44:47], v[128:131], v[198:201], v[44:47]
	v_mfma_f32_16x16x32_bf16 v[44:47], v[132:135], v[202:205], v[44:47]
	v_mfma_f32_16x16x32_bf16 v[40:43], v[136:139], v[198:201], v[40:43]
	v_mfma_f32_16x16x32_bf16 v[40:43], v[140:143], v[202:205], v[40:43]
	v_mfma_f32_16x16x32_bf16 v[28:31], v[128:131], v[206:209], v[28:31]
	v_mfma_f32_16x16x32_bf16 v[28:31], v[132:135], v[210:213], v[28:31]
	v_mfma_f32_16x16x32_bf16 v[24:27], v[136:139], v[206:209], v[24:27]
	v_mfma_f32_16x16x32_bf16 v[24:27], v[140:143], v[210:213], v[24:27]
	v_mfma_f32_16x16x32_bf16 v[12:15], v[128:131], v[214:217], v[12:15]
	v_mfma_f32_16x16x32_bf16 v[12:15], v[132:135], v[218:221], v[12:15]
	v_mfma_f32_16x16x32_bf16 v[8:11], v[136:139], v[214:217], v[8:11]
	v_mfma_f32_16x16x32_bf16 v[8:11], v[140:143], v[218:221], v[8:11]
	s_setprio 0
	s_setprio 1
	v_mfma_f32_16x16x32_bf16 v[52:55], v[144:147], v[180:183], v[52:55]
	v_mfma_f32_16x16x32_bf16 v[52:55], v[148:151], v[194:197], v[52:55]
	v_mfma_f32_16x16x32_bf16 v[48:51], v[172:175], v[180:183], v[48:51]
	v_mfma_f32_16x16x32_bf16 v[48:51], v[176:179], v[194:197], v[48:51]
	v_mfma_f32_16x16x32_bf16 v[36:39], v[144:147], v[198:201], v[36:39]
	v_mfma_f32_16x16x32_bf16 v[36:39], v[148:151], v[202:205], v[36:39]
	v_mfma_f32_16x16x32_bf16 v[32:35], v[172:175], v[198:201], v[32:35]
	v_mfma_f32_16x16x32_bf16 v[32:35], v[176:179], v[202:205], v[32:35]
	v_mfma_f32_16x16x32_bf16 v[20:23], v[144:147], v[206:209], v[20:23]
	v_mfma_f32_16x16x32_bf16 v[20:23], v[148:151], v[210:213], v[20:23]
	v_mfma_f32_16x16x32_bf16 v[16:19], v[172:175], v[206:209], v[16:19]
	v_mfma_f32_16x16x32_bf16 v[16:19], v[176:179], v[210:213], v[16:19]
	v_mfma_f32_16x16x32_bf16 v[4:7], v[144:147], v[214:217], v[4:7]
	v_mfma_f32_16x16x32_bf16 v[4:7], v[148:151], v[218:221], v[4:7]
	v_mfma_f32_16x16x32_bf16 v[0:3], v[172:175], v[214:217], v[0:3]
	v_mfma_f32_16x16x32_bf16 v[0:3], v[176:179], v[218:221], v[0:3]
	s_setprio 0
	s_barrier
	s_add_i32 s83, s83, 2
	s_add_u32 s81, s81, 0x100
	s_addc_u32 s82, s82, 0
	s_cmp_gt_u32 s83, 41
	s_mov_b64 s[54:55], s[56:57]
	s_cbranch_scc0 .LBB0_159
	s_and_b64 vcc, exec, s[30:31]
	s_cbranch_vccz .LBB0_162
	s_barrier

.LBB0_254:
	s_ashr_i32 s61, s60, 31
	s_lshl_b64 s[62:63], s[60:61], 19
	s_add_u32 s62, s35, s62
	s_addc_u32 s63, s47, s63
	s_and_b64 s[64:65], s[12:13], exec
	s_cselect_b32 s3, s63, s69
	s_cselect_b32 s61, s62, s68
	s_ashr_i32 s59, s58, 31
	s_lshl_b64 s[64:65], s[58:59], 19
	s_add_u32 s64, s49, s64
	s_addc_u32 s65, s70, s65
	s_and_b64 s[92:93], s[12:13], exec
	s_cselect_b32 s91, s65, s67
	s_cselect_b32 s92, s64, s66
	s_lshl_b32 s59, s14, 8
	v_add_u32_e32 v0, s59, v182
	s_add_u32 s93, s66, 0x100
	s_waitcnt lgkmcnt(0)
	v_ashrrev_i32_e32 v1, 31, v0
	s_addc_u32 s94, s67, 0
	v_lshl_add_u64 v[72:73], v[0:1], 4, s[26:27]
	s_add_u32 s14, s68, 0x40080
	s_addc_u32 s15, s69, 0
	s_mov_b32 s95, -2
	s_mov_b64 s[66:67], 0
	s_cmp_eq_u32 s90, 1
	s_cbranch_scc1 .Lfa_2
	v_add_u32_e32 v74, s83, v181
	ds_read_b128 v[88:91], v74
	ds_read_b128 v[108:111], v74 offset:1024
	ds_read_b128 v[128:131], v74 offset:2048
	ds_read_b128 v[144:147], v74 offset:3072
	v_add_u32_e32 v74, s84, v181
	ds_read_b128 v[148:151], v74
	ds_read_b128 v[152:155], v74 offset:1024
	ds_read_b128 v[176:179], v74 offset:2048
	ds_read_b128 v[190:193], v74 offset:3072
	s_add_u32 s68, s14, 0xfffc0080
	s_addc_u32 s69, s15, -1
	s_and_b64 s[66:67], s[66:67], exec
	s_cselect_b32 s69, s3, s69
	s_cselect_b32 s68, s61, s68
	s_cselect_b32 s67, s91, s94
	s_cselect_b32 s66, s92, s93
	v_lshl_add_u64 v[74:75], s[14:15], 0, v[170:171]
	s_add_i32 m0, s74, 0xc000
	ds_read_b128 v[194:197], v187
	ds_read_b128 v[198:201], v187 offset:1024
	ds_read_b128 v[202:205], v187 offset:2048
	ds_read_b128 v[206:209], v187 offset:3072
	ds_read_b128 v[210:213], v187 offset:4096
	ds_read_b128 v[214:217], v187 offset:5120
	ds_read_b128 v[218:221], v187 offset:6144
	ds_read_b128 v[222:225], v187 offset:7168
	global_load_lds_dwordx4 v[74:75], off
	v_lshl_add_u64 v[74:75], s[14:15], 0, v[168:169]
	s_add_i32 m0, s74, 0xe000
	s_nop 0
	global_load_lds_dwordx4 v[74:75], off
	s_waitcnt vmcnt(24)
	s_waitcnt lgkmcnt(0)
	s_barrier
	s_setprio 1
	s_waitcnt lgkmcnt(0)
	v_mfma_f32_16x16x32_bf16 v[140:143], v[88:91], v[194:197], 0
	v_mfma_f32_16x16x32_bf16 v[136:139], v[128:131], v[194:197], 0
	v_mfma_f32_16x16x32_bf16 v[120:123], v[88:91], v[202:205], 0
	v_mfma_f32_16x16x32_bf16 v[116:119], v[128:131], v[202:205], 0
	v_mfma_f32_16x16x32_bf16 v[100:103], v[88:91], v[210:213], 0
	v_mfma_f32_16x16x32_bf16 v[96:99], v[128:131], v[210:213], 0
	v_mfma_f32_16x16x32_bf16 v[80:83], v[88:91], v[218:221], 0
	v_mfma_f32_16x16x32_bf16 v[74:77], v[128:131], v[218:221], 0
	v_mfma_f32_16x16x32_bf16 v[140:143], v[108:111], v[198:201], v[140:143]
	v_mfma_f32_16x16x32_bf16 v[136:139], v[144:147], v[198:201], v[136:139]
	v_mfma_f32_16x16x32_bf16 v[120:123], v[108:111], v[206:209], v[120:123]
	v_mfma_f32_16x16x32_bf16 v[116:119], v[144:147], v[206:209], v[116:119]
	v_mfma_f32_16x16x32_bf16 v[100:103], v[108:111], v[214:217], v[100:103]
	v_mfma_f32_16x16x32_bf16 v[96:99], v[144:147], v[214:217], v[96:99]
	v_mfma_f32_16x16x32_bf16 v[80:83], v[108:111], v[222:225], v[80:83]
	v_mfma_f32_16x16x32_bf16 v[74:77], v[144:147], v[222:225], v[74:77]
	s_setprio 0
	s_setprio 1
	v_mfma_f32_16x16x32_bf16 v[132:135], v[148:151], v[194:197], 0
	v_mfma_f32_16x16x32_bf16 v[124:127], v[176:179], v[194:197], 0
	v_mfma_f32_16x16x32_bf16 v[112:115], v[148:151], v[202:205], 0
	v_mfma_f32_16x16x32_bf16 v[104:107], v[176:179], v[202:205], 0
	v_mfma_f32_16x16x32_bf16 v[92:95], v[148:151], v[210:213], 0
	v_mfma_f32_16x16x32_bf16 v[84:87], v[176:179], v[210:213], 0
	v_mfma_f32_16x16x32_bf16 v[68:71], v[148:151], v[218:221], 0
	v_mfma_f32_16x16x32_bf16 v[64:67], v[176:179], v[218:221], 0
	v_mfma_f32_16x16x32_bf16 v[132:135], v[152:155], v[198:201], v[132:135]
	v_mfma_f32_16x16x32_bf16 v[124:127], v[190:193], v[198:201], v[124:127]
	v_mfma_f32_16x16x32_bf16 v[112:115], v[152:155], v[206:209], v[112:115]
	v_mfma_f32_16x16x32_bf16 v[104:107], v[190:193], v[206:209], v[104:107]
	v_mfma_f32_16x16x32_bf16 v[92:95], v[152:155], v[214:217], v[92:95]
	v_mfma_f32_16x16x32_bf16 v[84:87], v[190:193], v[214:217], v[84:87]
	v_mfma_f32_16x16x32_bf16 v[68:71], v[152:155], v[222:225], v[68:71]
	v_mfma_f32_16x16x32_bf16 v[64:67], v[190:193], v[222:225], v[64:67]
	s_setprio 0
	s_barrier
	s_add_i32 s96, s83, s71
	v_lshl_add_u64 v[226:227], s[66:67], 0, v[162:163]
	s_mov_b32 m0, s96
	ds_read_b128 v[194:197], v187 offset:16384
	ds_read_b128 v[198:201], v187 offset:17408
	ds_read_b128 v[202:205], v187 offset:18432
	ds_read_b128 v[206:209], v187 offset:19456
	ds_read_b128 v[210:213], v187 offset:20480
	ds_read_b128 v[214:217], v187 offset:21504
	ds_read_b128 v[218:221], v187 offset:22528
	ds_read_b128 v[222:225], v187 offset:23552
	global_load_lds_dwordx4 v[226:227], off
	s_add_i32 m0, s96, 0x2000
	s_add_u32 s96, s66, 0x40000
	v_lshl_add_u64 v[228:229], s[66:67], 0, v[166:167]
	s_addc_u32 s97, s67, 0
	s_add_i32 vcc_lo, s84, s71
	global_load_lds_dwordx4 v[228:229], off
	v_lshl_add_u64 v[78:79], s[96:97], 0, v[162:163]
	s_mov_b32 m0, vcc_lo
	v_lshl_add_u64 v[230:231], s[68:69], 0, v[160:161]
	global_load_lds_dwordx4 v[78:79], off
	v_lshl_add_u64 v[78:79], s[96:97], 0, v[166:167]
	s_add_i32 m0, vcc_lo, 0x2000
	v_lshl_add_u64 v[232:233], s[68:69], 0, v[164:165]
	global_load_lds_dwordx4 v[78:79], off
	s_mov_b32 m0, s74
	s_nop 0
	global_load_lds_dwordx4 v[230:231], off
	s_mov_b32 m0, s75
	s_nop 0
	global_load_lds_dwordx4 v[232:233], off
	s_waitcnt vmcnt(24)
	s_waitcnt lgkmcnt(0)
	s_barrier
	s_setprio 1
	s_waitcnt lgkmcnt(0)
	v_mfma_f32_16x16x32_bf16 v[60:63], v[88:91], v[194:197], 0
	v_mfma_f32_16x16x32_bf16 v[56:59], v[128:131], v[194:197], 0
	v_mfma_f32_16x16x32_bf16 v[44:47], v[88:91], v[202:205], 0
	v_mfma_f32_16x16x32_bf16 v[40:43], v[128:131], v[202:205], 0
	v_mfma_f32_16x16x32_bf16 v[28:31], v[88:91], v[210:213], 0
	v_mfma_f32_16x16x32_bf16 v[24:27], v[128:131], v[210:213], 0
	v_mfma_f32_16x16x32_bf16 v[12:15], v[88:91], v[218:221], 0
	v_mfma_f32_16x16x32_bf16 v[8:11], v[128:131], v[218:221], 0
	v_mfma_f32_16x16x32_bf16 v[60:63], v[108:111], v[198:201], v[60:63]
	v_mfma_f32_16x16x32_bf16 v[56:59], v[144:147], v[198:201], v[56:59]
	v_mfma_f32_16x16x32_bf16 v[44:47], v[108:111], v[206:209], v[44:47]
	v_mfma_f32_16x16x32_bf16 v[40:43], v[144:147], v[206:209], v[40:43]
	v_mfma_f32_16x16x32_bf16 v[28:31], v[108:111], v[214:217], v[28:31]
	v_mfma_f32_16x16x32_bf16 v[24:27], v[144:147], v[214:217], v[24:27]
	v_mfma_f32_16x16x32_bf16 v[12:15], v[108:111], v[222:225], v[12:15]
	v_mfma_f32_16x16x32_bf16 v[8:11], v[144:147], v[222:225], v[8:11]
	s_setprio 0
	s_setprio 1
	v_mfma_f32_16x16x32_bf16 v[52:55], v[148:151], v[194:197], 0
	v_mfma_f32_16x16x32_bf16 v[48:51], v[176:179], v[194:197], 0
	v_mfma_f32_16x16x32_bf16 v[36:39], v[148:151], v[202:205], 0
	v_mfma_f32_16x16x32_bf16 v[32:35], v[176:179], v[202:205], 0
	v_mfma_f32_16x16x32_bf16 v[20:23], v[148:151], v[210:213], 0
	v_mfma_f32_16x16x32_bf16 v[16:19], v[176:179], v[210:213], 0
	v_mfma_f32_16x16x32_bf16 v[4:7], v[148:151], v[218:221], 0
	v_mfma_f32_16x16x32_bf16 v[0:3], v[176:179], v[218:221], 0
	v_mfma_f32_16x16x32_bf16 v[52:55], v[152:155], v[198:201], v[52:55]
	v_mfma_f32_16x16x32_bf16 v[48:51], v[190:193], v[198:201], v[48:51]
	v_mfma_f32_16x16x32_bf16 v[36:39], v[152:155], v[206:209], v[36:39]
	v_mfma_f32_16x16x32_bf16 v[32:35], v[190:193], v[206:209], v[32:35]
	v_mfma_f32_16x16x32_bf16 v[20:23], v[152:155], v[214:217], v[20:23]
	v_mfma_f32_16x16x32_bf16 v[16:19], v[190:193], v[214:217], v[16:19]
	v_mfma_f32_16x16x32_bf16 v[4:7], v[152:155], v[222:225], v[4:7]
	v_mfma_f32_16x16x32_bf16 v[0:3], v[190:193], v[222:225], v[0:3]
	s_setprio 0
	s_barrier
	s_add_i32 s96, 0, 0x18000
	v_add_u32_e32 v78, s96, v181
	s_add_i32 s97, 0, 0x1c000
	ds_read_b128 v[88:91], v78
	ds_read_b128 v[108:111], v78 offset:1024
	ds_read_b128 v[128:131], v78 offset:2048
	ds_read_b128 v[144:147], v78 offset:3072
	v_add_u32_e32 v78, s97, v181
	ds_read_b128 v[148:151], v78
	ds_read_b128 v[152:155], v78 offset:1024
	ds_read_b128 v[176:179], v78 offset:2048
	ds_read_b128 v[190:193], v78 offset:3072
	s_add_u32 s68, s68, 0x40000
	s_addc_u32 s69, s69, 0
	s_mov_b32 m0, s76
	v_lshl_add_u64 v[78:79], s[68:69], 0, v[160:161]
	ds_read_b128 v[194:197], v187 offset:32768
	ds_read_b128 v[198:201], v187 offset:33792
	ds_read_b128 v[202:205], v187 offset:34816
	ds_read_b128 v[206:209], v187 offset:35840
	ds_read_b128 v[210:213], v187 offset:36864
	ds_read_b128 v[214:217], v187 offset:37888
	ds_read_b128 v[218:221], v187 offset:38912
	ds_read_b128 v[222:225], v187 offset:39936
	global_load_lds_dwordx4 v[78:79], off
	v_lshl_add_u64 v[78:79], s[68:69], 0, v[164:165]
	s_mov_b32 m0, s77
	s_nop 0
	global_load_lds_dwordx4 v[78:79], off
	s_waitcnt vmcnt(8)
	s_waitcnt lgkmcnt(0)
	s_barrier
	s_setprio 1
	s_waitcnt lgkmcnt(0)
	v_mfma_f32_16x16x32_bf16 v[140:143], v[88:91], v[194:197], v[140:143]
	v_mfma_f32_16x16x32_bf16 v[136:139], v[128:131], v[194:197], v[136:139]
	v_mfma_f32_16x16x32_bf16 v[120:123], v[88:91], v[202:205], v[120:123]
	v_mfma_f32_16x16x32_bf16 v[116:119], v[128:131], v[202:205], v[116:119]
	v_mfma_f32_16x16x32_bf16 v[100:103], v[88:91], v[210:213], v[100:103]
	v_mfma_f32_16x16x32_bf16 v[96:99], v[128:131], v[210:213], v[96:99]
	v_mfma_f32_16x16x32_bf16 v[78:81], v[88:91], v[218:221], v[80:83]
	v_mfma_f32_16x16x32_bf16 v[74:77], v[128:131], v[218:221], v[74:77]
	v_mfma_f32_16x16x32_bf16 v[140:143], v[108:111], v[198:201], v[140:143]
	v_mfma_f32_16x16x32_bf16 v[136:139], v[144:147], v[198:201], v[136:139]
	v_mfma_f32_16x16x32_bf16 v[120:123], v[108:111], v[206:209], v[120:123]
	v_mfma_f32_16x16x32_bf16 v[116:119], v[144:147], v[206:209], v[116:119]
	v_mfma_f32_16x16x32_bf16 v[100:103], v[108:111], v[214:217], v[100:103]
	v_mfma_f32_16x16x32_bf16 v[96:99], v[144:147], v[214:217], v[96:99]
	v_mfma_f32_16x16x32_bf16 v[80:83], v[108:111], v[222:225], v[78:81]
	v_mfma_f32_16x16x32_bf16 v[76:79], v[144:147], v[222:225], v[74:77]
	s_setprio 0
	s_setprio 1
	v_mfma_f32_16x16x32_bf16 v[132:135], v[148:151], v[194:197], v[132:135]
	v_mfma_f32_16x16x32_bf16 v[132:135], v[152:155], v[198:201], v[132:135]
	v_mfma_f32_16x16x32_bf16 v[124:127], v[176:179], v[194:197], v[124:127]
	v_mfma_f32_16x16x32_bf16 v[124:127], v[190:193], v[198:201], v[124:127]
	v_mfma_f32_16x16x32_bf16 v[112:115], v[148:151], v[202:205], v[112:115]
	v_mfma_f32_16x16x32_bf16 v[112:115], v[152:155], v[206:209], v[112:115]
	v_mfma_f32_16x16x32_bf16 v[104:107], v[176:179], v[202:205], v[104:107]
	v_mfma_f32_16x16x32_bf16 v[104:107], v[190:193], v[206:209], v[104:107]
	v_mfma_f32_16x16x32_bf16 v[92:95], v[148:151], v[210:213], v[92:95]
	v_mfma_f32_16x16x32_bf16 v[92:95], v[152:155], v[214:217], v[92:95]
	v_mfma_f32_16x16x32_bf16 v[84:87], v[176:179], v[210:213], v[84:87]
	v_mfma_f32_16x16x32_bf16 v[84:87], v[190:193], v[214:217], v[84:87]
	v_mfma_f32_16x16x32_bf16 v[68:71], v[148:151], v[218:221], v[68:71]
	v_mfma_f32_16x16x32_bf16 v[68:71], v[152:155], v[222:225], v[68:71]
	v_mfma_f32_16x16x32_bf16 v[64:67], v[176:179], v[218:221], v[64:67]
	v_mfma_f32_16x16x32_bf16 v[64:67], v[190:193], v[222:225], v[64:67]
	s_setprio 0
	s_barrier
	s_add_i32 s68, s96, s71
	v_lshl_add_u64 v[74:75], v[226:227], 0, s[28:29]
	s_mov_b32 m0, s68
	ds_read_b128 v[194:197], v187 offset:49152
	ds_read_b128 v[198:201], v187 offset:50176
	ds_read_b128 v[202:205], v187 offset:51200
	ds_read_b128 v[206:209], v187 offset:52224
	ds_read_b128 v[210:213], v187 offset:53248
	ds_read_b128 v[214:217], v187 offset:54272
	ds_read_b128 v[218:221], v187 offset:55296
	ds_read_b128 v[222:225], v187 offset:56320
	global_load_lds_dwordx4 v[74:75], off
	s_add_i32 m0, s68, 0x2000
	s_add_u32 s66, s66, 0x40080
	v_lshl_add_u64 v[74:75], v[228:229], 0, s[28:29]
	s_addc_u32 s67, s67, 0
	s_add_i32 s68, s97, s71
	global_load_lds_dwordx4 v[74:75], off
	v_lshl_add_u64 v[74:75], s[66:67], 0, v[162:163]
	s_mov_b32 m0, s68
	s_nop 0
	global_load_lds_dwordx4 v[74:75], off
	v_lshl_add_u64 v[74:75], s[66:67], 0, v[166:167]
	s_add_i32 m0, s68, 0x2000
	s_nop 0
	global_load_lds_dwordx4 v[74:75], off
	v_lshl_add_u64 v[74:75], v[230:231], 0, s[28:29]
	s_mov_b32 m0, s78
	s_nop 0
	global_load_lds_dwordx4 v[74:75], off
	v_lshl_add_u64 v[74:75], v[232:233], 0, s[28:29]
	s_mov_b32 m0, s79
	s_nop 0
	global_load_lds_dwordx4 v[74:75], off
	s_waitcnt vmcnt(8)
	s_waitcnt lgkmcnt(0)
	s_barrier
	s_setprio 1
	s_waitcnt lgkmcnt(0)
	v_mfma_f32_16x16x32_bf16 v[60:63], v[88:91], v[194:197], v[60:63]
	v_mfma_f32_16x16x32_bf16 v[60:63], v[108:111], v[198:201], v[60:63]
	v_mfma_f32_16x16x32_bf16 v[56:59], v[128:131], v[194:197], v[56:59]
	v_mfma_f32_16x16x32_bf16 v[56:59], v[144:147], v[198:201], v[56:59]
	v_mfma_f32_16x16x32_bf16 v[44:47], v[88:91], v[202:205], v[44:47]
	v_mfma_f32_16x16x32_bf16 v[44:47], v[108:111], v[206:209], v[44:47]
	v_mfma_f32_16x16x32_bf16 v[40:43], v[128:131], v[202:205], v[40:43]
	v_mfma_f32_16x16x32_bf16 v[40:43], v[144:147], v[206:209], v[40:43]
	v_mfma_f32_16x16x32_bf16 v[28:31], v[88:91], v[210:213], v[28:31]
	v_mfma_f32_16x16x32_bf16 v[28:31], v[108:111], v[214:217], v[28:31]
	v_mfma_f32_16x16x32_bf16 v[24:27], v[128:131], v[210:213], v[24:27]
	v_mfma_f32_16x16x32_bf16 v[24:27], v[144:147], v[214:217], v[24:27]
	v_mfma_f32_16x16x32_bf16 v[12:15], v[88:91], v[218:221], v[12:15]
	v_mfma_f32_16x16x32_bf16 v[12:15], v[108:111], v[222:225], v[12:15]
	v_mfma_f32_16x16x32_bf16 v[8:11], v[128:131], v[218:221], v[8:11]
	v_mfma_f32_16x16x32_bf16 v[8:11], v[144:147], v[222:225], v[8:11]
	s_setprio 0
	s_setprio 1
	v_mfma_f32_16x16x32_bf16 v[52:55], v[148:151], v[194:197], v[52:55]
	v_mfma_f32_16x16x32_bf16 v[52:55], v[152:155], v[198:201], v[52:55]
	v_mfma_f32_16x16x32_bf16 v[48:51], v[176:179], v[194:197], v[48:51]
	v_mfma_f32_16x16x32_bf16 v[48:51], v[190:193], v[198:201], v[48:51]
	v_mfma_f32_16x16x32_bf16 v[36:39], v[148:151], v[202:205], v[36:39]
	v_mfma_f32_16x16x32_bf16 v[36:39], v[152:155], v[206:209], v[36:39]
	v_mfma_f32_16x16x32_bf16 v[32:35], v[176:179], v[202:205], v[32:35]
	v_mfma_f32_16x16x32_bf16 v[32:35], v[190:193], v[206:209], v[32:35]
	v_mfma_f32_16x16x32_bf16 v[20:23], v[148:151], v[210:213], v[20:23]
	v_mfma_f32_16x16x32_bf16 v[20:23], v[152:155], v[214:217], v[20:23]
	v_mfma_f32_16x16x32_bf16 v[16:19], v[176:179], v[210:213], v[16:19]
	v_mfma_f32_16x16x32_bf16 v[16:19], v[190:193], v[214:217], v[16:19]
	v_mfma_f32_16x16x32_bf16 v[4:7], v[148:151], v[218:221], v[4:7]
	v_mfma_f32_16x16x32_bf16 v[4:7], v[152:155], v[222:225], v[4:7]
	v_mfma_f32_16x16x32_bf16 v[0:3], v[176:179], v[218:221], v[0:3]
	v_mfma_f32_16x16x32_bf16 v[0:3], v[190:193], v[222:225], v[0:3]
	s_setprio 0
	s_barrier
	s_add_i32 s95, s95, 2
	s_add_u32 s93, s93, 0x100
	s_addc_u32 s94, s94, 0
	s_add_u32 s14, s14, 0x100
	s_addc_u32 s15, s15, 0
	s_branch .LBB0_256
.Lfa_2:
	v_add_u32_e32 v74, s83, v181
	ds_read_b128 v[88:91], v74
	ds_read_b128 v[108:111], v74 offset:1024
	ds_read_b128 v[128:131], v74 offset:2048
	ds_read_b128 v[144:147], v74 offset:3072
	v_add_u32_e32 v74, s84, v181
	ds_read_b128 v[148:151], v74
	ds_read_b128 v[152:155], v74 offset:1024
	ds_read_b128 v[176:179], v74 offset:2048
	ds_read_b128 v[190:193], v74 offset:3072
	s_add_u32 s68, s14, 0xfffc0080
	s_addc_u32 s69, s15, -1
	s_and_b64 s[66:67], s[66:67], exec
	s_cselect_b32 s69, s3, s69
	s_cselect_b32 s68, s61, s68
	s_cselect_b32 s67, s91, s94
	s_cselect_b32 s66, s92, s93
	v_lshl_add_u64 v[74:75], s[14:15], 0, v[170:171]
	s_add_i32 m0, s74, 0xc000
	ds_read_b128 v[194:197], v187
	ds_read_b128 v[198:201], v187 offset:1024
	ds_read_b128 v[202:205], v187 offset:2048
	ds_read_b128 v[206:209], v187 offset:3072
	ds_read_b128 v[210:213], v187 offset:4096
	ds_read_b128 v[214:217], v187 offset:5120
	ds_read_b128 v[218:221], v187 offset:6144
	ds_read_b128 v[222:225], v187 offset:7168
	global_load_lds_dwordx4 v[74:75], off
	v_lshl_add_u64 v[74:75], s[14:15], 0, v[168:169]
	s_add_i32 m0, s74, 0xe000
	s_nop 0
	global_load_lds_dwordx4 v[74:75], off
	s_waitcnt vmcnt(8)
	s_waitcnt lgkmcnt(0)
	s_barrier
	s_setprio 1
	s_waitcnt lgkmcnt(0)
	v_mfma_f32_16x16x32_bf16 v[140:143], v[88:91], v[194:197], 0
	v_mfma_f32_16x16x32_bf16 v[136:139], v[128:131], v[194:197], 0
	v_mfma_f32_16x16x32_bf16 v[120:123], v[88:91], v[202:205], 0
	v_mfma_f32_16x16x32_bf16 v[116:119], v[128:131], v[202:205], 0
	v_mfma_f32_16x16x32_bf16 v[100:103], v[88:91], v[210:213], 0
	v_mfma_f32_16x16x32_bf16 v[96:99], v[128:131], v[210:213], 0
	v_mfma_f32_16x16x32_bf16 v[80:83], v[88:91], v[218:221], 0
	v_mfma_f32_16x16x32_bf16 v[74:77], v[128:131], v[218:221], 0
	v_mfma_f32_16x16x32_bf16 v[140:143], v[108:111], v[198:201], v[140:143]
	v_mfma_f32_16x16x32_bf16 v[136:139], v[144:147], v[198:201], v[136:139]
	v_mfma_f32_16x16x32_bf16 v[120:123], v[108:111], v[206:209], v[120:123]
	v_mfma_f32_16x16x32_bf16 v[116:119], v[144:147], v[206:209], v[116:119]
	v_mfma_f32_16x16x32_bf16 v[100:103], v[108:111], v[214:217], v[100:103]
	v_mfma_f32_16x16x32_bf16 v[96:99], v[144:147], v[214:217], v[96:99]
	v_mfma_f32_16x16x32_bf16 v[80:83], v[108:111], v[222:225], v[80:83]
	v_mfma_f32_16x16x32_bf16 v[74:77], v[144:147], v[222:225], v[74:77]
	s_setprio 0
	s_setprio 1
	v_mfma_f32_16x16x32_bf16 v[132:135], v[148:151], v[194:197], 0
	v_mfma_f32_16x16x32_bf16 v[124:127], v[176:179], v[194:197], 0
	v_mfma_f32_16x16x32_bf16 v[112:115], v[148:151], v[202:205], 0
	v_mfma_f32_16x16x32_bf16 v[104:107], v[176:179], v[202:205], 0
	v_mfma_f32_16x16x32_bf16 v[92:95], v[148:151], v[210:213], 0
	v_mfma_f32_16x16x32_bf16 v[84:87], v[176:179], v[210:213], 0
	v_mfma_f32_16x16x32_bf16 v[68:71], v[148:151], v[218:221], 0
	v_mfma_f32_16x16x32_bf16 v[64:67], v[176:179], v[218:221], 0
	v_mfma_f32_16x16x32_bf16 v[132:135], v[152:155], v[198:201], v[132:135]
	v_mfma_f32_16x16x32_bf16 v[124:127], v[190:193], v[198:201], v[124:127]
	v_mfma_f32_16x16x32_bf16 v[112:115], v[152:155], v[206:209], v[112:115]
	v_mfma_f32_16x16x32_bf16 v[104:107], v[190:193], v[206:209], v[104:107]
	v_mfma_f32_16x16x32_bf16 v[92:95], v[152:155], v[214:217], v[92:95]
	v_mfma_f32_16x16x32_bf16 v[84:87], v[190:193], v[214:217], v[84:87]
	v_mfma_f32_16x16x32_bf16 v[68:71], v[152:155], v[222:225], v[68:71]
	v_mfma_f32_16x16x32_bf16 v[64:67], v[190:193], v[222:225], v[64:67]
	s_setprio 0
	s_barrier
	s_add_i32 s96, s83, s71
	v_lshl_add_u64 v[226:227], s[66:67], 0, v[162:163]
	s_mov_b32 m0, s96
	ds_read_b128 v[194:197], v187 offset:16384
	ds_read_b128 v[198:201], v187 offset:17408
	ds_read_b128 v[202:205], v187 offset:18432
	ds_read_b128 v[206:209], v187 offset:19456
	ds_read_b128 v[210:213], v187 offset:20480
	ds_read_b128 v[214:217], v187 offset:21504
	ds_read_b128 v[218:221], v187 offset:22528
	ds_read_b128 v[222:225], v187 offset:23552
	global_load_lds_dwordx4 v[226:227], off
	s_add_i32 m0, s96, 0x2000
	s_add_u32 s96, s66, 0x40000
	v_lshl_add_u64 v[228:229], s[66:67], 0, v[166:167]
	s_addc_u32 s97, s67, 0
	s_add_i32 vcc_lo, s84, s71
	global_load_lds_dwordx4 v[228:229], off
	v_lshl_add_u64 v[78:79], s[96:97], 0, v[162:163]
	s_mov_b32 m0, vcc_lo
	v_lshl_add_u64 v[230:231], s[68:69], 0, v[160:161]
	global_load_lds_dwordx4 v[78:79], off
	v_lshl_add_u64 v[78:79], s[96:97], 0, v[166:167]
	s_add_i32 m0, vcc_lo, 0x2000
	v_lshl_add_u64 v[232:233], s[68:69], 0, v[164:165]
	global_load_lds_dwordx4 v[78:79], off
	s_mov_b32 m0, s74
	s_nop 0
	global_load_lds_dwordx4 v[230:231], off
	s_mov_b32 m0, s75
	s_nop 0
	global_load_lds_dwordx4 v[232:233], off
	s_waitcnt vmcnt(8)
	s_waitcnt lgkmcnt(0)
	s_barrier
	s_setprio 1
	s_waitcnt lgkmcnt(0)
	v_mfma_f32_16x16x32_bf16 v[60:63], v[88:91], v[194:197], 0
	v_mfma_f32_16x16x32_bf16 v[56:59], v[128:131], v[194:197], 0
	v_mfma_f32_16x16x32_bf16 v[44:47], v[88:91], v[202:205], 0
	v_mfma_f32_16x16x32_bf16 v[40:43], v[128:131], v[202:205], 0
	v_mfma_f32_16x16x32_bf16 v[28:31], v[88:91], v[210:213], 0
	v_mfma_f32_16x16x32_bf16 v[24:27], v[128:131], v[210:213], 0
	v_mfma_f32_16x16x32_bf16 v[12:15], v[88:91], v[218:221], 0
	v_mfma_f32_16x16x32_bf16 v[8:11], v[128:131], v[218:221], 0
	v_mfma_f32_16x16x32_bf16 v[60:63], v[108:111], v[198:201], v[60:63]
	v_mfma_f32_16x16x32_bf16 v[56:59], v[144:147], v[198:201], v[56:59]
	v_mfma_f32_16x16x32_bf16 v[44:47], v[108:111], v[206:209], v[44:47]
	v_mfma_f32_16x16x32_bf16 v[40:43], v[144:147], v[206:209], v[40:43]
	v_mfma_f32_16x16x32_bf16 v[28:31], v[108:111], v[214:217], v[28:31]
	v_mfma_f32_16x16x32_bf16 v[24:27], v[144:147], v[214:217], v[24:27]
	v_mfma_f32_16x16x32_bf16 v[12:15], v[108:111], v[222:225], v[12:15]
	v_mfma_f32_16x16x32_bf16 v[8:11], v[144:147], v[222:225], v[8:11]
	s_setprio 0
	s_setprio 1
	v_mfma_f32_16x16x32_bf16 v[52:55], v[148:151], v[194:197], 0
	v_mfma_f32_16x16x32_bf16 v[48:51], v[176:179], v[194:197], 0
	v_mfma_f32_16x16x32_bf16 v[36:39], v[148:151], v[202:205], 0
	v_mfma_f32_16x16x32_bf16 v[32:35], v[176:179], v[202:205], 0
	v_mfma_f32_16x16x32_bf16 v[20:23], v[148:151], v[210:213], 0
	v_mfma_f32_16x16x32_bf16 v[16:19], v[176:179], v[210:213], 0
	v_mfma_f32_16x16x32_bf16 v[4:7], v[148:151], v[218:221], 0
	v_mfma_f32_16x16x32_bf16 v[0:3], v[176:179], v[218:221], 0
	v_mfma_f32_16x16x32_bf16 v[52:55], v[152:155], v[198:201], v[52:55]
	v_mfma_f32_16x16x32_bf16 v[48:51], v[190:193], v[198:201], v[48:51]
	v_mfma_f32_16x16x32_bf16 v[36:39], v[152:155], v[206:209], v[36:39]
	v_mfma_f32_16x16x32_bf16 v[32:35], v[190:193], v[206:209], v[32:35]
	v_mfma_f32_16x16x32_bf16 v[20:23], v[152:155], v[214:217], v[20:23]
	v_mfma_f32_16x16x32_bf16 v[16:19], v[190:193], v[214:217], v[16:19]
	v_mfma_f32_16x16x32_bf16 v[4:7], v[152:155], v[222:225], v[4:7]
	v_mfma_f32_16x16x32_bf16 v[0:3], v[190:193], v[222:225], v[0:3]
	s_setprio 0
	s_barrier
	s_add_i32 s96, 0, 0x18000
	v_add_u32_e32 v78, s96, v181
	s_add_i32 s97, 0, 0x1c000
	ds_read_b128 v[88:91], v78
	ds_read_b128 v[108:111], v78 offset:1024
	ds_read_b128 v[128:131], v78 offset:2048
	ds_read_b128 v[144:147], v78 offset:3072
	v_add_u32_e32 v78, s97, v181
	ds_read_b128 v[148:151], v78
	ds_read_b128 v[152:155], v78 offset:1024
	ds_read_b128 v[176:179], v78 offset:2048
	ds_read_b128 v[190:193], v78 offset:3072
	s_add_u32 s68, s68, 0x40000
	s_addc_u32 s69, s69, 0
	s_mov_b32 m0, s76
	v_lshl_add_u64 v[78:79], s[68:69], 0, v[160:161]
	ds_read_b128 v[194:197], v187 offset:32768
	ds_read_b128 v[198:201], v187 offset:33792
	ds_read_b128 v[202:205], v187 offset:34816
	ds_read_b128 v[206:209], v187 offset:35840
	ds_read_b128 v[210:213], v187 offset:36864
	ds_read_b128 v[214:217], v187 offset:37888
	ds_read_b128 v[218:221], v187 offset:38912
	ds_read_b128 v[222:225], v187 offset:39936
	global_load_lds_dwordx4 v[78:79], off
	v_lshl_add_u64 v[78:79], s[68:69], 0, v[164:165]
	s_mov_b32 m0, s77
	s_nop 0
	global_load_lds_dwordx4 v[78:79], off
	s_waitcnt vmcnt(8)
	s_waitcnt lgkmcnt(0)
	s_barrier
	s_setprio 1
	s_waitcnt lgkmcnt(0)
	v_mfma_f32_16x16x32_bf16 v[140:143], v[88:91], v[194:197], v[140:143]
	v_mfma_f32_16x16x32_bf16 v[136:139], v[128:131], v[194:197], v[136:139]
	v_mfma_f32_16x16x32_bf16 v[120:123], v[88:91], v[202:205], v[120:123]
	v_mfma_f32_16x16x32_bf16 v[116:119], v[128:131], v[202:205], v[116:119]
	v_mfma_f32_16x16x32_bf16 v[100:103], v[88:91], v[210:213], v[100:103]
	v_mfma_f32_16x16x32_bf16 v[96:99], v[128:131], v[210:213], v[96:99]
	v_mfma_f32_16x16x32_bf16 v[78:81], v[88:91], v[218:221], v[80:83]
	v_mfma_f32_16x16x32_bf16 v[74:77], v[128:131], v[218:221], v[74:77]
	v_mfma_f32_16x16x32_bf16 v[140:143], v[108:111], v[198:201], v[140:143]
	v_mfma_f32_16x16x32_bf16 v[136:139], v[144:147], v[198:201], v[136:139]
	v_mfma_f32_16x16x32_bf16 v[120:123], v[108:111], v[206:209], v[120:123]
	v_mfma_f32_16x16x32_bf16 v[116:119], v[144:147], v[206:209], v[116:119]
	v_mfma_f32_16x16x32_bf16 v[100:103], v[108:111], v[214:217], v[100:103]
	v_mfma_f32_16x16x32_bf16 v[96:99], v[144:147], v[214:217], v[96:99]
	v_mfma_f32_16x16x32_bf16 v[80:83], v[108:111], v[222:225], v[78:81]
	v_mfma_f32_16x16x32_bf16 v[76:79], v[144:147], v[222:225], v[74:77]
	s_setprio 0
	s_setprio 1
	v_mfma_f32_16x16x32_bf16 v[132:135], v[148:151], v[194:197], v[132:135]
	v_mfma_f32_16x16x32_bf16 v[132:135], v[152:155], v[198:201], v[132:135]
	v_mfma_f32_16x16x32_bf16 v[124:127], v[176:179], v[194:197], v[124:127]
	v_mfma_f32_16x16x32_bf16 v[124:127], v[190:193], v[198:201], v[124:127]
	v_mfma_f32_16x16x32_bf16 v[112:115], v[148:151], v[202:205], v[112:115]
	v_mfma_f32_16x16x32_bf16 v[112:115], v[152:155], v[206:209], v[112:115]
	v_mfma_f32_16x16x32_bf16 v[104:107], v[176:179], v[202:205], v[104:107]
	v_mfma_f32_16x16x32_bf16 v[104:107], v[190:193], v[206:209], v[104:107]
	v_mfma_f32_16x16x32_bf16 v[92:95], v[148:151], v[210:213], v[92:95]
	v_mfma_f32_16x16x32_bf16 v[92:95], v[152:155], v[214:217], v[92:95]
	v_mfma_f32_16x16x32_bf16 v[84:87], v[176:179], v[210:213], v[84:87]
	v_mfma_f32_16x16x32_bf16 v[84:87], v[190:193], v[214:217], v[84:87]
	v_mfma_f32_16x16x32_bf16 v[68:71], v[148:151], v[218:221], v[68:71]
	v_mfma_f32_16x16x32_bf16 v[68:71], v[152:155], v[222:225], v[68:71]
	v_mfma_f32_16x16x32_bf16 v[64:67], v[176:179], v[218:221], v[64:67]
	v_mfma_f32_16x16x32_bf16 v[64:67], v[190:193], v[222:225], v[64:67]
	s_setprio 0
	s_barrier
	s_add_i32 s68, s96, s71
	v_lshl_add_u64 v[74:75], v[226:227], 0, s[28:29]
	s_mov_b32 m0, s68
	ds_read_b128 v[194:197], v187 offset:49152
	ds_read_b128 v[198:201], v187 offset:50176
	ds_read_b128 v[202:205], v187 offset:51200
	ds_read_b128 v[206:209], v187 offset:52224
	ds_read_b128 v[210:213], v187 offset:53248
	ds_read_b128 v[214:217], v187 offset:54272
	ds_read_b128 v[218:221], v187 offset:55296
	ds_read_b128 v[222:225], v187 offset:56320
	global_load_lds_dwordx4 v[74:75], off
	s_add_i32 m0, s68, 0x2000
	s_add_u32 s66, s66, 0x40080
	v_lshl_add_u64 v[74:75], v[228:229], 0, s[28:29]
	s_addc_u32 s67, s67, 0
	s_add_i32 s68, s97, s71
	global_load_lds_dwordx4 v[74:75], off
	v_lshl_add_u64 v[74:75], s[66:67], 0, v[162:163]
	s_mov_b32 m0, s68
	s_nop 0
	global_load_lds_dwordx4 v[74:75], off
	v_lshl_add_u64 v[74:75], s[66:67], 0, v[166:167]
	s_add_i32 m0, s68, 0x2000
	s_nop 0
	global_load_lds_dwordx4 v[74:75], off
	v_lshl_add_u64 v[74:75], v[230:231], 0, s[28:29]
	s_mov_b32 m0, s78
	s_nop 0
	global_load_lds_dwordx4 v[74:75], off
	v_lshl_add_u64 v[74:75], v[232:233], 0, s[28:29]
	s_mov_b32 m0, s79
	s_nop 0
	global_load_lds_dwordx4 v[74:75], off
	s_waitcnt vmcnt(8)
	s_waitcnt lgkmcnt(0)
	s_barrier
	s_setprio 1
	s_waitcnt lgkmcnt(0)
	v_mfma_f32_16x16x32_bf16 v[60:63], v[88:91], v[194:197], v[60:63]
	v_mfma_f32_16x16x32_bf16 v[60:63], v[108:111], v[198:201], v[60:63]
	v_mfma_f32_16x16x32_bf16 v[56:59], v[128:131], v[194:197], v[56:59]
	v_mfma_f32_16x16x32_bf16 v[56:59], v[144:147], v[198:201], v[56:59]
	v_mfma_f32_16x16x32_bf16 v[44:47], v[88:91], v[202:205], v[44:47]
	v_mfma_f32_16x16x32_bf16 v[44:47], v[108:111], v[206:209], v[44:47]
	v_mfma_f32_16x16x32_bf16 v[40:43], v[128:131], v[202:205], v[40:43]
	v_mfma_f32_16x16x32_bf16 v[40:43], v[144:147], v[206:209], v[40:43]
	v_mfma_f32_16x16x32_bf16 v[28:31], v[88:91], v[210:213], v[28:31]
	v_mfma_f32_16x16x32_bf16 v[28:31], v[108:111], v[214:217], v[28:31]
	v_mfma_f32_16x16x32_bf16 v[24:27], v[128:131], v[210:213], v[24:27]
	v_mfma_f32_16x16x32_bf16 v[24:27], v[144:147], v[214:217], v[24:27]
	v_mfma_f32_16x16x32_bf16 v[12:15], v[88:91], v[218:221], v[12:15]
	v_mfma_f32_16x16x32_bf16 v[12:15], v[108:111], v[222:225], v[12:15]
	v_mfma_f32_16x16x32_bf16 v[8:11], v[128:131], v[218:221], v[8:11]
	v_mfma_f32_16x16x32_bf16 v[8:11], v[144:147], v[222:225], v[8:11]
	s_setprio 0
	s_setprio 1
	v_mfma_f32_16x16x32_bf16 v[52:55], v[148:151], v[194:197], v[52:55]
	v_mfma_f32_16x16x32_bf16 v[52:55], v[152:155], v[198:201], v[52:55]
	v_mfma_f32_16x16x32_bf16 v[48:51], v[176:179], v[194:197], v[48:51]
	v_mfma_f32_16x16x32_bf16 v[48:51], v[190:193], v[198:201], v[48:51]
	v_mfma_f32_16x16x32_bf16 v[36:39], v[148:151], v[202:205], v[36:39]
	v_mfma_f32_16x16x32_bf16 v[36:39], v[152:155], v[206:209], v[36:39]
	v_mfma_f32_16x16x32_bf16 v[32:35], v[176:179], v[202:205], v[32:35]
	v_mfma_f32_16x16x32_bf16 v[32:35], v[190:193], v[206:209], v[32:35]
	v_mfma_f32_16x16x32_bf16 v[20:23], v[148:151], v[210:213], v[20:23]
	v_mfma_f32_16x16x32_bf16 v[20:23], v[152:155], v[214:217], v[20:23]
	v_mfma_f32_16x16x32_bf16 v[16:19], v[176:179], v[210:213], v[16:19]
	v_mfma_f32_16x16x32_bf16 v[16:19], v[190:193], v[214:217], v[16:19]
	v_mfma_f32_16x16x32_bf16 v[4:7], v[148:151], v[218:221], v[4:7]
	v_mfma_f32_16x16x32_bf16 v[4:7], v[152:155], v[222:225], v[4:7]
	v_mfma_f32_16x16x32_bf16 v[0:3], v[176:179], v[218:221], v[0:3]
	v_mfma_f32_16x16x32_bf16 v[0:3], v[190:193], v[222:225], v[0:3]
	s_setprio 0
	s_barrier
	s_add_i32 s95, s95, 2
	s_add_u32 s93, s93, 0x100
	s_addc_u32 s94, s94, 0
	s_add_u32 s14, s14, 0x100
	s_addc_u32 s15, s15, 0
	s_branch .LBB0_256
.LBB0_255:
	v_add_u32_e32 v74, s83, v181
	ds_read_b128 v[88:91], v74
	ds_read_b128 v[108:111], v74 offset:1024
	ds_read_b128 v[128:131], v74 offset:2048
	ds_read_b128 v[144:147], v74 offset:3072
	v_add_u32_e32 v74, s84, v181
	ds_read_b128 v[148:151], v74
	ds_read_b128 v[152:155], v74 offset:1024
	ds_read_b128 v[176:179], v74 offset:2048
	ds_read_b128 v[190:193], v74 offset:3072
	s_add_u32 s68, s14, 0xfffc0080
	s_addc_u32 s69, s15, -1
	s_and_b64 s[66:67], s[66:67], exec
	s_cselect_b32 s69, s3, s69
	s_cselect_b32 s68, s61, s68
	s_cselect_b32 s67, s91, s94
	s_cselect_b32 s66, s92, s93
	v_lshl_add_u64 v[74:75], s[14:15], 0, v[170:171]
	s_add_i32 m0, s74, 0xc000
	ds_read_b128 v[194:197], v187
	ds_read_b128 v[198:201], v187 offset:1024
	ds_read_b128 v[202:205], v187 offset:2048
	ds_read_b128 v[206:209], v187 offset:3072
	ds_read_b128 v[210:213], v187 offset:4096
	ds_read_b128 v[214:217], v187 offset:5120
	ds_read_b128 v[218:221], v187 offset:6144
	ds_read_b128 v[222:225], v187 offset:7168
	global_load_lds_dwordx4 v[74:75], off
	v_lshl_add_u64 v[74:75], s[14:15], 0, v[168:169]
	s_add_i32 m0, s74, 0xe000
	s_nop 0
	global_load_lds_dwordx4 v[74:75], off
	s_waitcnt vmcnt(8)
	s_waitcnt lgkmcnt(0)
	s_barrier
	s_setprio 1
	s_waitcnt lgkmcnt(0)
	v_mfma_f32_16x16x32_bf16 v[140:143], v[88:91], v[194:197], v[140:143]
	v_mfma_f32_16x16x32_bf16 v[136:139], v[128:131], v[194:197], v[136:139]
	v_mfma_f32_16x16x32_bf16 v[120:123], v[88:91], v[202:205], v[120:123]
	v_mfma_f32_16x16x32_bf16 v[116:119], v[128:131], v[202:205], v[116:119]
	v_mfma_f32_16x16x32_bf16 v[100:103], v[88:91], v[210:213], v[100:103]
	v_mfma_f32_16x16x32_bf16 v[96:99], v[128:131], v[210:213], v[96:99]
	v_mfma_f32_16x16x32_bf16 v[80:83], v[88:91], v[218:221], v[80:83]
	v_mfma_f32_16x16x32_bf16 v[74:77], v[128:131], v[218:221], v[76:79]
	v_mfma_f32_16x16x32_bf16 v[140:143], v[108:111], v[198:201], v[140:143]
	v_mfma_f32_16x16x32_bf16 v[136:139], v[144:147], v[198:201], v[136:139]
	v_mfma_f32_16x16x32_bf16 v[120:123], v[108:111], v[206:209], v[120:123]
	v_mfma_f32_16x16x32_bf16 v[116:119], v[144:147], v[206:209], v[116:119]
	v_mfma_f32_16x16x32_bf16 v[100:103], v[108:111], v[214:217], v[100:103]
	v_mfma_f32_16x16x32_bf16 v[96:99], v[144:147], v[214:217], v[96:99]
	v_mfma_f32_16x16x32_bf16 v[80:83], v[108:111], v[222:225], v[80:83]
	v_mfma_f32_16x16x32_bf16 v[74:77], v[144:147], v[222:225], v[74:77]
	s_setprio 0
	s_setprio 1
	v_mfma_f32_16x16x32_bf16 v[132:135], v[148:151], v[194:197], v[132:135]
	v_mfma_f32_16x16x32_bf16 v[132:135], v[152:155], v[198:201], v[132:135]
	v_mfma_f32_16x16x32_bf16 v[124:127], v[176:179], v[194:197], v[124:127]
	v_mfma_f32_16x16x32_bf16 v[124:127], v[190:193], v[198:201], v[124:127]
	v_mfma_f32_16x16x32_bf16 v[112:115], v[148:151], v[202:205], v[112:115]
	v_mfma_f32_16x16x32_bf16 v[112:115], v[152:155], v[206:209], v[112:115]
	v_mfma_f32_16x16x32_bf16 v[104:107], v[176:179], v[202:205], v[104:107]
	v_mfma_f32_16x16x32_bf16 v[104:107], v[190:193], v[206:209], v[104:107]
	v_mfma_f32_16x16x32_bf16 v[92:95], v[148:151], v[210:213], v[92:95]
	v_mfma_f32_16x16x32_bf16 v[92:95], v[152:155], v[214:217], v[92:95]
	v_mfma_f32_16x16x32_bf16 v[84:87], v[176:179], v[210:213], v[84:87]
	v_mfma_f32_16x16x32_bf16 v[84:87], v[190:193], v[214:217], v[84:87]
	v_mfma_f32_16x16x32_bf16 v[68:71], v[148:151], v[218:221], v[68:71]
	v_mfma_f32_16x16x32_bf16 v[68:71], v[152:155], v[222:225], v[68:71]
	v_mfma_f32_16x16x32_bf16 v[64:67], v[176:179], v[218:221], v[64:67]
	v_mfma_f32_16x16x32_bf16 v[64:67], v[190:193], v[222:225], v[64:67]
	s_setprio 0
	s_barrier
	s_add_i32 s96, s83, s71
	v_lshl_add_u64 v[226:227], s[66:67], 0, v[162:163]
	s_mov_b32 m0, s96
	ds_read_b128 v[194:197], v187 offset:16384
	ds_read_b128 v[198:201], v187 offset:17408
	ds_read_b128 v[202:205], v187 offset:18432
	ds_read_b128 v[206:209], v187 offset:19456
	ds_read_b128 v[210:213], v187 offset:20480
	ds_read_b128 v[214:217], v187 offset:21504
	ds_read_b128 v[218:221], v187 offset:22528
	ds_read_b128 v[222:225], v187 offset:23552
	global_load_lds_dwordx4 v[226:227], off
	s_add_i32 m0, s96, 0x2000
	s_add_u32 s96, s66, 0x40000
	v_lshl_add_u64 v[228:229], s[66:67], 0, v[166:167]
	s_addc_u32 s97, s67, 0
	s_add_i32 vcc_lo, s84, s71
	global_load_lds_dwordx4 v[228:229], off
	v_lshl_add_u64 v[78:79], s[96:97], 0, v[162:163]
	s_mov_b32 m0, vcc_lo
	v_lshl_add_u64 v[230:231], s[68:69], 0, v[160:161]
	global_load_lds_dwordx4 v[78:79], off
	v_lshl_add_u64 v[78:79], s[96:97], 0, v[166:167]
	s_add_i32 m0, vcc_lo, 0x2000
	v_lshl_add_u64 v[232:233], s[68:69], 0, v[164:165]
	global_load_lds_dwordx4 v[78:79], off
	s_mov_b32 m0, s74
	s_nop 0
	global_load_lds_dwordx4 v[230:231], off
	s_mov_b32 m0, s75
	s_nop 0
	global_load_lds_dwordx4 v[232:233], off
	s_waitcnt vmcnt(8)
	s_waitcnt lgkmcnt(0)
	s_barrier
	s_setprio 1
	s_waitcnt lgkmcnt(0)
	v_mfma_f32_16x16x32_bf16 v[60:63], v[88:91], v[194:197], v[60:63]
	v_mfma_f32_16x16x32_bf16 v[60:63], v[108:111], v[198:201], v[60:63]
	v_mfma_f32_16x16x32_bf16 v[56:59], v[128:131], v[194:197], v[56:59]
	v_mfma_f32_16x16x32_bf16 v[56:59], v[144:147], v[198:201], v[56:59]
	v_mfma_f32_16x16x32_bf16 v[44:47], v[88:91], v[202:205], v[44:47]
	v_mfma_f32_16x16x32_bf16 v[44:47], v[108:111], v[206:209], v[44:47]
	v_mfma_f32_16x16x32_bf16 v[40:43], v[128:131], v[202:205], v[40:43]
	v_mfma_f32_16x16x32_bf16 v[40:43], v[144:147], v[206:209], v[40:43]
	v_mfma_f32_16x16x32_bf16 v[28:31], v[88:91], v[210:213], v[28:31]
	v_mfma_f32_16x16x32_bf16 v[28:31], v[108:111], v[214:217], v[28:31]
	v_mfma_f32_16x16x32_bf16 v[24:27], v[128:131], v[210:213], v[24:27]
	v_mfma_f32_16x16x32_bf16 v[24:27], v[144:147], v[214:217], v[24:27]
	v_mfma_f32_16x16x32_bf16 v[12:15], v[88:91], v[218:221], v[12:15]
	v_mfma_f32_16x16x32_bf16 v[12:15], v[108:111], v[222:225], v[12:15]
	v_mfma_f32_16x16x32_bf16 v[8:11], v[128:131], v[218:221], v[8:11]
	v_mfma_f32_16x16x32_bf16 v[8:11], v[144:147], v[222:225], v[8:11]
	s_setprio 0
	s_setprio 1
	v_mfma_f32_16x16x32_bf16 v[52:55], v[148:151], v[194:197], v[52:55]
	v_mfma_f32_16x16x32_bf16 v[52:55], v[152:155], v[198:201], v[52:55]
	v_mfma_f32_16x16x32_bf16 v[48:51], v[176:179], v[194:197], v[48:51]
	v_mfma_f32_16x16x32_bf16 v[48:51], v[190:193], v[198:201], v[48:51]
	v_mfma_f32_16x16x32_bf16 v[36:39], v[148:151], v[202:205], v[36:39]
	v_mfma_f32_16x16x32_bf16 v[36:39], v[152:155], v[206:209], v[36:39]
	v_mfma_f32_16x16x32_bf16 v[32:35], v[176:179], v[202:205], v[32:35]
	v_mfma_f32_16x16x32_bf16 v[32:35], v[190:193], v[206:209], v[32:35]
	v_mfma_f32_16x16x32_bf16 v[20:23], v[148:151], v[210:213], v[20:23]
	v_mfma_f32_16x16x32_bf16 v[20:23], v[152:155], v[214:217], v[20:23]
	v_mfma_f32_16x16x32_bf16 v[16:19], v[176:179], v[210:213], v[16:19]
	v_mfma_f32_16x16x32_bf16 v[16:19], v[190:193], v[214:217], v[16:19]
	v_mfma_f32_16x16x32_bf16 v[4:7], v[148:151], v[218:221], v[4:7]
	v_mfma_f32_16x16x32_bf16 v[4:7], v[152:155], v[222:225], v[4:7]
	v_mfma_f32_16x16x32_bf16 v[0:3], v[176:179], v[218:221], v[0:3]
	v_mfma_f32_16x16x32_bf16 v[0:3], v[190:193], v[222:225], v[0:3]
	s_setprio 0
	s_barrier
	s_add_i32 s96, 0, 0x18000
	v_add_u32_e32 v78, s96, v181
	s_add_i32 s97, 0, 0x1c000
	ds_read_b128 v[88:91], v78
	ds_read_b128 v[108:111], v78 offset:1024
	ds_read_b128 v[128:131], v78 offset:2048
	ds_read_b128 v[144:147], v78 offset:3072
	v_add_u32_e32 v78, s97, v181
	ds_read_b128 v[148:151], v78
	ds_read_b128 v[152:155], v78 offset:1024
	ds_read_b128 v[176:179], v78 offset:2048
	ds_read_b128 v[190:193], v78 offset:3072
	s_add_u32 s68, s68, 0x40000
	s_addc_u32 s69, s69, 0
	s_mov_b32 m0, s76
	v_lshl_add_u64 v[78:79], s[68:69], 0, v[160:161]
	ds_read_b128 v[194:197], v187 offset:32768
	ds_read_b128 v[198:201], v187 offset:33792
	ds_read_b128 v[202:205], v187 offset:34816
	ds_read_b128 v[206:209], v187 offset:35840
	ds_read_b128 v[210:213], v187 offset:36864
	ds_read_b128 v[214:217], v187 offset:37888
	ds_read_b128 v[218:221], v187 offset:38912
	ds_read_b128 v[222:225], v187 offset:39936
	global_load_lds_dwordx4 v[78:79], off
	v_lshl_add_u64 v[78:79], s[68:69], 0, v[164:165]
	s_mov_b32 m0, s77
	s_nop 0
	global_load_lds_dwordx4 v[78:79], off
	s_waitcnt vmcnt(8)
	s_waitcnt lgkmcnt(0)
	s_barrier
	s_setprio 1
	s_waitcnt lgkmcnt(0)
	v_mfma_f32_16x16x32_bf16 v[140:143], v[88:91], v[194:197], v[140:143]
	v_mfma_f32_16x16x32_bf16 v[136:139], v[128:131], v[194:197], v[136:139]
	v_mfma_f32_16x16x32_bf16 v[120:123], v[88:91], v[202:205], v[120:123]
	v_mfma_f32_16x16x32_bf16 v[116:119], v[128:131], v[202:205], v[116:119]
	v_mfma_f32_16x16x32_bf16 v[100:103], v[88:91], v[210:213], v[100:103]
	v_mfma_f32_16x16x32_bf16 v[96:99], v[128:131], v[210:213], v[96:99]
	v_mfma_f32_16x16x32_bf16 v[78:81], v[88:91], v[218:221], v[80:83]
	v_mfma_f32_16x16x32_bf16 v[74:77], v[128:131], v[218:221], v[74:77]
	v_mfma_f32_16x16x32_bf16 v[140:143], v[108:111], v[198:201], v[140:143]
	v_mfma_f32_16x16x32_bf16 v[136:139], v[144:147], v[198:201], v[136:139]
	v_mfma_f32_16x16x32_bf16 v[120:123], v[108:111], v[206:209], v[120:123]
	v_mfma_f32_16x16x32_bf16 v[116:119], v[144:147], v[206:209], v[116:119]
	v_mfma_f32_16x16x32_bf16 v[100:103], v[108:111], v[214:217], v[100:103]
	v_mfma_f32_16x16x32_bf16 v[96:99], v[144:147], v[214:217], v[96:99]
	v_mfma_f32_16x16x32_bf16 v[80:83], v[108:111], v[222:225], v[78:81]
	v_mfma_f32_16x16x32_bf16 v[76:79], v[144:147], v[222:225], v[74:77]
	s_setprio 0
	s_setprio 1
	v_mfma_f32_16x16x32_bf16 v[132:135], v[148:151], v[194:197], v[132:135]
	v_mfma_f32_16x16x32_bf16 v[132:135], v[152:155], v[198:201], v[132:135]
	v_mfma_f32_16x16x32_bf16 v[124:127], v[176:179], v[194:197], v[124:127]
	v_mfma_f32_16x16x32_bf16 v[124:127], v[190:193], v[198:201], v[124:127]
	v_mfma_f32_16x16x32_bf16 v[112:115], v[148:151], v[202:205], v[112:115]
	v_mfma_f32_16x16x32_bf16 v[112:115], v[152:155], v[206:209], v[112:115]
	v_mfma_f32_16x16x32_bf16 v[104:107], v[176:179], v[202:205], v[104:107]
	v_mfma_f32_16x16x32_bf16 v[104:107], v[190:193], v[206:209], v[104:107]
	v_mfma_f32_16x16x32_bf16 v[92:95], v[148:151], v[210:213], v[92:95]
	v_mfma_f32_16x16x32_bf16 v[92:95], v[152:155], v[214:217], v[92:95]
	v_mfma_f32_16x16x32_bf16 v[84:87], v[176:179], v[210:213], v[84:87]
	v_mfma_f32_16x16x32_bf16 v[84:87], v[190:193], v[214:217], v[84:87]
	v_mfma_f32_16x16x32_bf16 v[68:71], v[148:151], v[218:221], v[68:71]
	v_mfma_f32_16x16x32_bf16 v[68:71], v[152:155], v[222:225], v[68:71]
	v_mfma_f32_16x16x32_bf16 v[64:67], v[176:179], v[218:221], v[64:67]
	v_mfma_f32_16x16x32_bf16 v[64:67], v[190:193], v[222:225], v[64:67]
	s_setprio 0
	s_barrier
	s_add_i32 s68, s96, s71
	v_lshl_add_u64 v[74:75], v[226:227], 0, s[28:29]
	s_mov_b32 m0, s68
	ds_read_b128 v[194:197], v187 offset:49152
	ds_read_b128 v[198:201], v187 offset:50176
	ds_read_b128 v[202:205], v187 offset:51200
	ds_read_b128 v[206:209], v187 offset:52224
	ds_read_b128 v[210:213], v187 offset:53248
	ds_read_b128 v[214:217], v187 offset:54272
	ds_read_b128 v[218:221], v187 offset:55296
	ds_read_b128 v[222:225], v187 offset:56320
	global_load_lds_dwordx4 v[74:75], off
	s_add_i32 m0, s68, 0x2000
	s_add_u32 s66, s66, 0x40080
	v_lshl_add_u64 v[74:75], v[228:229], 0, s[28:29]
	s_addc_u32 s67, s67, 0
	s_add_i32 s68, s97, s71
	global_load_lds_dwordx4 v[74:75], off
	v_lshl_add_u64 v[74:75], s[66:67], 0, v[162:163]
	s_mov_b32 m0, s68
	s_nop 0
	global_load_lds_dwordx4 v[74:75], off
	v_lshl_add_u64 v[74:75], s[66:67], 0, v[166:167]
	s_add_i32 m0, s68, 0x2000
	s_nop 0
	global_load_lds_dwordx4 v[74:75], off
	v_lshl_add_u64 v[74:75], v[230:231], 0, s[28:29]
	s_mov_b32 m0, s78
	s_nop 0
	global_load_lds_dwordx4 v[74:75], off
	v_lshl_add_u64 v[74:75], v[232:233], 0, s[28:29]
	s_mov_b32 m0, s79
	s_nop 0
	global_load_lds_dwordx4 v[74:75], off
	s_waitcnt vmcnt(8)
	s_waitcnt lgkmcnt(0)
	s_barrier
	s_setprio 1
	s_waitcnt lgkmcnt(0)
	v_mfma_f32_16x16x32_bf16 v[60:63], v[88:91], v[194:197], v[60:63]
	v_mfma_f32_16x16x32_bf16 v[60:63], v[108:111], v[198:201], v[60:63]
	v_mfma_f32_16x16x32_bf16 v[56:59], v[128:131], v[194:197], v[56:59]
	v_mfma_f32_16x16x32_bf16 v[56:59], v[144:147], v[198:201], v[56:59]
	v_mfma_f32_16x16x32_bf16 v[44:47], v[88:91], v[202:205], v[44:47]
	v_mfma_f32_16x16x32_bf16 v[44:47], v[108:111], v[206:209], v[44:47]
	v_mfma_f32_16x16x32_bf16 v[40:43], v[128:131], v[202:205], v[40:43]
	v_mfma_f32_16x16x32_bf16 v[40:43], v[144:147], v[206:209], v[40:43]
	v_mfma_f32_16x16x32_bf16 v[28:31], v[88:91], v[210:213], v[28:31]
	v_mfma_f32_16x16x32_bf16 v[28:31], v[108:111], v[214:217], v[28:31]
	v_mfma_f32_16x16x32_bf16 v[24:27], v[128:131], v[210:213], v[24:27]
	v_mfma_f32_16x16x32_bf16 v[24:27], v[144:147], v[214:217], v[24:27]
	v_mfma_f32_16x16x32_bf16 v[12:15], v[88:91], v[218:221], v[12:15]
	v_mfma_f32_16x16x32_bf16 v[12:15], v[108:111], v[222:225], v[12:15]
	v_mfma_f32_16x16x32_bf16 v[8:11], v[128:131], v[218:221], v[8:11]
	v_mfma_f32_16x16x32_bf16 v[8:11], v[144:147], v[222:225], v[8:11]
	s_setprio 0
	s_setprio 1
	v_mfma_f32_16x16x32_bf16 v[52:55], v[148:151], v[194:197], v[52:55]
	v_mfma_f32_16x16x32_bf16 v[52:55], v[152:155], v[198:201], v[52:55]
	v_mfma_f32_16x16x32_bf16 v[48:51], v[176:179], v[194:197], v[48:51]
	v_mfma_f32_16x16x32_bf16 v[48:51], v[190:193], v[198:201], v[48:51]
	v_mfma_f32_16x16x32_bf16 v[36:39], v[148:151], v[202:205], v[36:39]
	v_mfma_f32_16x16x32_bf16 v[36:39], v[152:155], v[206:209], v[36:39]
	v_mfma_f32_16x16x32_bf16 v[32:35], v[176:179], v[202:205], v[32:35]
	v_mfma_f32_16x16x32_bf16 v[32:35], v[190:193], v[206:209], v[32:35]
	v_mfma_f32_16x16x32_bf16 v[20:23], v[148:151], v[210:213], v[20:23]
	v_mfma_f32_16x16x32_bf16 v[20:23], v[152:155], v[214:217], v[20:23]
	v_mfma_f32_16x16x32_bf16 v[16:19], v[176:179], v[210:213], v[16:19]
	v_mfma_f32_16x16x32_bf16 v[16:19], v[190:193], v[214:217], v[16:19]
	v_mfma_f32_16x16x32_bf16 v[4:7], v[148:151], v[218:221], v[4:7]
	v_mfma_f32_16x16x32_bf16 v[4:7], v[152:155], v[222:225], v[4:7]
	v_mfma_f32_16x16x32_bf16 v[0:3], v[176:179], v[218:221], v[0:3]
	v_mfma_f32_16x16x32_bf16 v[0:3], v[190:193], v[222:225], v[0:3]
	s_setprio 0
	s_barrier
	s_add_i32 s95, s95, 2
	s_add_u32 s93, s93, 0x100
	s_addc_u32 s94, s94, 0
	s_add_u32 s14, s14, 0x100
	s_addc_u32 s15, s15, 0
	s_cmp_gt_u32 s95, 13
	s_cbranch_scc1 .LBB0_258

.LBB0_439:
	s_ashr_i32 s53, s52, 31
	s_lshl_b64 s[54:55], s[52:53], 20
	s_add_u32 s54, s35, s54
	s_addc_u32 s55, s66, s55
	s_and_b64 s[56:57], s[12:13], exec
	s_cselect_b32 s15, s55, s63
	s_cselect_b32 s53, s54, s62
	s_ashr_i32 s51, s50, 31
	s_lshl_b64 s[56:57], s[50:51], 20
	s_add_u32 s56, s67, s56
	s_addc_u32 s57, s68, s57
	s_and_b64 s[64:65], s[12:13], exec
	s_cselect_b32 s51, s57, s61
	s_cselect_b32 s59, s56, s60
	s_add_u32 s81, s60, 0x100
	s_addc_u32 s82, s61, 0
	s_add_u32 s60, s62, 0x80080
	s_addc_u32 s61, s63, 0
	s_mov_b32 s83, -2
	s_waitcnt lgkmcnt(0)
	s_cmp_eq_u32 s74, 1
	s_cbranch_scc1 .Lfa_3
	ds_read_b128 v[128:131], v189
	ds_read_b128 v[132:135], v189 offset:1024
	ds_read_b128 v[136:139], v189 offset:2048
	ds_read_b128 v[140:143], v189 offset:3072
	ds_read_b128 v[144:147], v190
	ds_read_b128 v[148:151], v190 offset:1024
	ds_read_b128 v[172:175], v190 offset:2048
	ds_read_b128 v[176:179], v190 offset:3072
	s_add_u32 s62, s60, 0xfff80080
	s_addc_u32 s63, s61, -1
	s_cmp_eq_u32 s83, 28
	s_cselect_b32 s65, s15, s63
	s_cselect_b32 s64, s53, s62
	s_cselect_b32 s63, s51, s82
	s_cselect_b32 s62, s59, s81
	v_lshl_add_u64 v[222:223], s[60:61], 0, v[166:167]
	s_add_i32 m0, s70, 0xc000
	ds_read_b128 v[180:183], v191
	ds_read_b128 v[194:197], v191 offset:1024
	ds_read_b128 v[198:201], v191 offset:2048
	ds_read_b128 v[202:205], v191 offset:3072
	ds_read_b128 v[206:209], v191 offset:4096
	ds_read_b128 v[210:213], v191 offset:5120
	ds_read_b128 v[214:217], v191 offset:6144
	ds_read_b128 v[218:221], v191 offset:7168
	global_load_lds_dwordx4 v[222:223], off
	v_lshl_add_u64 v[222:223], s[60:61], 0, v[164:165]
	s_add_i32 m0, s70, 0xe000
	s_nop 0
	global_load_lds_dwordx4 v[222:223], off
	s_waitcnt vmcnt(24)
	s_waitcnt lgkmcnt(0)
	s_barrier
	s_setprio 1
	s_waitcnt lgkmcnt(0)
	v_mfma_f32_16x16x32_bf16 v[124:127], v[128:131], v[180:183], 0
	v_mfma_f32_16x16x32_bf16 v[120:123], v[136:139], v[180:183], 0
	v_mfma_f32_16x16x32_bf16 v[108:111], v[128:131], v[198:201], 0
	v_mfma_f32_16x16x32_bf16 v[104:107], v[136:139], v[198:201], 0
	v_mfma_f32_16x16x32_bf16 v[92:95], v[128:131], v[206:209], 0
	v_mfma_f32_16x16x32_bf16 v[88:91], v[136:139], v[206:209], 0
	v_mfma_f32_16x16x32_bf16 v[76:79], v[128:131], v[214:217], 0
	v_mfma_f32_16x16x32_bf16 v[72:75], v[136:139], v[214:217], 0
	v_mfma_f32_16x16x32_bf16 v[124:127], v[132:135], v[194:197], v[124:127]
	v_mfma_f32_16x16x32_bf16 v[120:123], v[140:143], v[194:197], v[120:123]
	v_mfma_f32_16x16x32_bf16 v[108:111], v[132:135], v[202:205], v[108:111]
	v_mfma_f32_16x16x32_bf16 v[104:107], v[140:143], v[202:205], v[104:107]
	v_mfma_f32_16x16x32_bf16 v[92:95], v[132:135], v[210:213], v[92:95]
	v_mfma_f32_16x16x32_bf16 v[88:91], v[140:143], v[210:213], v[88:91]
	v_mfma_f32_16x16x32_bf16 v[76:79], v[132:135], v[218:221], v[76:79]
	v_mfma_f32_16x16x32_bf16 v[72:75], v[140:143], v[218:221], v[72:75]
	s_setprio 0
	s_setprio 1
	v_mfma_f32_16x16x32_bf16 v[116:119], v[144:147], v[180:183], 0
	v_mfma_f32_16x16x32_bf16 v[112:115], v[172:175], v[180:183], 0
	v_mfma_f32_16x16x32_bf16 v[100:103], v[144:147], v[198:201], 0
	v_mfma_f32_16x16x32_bf16 v[96:99], v[172:175], v[198:201], 0
	v_mfma_f32_16x16x32_bf16 v[84:87], v[144:147], v[206:209], 0
	v_mfma_f32_16x16x32_bf16 v[80:83], v[172:175], v[206:209], 0
	v_mfma_f32_16x16x32_bf16 v[68:71], v[144:147], v[214:217], 0
	v_mfma_f32_16x16x32_bf16 v[64:67], v[172:175], v[214:217], 0
	v_mfma_f32_16x16x32_bf16 v[116:119], v[148:151], v[194:197], v[116:119]
	v_mfma_f32_16x16x32_bf16 v[112:115], v[176:179], v[194:197], v[112:115]
	v_mfma_f32_16x16x32_bf16 v[100:103], v[148:151], v[202:205], v[100:103]
	v_mfma_f32_16x16x32_bf16 v[96:99], v[176:179], v[202:205], v[96:99]
	v_mfma_f32_16x16x32_bf16 v[84:87], v[148:151], v[210:213], v[84:87]
	v_mfma_f32_16x16x32_bf16 v[80:83], v[176:179], v[210:213], v[80:83]
	v_mfma_f32_16x16x32_bf16 v[68:71], v[148:151], v[218:221], v[68:71]
	v_mfma_f32_16x16x32_bf16 v[64:67], v[176:179], v[218:221], v[64:67]
	s_setprio 0
	s_barrier
	s_add_i32 s84, s79, s69
	v_lshl_add_u64 v[222:223], s[62:63], 0, v[154:155]
	s_mov_b32 m0, s84
	ds_read_b128 v[180:183], v191 offset:16384
	ds_read_b128 v[194:197], v191 offset:17408
	ds_read_b128 v[198:201], v191 offset:18432
	ds_read_b128 v[202:205], v191 offset:19456
	ds_read_b128 v[206:209], v191 offset:20480
	ds_read_b128 v[210:213], v191 offset:21504
	ds_read_b128 v[214:217], v191 offset:22528
	ds_read_b128 v[218:221], v191 offset:23552
	global_load_lds_dwordx4 v[222:223], off
	s_add_i32 m0, s84, 0x2000
	s_add_u32 s84, s62, 0x80000
	v_lshl_add_u64 v[224:225], s[62:63], 0, v[162:163]
	s_addc_u32 s85, s63, 0
	s_add_i32 s86, s80, s69
	global_load_lds_dwordx4 v[224:225], off
	v_lshl_add_u64 v[226:227], s[84:85], 0, v[154:155]
	s_mov_b32 m0, s86
	v_lshl_add_u64 v[228:229], s[64:65], 0, v[160:161]
	global_load_lds_dwordx4 v[226:227], off
	v_lshl_add_u64 v[226:227], s[84:85], 0, v[162:163]
	s_add_i32 m0, s86, 0x2000
	s_nop 0
	global_load_lds_dwordx4 v[226:227], off
	v_lshl_add_u64 v[226:227], s[64:65], 0, v[152:153]
	s_mov_b32 m0, s70
	s_nop 0
	global_load_lds_dwordx4 v[226:227], off
	s_mov_b32 m0, s71
	s_nop 0
	global_load_lds_dwordx4 v[228:229], off
	s_waitcnt vmcnt(24)
	s_waitcnt lgkmcnt(0)
	s_barrier
	s_setprio 1
	s_waitcnt lgkmcnt(0)
	v_mfma_f32_16x16x32_bf16 v[60:63], v[128:131], v[180:183], 0
	v_mfma_f32_16x16x32_bf16 v[56:59], v[136:139], v[180:183], 0
	v_mfma_f32_16x16x32_bf16 v[44:47], v[128:131], v[198:201], 0
	v_mfma_f32_16x16x32_bf16 v[40:43], v[136:139], v[198:201], 0
	v_mfma_f32_16x16x32_bf16 v[28:31], v[128:131], v[206:209], 0
	v_mfma_f32_16x16x32_bf16 v[24:27], v[136:139], v[206:209], 0
	v_mfma_f32_16x16x32_bf16 v[12:15], v[128:131], v[214:217], 0
	v_mfma_f32_16x16x32_bf16 v[8:11], v[136:139], v[214:217], 0
	v_mfma_f32_16x16x32_bf16 v[60:63], v[132:135], v[194:197], v[60:63]
	v_mfma_f32_16x16x32_bf16 v[56:59], v[140:143], v[194:197], v[56:59]
	v_mfma_f32_16x16x32_bf16 v[44:47], v[132:135], v[202:205], v[44:47]
	v_mfma_f32_16x16x32_bf16 v[40:43], v[140:143], v[202:205], v[40:43]
	v_mfma_f32_16x16x32_bf16 v[28:31], v[132:135], v[210:213], v[28:31]
	v_mfma_f32_16x16x32_bf16 v[24:27], v[140:143], v[210:213], v[24:27]
	v_mfma_f32_16x16x32_bf16 v[12:15], v[132:135], v[218:221], v[12:15]
	v_mfma_f32_16x16x32_bf16 v[8:11], v[140:143], v[218:221], v[8:11]
	s_setprio 0
	s_setprio 1
	v_mfma_f32_16x16x32_bf16 v[52:55], v[144:147], v[180:183], 0
	v_mfma_f32_16x16x32_bf16 v[48:51], v[172:175], v[180:183], 0
	v_mfma_f32_16x16x32_bf16 v[36:39], v[144:147], v[198:201], 0
	v_mfma_f32_16x16x32_bf16 v[32:35], v[172:175], v[198:201], 0
	v_mfma_f32_16x16x32_bf16 v[20:23], v[144:147], v[206:209], 0
	v_mfma_f32_16x16x32_bf16 v[16:19], v[172:175], v[206:209], 0
	v_mfma_f32_16x16x32_bf16 v[4:7], v[144:147], v[214:217], 0
	v_mfma_f32_16x16x32_bf16 v[0:3], v[172:175], v[214:217], 0
	v_mfma_f32_16x16x32_bf16 v[52:55], v[148:151], v[194:197], v[52:55]
	v_mfma_f32_16x16x32_bf16 v[48:51], v[176:179], v[194:197], v[48:51]
	v_mfma_f32_16x16x32_bf16 v[36:39], v[148:151], v[202:205], v[36:39]
	v_mfma_f32_16x16x32_bf16 v[32:35], v[176:179], v[202:205], v[32:35]
	v_mfma_f32_16x16x32_bf16 v[20:23], v[148:151], v[210:213], v[20:23]
	v_mfma_f32_16x16x32_bf16 v[16:19], v[176:179], v[210:213], v[16:19]
	v_mfma_f32_16x16x32_bf16 v[4:7], v[148:151], v[218:221], v[4:7]
	v_mfma_f32_16x16x32_bf16 v[0:3], v[176:179], v[218:221], v[0:3]
	s_setprio 0
	s_barrier
	s_add_i32 s84, 0, 0x18000
	s_add_i32 s85, 0, 0x1c000
	v_add_u32_e32 v140, s84, v186
	v_add_u32_e32 v176, s85, v186
	ds_read_b128 v[128:131], v140
	ds_read_b128 v[132:135], v140 offset:1024
	ds_read_b128 v[136:139], v140 offset:2048
	ds_read_b128 v[140:143], v140 offset:3072
	ds_read_b128 v[144:147], v176
	ds_read_b128 v[148:151], v176 offset:1024
	ds_read_b128 v[172:175], v176 offset:2048
	ds_read_b128 v[176:179], v176 offset:3072
	s_add_u32 s64, s64, 0x80000
	s_addc_u32 s65, s65, 0
	s_mov_b32 m0, s72
	v_lshl_add_u64 v[230:231], s[64:65], 0, v[152:153]
	ds_read_b128 v[180:183], v191 offset:32768
	ds_read_b128 v[194:197], v191 offset:33792
	ds_read_b128 v[198:201], v191 offset:34816
	ds_read_b128 v[202:205], v191 offset:35840
	ds_read_b128 v[206:209], v191 offset:36864
	ds_read_b128 v[210:213], v191 offset:37888
	ds_read_b128 v[214:217], v191 offset:38912
	ds_read_b128 v[218:221], v191 offset:39936
	global_load_lds_dwordx4 v[230:231], off
	v_lshl_add_u64 v[230:231], s[64:65], 0, v[160:161]
	s_mov_b32 m0, s73
	s_nop 0
	global_load_lds_dwordx4 v[230:231], off
	s_waitcnt vmcnt(8)
	s_waitcnt lgkmcnt(0)
	s_barrier
	s_setprio 1
	s_waitcnt lgkmcnt(0)
	v_mfma_f32_16x16x32_bf16 v[124:127], v[128:131], v[180:183], v[124:127]
	v_mfma_f32_16x16x32_bf16 v[124:127], v[132:135], v[194:197], v[124:127]
	v_mfma_f32_16x16x32_bf16 v[120:123], v[136:139], v[180:183], v[120:123]
	v_mfma_f32_16x16x32_bf16 v[120:123], v[140:143], v[194:197], v[120:123]
	v_mfma_f32_16x16x32_bf16 v[108:111], v[128:131], v[198:201], v[108:111]
	v_mfma_f32_16x16x32_bf16 v[108:111], v[132:135], v[202:205], v[108:111]
	v_mfma_f32_16x16x32_bf16 v[104:107], v[136:139], v[198:201], v[104:107]
	v_mfma_f32_16x16x32_bf16 v[104:107], v[140:143], v[202:205], v[104:107]
	v_mfma_f32_16x16x32_bf16 v[92:95], v[128:131], v[206:209], v[92:95]
	v_mfma_f32_16x16x32_bf16 v[92:95], v[132:135], v[210:213], v[92:95]
	v_mfma_f32_16x16x32_bf16 v[88:91], v[136:139], v[206:209], v[88:91]
	v_mfma_f32_16x16x32_bf16 v[88:91], v[140:143], v[210:213], v[88:91]
	v_mfma_f32_16x16x32_bf16 v[76:79], v[128:131], v[214:217], v[76:79]
	v_mfma_f32_16x16x32_bf16 v[76:79], v[132:135], v[218:221], v[76:79]
	v_mfma_f32_16x16x32_bf16 v[72:75], v[136:139], v[214:217], v[72:75]
	v_mfma_f32_16x16x32_bf16 v[72:75], v[140:143], v[218:221], v[72:75]
	s_setprio 0
	s_setprio 1
	v_mfma_f32_16x16x32_bf16 v[116:119], v[144:147], v[180:183], v[116:119]
	v_mfma_f32_16x16x32_bf16 v[116:119], v[148:151], v[194:197], v[116:119]
	v_mfma_f32_16x16x32_bf16 v[112:115], v[172:175], v[180:183], v[112:115]
	v_mfma_f32_16x16x32_bf16 v[112:115], v[176:179], v[194:197], v[112:115]
	v_mfma_f32_16x16x32_bf16 v[100:103], v[144:147], v[198:201], v[100:103]
	v_mfma_f32_16x16x32_bf16 v[100:103], v[148:151], v[202:205], v[100:103]
	v_mfma_f32_16x16x32_bf16 v[96:99], v[172:175], v[198:201], v[96:99]
	v_mfma_f32_16x16x32_bf16 v[96:99], v[176:179], v[202:205], v[96:99]
	v_mfma_f32_16x16x32_bf16 v[84:87], v[144:147], v[206:209], v[84:87]
	v_mfma_f32_16x16x32_bf16 v[84:87], v[148:151], v[210:213], v[84:87]
	v_mfma_f32_16x16x32_bf16 v[80:83], v[172:175], v[206:209], v[80:83]
	v_mfma_f32_16x16x32_bf16 v[80:83], v[176:179], v[210:213], v[80:83]
	v_mfma_f32_16x16x32_bf16 v[68:71], v[144:147], v[214:217], v[68:71]
	v_mfma_f32_16x16x32_bf16 v[68:71], v[148:151], v[218:221], v[68:71]
	v_mfma_f32_16x16x32_bf16 v[64:67], v[172:175], v[214:217], v[64:67]
	v_mfma_f32_16x16x32_bf16 v[64:67], v[176:179], v[218:221], v[64:67]
	s_setprio 0
	s_barrier
	s_add_i32 s64, s84, s69
	v_lshl_add_u64 v[222:223], v[222:223], 0, s[26:27]
	s_mov_b32 m0, s64
	ds_read_b128 v[180:183], v191 offset:49152
	ds_read_b128 v[194:197], v191 offset:50176
	ds_read_b128 v[198:201], v191 offset:51200
	ds_read_b128 v[202:205], v191 offset:52224
	ds_read_b128 v[206:209], v191 offset:53248
	ds_read_b128 v[210:213], v191 offset:54272
	ds_read_b128 v[214:217], v191 offset:55296
	ds_read_b128 v[218:221], v191 offset:56320
	global_load_lds_dwordx4 v[222:223], off
	s_add_i32 m0, s64, 0x2000
	s_add_u32 s62, s62, 0x80080
	v_lshl_add_u64 v[222:223], v[224:225], 0, s[26:27]
	s_addc_u32 s63, s63, 0
	s_add_i32 s64, s85, s69
	global_load_lds_dwordx4 v[222:223], off
	v_lshl_add_u64 v[222:223], s[62:63], 0, v[154:155]
	s_mov_b32 m0, s64
	s_nop 0
	global_load_lds_dwordx4 v[222:223], off
	v_lshl_add_u64 v[222:223], s[62:63], 0, v[162:163]
	s_add_i32 m0, s64, 0x2000
	s_nop 0
	global_load_lds_dwordx4 v[222:223], off
	v_lshl_add_u64 v[222:223], v[226:227], 0, s[26:27]
	s_mov_b32 m0, s3
	s_nop 0
	global_load_lds_dwordx4 v[222:223], off
	v_lshl_add_u64 v[222:223], v[228:229], 0, s[26:27]
	s_mov_b32 m0, s75
	s_nop 0
	global_load_lds_dwordx4 v[222:223], off
	s_waitcnt vmcnt(8)
	s_waitcnt lgkmcnt(0)
	s_barrier
	s_setprio 1
	s_waitcnt lgkmcnt(0)
	v_mfma_f32_16x16x32_bf16 v[60:63], v[128:131], v[180:183], v[60:63]
	v_mfma_f32_16x16x32_bf16 v[60:63], v[132:135], v[194:197], v[60:63]
	v_mfma_f32_16x16x32_bf16 v[56:59], v[136:139], v[180:183], v[56:59]
	v_mfma_f32_16x16x32_bf16 v[56:59], v[140:143], v[194:197], v[56:59]
	v_mfma_f32_16x16x32_bf16 v[44:47], v[128:131], v[198:201], v[44:47]
	v_mfma_f32_16x16x32_bf16 v[44:47], v[132:135], v[202:205], v[44:47]
	v_mfma_f32_16x16x32_bf16 v[40:43], v[136:139], v[198:201], v[40:43]
	v_mfma_f32_16x16x32_bf16 v[40:43], v[140:143], v[202:205], v[40:43]
	v_mfma_f32_16x16x32_bf16 v[28:31], v[128:131], v[206:209], v[28:31]
	v_mfma_f32_16x16x32_bf16 v[28:31], v[132:135], v[210:213], v[28:31]
	v_mfma_f32_16x16x32_bf16 v[24:27], v[136:139], v[206:209], v[24:27]
	v_mfma_f32_16x16x32_bf16 v[24:27], v[140:143], v[210:213], v[24:27]
	v_mfma_f32_16x16x32_bf16 v[12:15], v[128:131], v[214:217], v[12:15]
	v_mfma_f32_16x16x32_bf16 v[12:15], v[132:135], v[218:221], v[12:15]
	v_mfma_f32_16x16x32_bf16 v[8:11], v[136:139], v[214:217], v[8:11]
	v_mfma_f32_16x16x32_bf16 v[8:11], v[140:143], v[218:221], v[8:11]
	s_setprio 0
	s_setprio 1
	v_mfma_f32_16x16x32_bf16 v[52:55], v[144:147], v[180:183], v[52:55]
	v_mfma_f32_16x16x32_bf16 v[52:55], v[148:151], v[194:197], v[52:55]
	v_mfma_f32_16x16x32_bf16 v[48:51], v[172:175], v[180:183], v[48:51]
	v_mfma_f32_16x16x32_bf16 v[48:51], v[176:179], v[194:197], v[48:51]
	v_mfma_f32_16x16x32_bf16 v[36:39], v[144:147], v[198:201], v[36:39]
	v_mfma_f32_16x16x32_bf16 v[36:39], v[148:151], v[202:205], v[36:39]
	v_mfma_f32_16x16x32_bf16 v[32:35], v[172:175], v[198:201], v[32:35]
	v_mfma_f32_16x16x32_bf16 v[32:35], v[176:179], v[202:205], v[32:35]
	v_mfma_f32_16x16x32_bf16 v[20:23], v[144:147], v[206:209], v[20:23]
	v_mfma_f32_16x16x32_bf16 v[20:23], v[148:151], v[210:213], v[20:23]
	v_mfma_f32_16x16x32_bf16 v[16:19], v[172:175], v[206:209], v[16:19]
	v_mfma_f32_16x16x32_bf16 v[16:19], v[176:179], v[210:213], v[16:19]
	v_mfma_f32_16x16x32_bf16 v[4:7], v[144:147], v[214:217], v[4:7]
	v_mfma_f32_16x16x32_bf16 v[4:7], v[148:151], v[218:221], v[4:7]
	v_mfma_f32_16x16x32_bf16 v[0:3], v[172:175], v[214:217], v[0:3]
	v_mfma_f32_16x16x32_bf16 v[0:3], v[176:179], v[218:221], v[0:3]
	s_setprio 0
	s_barrier
	s_add_i32 s83, s83, 2
	s_add_u32 s81, s81, 0x100
	s_addc_u32 s82, s82, 0
	s_add_u32 s60, s60, 0x100
	s_addc_u32 s61, s61, 0
	s_cmp_gt_u32 s83, 29
	s_branch .LBB0_440
.Lfa_3:
	ds_read_b128 v[128:131], v189
	ds_read_b128 v[132:135], v189 offset:1024
	ds_read_b128 v[136:139], v189 offset:2048
	ds_read_b128 v[140:143], v189 offset:3072
	ds_read_b128 v[144:147], v190
	ds_read_b128 v[148:151], v190 offset:1024
	ds_read_b128 v[172:175], v190 offset:2048
	ds_read_b128 v[176:179], v190 offset:3072
	s_add_u32 s62, s60, 0xfff80080
	s_addc_u32 s63, s61, -1
	s_cmp_eq_u32 s83, 28
	s_cselect_b32 s65, s15, s63
	s_cselect_b32 s64, s53, s62
	s_cselect_b32 s63, s51, s82
	s_cselect_b32 s62, s59, s81
	v_lshl_add_u64 v[222:223], s[60:61], 0, v[166:167]
	s_add_i32 m0, s70, 0xc000
	ds_read_b128 v[180:183], v191
	ds_read_b128 v[194:197], v191 offset:1024
	ds_read_b128 v[198:201], v191 offset:2048
	ds_read_b128 v[202:205], v191 offset:3072
	ds_read_b128 v[206:209], v191 offset:4096
	ds_read_b128 v[210:213], v191 offset:5120
	ds_read_b128 v[214:217], v191 offset:6144
	ds_read_b128 v[218:221], v191 offset:7168
	global_load_lds_dwordx4 v[222:223], off
	v_lshl_add_u64 v[222:223], s[60:61], 0, v[164:165]
	s_add_i32 m0, s70, 0xe000
	s_nop 0
	global_load_lds_dwordx4 v[222:223], off
	s_waitcnt vmcnt(8)
	s_waitcnt lgkmcnt(0)
	s_barrier
	s_setprio 1
	s_waitcnt lgkmcnt(0)
	v_mfma_f32_16x16x32_bf16 v[124:127], v[128:131], v[180:183], 0
	v_mfma_f32_16x16x32_bf16 v[120:123], v[136:139], v[180:183], 0
	v_mfma_f32_16x16x32_bf16 v[108:111], v[128:131], v[198:201], 0
	v_mfma_f32_16x16x32_bf16 v[104:107], v[136:139], v[198:201], 0
	v_mfma_f32_16x16x32_bf16 v[92:95], v[128:131], v[206:209], 0
	v_mfma_f32_16x16x32_bf16 v[88:91], v[136:139], v[206:209], 0
	v_mfma_f32_16x16x32_bf16 v[76:79], v[128:131], v[214:217], 0
	v_mfma_f32_16x16x32_bf16 v[72:75], v[136:139], v[214:217], 0
	v_mfma_f32_16x16x32_bf16 v[124:127], v[132:135], v[194:197], v[124:127]
	v_mfma_f32_16x16x32_bf16 v[120:123], v[140:143], v[194:197], v[120:123]
	v_mfma_f32_16x16x32_bf16 v[108:111], v[132:135], v[202:205], v[108:111]
	v_mfma_f32_16x16x32_bf16 v[104:107], v[140:143], v[202:205], v[104:107]
	v_mfma_f32_16x16x32_bf16 v[92:95], v[132:135], v[210:213], v[92:95]
	v_mfma_f32_16x16x32_bf16 v[88:91], v[140:143], v[210:213], v[88:91]
	v_mfma_f32_16x16x32_bf16 v[76:79], v[132:135], v[218:221], v[76:79]
	v_mfma_f32_16x16x32_bf16 v[72:75], v[140:143], v[218:221], v[72:75]
	s_setprio 0
	s_setprio 1
	v_mfma_f32_16x16x32_bf16 v[116:119], v[144:147], v[180:183], 0
	v_mfma_f32_16x16x32_bf16 v[112:115], v[172:175], v[180:183], 0
	v_mfma_f32_16x16x32_bf16 v[100:103], v[144:147], v[198:201], 0
	v_mfma_f32_16x16x32_bf16 v[96:99], v[172:175], v[198:201], 0
	v_mfma_f32_16x16x32_bf16 v[84:87], v[144:147], v[206:209], 0
	v_mfma_f32_16x16x32_bf16 v[80:83], v[172:175], v[206:209], 0
	v_mfma_f32_16x16x32_bf16 v[68:71], v[144:147], v[214:217], 0
	v_mfma_f32_16x16x32_bf16 v[64:67], v[172:175], v[214:217], 0
	v_mfma_f32_16x16x32_bf16 v[116:119], v[148:151], v[194:197], v[116:119]
	v_mfma_f32_16x16x32_bf16 v[112:115], v[176:179], v[194:197], v[112:115]
	v_mfma_f32_16x16x32_bf16 v[100:103], v[148:151], v[202:205], v[100:103]
	v_mfma_f32_16x16x32_bf16 v[96:99], v[176:179], v[202:205], v[96:99]
	v_mfma_f32_16x16x32_bf16 v[84:87], v[148:151], v[210:213], v[84:87]
	v_mfma_f32_16x16x32_bf16 v[80:83], v[176:179], v[210:213], v[80:83]
	v_mfma_f32_16x16x32_bf16 v[68:71], v[148:151], v[218:221], v[68:71]
	v_mfma_f32_16x16x32_bf16 v[64:67], v[176:179], v[218:221], v[64:67]
	s_setprio 0
	s_barrier
	s_add_i32 s84, s79, s69
	v_lshl_add_u64 v[222:223], s[62:63], 0, v[154:155]
	s_mov_b32 m0, s84
	ds_read_b128 v[180:183], v191 offset:16384
	ds_read_b128 v[194:197], v191 offset:17408
	ds_read_b128 v[198:201], v191 offset:18432
	ds_read_b128 v[202:205], v191 offset:19456
	ds_read_b128 v[206:209], v191 offset:20480
	ds_read_b128 v[210:213], v191 offset:21504
	ds_read_b128 v[214:217], v191 offset:22528
	ds_read_b128 v[218:221], v191 offset:23552
	global_load_lds_dwordx4 v[222:223], off
	s_add_i32 m0, s84, 0x2000
	s_add_u32 s84, s62, 0x80000
	v_lshl_add_u64 v[224:225], s[62:63], 0, v[162:163]
	s_addc_u32 s85, s63, 0
	s_add_i32 s86, s80, s69
	global_load_lds_dwordx4 v[224:225], off
	v_lshl_add_u64 v[226:227], s[84:85], 0, v[154:155]
	s_mov_b32 m0, s86
	v_lshl_add_u64 v[228:229], s[64:65], 0, v[160:161]
	global_load_lds_dwordx4 v[226:227], off
	v_lshl_add_u64 v[226:227], s[84:85], 0, v[162:163]
	s_add_i32 m0, s86, 0x2000
	s_nop 0
	global_load_lds_dwordx4 v[226:227], off
	v_lshl_add_u64 v[226:227], s[64:65], 0, v[152:153]
	s_mov_b32 m0, s70
	s_nop 0
	global_load_lds_dwordx4 v[226:227], off
	s_mov_b32 m0, s71
	s_nop 0
	global_load_lds_dwordx4 v[228:229], off
	s_waitcnt vmcnt(8)
	s_waitcnt lgkmcnt(0)
	s_barrier
	s_setprio 1
	s_waitcnt lgkmcnt(0)
	v_mfma_f32_16x16x32_bf16 v[60:63], v[128:131], v[180:183], 0
	v_mfma_f32_16x16x32_bf16 v[56:59], v[136:139], v[180:183], 0
	v_mfma_f32_16x16x32_bf16 v[44:47], v[128:131], v[198:201], 0
	v_mfma_f32_16x16x32_bf16 v[40:43], v[136:139], v[198:201], 0
	v_mfma_f32_16x16x32_bf16 v[28:31], v[128:131], v[206:209], 0
	v_mfma_f32_16x16x32_bf16 v[24:27], v[136:139], v[206:209], 0
	v_mfma_f32_16x16x32_bf16 v[12:15], v[128:131], v[214:217], 0
	v_mfma_f32_16x16x32_bf16 v[8:11], v[136:139], v[214:217], 0
	v_mfma_f32_16x16x32_bf16 v[60:63], v[132:135], v[194:197], v[60:63]
	v_mfma_f32_16x16x32_bf16 v[56:59], v[140:143], v[194:197], v[56:59]
	v_mfma_f32_16x16x32_bf16 v[44:47], v[132:135], v[202:205], v[44:47]
	v_mfma_f32_16x16x32_bf16 v[40:43], v[140:143], v[202:205], v[40:43]
	v_mfma_f32_16x16x32_bf16 v[28:31], v[132:135], v[210:213], v[28:31]
	v_mfma_f32_16x16x32_bf16 v[24:27], v[140:143], v[210:213], v[24:27]
	v_mfma_f32_16x16x32_bf16 v[12:15], v[132:135], v[218:221], v[12:15]
	v_mfma_f32_16x16x32_bf16 v[8:11], v[140:143], v[218:221], v[8:11]
	s_setprio 0
	s_setprio 1
	v_mfma_f32_16x16x32_bf16 v[52:55], v[144:147], v[180:183], 0
	v_mfma_f32_16x16x32_bf16 v[48:51], v[172:175], v[180:183], 0
	v_mfma_f32_16x16x32_bf16 v[36:39], v[144:147], v[198:201], 0
	v_mfma_f32_16x16x32_bf16 v[32:35], v[172:175], v[198:201], 0
	v_mfma_f32_16x16x32_bf16 v[20:23], v[144:147], v[206:209], 0
	v_mfma_f32_16x16x32_bf16 v[16:19], v[172:175], v[206:209], 0
	v_mfma_f32_16x16x32_bf16 v[4:7], v[144:147], v[214:217], 0
	v_mfma_f32_16x16x32_bf16 v[0:3], v[172:175], v[214:217], 0
	v_mfma_f32_16x16x32_bf16 v[52:55], v[148:151], v[194:197], v[52:55]
	v_mfma_f32_16x16x32_bf16 v[48:51], v[176:179], v[194:197], v[48:51]
	v_mfma_f32_16x16x32_bf16 v[36:39], v[148:151], v[202:205], v[36:39]
	v_mfma_f32_16x16x32_bf16 v[32:35], v[176:179], v[202:205], v[32:35]
	v_mfma_f32_16x16x32_bf16 v[20:23], v[148:151], v[210:213], v[20:23]
	v_mfma_f32_16x16x32_bf16 v[16:19], v[176:179], v[210:213], v[16:19]
	v_mfma_f32_16x16x32_bf16 v[4:7], v[148:151], v[218:221], v[4:7]
	v_mfma_f32_16x16x32_bf16 v[0:3], v[176:179], v[218:221], v[0:3]
	s_setprio 0
	s_barrier
	s_add_i32 s84, 0, 0x18000
	s_add_i32 s85, 0, 0x1c000
	v_add_u32_e32 v140, s84, v186
	v_add_u32_e32 v176, s85, v186
	ds_read_b128 v[128:131], v140
	ds_read_b128 v[132:135], v140 offset:1024
	ds_read_b128 v[136:139], v140 offset:2048
	ds_read_b128 v[140:143], v140 offset:3072
	ds_read_b128 v[144:147], v176
	ds_read_b128 v[148:151], v176 offset:1024
	ds_read_b128 v[172:175], v176 offset:2048
	ds_read_b128 v[176:179], v176 offset:3072
	s_add_u32 s64, s64, 0x80000
	s_addc_u32 s65, s65, 0
	s_mov_b32 m0, s72
	v_lshl_add_u64 v[230:231], s[64:65], 0, v[152:153]
	ds_read_b128 v[180:183], v191 offset:32768
	ds_read_b128 v[194:197], v191 offset:33792
	ds_read_b128 v[198:201], v191 offset:34816
	ds_read_b128 v[202:205], v191 offset:35840
	ds_read_b128 v[206:209], v191 offset:36864
	ds_read_b128 v[210:213], v191 offset:37888
	ds_read_b128 v[214:217], v191 offset:38912
	ds_read_b128 v[218:221], v191 offset:39936
	global_load_lds_dwordx4 v[230:231], off
	v_lshl_add_u64 v[230:231], s[64:65], 0, v[160:161]
	s_mov_b32 m0, s73
	s_nop 0
	global_load_lds_dwordx4 v[230:231], off
	s_waitcnt vmcnt(8)
	s_waitcnt lgkmcnt(0)
	s_barrier
	s_setprio 1
	s_waitcnt lgkmcnt(0)
	v_mfma_f32_16x16x32_bf16 v[124:127], v[128:131], v[180:183], v[124:127]
	v_mfma_f32_16x16x32_bf16 v[124:127], v[132:135], v[194:197], v[124:127]
	v_mfma_f32_16x16x32_bf16 v[120:123], v[136:139], v[180:183], v[120:123]
	v_mfma_f32_16x16x32_bf16 v[120:123], v[140:143], v[194:197], v[120:123]
	v_mfma_f32_16x16x32_bf16 v[108:111], v[128:131], v[198:201], v[108:111]
	v_mfma_f32_16x16x32_bf16 v[108:111], v[132:135], v[202:205], v[108:111]
	v_mfma_f32_16x16x32_bf16 v[104:107], v[136:139], v[198:201], v[104:107]
	v_mfma_f32_16x16x32_bf16 v[104:107], v[140:143], v[202:205], v[104:107]
	v_mfma_f32_16x16x32_bf16 v[92:95], v[128:131], v[206:209], v[92:95]
	v_mfma_f32_16x16x32_bf16 v[92:95], v[132:135], v[210:213], v[92:95]
	v_mfma_f32_16x16x32_bf16 v[88:91], v[136:139], v[206:209], v[88:91]
	v_mfma_f32_16x16x32_bf16 v[88:91], v[140:143], v[210:213], v[88:91]
	v_mfma_f32_16x16x32_bf16 v[76:79], v[128:131], v[214:217], v[76:79]
	v_mfma_f32_16x16x32_bf16 v[76:79], v[132:135], v[218:221], v[76:79]
	v_mfma_f32_16x16x32_bf16 v[72:75], v[136:139], v[214:217], v[72:75]
	v_mfma_f32_16x16x32_bf16 v[72:75], v[140:143], v[218:221], v[72:75]
	s_setprio 0
	s_setprio 1
	v_mfma_f32_16x16x32_bf16 v[116:119], v[144:147], v[180:183], v[116:119]
	v_mfma_f32_16x16x32_bf16 v[116:119], v[148:151], v[194:197], v[116:119]
	v_mfma_f32_16x16x32_bf16 v[112:115], v[172:175], v[180:183], v[112:115]
	v_mfma_f32_16x16x32_bf16 v[112:115], v[176:179], v[194:197], v[112:115]
	v_mfma_f32_16x16x32_bf16 v[100:103], v[144:147], v[198:201], v[100:103]
	v_mfma_f32_16x16x32_bf16 v[100:103], v[148:151], v[202:205], v[100:103]
	v_mfma_f32_16x16x32_bf16 v[96:99], v[172:175], v[198:201], v[96:99]
	v_mfma_f32_16x16x32_bf16 v[96:99], v[176:179], v[202:205], v[96:99]
	v_mfma_f32_16x16x32_bf16 v[84:87], v[144:147], v[206:209], v[84:87]
	v_mfma_f32_16x16x32_bf16 v[84:87], v[148:151], v[210:213], v[84:87]
	v_mfma_f32_16x16x32_bf16 v[80:83], v[172:175], v[206:209], v[80:83]
	v_mfma_f32_16x16x32_bf16 v[80:83], v[176:179], v[210:213], v[80:83]
	v_mfma_f32_16x16x32_bf16 v[68:71], v[144:147], v[214:217], v[68:71]
	v_mfma_f32_16x16x32_bf16 v[68:71], v[148:151], v[218:221], v[68:71]
	v_mfma_f32_16x16x32_bf16 v[64:67], v[172:175], v[214:217], v[64:67]
	v_mfma_f32_16x16x32_bf16 v[64:67], v[176:179], v[218:221], v[64:67]
	s_setprio 0
	s_barrier
	s_add_i32 s64, s84, s69
	v_lshl_add_u64 v[222:223], v[222:223], 0, s[26:27]
	s_mov_b32 m0, s64
	ds_read_b128 v[180:183], v191 offset:49152
	ds_read_b128 v[194:197], v191 offset:50176
	ds_read_b128 v[198:201], v191 offset:51200
	ds_read_b128 v[202:205], v191 offset:52224
	ds_read_b128 v[206:209], v191 offset:53248
	ds_read_b128 v[210:213], v191 offset:54272
	ds_read_b128 v[214:217], v191 offset:55296
	ds_read_b128 v[218:221], v191 offset:56320
	global_load_lds_dwordx4 v[222:223], off
	s_add_i32 m0, s64, 0x2000
	s_add_u32 s62, s62, 0x80080
	v_lshl_add_u64 v[222:223], v[224:225], 0, s[26:27]
	s_addc_u32 s63, s63, 0
	s_add_i32 s64, s85, s69
	global_load_lds_dwordx4 v[222:223], off
	v_lshl_add_u64 v[222:223], s[62:63], 0, v[154:155]
	s_mov_b32 m0, s64
	s_nop 0
	global_load_lds_dwordx4 v[222:223], off
	v_lshl_add_u64 v[222:223], s[62:63], 0, v[162:163]
	s_add_i32 m0, s64, 0x2000
	s_nop 0
	global_load_lds_dwordx4 v[222:223], off
	v_lshl_add_u64 v[222:223], v[226:227], 0, s[26:27]
	s_mov_b32 m0, s3
	s_nop 0
	global_load_lds_dwordx4 v[222:223], off
	v_lshl_add_u64 v[222:223], v[228:229], 0, s[26:27]
	s_mov_b32 m0, s75
	s_nop 0
	global_load_lds_dwordx4 v[222:223], off
	s_waitcnt vmcnt(8)
	s_waitcnt lgkmcnt(0)
	s_barrier
	s_setprio 1
	s_waitcnt lgkmcnt(0)
	v_mfma_f32_16x16x32_bf16 v[60:63], v[128:131], v[180:183], v[60:63]
	v_mfma_f32_16x16x32_bf16 v[60:63], v[132:135], v[194:197], v[60:63]
	v_mfma_f32_16x16x32_bf16 v[56:59], v[136:139], v[180:183], v[56:59]
	v_mfma_f32_16x16x32_bf16 v[56:59], v[140:143], v[194:197], v[56:59]
	v_mfma_f32_16x16x32_bf16 v[44:47], v[128:131], v[198:201], v[44:47]
	v_mfma_f32_16x16x32_bf16 v[44:47], v[132:135], v[202:205], v[44:47]
	v_mfma_f32_16x16x32_bf16 v[40:43], v[136:139], v[198:201], v[40:43]
	v_mfma_f32_16x16x32_bf16 v[40:43], v[140:143], v[202:205], v[40:43]
	v_mfma_f32_16x16x32_bf16 v[28:31], v[128:131], v[206:209], v[28:31]
	v_mfma_f32_16x16x32_bf16 v[28:31], v[132:135], v[210:213], v[28:31]
	v_mfma_f32_16x16x32_bf16 v[24:27], v[136:139], v[206:209], v[24:27]
	v_mfma_f32_16x16x32_bf16 v[24:27], v[140:143], v[210:213], v[24:27]
	v_mfma_f32_16x16x32_bf16 v[12:15], v[128:131], v[214:217], v[12:15]
	v_mfma_f32_16x16x32_bf16 v[12:15], v[132:135], v[218:221], v[12:15]
	v_mfma_f32_16x16x32_bf16 v[8:11], v[136:139], v[214:217], v[8:11]
	v_mfma_f32_16x16x32_bf16 v[8:11], v[140:143], v[218:221], v[8:11]
	s_setprio 0
	s_setprio 1
	v_mfma_f32_16x16x32_bf16 v[52:55], v[144:147], v[180:183], v[52:55]
	v_mfma_f32_16x16x32_bf16 v[52:55], v[148:151], v[194:197], v[52:55]
	v_mfma_f32_16x16x32_bf16 v[48:51], v[172:175], v[180:183], v[48:51]
	v_mfma_f32_16x16x32_bf16 v[48:51], v[176:179], v[194:197], v[48:51]
	v_mfma_f32_16x16x32_bf16 v[36:39], v[144:147], v[198:201], v[36:39]
	v_mfma_f32_16x16x32_bf16 v[36:39], v[148:151], v[202:205], v[36:39]
	v_mfma_f32_16x16x32_bf16 v[32:35], v[172:175], v[198:201], v[32:35]
	v_mfma_f32_16x16x32_bf16 v[32:35], v[176:179], v[202:205], v[32:35]
	v_mfma_f32_16x16x32_bf16 v[20:23], v[144:147], v[206:209], v[20:23]
	v_mfma_f32_16x16x32_bf16 v[20:23], v[148:151], v[210:213], v[20:23]
	v_mfma_f32_16x16x32_bf16 v[16:19], v[172:175], v[206:209], v[16:19]
	v_mfma_f32_16x16x32_bf16 v[16:19], v[176:179], v[210:213], v[16:19]
	v_mfma_f32_16x16x32_bf16 v[4:7], v[144:147], v[214:217], v[4:7]
	v_mfma_f32_16x16x32_bf16 v[4:7], v[148:151], v[218:221], v[4:7]
	v_mfma_f32_16x16x32_bf16 v[0:3], v[172:175], v[214:217], v[0:3]
	v_mfma_f32_16x16x32_bf16 v[0:3], v[176:179], v[218:221], v[0:3]
	s_setprio 0
	s_barrier
	s_add_i32 s83, s83, 2
	s_add_u32 s81, s81, 0x100
	s_addc_u32 s82, s82, 0
	s_add_u32 s60, s60, 0x100
	s_addc_u32 s61, s61, 0
	s_cmp_gt_u32 s83, 29
.LBB0_440:
	ds_read_b128 v[128:131], v189
	ds_read_b128 v[132:135], v189 offset:1024
	ds_read_b128 v[136:139], v189 offset:2048
	ds_read_b128 v[140:143], v189 offset:3072
	ds_read_b128 v[144:147], v190
	ds_read_b128 v[148:151], v190 offset:1024
	ds_read_b128 v[172:175], v190 offset:2048
	ds_read_b128 v[176:179], v190 offset:3072
	s_add_u32 s62, s60, 0xfff80080
	s_addc_u32 s63, s61, -1
	s_cmp_eq_u32 s83, 28
	s_cselect_b32 s65, s15, s63
	s_cselect_b32 s64, s53, s62
	s_cselect_b32 s63, s51, s82
	s_cselect_b32 s62, s59, s81
	v_lshl_add_u64 v[222:223], s[60:61], 0, v[166:167]
	s_add_i32 m0, s70, 0xc000
	ds_read_b128 v[180:183], v191
	ds_read_b128 v[194:197], v191 offset:1024
	ds_read_b128 v[198:201], v191 offset:2048
	ds_read_b128 v[202:205], v191 offset:3072
	ds_read_b128 v[206:209], v191 offset:4096
	ds_read_b128 v[210:213], v191 offset:5120
	ds_read_b128 v[214:217], v191 offset:6144
	ds_read_b128 v[218:221], v191 offset:7168
	global_load_lds_dwordx4 v[222:223], off
	v_lshl_add_u64 v[222:223], s[60:61], 0, v[164:165]
	s_add_i32 m0, s70, 0xe000
	s_nop 0
	global_load_lds_dwordx4 v[222:223], off
	s_waitcnt vmcnt(8)
	s_waitcnt lgkmcnt(0)
	s_barrier
	s_setprio 1
	s_waitcnt lgkmcnt(0)
	v_mfma_f32_16x16x32_bf16 v[124:127], v[128:131], v[180:183], v[124:127]
	v_mfma_f32_16x16x32_bf16 v[124:127], v[132:135], v[194:197], v[124:127]
	v_mfma_f32_16x16x32_bf16 v[120:123], v[136:139], v[180:183], v[120:123]
	v_mfma_f32_16x16x32_bf16 v[120:123], v[140:143], v[194:197], v[120:123]
	v_mfma_f32_16x16x32_bf16 v[108:111], v[128:131], v[198:201], v[108:111]
	v_mfma_f32_16x16x32_bf16 v[108:111], v[132:135], v[202:205], v[108:111]
	v_mfma_f32_16x16x32_bf16 v[104:107], v[136:139], v[198:201], v[104:107]
	v_mfma_f32_16x16x32_bf16 v[104:107], v[140:143], v[202:205], v[104:107]
	v_mfma_f32_16x16x32_bf16 v[92:95], v[128:131], v[206:209], v[92:95]
	v_mfma_f32_16x16x32_bf16 v[92:95], v[132:135], v[210:213], v[92:95]
	v_mfma_f32_16x16x32_bf16 v[88:91], v[136:139], v[206:209], v[88:91]
	v_mfma_f32_16x16x32_bf16 v[88:91], v[140:143], v[210:213], v[88:91]
	v_mfma_f32_16x16x32_bf16 v[76:79], v[128:131], v[214:217], v[76:79]
	v_mfma_f32_16x16x32_bf16 v[76:79], v[132:135], v[218:221], v[76:79]
	v_mfma_f32_16x16x32_bf16 v[72:75], v[136:139], v[214:217], v[72:75]
	v_mfma_f32_16x16x32_bf16 v[72:75], v[140:143], v[218:221], v[72:75]
	s_setprio 0
	s_setprio 1
	v_mfma_f32_16x16x32_bf16 v[116:119], v[144:147], v[180:183], v[116:119]
	v_mfma_f32_16x16x32_bf16 v[116:119], v[148:151], v[194:197], v[116:119]
	v_mfma_f32_16x16x32_bf16 v[112:115], v[172:175], v[180:183], v[112:115]
	v_mfma_f32_16x16x32_bf16 v[112:115], v[176:179], v[194:197], v[112:115]
	v_mfma_f32_16x16x32_bf16 v[100:103], v[144:147], v[198:201], v[100:103]
	v_mfma_f32_16x16x32_bf16 v[100:103], v[148:151], v[202:205], v[100:103]
	v_mfma_f32_16x16x32_bf16 v[96:99], v[172:175], v[198:201], v[96:99]
	v_mfma_f32_16x16x32_bf16 v[96:99], v[176:179], v[202:205], v[96:99]
	v_mfma_f32_16x16x32_bf16 v[84:87], v[144:147], v[206:209], v[84:87]
	v_mfma_f32_16x16x32_bf16 v[84:87], v[148:151], v[210:213], v[84:87]
	v_mfma_f32_16x16x32_bf16 v[80:83], v[172:175], v[206:209], v[80:83]
	v_mfma_f32_16x16x32_bf16 v[80:83], v[176:179], v[210:213], v[80:83]
	v_mfma_f32_16x16x32_bf16 v[68:71], v[144:147], v[214:217], v[68:71]
	v_mfma_f32_16x16x32_bf16 v[68:71], v[148:151], v[218:221], v[68:71]
	v_mfma_f32_16x16x32_bf16 v[64:67], v[172:175], v[214:217], v[64:67]
	v_mfma_f32_16x16x32_bf16 v[64:67], v[176:179], v[218:221], v[64:67]
	s_setprio 0
	s_barrier
	s_add_i32 s84, s79, s69
	v_lshl_add_u64 v[222:223], s[62:63], 0, v[154:155]
	s_mov_b32 m0, s84
	ds_read_b128 v[180:183], v191 offset:16384
	ds_read_b128 v[194:197], v191 offset:17408
	ds_read_b128 v[198:201], v191 offset:18432
	ds_read_b128 v[202:205], v191 offset:19456
	ds_read_b128 v[206:209], v191 offset:20480
	ds_read_b128 v[210:213], v191 offset:21504
	ds_read_b128 v[214:217], v191 offset:22528
	ds_read_b128 v[218:221], v191 offset:23552
	global_load_lds_dwordx4 v[222:223], off
	s_add_i32 m0, s84, 0x2000
	s_add_u32 s84, s62, 0x80000
	v_lshl_add_u64 v[224:225], s[62:63], 0, v[162:163]
	s_addc_u32 s85, s63, 0
	s_add_i32 s86, s80, s69
	global_load_lds_dwordx4 v[224:225], off
	v_lshl_add_u64 v[226:227], s[84:85], 0, v[154:155]
	s_mov_b32 m0, s86
	v_lshl_add_u64 v[228:229], s[64:65], 0, v[160:161]
	global_load_lds_dwordx4 v[226:227], off
	v_lshl_add_u64 v[226:227], s[84:85], 0, v[162:163]
	s_add_i32 m0, s86, 0x2000
	s_nop 0
	global_load_lds_dwordx4 v[226:227], off
	v_lshl_add_u64 v[226:227], s[64:65], 0, v[152:153]
	s_mov_b32 m0, s70
	s_nop 0
	global_load_lds_dwordx4 v[226:227], off
	s_mov_b32 m0, s71
	s_nop 0
	global_load_lds_dwordx4 v[228:229], off
	s_waitcnt vmcnt(8)
	s_waitcnt lgkmcnt(0)
	s_barrier
	s_setprio 1
	s_waitcnt lgkmcnt(0)
	v_mfma_f32_16x16x32_bf16 v[60:63], v[128:131], v[180:183], v[60:63]
	v_mfma_f32_16x16x32_bf16 v[60:63], v[132:135], v[194:197], v[60:63]
	v_mfma_f32_16x16x32_bf16 v[56:59], v[136:139], v[180:183], v[56:59]
	v_mfma_f32_16x16x32_bf16 v[56:59], v[140:143], v[194:197], v[56:59]
	v_mfma_f32_16x16x32_bf16 v[44:47], v[128:131], v[198:201], v[44:47]
	v_mfma_f32_16x16x32_bf16 v[44:47], v[132:135], v[202:205], v[44:47]
	v_mfma_f32_16x16x32_bf16 v[40:43], v[136:139], v[198:201], v[40:43]
	v_mfma_f32_16x16x32_bf16 v[40:43], v[140:143], v[202:205], v[40:43]
	v_mfma_f32_16x16x32_bf16 v[28:31], v[128:131], v[206:209], v[28:31]
	v_mfma_f32_16x16x32_bf16 v[28:31], v[132:135], v[210:213], v[28:31]
	v_mfma_f32_16x16x32_bf16 v[24:27], v[136:139], v[206:209], v[24:27]
	v_mfma_f32_16x16x32_bf16 v[24:27], v[140:143], v[210:213], v[24:27]
	v_mfma_f32_16x16x32_bf16 v[12:15], v[128:131], v[214:217], v[12:15]
	v_mfma_f32_16x16x32_bf16 v[12:15], v[132:135], v[218:221], v[12:15]
	v_mfma_f32_16x16x32_bf16 v[8:11], v[136:139], v[214:217], v[8:11]
	v_mfma_f32_16x16x32_bf16 v[8:11], v[140:143], v[218:221], v[8:11]
	s_setprio 0
	s_setprio 1
	v_mfma_f32_16x16x32_bf16 v[52:55], v[144:147], v[180:183], v[52:55]
	v_mfma_f32_16x16x32_bf16 v[52:55], v[148:151], v[194:197], v[52:55]
	v_mfma_f32_16x16x32_bf16 v[48:51], v[172:175], v[180:183], v[48:51]
	v_mfma_f32_16x16x32_bf16 v[48:51], v[176:179], v[194:197], v[48:51]
	v_mfma_f32_16x16x32_bf16 v[36:39], v[144:147], v[198:201], v[36:39]
	v_mfma_f32_16x16x32_bf16 v[36:39], v[148:151], v[202:205], v[36:39]
	v_mfma_f32_16x16x32_bf16 v[32:35], v[172:175], v[198:201], v[32:35]
	v_mfma_f32_16x16x32_bf16 v[32:35], v[176:179], v[202:205], v[32:35]
	v_mfma_f32_16x16x32_bf16 v[20:23], v[144:147], v[206:209], v[20:23]
	v_mfma_f32_16x16x32_bf16 v[20:23], v[148:151], v[210:213], v[20:23]
	v_mfma_f32_16x16x32_bf16 v[16:19], v[172:175], v[206:209], v[16:19]
	v_mfma_f32_16x16x32_bf16 v[16:19], v[176:179], v[210:213], v[16:19]
	v_mfma_f32_16x16x32_bf16 v[4:7], v[144:147], v[214:217], v[4:7]
	v_mfma_f32_16x16x32_bf16 v[4:7], v[148:151], v[218:221], v[4:7]
	v_mfma_f32_16x16x32_bf16 v[0:3], v[172:175], v[214:217], v[0:3]
	v_mfma_f32_16x16x32_bf16 v[0:3], v[176:179], v[218:221], v[0:3]
	s_setprio 0
	s_barrier
	s_add_i32 s84, 0, 0x18000
	s_add_i32 s85, 0, 0x1c000
	v_add_u32_e32 v140, s84, v186
	v_add_u32_e32 v176, s85, v186
	ds_read_b128 v[128:131], v140
	ds_read_b128 v[132:135], v140 offset:1024
	ds_read_b128 v[136:139], v140 offset:2048
	ds_read_b128 v[140:143], v140 offset:3072
	ds_read_b128 v[144:147], v176
	ds_read_b128 v[148:151], v176 offset:1024
	ds_read_b128 v[172:175], v176 offset:2048
	ds_read_b128 v[176:179], v176 offset:3072
	s_add_u32 s64, s64, 0x80000
	s_addc_u32 s65, s65, 0
	s_mov_b32 m0, s72
	v_lshl_add_u64 v[230:231], s[64:65], 0, v[152:153]
	ds_read_b128 v[180:183], v191 offset:32768
	ds_read_b128 v[194:197], v191 offset:33792
	ds_read_b128 v[198:201], v191 offset:34816
	ds_read_b128 v[202:205], v191 offset:35840
	ds_read_b128 v[206:209], v191 offset:36864
	ds_read_b128 v[210:213], v191 offset:37888
	ds_read_b128 v[214:217], v191 offset:38912
	ds_read_b128 v[218:221], v191 offset:39936
	global_load_lds_dwordx4 v[230:231], off
	v_lshl_add_u64 v[230:231], s[64:65], 0, v[160:161]
	s_mov_b32 m0, s73
	s_nop 0
	global_load_lds_dwordx4 v[230:231], off
	s_waitcnt vmcnt(8)
	s_waitcnt lgkmcnt(0)
	s_barrier
	s_setprio 1
	s_waitcnt lgkmcnt(0)
	v_mfma_f32_16x16x32_bf16 v[124:127], v[128:131], v[180:183], v[124:127]
	v_mfma_f32_16x16x32_bf16 v[124:127], v[132:135], v[194:197], v[124:127]
	v_mfma_f32_16x16x32_bf16 v[120:123], v[136:139], v[180:183], v[120:123]
	v_mfma_f32_16x16x32_bf16 v[120:123], v[140:143], v[194:197], v[120:123]
	v_mfma_f32_16x16x32_bf16 v[108:111], v[128:131], v[198:201], v[108:111]
	v_mfma_f32_16x16x32_bf16 v[108:111], v[132:135], v[202:205], v[108:111]
	v_mfma_f32_16x16x32_bf16 v[104:107], v[136:139], v[198:201], v[104:107]
	v_mfma_f32_16x16x32_bf16 v[104:107], v[140:143], v[202:205], v[104:107]
	v_mfma_f32_16x16x32_bf16 v[92:95], v[128:131], v[206:209], v[92:95]
	v_mfma_f32_16x16x32_bf16 v[92:95], v[132:135], v[210:213], v[92:95]
	v_mfma_f32_16x16x32_bf16 v[88:91], v[136:139], v[206:209], v[88:91]
	v_mfma_f32_16x16x32_bf16 v[88:91], v[140:143], v[210:213], v[88:91]
	v_mfma_f32_16x16x32_bf16 v[76:79], v[128:131], v[214:217], v[76:79]
	v_mfma_f32_16x16x32_bf16 v[76:79], v[132:135], v[218:221], v[76:79]
	v_mfma_f32_16x16x32_bf16 v[72:75], v[136:139], v[214:217], v[72:75]
	v_mfma_f32_16x16x32_bf16 v[72:75], v[140:143], v[218:221], v[72:75]
	s_setprio 0
	s_setprio 1
	v_mfma_f32_16x16x32_bf16 v[116:119], v[144:147], v[180:183], v[116:119]
	v_mfma_f32_16x16x32_bf16 v[116:119], v[148:151], v[194:197], v[116:119]
	v_mfma_f32_16x16x32_bf16 v[112:115], v[172:175], v[180:183], v[112:115]
	v_mfma_f32_16x16x32_bf16 v[112:115], v[176:179], v[194:197], v[112:115]
	v_mfma_f32_16x16x32_bf16 v[100:103], v[144:147], v[198:201], v[100:103]
	v_mfma_f32_16x16x32_bf16 v[100:103], v[148:151], v[202:205], v[100:103]
	v_mfma_f32_16x16x32_bf16 v[96:99], v[172:175], v[198:201], v[96:99]
	v_mfma_f32_16x16x32_bf16 v[96:99], v[176:179], v[202:205], v[96:99]
	v_mfma_f32_16x16x32_bf16 v[84:87], v[144:147], v[206:209], v[84:87]
	v_mfma_f32_16x16x32_bf16 v[84:87], v[148:151], v[210:213], v[84:87]
	v_mfma_f32_16x16x32_bf16 v[80:83], v[172:175], v[206:209], v[80:83]
	v_mfma_f32_16x16x32_bf16 v[80:83], v[176:179], v[210:213], v[80:83]
	v_mfma_f32_16x16x32_bf16 v[68:71], v[144:147], v[214:217], v[68:71]
	v_mfma_f32_16x16x32_bf16 v[68:71], v[148:151], v[218:221], v[68:71]
	v_mfma_f32_16x16x32_bf16 v[64:67], v[172:175], v[214:217], v[64:67]
	v_mfma_f32_16x16x32_bf16 v[64:67], v[176:179], v[218:221], v[64:67]
	s_setprio 0
	s_barrier
	s_add_i32 s64, s84, s69
	v_lshl_add_u64 v[222:223], v[222:223], 0, s[26:27]
	s_mov_b32 m0, s64
	ds_read_b128 v[180:183], v191 offset:49152
	ds_read_b128 v[194:197], v191 offset:50176
	ds_read_b128 v[198:201], v191 offset:51200
	ds_read_b128 v[202:205], v191 offset:52224
	ds_read_b128 v[206:209], v191 offset:53248
	ds_read_b128 v[210:213], v191 offset:54272
	ds_read_b128 v[214:217], v191 offset:55296
	ds_read_b128 v[218:221], v191 offset:56320
	global_load_lds_dwordx4 v[222:223], off
	s_add_i32 m0, s64, 0x2000
	s_add_u32 s62, s62, 0x80080
	v_lshl_add_u64 v[222:223], v[224:225], 0, s[26:27]
	s_addc_u32 s63, s63, 0
	s_add_i32 s64, s85, s69
	global_load_lds_dwordx4 v[222:223], off
	v_lshl_add_u64 v[222:223], s[62:63], 0, v[154:155]
	s_mov_b32 m0, s64
	s_nop 0
	global_load_lds_dwordx4 v[222:223], off
	v_lshl_add_u64 v[222:223], s[62:63], 0, v[162:163]
	s_add_i32 m0, s64, 0x2000
	s_nop 0
	global_load_lds_dwordx4 v[222:223], off
	v_lshl_add_u64 v[222:223], v[226:227], 0, s[26:27]
	s_mov_b32 m0, s3
	s_nop 0
	global_load_lds_dwordx4 v[222:223], off
	v_lshl_add_u64 v[222:223], v[228:229], 0, s[26:27]
	s_mov_b32 m0, s75
	s_nop 0
	global_load_lds_dwordx4 v[222:223], off
	s_waitcnt vmcnt(8)
	s_waitcnt lgkmcnt(0)
	s_barrier
	s_setprio 1
	s_waitcnt lgkmcnt(0)
	v_mfma_f32_16x16x32_bf16 v[60:63], v[128:131], v[180:183], v[60:63]
	v_mfma_f32_16x16x32_bf16 v[60:63], v[132:135], v[194:197], v[60:63]
	v_mfma_f32_16x16x32_bf16 v[56:59], v[136:139], v[180:183], v[56:59]
	v_mfma_f32_16x16x32_bf16 v[56:59], v[140:143], v[194:197], v[56:59]
	v_mfma_f32_16x16x32_bf16 v[44:47], v[128:131], v[198:201], v[44:47]
	v_mfma_f32_16x16x32_bf16 v[44:47], v[132:135], v[202:205], v[44:47]
	v_mfma_f32_16x16x32_bf16 v[40:43], v[136:139], v[198:201], v[40:43]
	v_mfma_f32_16x16x32_bf16 v[40:43], v[140:143], v[202:205], v[40:43]
	v_mfma_f32_16x16x32_bf16 v[28:31], v[128:131], v[206:209], v[28:31]
	v_mfma_f32_16x16x32_bf16 v[28:31], v[132:135], v[210:213], v[28:31]
	v_mfma_f32_16x16x32_bf16 v[24:27], v[136:139], v[206:209], v[24:27]
	v_mfma_f32_16x16x32_bf16 v[24:27], v[140:143], v[210:213], v[24:27]
	v_mfma_f32_16x16x32_bf16 v[12:15], v[128:131], v[214:217], v[12:15]
	v_mfma_f32_16x16x32_bf16 v[12:15], v[132:135], v[218:221], v[12:15]
	v_mfma_f32_16x16x32_bf16 v[8:11], v[136:139], v[214:217], v[8:11]
	v_mfma_f32_16x16x32_bf16 v[8:11], v[140:143], v[218:221], v[8:11]
	s_setprio 0
	s_setprio 1
	v_mfma_f32_16x16x32_bf16 v[52:55], v[144:147], v[180:183], v[52:55]
	v_mfma_f32_16x16x32_bf16 v[52:55], v[148:151], v[194:197], v[52:55]
	v_mfma_f32_16x16x32_bf16 v[48:51], v[172:175], v[180:183], v[48:51]
	v_mfma_f32_16x16x32_bf16 v[48:51], v[176:179], v[194:197], v[48:51]
	v_mfma_f32_16x16x32_bf16 v[36:39], v[144:147], v[198:201], v[36:39]
	v_mfma_f32_16x16x32_bf16 v[36:39], v[148:151], v[202:205], v[36:39]
	v_mfma_f32_16x16x32_bf16 v[32:35], v[172:175], v[198:201], v[32:35]
	v_mfma_f32_16x16x32_bf16 v[32:35], v[176:179], v[202:205], v[32:35]
	v_mfma_f32_16x16x32_bf16 v[20:23], v[144:147], v[206:209], v[20:23]
	v_mfma_f32_16x16x32_bf16 v[20:23], v[148:151], v[210:213], v[20:23]
	v_mfma_f32_16x16x32_bf16 v[16:19], v[172:175], v[206:209], v[16:19]
	v_mfma_f32_16x16x32_bf16 v[16:19], v[176:179], v[210:213], v[16:19]
	v_mfma_f32_16x16x32_bf16 v[4:7], v[144:147], v[214:217], v[4:7]
	v_mfma_f32_16x16x32_bf16 v[4:7], v[148:151], v[218:221], v[4:7]
	v_mfma_f32_16x16x32_bf16 v[0:3], v[172:175], v[214:217], v[0:3]
	v_mfma_f32_16x16x32_bf16 v[0:3], v[176:179], v[218:221], v[0:3]
	s_setprio 0
	s_barrier
	s_add_i32 s83, s83, 2
	s_add_u32 s81, s81, 0x100
	s_addc_u32 s82, s82, 0
	s_add_u32 s60, s60, 0x100
	s_addc_u32 s61, s61, 0
	s_cmp_gt_u32 s83, 29
	s_cbranch_scc0 .LBB0_440
	s_and_b64 vcc, exec, s[28:29]
	s_cbranch_vccz .LBB0_443
	s_barrier

.LBB0_525:
	s_ashr_i32 s29, s28, 31
	s_lshl_b64 s[30:31], s[28:29], 19
	s_add_u32 s30, s3, s30
	s_addc_u32 s31, s35, s31
	s_and_b64 s[44:45], s[10:11], exec
	s_cselect_b32 s29, s31, s51
	s_cselect_b32 s70, s30, s50
	s_ashr_i32 s27, s26, 31
	s_lshl_b64 s[44:45], s[26:27], 19
	s_add_u32 s44, s52, s44
	s_addc_u32 s45, s53, s45
	s_and_b64 s[72:73], s[10:11], exec
	s_cselect_b32 s71, s45, s49
	s_cselect_b32 s72, s44, s48
	s_lshl_b32 s27, s46, 8
	v_add_u32_e32 v0, s27, v148
	s_add_u32 s73, s48, 0x100
	v_ashrrev_i32_e32 v1, 31, v0
	s_addc_u32 s74, s49, 0
	v_lshl_add_u64 v[144:145], v[0:1], 4, s[16:17]
	s_add_u32 s46, s50, 0x40080
	s_addc_u32 s47, s51, 0
	s_mov_b32 s75, -2
	s_mov_b64 s[48:49], 0
	s_cmp_eq_u32 s61, 1
	s_cbranch_scc1 .Lfa_4
	v_add_u32_e32 v153, s66, v147
	ds_read_b128 v[160:163], v153
	ds_read_b128 v[164:167], v153 offset:1024
	ds_read_b128 v[168:171], v153 offset:2048
	ds_read_b128 v[172:175], v153 offset:3072
	v_add_u32_e32 v153, s67, v147
	ds_read_b128 v[176:179], v153
	ds_read_b128 v[180:183], v153 offset:1024
	ds_read_b128 v[186:189], v153 offset:2048
	ds_read_b128 v[190:193], v153 offset:3072
	s_add_u32 s50, s46, 0xfffc0080
	s_addc_u32 s51, s47, -1
	s_and_b64 s[48:49], s[48:49], exec
	s_cselect_b32 s51, s29, s51
	s_cselect_b32 s50, s70, s50
	s_cselect_b32 s49, s71, s74
	s_cselect_b32 s48, s72, s73
	v_lshl_add_u64 v[154:155], s[46:47], 0, v[138:139]
	s_add_i32 m0, s57, 0xc000
	ds_read_b128 v[194:197], v150
	ds_read_b128 v[198:201], v150 offset:1024
	ds_read_b128 v[202:205], v150 offset:2048
	ds_read_b128 v[206:209], v150 offset:3072
	ds_read_b128 v[210:213], v150 offset:4096
	ds_read_b128 v[214:217], v150 offset:5120
	ds_read_b128 v[218:221], v150 offset:6144
	ds_read_b128 v[222:225], v150 offset:7168
	global_load_lds_dwordx4 v[154:155], off
	v_lshl_add_u64 v[154:155], s[46:47], 0, v[136:137]
	s_add_i32 m0, s57, 0xe000
	s_nop 0
	global_load_lds_dwordx4 v[154:155], off
	s_waitcnt vmcnt(16)
	s_waitcnt lgkmcnt(0)
	s_barrier
	s_setprio 1
	s_waitcnt lgkmcnt(0)
	v_mfma_f32_16x16x32_bf16 v[124:127], v[160:163], v[194:197], 0
	v_mfma_f32_16x16x32_bf16 v[116:119], v[168:171], v[194:197], 0
	v_mfma_f32_16x16x32_bf16 v[108:111], v[160:163], v[202:205], 0
	v_mfma_f32_16x16x32_bf16 v[100:103], v[168:171], v[202:205], 0
	v_mfma_f32_16x16x32_bf16 v[92:95], v[160:163], v[210:213], 0
	v_mfma_f32_16x16x32_bf16 v[84:87], v[168:171], v[210:213], 0
	v_mfma_f32_16x16x32_bf16 v[76:79], v[160:163], v[218:221], 0
	v_mfma_f32_16x16x32_bf16 v[68:71], v[168:171], v[218:221], 0
	v_mfma_f32_16x16x32_bf16 v[124:127], v[164:167], v[198:201], v[124:127]
	v_mfma_f32_16x16x32_bf16 v[116:119], v[172:175], v[198:201], v[116:119]
	v_mfma_f32_16x16x32_bf16 v[108:111], v[164:167], v[206:209], v[108:111]
	v_mfma_f32_16x16x32_bf16 v[100:103], v[172:175], v[206:209], v[100:103]
	v_mfma_f32_16x16x32_bf16 v[92:95], v[164:167], v[214:217], v[92:95]
	v_mfma_f32_16x16x32_bf16 v[84:87], v[172:175], v[214:217], v[84:87]
	v_mfma_f32_16x16x32_bf16 v[76:79], v[164:167], v[222:225], v[76:79]
	v_mfma_f32_16x16x32_bf16 v[68:71], v[172:175], v[222:225], v[68:71]
	s_setprio 0
	s_setprio 1
	v_mfma_f32_16x16x32_bf16 v[120:123], v[176:179], v[194:197], 0
	v_mfma_f32_16x16x32_bf16 v[112:115], v[186:189], v[194:197], 0
	v_mfma_f32_16x16x32_bf16 v[104:107], v[176:179], v[202:205], 0
	v_mfma_f32_16x16x32_bf16 v[96:99], v[186:189], v[202:205], 0
	v_mfma_f32_16x16x32_bf16 v[88:91], v[176:179], v[210:213], 0
	v_mfma_f32_16x16x32_bf16 v[80:83], v[186:189], v[210:213], 0
	v_mfma_f32_16x16x32_bf16 v[72:75], v[176:179], v[218:221], 0
	v_mfma_f32_16x16x32_bf16 v[64:67], v[186:189], v[218:221], 0
	v_mfma_f32_16x16x32_bf16 v[120:123], v[180:183], v[198:201], v[120:123]
	v_mfma_f32_16x16x32_bf16 v[112:115], v[190:193], v[198:201], v[112:115]
	v_mfma_f32_16x16x32_bf16 v[104:107], v[180:183], v[206:209], v[104:107]
	v_mfma_f32_16x16x32_bf16 v[96:99], v[190:193], v[206:209], v[96:99]
	v_mfma_f32_16x16x32_bf16 v[88:91], v[180:183], v[214:217], v[88:91]
	v_mfma_f32_16x16x32_bf16 v[80:83], v[190:193], v[214:217], v[80:83]
	v_mfma_f32_16x16x32_bf16 v[72:75], v[180:183], v[222:225], v[72:75]
	v_mfma_f32_16x16x32_bf16 v[64:67], v[190:193], v[222:225], v[64:67]
	s_setprio 0
	s_barrier
	s_add_i32 s76, s66, s54
	v_lshl_add_u64 v[154:155], s[48:49], 0, v[132:133]
	s_mov_b32 m0, s76
	ds_read_b128 v[194:197], v150 offset:16384
	ds_read_b128 v[198:201], v150 offset:17408
	ds_read_b128 v[202:205], v150 offset:18432
	ds_read_b128 v[206:209], v150 offset:19456
	ds_read_b128 v[210:213], v150 offset:20480
	ds_read_b128 v[214:217], v150 offset:21504
	ds_read_b128 v[218:221], v150 offset:22528
	ds_read_b128 v[222:225], v150 offset:23552
	global_load_lds_dwordx4 v[154:155], off
	s_add_i32 m0, s76, 0x2000
	s_add_u32 s76, s48, 0x40000
	v_lshl_add_u64 v[226:227], s[48:49], 0, v[128:129]
	s_addc_u32 s77, s49, 0
	s_add_i32 s78, s67, s54
	global_load_lds_dwordx4 v[226:227], off
	v_lshl_add_u64 v[228:229], s[76:77], 0, v[132:133]
	s_mov_b32 m0, s78
	v_lshl_add_u64 v[230:231], s[50:51], 0, v[130:131]
	global_load_lds_dwordx4 v[228:229], off
	v_lshl_add_u64 v[228:229], s[76:77], 0, v[128:129]
	s_add_i32 m0, s78, 0x2000
	s_nop 0
	global_load_lds_dwordx4 v[228:229], off
	v_lshl_add_u64 v[228:229], s[50:51], 0, v[134:135]
	s_mov_b32 m0, s57
	s_nop 0
	global_load_lds_dwordx4 v[228:229], off
	s_mov_b32 m0, s58
	s_nop 0
	global_load_lds_dwordx4 v[230:231], off
	s_waitcnt vmcnt(16)
	s_waitcnt lgkmcnt(0)
	s_barrier
	s_setprio 1
	s_waitcnt lgkmcnt(0)
	v_mfma_f32_16x16x32_bf16 v[60:63], v[160:163], v[194:197], 0
	v_mfma_f32_16x16x32_bf16 v[52:55], v[168:171], v[194:197], 0
	v_mfma_f32_16x16x32_bf16 v[44:47], v[160:163], v[202:205], 0
	v_mfma_f32_16x16x32_bf16 v[36:39], v[168:171], v[202:205], 0
	v_mfma_f32_16x16x32_bf16 v[28:31], v[160:163], v[210:213], 0
	v_mfma_f32_16x16x32_bf16 v[20:23], v[168:171], v[210:213], 0
	v_mfma_f32_16x16x32_bf16 v[12:15], v[160:163], v[218:221], 0
	v_mfma_f32_16x16x32_bf16 v[4:7], v[168:171], v[218:221], 0
	v_mfma_f32_16x16x32_bf16 v[60:63], v[164:167], v[198:201], v[60:63]
	v_mfma_f32_16x16x32_bf16 v[52:55], v[172:175], v[198:201], v[52:55]
	v_mfma_f32_16x16x32_bf16 v[44:47], v[164:167], v[206:209], v[44:47]
	v_mfma_f32_16x16x32_bf16 v[36:39], v[172:175], v[206:209], v[36:39]
	v_mfma_f32_16x16x32_bf16 v[28:31], v[164:167], v[214:217], v[28:31]
	v_mfma_f32_16x16x32_bf16 v[20:23], v[172:175], v[214:217], v[20:23]
	v_mfma_f32_16x16x32_bf16 v[12:15], v[164:167], v[222:225], v[12:15]
	v_mfma_f32_16x16x32_bf16 v[4:7], v[172:175], v[222:225], v[4:7]
	s_setprio 0
	s_setprio 1
	v_mfma_f32_16x16x32_bf16 v[56:59], v[176:179], v[194:197], 0
	v_mfma_f32_16x16x32_bf16 v[48:51], v[186:189], v[194:197], 0
	v_mfma_f32_16x16x32_bf16 v[40:43], v[176:179], v[202:205], 0
	v_mfma_f32_16x16x32_bf16 v[32:35], v[186:189], v[202:205], 0
	v_mfma_f32_16x16x32_bf16 v[24:27], v[176:179], v[210:213], 0
	v_mfma_f32_16x16x32_bf16 v[16:19], v[186:189], v[210:213], 0
	v_mfma_f32_16x16x32_bf16 v[8:11], v[176:179], v[218:221], 0
	v_mfma_f32_16x16x32_bf16 v[0:3], v[186:189], v[218:221], 0
	v_mfma_f32_16x16x32_bf16 v[56:59], v[180:183], v[198:201], v[56:59]
	v_mfma_f32_16x16x32_bf16 v[48:51], v[190:193], v[198:201], v[48:51]
	v_mfma_f32_16x16x32_bf16 v[40:43], v[180:183], v[206:209], v[40:43]
	v_mfma_f32_16x16x32_bf16 v[32:35], v[190:193], v[206:209], v[32:35]
	v_mfma_f32_16x16x32_bf16 v[24:27], v[180:183], v[214:217], v[24:27]
	v_mfma_f32_16x16x32_bf16 v[16:19], v[190:193], v[214:217], v[16:19]
	v_mfma_f32_16x16x32_bf16 v[8:11], v[180:183], v[222:225], v[8:11]
	v_mfma_f32_16x16x32_bf16 v[0:3], v[190:193], v[222:225], v[0:3]
	s_setprio 0
	s_barrier
	s_add_i32 s76, 0, 0x18000
	v_add_u32_e32 v153, s76, v147
	s_add_i32 s77, 0, 0x1c000
	ds_read_b128 v[160:163], v153
	ds_read_b128 v[164:167], v153 offset:1024
	ds_read_b128 v[168:171], v153 offset:2048
	ds_read_b128 v[172:175], v153 offset:3072
	v_add_u32_e32 v153, s77, v147
	ds_read_b128 v[176:179], v153
	ds_read_b128 v[180:183], v153 offset:1024
	ds_read_b128 v[186:189], v153 offset:2048
	ds_read_b128 v[190:193], v153 offset:3072
	s_add_u32 s50, s50, 0x40000
	s_addc_u32 s51, s51, 0
	s_mov_b32 m0, s59
	v_lshl_add_u64 v[232:233], s[50:51], 0, v[134:135]
	ds_read_b128 v[194:197], v150 offset:32768
	ds_read_b128 v[198:201], v150 offset:33792
	ds_read_b128 v[202:205], v150 offset:34816
	ds_read_b128 v[206:209], v150 offset:35840
	ds_read_b128 v[210:213], v150 offset:36864
	ds_read_b128 v[214:217], v150 offset:37888
	ds_read_b128 v[218:221], v150 offset:38912
	ds_read_b128 v[222:225], v150 offset:39936
	global_load_lds_dwordx4 v[232:233], off
	v_lshl_add_u64 v[232:233], s[50:51], 0, v[130:131]
	s_mov_b32 m0, s60
	s_nop 0
	global_load_lds_dwordx4 v[232:233], off
	s_waitcnt vmcnt(8)
	s_waitcnt lgkmcnt(0)
	s_barrier
	s_setprio 1
	s_waitcnt lgkmcnt(0)
	v_mfma_f32_16x16x32_bf16 v[124:127], v[160:163], v[194:197], v[124:127]
	v_mfma_f32_16x16x32_bf16 v[124:127], v[164:167], v[198:201], v[124:127]
	v_mfma_f32_16x16x32_bf16 v[116:119], v[168:171], v[194:197], v[116:119]
	v_mfma_f32_16x16x32_bf16 v[116:119], v[172:175], v[198:201], v[116:119]
	v_mfma_f32_16x16x32_bf16 v[108:111], v[160:163], v[202:205], v[108:111]
	v_mfma_f32_16x16x32_bf16 v[108:111], v[164:167], v[206:209], v[108:111]
	v_mfma_f32_16x16x32_bf16 v[100:103], v[168:171], v[202:205], v[100:103]
	v_mfma_f32_16x16x32_bf16 v[100:103], v[172:175], v[206:209], v[100:103]
	v_mfma_f32_16x16x32_bf16 v[92:95], v[160:163], v[210:213], v[92:95]
	v_mfma_f32_16x16x32_bf16 v[92:95], v[164:167], v[214:217], v[92:95]
	v_mfma_f32_16x16x32_bf16 v[84:87], v[168:171], v[210:213], v[84:87]
	v_mfma_f32_16x16x32_bf16 v[84:87], v[172:175], v[214:217], v[84:87]
	v_mfma_f32_16x16x32_bf16 v[76:79], v[160:163], v[218:221], v[76:79]
	v_mfma_f32_16x16x32_bf16 v[76:79], v[164:167], v[222:225], v[76:79]
	v_mfma_f32_16x16x32_bf16 v[68:71], v[168:171], v[218:221], v[68:71]
	v_mfma_f32_16x16x32_bf16 v[68:71], v[172:175], v[222:225], v[68:71]
	s_setprio 0
	s_setprio 1
	v_mfma_f32_16x16x32_bf16 v[120:123], v[176:179], v[194:197], v[120:123]
	v_mfma_f32_16x16x32_bf16 v[120:123], v[180:183], v[198:201], v[120:123]
	v_mfma_f32_16x16x32_bf16 v[112:115], v[186:189], v[194:197], v[112:115]
	v_mfma_f32_16x16x32_bf16 v[112:115], v[190:193], v[198:201], v[112:115]
	v_mfma_f32_16x16x32_bf16 v[104:107], v[176:179], v[202:205], v[104:107]
	v_mfma_f32_16x16x32_bf16 v[104:107], v[180:183], v[206:209], v[104:107]
	v_mfma_f32_16x16x32_bf16 v[96:99], v[186:189], v[202:205], v[96:99]
	v_mfma_f32_16x16x32_bf16 v[96:99], v[190:193], v[206:209], v[96:99]
	v_mfma_f32_16x16x32_bf16 v[88:91], v[176:179], v[210:213], v[88:91]
	v_mfma_f32_16x16x32_bf16 v[88:91], v[180:183], v[214:217], v[88:91]
	v_mfma_f32_16x16x32_bf16 v[80:83], v[186:189], v[210:213], v[80:83]
	v_mfma_f32_16x16x32_bf16 v[80:83], v[190:193], v[214:217], v[80:83]
	v_mfma_f32_16x16x32_bf16 v[72:75], v[176:179], v[218:221], v[72:75]
	v_mfma_f32_16x16x32_bf16 v[72:75], v[180:183], v[222:225], v[72:75]
	v_mfma_f32_16x16x32_bf16 v[64:67], v[186:189], v[218:221], v[64:67]
	v_mfma_f32_16x16x32_bf16 v[64:67], v[190:193], v[222:225], v[64:67]
	s_setprio 0
	s_barrier
	s_add_i32 s50, s76, s54
	v_lshl_add_u64 v[154:155], v[154:155], 0, s[20:21]
	s_mov_b32 m0, s50
	ds_read_b128 v[194:197], v150 offset:49152
	ds_read_b128 v[198:201], v150 offset:50176
	ds_read_b128 v[202:205], v150 offset:51200
	ds_read_b128 v[206:209], v150 offset:52224
	ds_read_b128 v[210:213], v150 offset:53248
	ds_read_b128 v[214:217], v150 offset:54272
	ds_read_b128 v[218:221], v150 offset:55296
	ds_read_b128 v[222:225], v150 offset:56320
	global_load_lds_dwordx4 v[154:155], off
	s_add_i32 m0, s50, 0x2000
	s_add_u32 s48, s48, 0x40080
	v_lshl_add_u64 v[154:155], v[226:227], 0, s[20:21]
	s_addc_u32 s49, s49, 0
	s_add_i32 s50, s77, s54
	global_load_lds_dwordx4 v[154:155], off
	v_lshl_add_u64 v[154:155], s[48:49], 0, v[132:133]
	s_mov_b32 m0, s50
	s_nop 0
	global_load_lds_dwordx4 v[154:155], off
	v_lshl_add_u64 v[154:155], s[48:49], 0, v[128:129]
	s_add_i32 m0, s50, 0x2000
	s_nop 0
	global_load_lds_dwordx4 v[154:155], off
	v_lshl_add_u64 v[154:155], v[228:229], 0, s[20:21]
	s_mov_b32 m0, s62
	s_nop 0
	global_load_lds_dwordx4 v[154:155], off
	v_lshl_add_u64 v[154:155], v[230:231], 0, s[20:21]
	s_mov_b32 m0, s63
	s_nop 0
	global_load_lds_dwordx4 v[154:155], off
	s_waitcnt vmcnt(8)
	s_waitcnt lgkmcnt(0)
	s_barrier
	s_setprio 1
	s_waitcnt lgkmcnt(0)
	v_mfma_f32_16x16x32_bf16 v[60:63], v[160:163], v[194:197], v[60:63]
	v_mfma_f32_16x16x32_bf16 v[60:63], v[164:167], v[198:201], v[60:63]
	v_mfma_f32_16x16x32_bf16 v[52:55], v[168:171], v[194:197], v[52:55]
	v_mfma_f32_16x16x32_bf16 v[52:55], v[172:175], v[198:201], v[52:55]
	v_mfma_f32_16x16x32_bf16 v[44:47], v[160:163], v[202:205], v[44:47]
	v_mfma_f32_16x16x32_bf16 v[44:47], v[164:167], v[206:209], v[44:47]
	v_mfma_f32_16x16x32_bf16 v[36:39], v[168:171], v[202:205], v[36:39]
	v_mfma_f32_16x16x32_bf16 v[36:39], v[172:175], v[206:209], v[36:39]
	v_mfma_f32_16x16x32_bf16 v[28:31], v[160:163], v[210:213], v[28:31]
	v_mfma_f32_16x16x32_bf16 v[28:31], v[164:167], v[214:217], v[28:31]
	v_mfma_f32_16x16x32_bf16 v[20:23], v[168:171], v[210:213], v[20:23]
	v_mfma_f32_16x16x32_bf16 v[20:23], v[172:175], v[214:217], v[20:23]
	v_mfma_f32_16x16x32_bf16 v[12:15], v[160:163], v[218:221], v[12:15]
	v_mfma_f32_16x16x32_bf16 v[12:15], v[164:167], v[222:225], v[12:15]
	v_mfma_f32_16x16x32_bf16 v[4:7], v[168:171], v[218:221], v[4:7]
	v_mfma_f32_16x16x32_bf16 v[4:7], v[172:175], v[222:225], v[4:7]
	s_setprio 0
	s_setprio 1
	v_mfma_f32_16x16x32_bf16 v[56:59], v[176:179], v[194:197], v[56:59]
	v_mfma_f32_16x16x32_bf16 v[56:59], v[180:183], v[198:201], v[56:59]
	v_mfma_f32_16x16x32_bf16 v[48:51], v[186:189], v[194:197], v[48:51]
	v_mfma_f32_16x16x32_bf16 v[48:51], v[190:193], v[198:201], v[48:51]
	v_mfma_f32_16x16x32_bf16 v[40:43], v[176:179], v[202:205], v[40:43]
	v_mfma_f32_16x16x32_bf16 v[40:43], v[180:183], v[206:209], v[40:43]
	v_mfma_f32_16x16x32_bf16 v[32:35], v[186:189], v[202:205], v[32:35]
	v_mfma_f32_16x16x32_bf16 v[32:35], v[190:193], v[206:209], v[32:35]
	v_mfma_f32_16x16x32_bf16 v[24:27], v[176:179], v[210:213], v[24:27]
	v_mfma_f32_16x16x32_bf16 v[24:27], v[180:183], v[214:217], v[24:27]
	v_mfma_f32_16x16x32_bf16 v[16:19], v[186:189], v[210:213], v[16:19]
	v_mfma_f32_16x16x32_bf16 v[16:19], v[190:193], v[214:217], v[16:19]
	v_mfma_f32_16x16x32_bf16 v[8:11], v[176:179], v[218:221], v[8:11]
	v_mfma_f32_16x16x32_bf16 v[8:11], v[180:183], v[222:225], v[8:11]
	v_mfma_f32_16x16x32_bf16 v[0:3], v[186:189], v[218:221], v[0:3]
	v_mfma_f32_16x16x32_bf16 v[0:3], v[190:193], v[222:225], v[0:3]
	s_setprio 0
	s_barrier
	s_add_i32 s75, s75, 2
	s_add_u32 s73, s73, 0x100
	s_addc_u32 s74, s74, 0
	s_add_u32 s46, s46, 0x100
	s_addc_u32 s47, s47, 0
	s_branch .LBB0_527
.Lfa_4:
	v_add_u32_e32 v153, s66, v147
	ds_read_b128 v[160:163], v153
	ds_read_b128 v[164:167], v153 offset:1024
	ds_read_b128 v[168:171], v153 offset:2048
	ds_read_b128 v[172:175], v153 offset:3072
	v_add_u32_e32 v153, s67, v147
	ds_read_b128 v[176:179], v153
	ds_read_b128 v[180:183], v153 offset:1024
	ds_read_b128 v[186:189], v153 offset:2048
	ds_read_b128 v[190:193], v153 offset:3072
	s_add_u32 s50, s46, 0xfffc0080
	s_addc_u32 s51, s47, -1
	s_and_b64 s[48:49], s[48:49], exec
	s_cselect_b32 s51, s29, s51
	s_cselect_b32 s50, s70, s50
	s_cselect_b32 s49, s71, s74
	s_cselect_b32 s48, s72, s73
	v_lshl_add_u64 v[154:155], s[46:47], 0, v[138:139]
	s_add_i32 m0, s57, 0xc000
	ds_read_b128 v[194:197], v150
	ds_read_b128 v[198:201], v150 offset:1024
	ds_read_b128 v[202:205], v150 offset:2048
	ds_read_b128 v[206:209], v150 offset:3072
	ds_read_b128 v[210:213], v150 offset:4096
	ds_read_b128 v[214:217], v150 offset:5120
	ds_read_b128 v[218:221], v150 offset:6144
	ds_read_b128 v[222:225], v150 offset:7168
	global_load_lds_dwordx4 v[154:155], off
	v_lshl_add_u64 v[154:155], s[46:47], 0, v[136:137]
	s_add_i32 m0, s57, 0xe000
	s_nop 0
	global_load_lds_dwordx4 v[154:155], off
	s_waitcnt vmcnt(8)
	s_waitcnt lgkmcnt(0)
	s_barrier
	s_setprio 1
	s_waitcnt lgkmcnt(0)
	v_mfma_f32_16x16x32_bf16 v[124:127], v[160:163], v[194:197], 0
	v_mfma_f32_16x16x32_bf16 v[116:119], v[168:171], v[194:197], 0
	v_mfma_f32_16x16x32_bf16 v[108:111], v[160:163], v[202:205], 0
	v_mfma_f32_16x16x32_bf16 v[100:103], v[168:171], v[202:205], 0
	v_mfma_f32_16x16x32_bf16 v[92:95], v[160:163], v[210:213], 0
	v_mfma_f32_16x16x32_bf16 v[84:87], v[168:171], v[210:213], 0
	v_mfma_f32_16x16x32_bf16 v[76:79], v[160:163], v[218:221], 0
	v_mfma_f32_16x16x32_bf16 v[68:71], v[168:171], v[218:221], 0
	v_mfma_f32_16x16x32_bf16 v[124:127], v[164:167], v[198:201], v[124:127]
	v_mfma_f32_16x16x32_bf16 v[116:119], v[172:175], v[198:201], v[116:119]
	v_mfma_f32_16x16x32_bf16 v[108:111], v[164:167], v[206:209], v[108:111]
	v_mfma_f32_16x16x32_bf16 v[100:103], v[172:175], v[206:209], v[100:103]
	v_mfma_f32_16x16x32_bf16 v[92:95], v[164:167], v[214:217], v[92:95]
	v_mfma_f32_16x16x32_bf16 v[84:87], v[172:175], v[214:217], v[84:87]
	v_mfma_f32_16x16x32_bf16 v[76:79], v[164:167], v[222:225], v[76:79]
	v_mfma_f32_16x16x32_bf16 v[68:71], v[172:175], v[222:225], v[68:71]
	s_setprio 0
	s_setprio 1
	v_mfma_f32_16x16x32_bf16 v[120:123], v[176:179], v[194:197], 0
	v_mfma_f32_16x16x32_bf16 v[112:115], v[186:189], v[194:197], 0
	v_mfma_f32_16x16x32_bf16 v[104:107], v[176:179], v[202:205], 0
	v_mfma_f32_16x16x32_bf16 v[96:99], v[186:189], v[202:205], 0
	v_mfma_f32_16x16x32_bf16 v[88:91], v[176:179], v[210:213], 0
	v_mfma_f32_16x16x32_bf16 v[80:83], v[186:189], v[210:213], 0
	v_mfma_f32_16x16x32_bf16 v[72:75], v[176:179], v[218:221], 0
	v_mfma_f32_16x16x32_bf16 v[64:67], v[186:189], v[218:221], 0
	v_mfma_f32_16x16x32_bf16 v[120:123], v[180:183], v[198:201], v[120:123]
	v_mfma_f32_16x16x32_bf16 v[112:115], v[190:193], v[198:201], v[112:115]
	v_mfma_f32_16x16x32_bf16 v[104:107], v[180:183], v[206:209], v[104:107]
	v_mfma_f32_16x16x32_bf16 v[96:99], v[190:193], v[206:209], v[96:99]
	v_mfma_f32_16x16x32_bf16 v[88:91], v[180:183], v[214:217], v[88:91]
	v_mfma_f32_16x16x32_bf16 v[80:83], v[190:193], v[214:217], v[80:83]
	v_mfma_f32_16x16x32_bf16 v[72:75], v[180:183], v[222:225], v[72:75]
	v_mfma_f32_16x16x32_bf16 v[64:67], v[190:193], v[222:225], v[64:67]
	s_setprio 0
	s_barrier
	s_add_i32 s76, s66, s54
	v_lshl_add_u64 v[154:155], s[48:49], 0, v[132:133]
	s_mov_b32 m0, s76
	ds_read_b128 v[194:197], v150 offset:16384
	ds_read_b128 v[198:201], v150 offset:17408
	ds_read_b128 v[202:205], v150 offset:18432
	ds_read_b128 v[206:209], v150 offset:19456
	ds_read_b128 v[210:213], v150 offset:20480
	ds_read_b128 v[214:217], v150 offset:21504
	ds_read_b128 v[218:221], v150 offset:22528
	ds_read_b128 v[222:225], v150 offset:23552
	global_load_lds_dwordx4 v[154:155], off
	s_add_i32 m0, s76, 0x2000
	s_add_u32 s76, s48, 0x40000
	v_lshl_add_u64 v[226:227], s[48:49], 0, v[128:129]
	s_addc_u32 s77, s49, 0
	s_add_i32 s78, s67, s54
	global_load_lds_dwordx4 v[226:227], off
	v_lshl_add_u64 v[228:229], s[76:77], 0, v[132:133]
	s_mov_b32 m0, s78
	v_lshl_add_u64 v[230:231], s[50:51], 0, v[130:131]
	global_load_lds_dwordx4 v[228:229], off
	v_lshl_add_u64 v[228:229], s[76:77], 0, v[128:129]
	s_add_i32 m0, s78, 0x2000
	s_nop 0
	global_load_lds_dwordx4 v[228:229], off
	v_lshl_add_u64 v[228:229], s[50:51], 0, v[134:135]
	s_mov_b32 m0, s57
	s_nop 0
	global_load_lds_dwordx4 v[228:229], off
	s_mov_b32 m0, s58
	s_nop 0
	global_load_lds_dwordx4 v[230:231], off
	s_waitcnt vmcnt(8)
	s_waitcnt lgkmcnt(0)
	s_barrier
	s_setprio 1
	s_waitcnt lgkmcnt(0)
	v_mfma_f32_16x16x32_bf16 v[60:63], v[160:163], v[194:197], 0
	v_mfma_f32_16x16x32_bf16 v[52:55], v[168:171], v[194:197], 0
	v_mfma_f32_16x16x32_bf16 v[44:47], v[160:163], v[202:205], 0
	v_mfma_f32_16x16x32_bf16 v[36:39], v[168:171], v[202:205], 0
	v_mfma_f32_16x16x32_bf16 v[28:31], v[160:163], v[210:213], 0
	v_mfma_f32_16x16x32_bf16 v[20:23], v[168:171], v[210:213], 0
	v_mfma_f32_16x16x32_bf16 v[12:15], v[160:163], v[218:221], 0
	v_mfma_f32_16x16x32_bf16 v[4:7], v[168:171], v[218:221], 0
	v_mfma_f32_16x16x32_bf16 v[60:63], v[164:167], v[198:201], v[60:63]
	v_mfma_f32_16x16x32_bf16 v[52:55], v[172:175], v[198:201], v[52:55]
	v_mfma_f32_16x16x32_bf16 v[44:47], v[164:167], v[206:209], v[44:47]
	v_mfma_f32_16x16x32_bf16 v[36:39], v[172:175], v[206:209], v[36:39]
	v_mfma_f32_16x16x32_bf16 v[28:31], v[164:167], v[214:217], v[28:31]
	v_mfma_f32_16x16x32_bf16 v[20:23], v[172:175], v[214:217], v[20:23]
	v_mfma_f32_16x16x32_bf16 v[12:15], v[164:167], v[222:225], v[12:15]
	v_mfma_f32_16x16x32_bf16 v[4:7], v[172:175], v[222:225], v[4:7]
	s_setprio 0
	s_setprio 1
	v_mfma_f32_16x16x32_bf16 v[56:59], v[176:179], v[194:197], 0
	v_mfma_f32_16x16x32_bf16 v[48:51], v[186:189], v[194:197], 0
	v_mfma_f32_16x16x32_bf16 v[40:43], v[176:179], v[202:205], 0
	v_mfma_f32_16x16x32_bf16 v[32:35], v[186:189], v[202:205], 0
	v_mfma_f32_16x16x32_bf16 v[24:27], v[176:179], v[210:213], 0
	v_mfma_f32_16x16x32_bf16 v[16:19], v[186:189], v[210:213], 0
	v_mfma_f32_16x16x32_bf16 v[8:11], v[176:179], v[218:221], 0
	v_mfma_f32_16x16x32_bf16 v[0:3], v[186:189], v[218:221], 0
	v_mfma_f32_16x16x32_bf16 v[56:59], v[180:183], v[198:201], v[56:59]
	v_mfma_f32_16x16x32_bf16 v[48:51], v[190:193], v[198:201], v[48:51]
	v_mfma_f32_16x16x32_bf16 v[40:43], v[180:183], v[206:209], v[40:43]
	v_mfma_f32_16x16x32_bf16 v[32:35], v[190:193], v[206:209], v[32:35]
	v_mfma_f32_16x16x32_bf16 v[24:27], v[180:183], v[214:217], v[24:27]
	v_mfma_f32_16x16x32_bf16 v[16:19], v[190:193], v[214:217], v[16:19]
	v_mfma_f32_16x16x32_bf16 v[8:11], v[180:183], v[222:225], v[8:11]
	v_mfma_f32_16x16x32_bf16 v[0:3], v[190:193], v[222:225], v[0:3]
	s_setprio 0
	s_barrier
	s_add_i32 s76, 0, 0x18000
	v_add_u32_e32 v153, s76, v147
	s_add_i32 s77, 0, 0x1c000
	ds_read_b128 v[160:163], v153
	ds_read_b128 v[164:167], v153 offset:1024
	ds_read_b128 v[168:171], v153 offset:2048
	ds_read_b128 v[172:175], v153 offset:3072
	v_add_u32_e32 v153, s77, v147
	ds_read_b128 v[176:179], v153
	ds_read_b128 v[180:183], v153 offset:1024
	ds_read_b128 v[186:189], v153 offset:2048
	ds_read_b128 v[190:193], v153 offset:3072
	s_add_u32 s50, s50, 0x40000
	s_addc_u32 s51, s51, 0
	s_mov_b32 m0, s59
	v_lshl_add_u64 v[232:233], s[50:51], 0, v[134:135]
	ds_read_b128 v[194:197], v150 offset:32768
	ds_read_b128 v[198:201], v150 offset:33792
	ds_read_b128 v[202:205], v150 offset:34816
	ds_read_b128 v[206:209], v150 offset:35840
	ds_read_b128 v[210:213], v150 offset:36864
	ds_read_b128 v[214:217], v150 offset:37888
	ds_read_b128 v[218:221], v150 offset:38912
	ds_read_b128 v[222:225], v150 offset:39936
	global_load_lds_dwordx4 v[232:233], off
	v_lshl_add_u64 v[232:233], s[50:51], 0, v[130:131]
	s_mov_b32 m0, s60
	s_nop 0
	global_load_lds_dwordx4 v[232:233], off
	s_waitcnt vmcnt(8)
	s_waitcnt lgkmcnt(0)
	s_barrier
	s_setprio 1
	s_waitcnt lgkmcnt(0)
	v_mfma_f32_16x16x32_bf16 v[124:127], v[160:163], v[194:197], v[124:127]
	v_mfma_f32_16x16x32_bf16 v[124:127], v[164:167], v[198:201], v[124:127]
	v_mfma_f32_16x16x32_bf16 v[116:119], v[168:171], v[194:197], v[116:119]
	v_mfma_f32_16x16x32_bf16 v[116:119], v[172:175], v[198:201], v[116:119]
	v_mfma_f32_16x16x32_bf16 v[108:111], v[160:163], v[202:205], v[108:111]
	v_mfma_f32_16x16x32_bf16 v[108:111], v[164:167], v[206:209], v[108:111]
	v_mfma_f32_16x16x32_bf16 v[100:103], v[168:171], v[202:205], v[100:103]
	v_mfma_f32_16x16x32_bf16 v[100:103], v[172:175], v[206:209], v[100:103]
	v_mfma_f32_16x16x32_bf16 v[92:95], v[160:163], v[210:213], v[92:95]
	v_mfma_f32_16x16x32_bf16 v[92:95], v[164:167], v[214:217], v[92:95]
	v_mfma_f32_16x16x32_bf16 v[84:87], v[168:171], v[210:213], v[84:87]
	v_mfma_f32_16x16x32_bf16 v[84:87], v[172:175], v[214:217], v[84:87]
	v_mfma_f32_16x16x32_bf16 v[76:79], v[160:163], v[218:221], v[76:79]
	v_mfma_f32_16x16x32_bf16 v[76:79], v[164:167], v[222:225], v[76:79]
	v_mfma_f32_16x16x32_bf16 v[68:71], v[168:171], v[218:221], v[68:71]
	v_mfma_f32_16x16x32_bf16 v[68:71], v[172:175], v[222:225], v[68:71]
	s_setprio 0
	s_setprio 1
	v_mfma_f32_16x16x32_bf16 v[120:123], v[176:179], v[194:197], v[120:123]
	v_mfma_f32_16x16x32_bf16 v[120:123], v[180:183], v[198:201], v[120:123]
	v_mfma_f32_16x16x32_bf16 v[112:115], v[186:189], v[194:197], v[112:115]
	v_mfma_f32_16x16x32_bf16 v[112:115], v[190:193], v[198:201], v[112:115]
	v_mfma_f32_16x16x32_bf16 v[104:107], v[176:179], v[202:205], v[104:107]
	v_mfma_f32_16x16x32_bf16 v[104:107], v[180:183], v[206:209], v[104:107]
	v_mfma_f32_16x16x32_bf16 v[96:99], v[186:189], v[202:205], v[96:99]
	v_mfma_f32_16x16x32_bf16 v[96:99], v[190:193], v[206:209], v[96:99]
	v_mfma_f32_16x16x32_bf16 v[88:91], v[176:179], v[210:213], v[88:91]
	v_mfma_f32_16x16x32_bf16 v[88:91], v[180:183], v[214:217], v[88:91]
	v_mfma_f32_16x16x32_bf16 v[80:83], v[186:189], v[210:213], v[80:83]
	v_mfma_f32_16x16x32_bf16 v[80:83], v[190:193], v[214:217], v[80:83]
	v_mfma_f32_16x16x32_bf16 v[72:75], v[176:179], v[218:221], v[72:75]
	v_mfma_f32_16x16x32_bf16 v[72:75], v[180:183], v[222:225], v[72:75]
	v_mfma_f32_16x16x32_bf16 v[64:67], v[186:189], v[218:221], v[64:67]
	v_mfma_f32_16x16x32_bf16 v[64:67], v[190:193], v[222:225], v[64:67]
	s_setprio 0
	s_barrier
	s_add_i32 s50, s76, s54
	v_lshl_add_u64 v[154:155], v[154:155], 0, s[20:21]
	s_mov_b32 m0, s50
	ds_read_b128 v[194:197], v150 offset:49152
	ds_read_b128 v[198:201], v150 offset:50176
	ds_read_b128 v[202:205], v150 offset:51200
	ds_read_b128 v[206:209], v150 offset:52224
	ds_read_b128 v[210:213], v150 offset:53248
	ds_read_b128 v[214:217], v150 offset:54272
	ds_read_b128 v[218:221], v150 offset:55296
	ds_read_b128 v[222:225], v150 offset:56320
	global_load_lds_dwordx4 v[154:155], off
	s_add_i32 m0, s50, 0x2000
	s_add_u32 s48, s48, 0x40080
	v_lshl_add_u64 v[154:155], v[226:227], 0, s[20:21]
	s_addc_u32 s49, s49, 0
	s_add_i32 s50, s77, s54
	global_load_lds_dwordx4 v[154:155], off
	v_lshl_add_u64 v[154:155], s[48:49], 0, v[132:133]
	s_mov_b32 m0, s50
	s_nop 0
	global_load_lds_dwordx4 v[154:155], off
	v_lshl_add_u64 v[154:155], s[48:49], 0, v[128:129]
	s_add_i32 m0, s50, 0x2000
	s_nop 0
	global_load_lds_dwordx4 v[154:155], off
	v_lshl_add_u64 v[154:155], v[228:229], 0, s[20:21]
	s_mov_b32 m0, s62
	s_nop 0
	global_load_lds_dwordx4 v[154:155], off
	v_lshl_add_u64 v[154:155], v[230:231], 0, s[20:21]
	s_mov_b32 m0, s63
	s_nop 0
	global_load_lds_dwordx4 v[154:155], off
	s_waitcnt vmcnt(8)
	s_waitcnt lgkmcnt(0)
	s_barrier
	s_setprio 1
	s_waitcnt lgkmcnt(0)
	v_mfma_f32_16x16x32_bf16 v[60:63], v[160:163], v[194:197], v[60:63]
	v_mfma_f32_16x16x32_bf16 v[60:63], v[164:167], v[198:201], v[60:63]
	v_mfma_f32_16x16x32_bf16 v[52:55], v[168:171], v[194:197], v[52:55]
	v_mfma_f32_16x16x32_bf16 v[52:55], v[172:175], v[198:201], v[52:55]
	v_mfma_f32_16x16x32_bf16 v[44:47], v[160:163], v[202:205], v[44:47]
	v_mfma_f32_16x16x32_bf16 v[44:47], v[164:167], v[206:209], v[44:47]
	v_mfma_f32_16x16x32_bf16 v[36:39], v[168:171], v[202:205], v[36:39]
	v_mfma_f32_16x16x32_bf16 v[36:39], v[172:175], v[206:209], v[36:39]
	v_mfma_f32_16x16x32_bf16 v[28:31], v[160:163], v[210:213], v[28:31]
	v_mfma_f32_16x16x32_bf16 v[28:31], v[164:167], v[214:217], v[28:31]
	v_mfma_f32_16x16x32_bf16 v[20:23], v[168:171], v[210:213], v[20:23]
	v_mfma_f32_16x16x32_bf16 v[20:23], v[172:175], v[214:217], v[20:23]
	v_mfma_f32_16x16x32_bf16 v[12:15], v[160:163], v[218:221], v[12:15]
	v_mfma_f32_16x16x32_bf16 v[12:15], v[164:167], v[222:225], v[12:15]
	v_mfma_f32_16x16x32_bf16 v[4:7], v[168:171], v[218:221], v[4:7]
	v_mfma_f32_16x16x32_bf16 v[4:7], v[172:175], v[222:225], v[4:7]
	s_setprio 0
	s_setprio 1
	v_mfma_f32_16x16x32_bf16 v[56:59], v[176:179], v[194:197], v[56:59]
	v_mfma_f32_16x16x32_bf16 v[56:59], v[180:183], v[198:201], v[56:59]
	v_mfma_f32_16x16x32_bf16 v[48:51], v[186:189], v[194:197], v[48:51]
	v_mfma_f32_16x16x32_bf16 v[48:51], v[190:193], v[198:201], v[48:51]
	v_mfma_f32_16x16x32_bf16 v[40:43], v[176:179], v[202:205], v[40:43]
	v_mfma_f32_16x16x32_bf16 v[40:43], v[180:183], v[206:209], v[40:43]
	v_mfma_f32_16x16x32_bf16 v[32:35], v[186:189], v[202:205], v[32:35]
	v_mfma_f32_16x16x32_bf16 v[32:35], v[190:193], v[206:209], v[32:35]
	v_mfma_f32_16x16x32_bf16 v[24:27], v[176:179], v[210:213], v[24:27]
	v_mfma_f32_16x16x32_bf16 v[24:27], v[180:183], v[214:217], v[24:27]
	v_mfma_f32_16x16x32_bf16 v[16:19], v[186:189], v[210:213], v[16:19]
	v_mfma_f32_16x16x32_bf16 v[16:19], v[190:193], v[214:217], v[16:19]
	v_mfma_f32_16x16x32_bf16 v[8:11], v[176:179], v[218:221], v[8:11]
	v_mfma_f32_16x16x32_bf16 v[8:11], v[180:183], v[222:225], v[8:11]
	v_mfma_f32_16x16x32_bf16 v[0:3], v[186:189], v[218:221], v[0:3]
	v_mfma_f32_16x16x32_bf16 v[0:3], v[190:193], v[222:225], v[0:3]
	s_setprio 0
	s_barrier
	s_add_i32 s75, s75, 2
	s_add_u32 s73, s73, 0x100
	s_addc_u32 s74, s74, 0
	s_add_u32 s46, s46, 0x100
	s_addc_u32 s47, s47, 0
	s_branch .LBB0_527
.LBB0_526:
	v_add_u32_e32 v153, s66, v147
	ds_read_b128 v[160:163], v153
	ds_read_b128 v[164:167], v153 offset:1024
	ds_read_b128 v[168:171], v153 offset:2048
	ds_read_b128 v[172:175], v153 offset:3072
	v_add_u32_e32 v153, s67, v147
	ds_read_b128 v[176:179], v153
	ds_read_b128 v[180:183], v153 offset:1024
	ds_read_b128 v[186:189], v153 offset:2048
	ds_read_b128 v[190:193], v153 offset:3072
	s_add_u32 s50, s46, 0xfffc0080
	s_addc_u32 s51, s47, -1
	s_and_b64 s[48:49], s[48:49], exec
	s_cselect_b32 s51, s29, s51
	s_cselect_b32 s50, s70, s50
	s_cselect_b32 s49, s71, s74
	s_cselect_b32 s48, s72, s73
	v_lshl_add_u64 v[154:155], s[46:47], 0, v[138:139]
	s_add_i32 m0, s57, 0xc000
	ds_read_b128 v[194:197], v150
	ds_read_b128 v[198:201], v150 offset:1024
	ds_read_b128 v[202:205], v150 offset:2048
	ds_read_b128 v[206:209], v150 offset:3072
	ds_read_b128 v[210:213], v150 offset:4096
	ds_read_b128 v[214:217], v150 offset:5120
	ds_read_b128 v[218:221], v150 offset:6144
	ds_read_b128 v[222:225], v150 offset:7168
	global_load_lds_dwordx4 v[154:155], off
	v_lshl_add_u64 v[154:155], s[46:47], 0, v[136:137]
	s_add_i32 m0, s57, 0xe000
	s_nop 0
	global_load_lds_dwordx4 v[154:155], off
	s_waitcnt vmcnt(8)
	s_waitcnt lgkmcnt(0)
	s_barrier
	s_setprio 1
	s_waitcnt lgkmcnt(0)
	v_mfma_f32_16x16x32_bf16 v[124:127], v[160:163], v[194:197], v[124:127]
	v_mfma_f32_16x16x32_bf16 v[124:127], v[164:167], v[198:201], v[124:127]
	v_mfma_f32_16x16x32_bf16 v[116:119], v[168:171], v[194:197], v[116:119]
	v_mfma_f32_16x16x32_bf16 v[116:119], v[172:175], v[198:201], v[116:119]
	v_mfma_f32_16x16x32_bf16 v[108:111], v[160:163], v[202:205], v[108:111]
	v_mfma_f32_16x16x32_bf16 v[108:111], v[164:167], v[206:209], v[108:111]
	v_mfma_f32_16x16x32_bf16 v[100:103], v[168:171], v[202:205], v[100:103]
	v_mfma_f32_16x16x32_bf16 v[100:103], v[172:175], v[206:209], v[100:103]
	v_mfma_f32_16x16x32_bf16 v[92:95], v[160:163], v[210:213], v[92:95]
	v_mfma_f32_16x16x32_bf16 v[92:95], v[164:167], v[214:217], v[92:95]
	v_mfma_f32_16x16x32_bf16 v[84:87], v[168:171], v[210:213], v[84:87]
	v_mfma_f32_16x16x32_bf16 v[84:87], v[172:175], v[214:217], v[84:87]
	v_mfma_f32_16x16x32_bf16 v[76:79], v[160:163], v[218:221], v[76:79]
	v_mfma_f32_16x16x32_bf16 v[76:79], v[164:167], v[222:225], v[76:79]
	v_mfma_f32_16x16x32_bf16 v[68:71], v[168:171], v[218:221], v[68:71]
	v_mfma_f32_16x16x32_bf16 v[68:71], v[172:175], v[222:225], v[68:71]
	s_setprio 0
	s_setprio 1
	v_mfma_f32_16x16x32_bf16 v[120:123], v[176:179], v[194:197], v[120:123]
	v_mfma_f32_16x16x32_bf16 v[120:123], v[180:183], v[198:201], v[120:123]
	v_mfma_f32_16x16x32_bf16 v[112:115], v[186:189], v[194:197], v[112:115]
	v_mfma_f32_16x16x32_bf16 v[112:115], v[190:193], v[198:201], v[112:115]
	v_mfma_f32_16x16x32_bf16 v[104:107], v[176:179], v[202:205], v[104:107]
	v_mfma_f32_16x16x32_bf16 v[104:107], v[180:183], v[206:209], v[104:107]
	v_mfma_f32_16x16x32_bf16 v[96:99], v[186:189], v[202:205], v[96:99]
	v_mfma_f32_16x16x32_bf16 v[96:99], v[190:193], v[206:209], v[96:99]
	v_mfma_f32_16x16x32_bf16 v[88:91], v[176:179], v[210:213], v[88:91]
	v_mfma_f32_16x16x32_bf16 v[88:91], v[180:183], v[214:217], v[88:91]
	v_mfma_f32_16x16x32_bf16 v[80:83], v[186:189], v[210:213], v[80:83]
	v_mfma_f32_16x16x32_bf16 v[80:83], v[190:193], v[214:217], v[80:83]
	v_mfma_f32_16x16x32_bf16 v[72:75], v[176:179], v[218:221], v[72:75]
	v_mfma_f32_16x16x32_bf16 v[72:75], v[180:183], v[222:225], v[72:75]
	v_mfma_f32_16x16x32_bf16 v[64:67], v[186:189], v[218:221], v[64:67]
	v_mfma_f32_16x16x32_bf16 v[64:67], v[190:193], v[222:225], v[64:67]
	s_setprio 0
	s_barrier
	s_add_i32 s76, s66, s54
	v_lshl_add_u64 v[154:155], s[48:49], 0, v[132:133]
	s_mov_b32 m0, s76
	ds_read_b128 v[194:197], v150 offset:16384
	ds_read_b128 v[198:201], v150 offset:17408
	ds_read_b128 v[202:205], v150 offset:18432
	ds_read_b128 v[206:209], v150 offset:19456
	ds_read_b128 v[210:213], v150 offset:20480
	ds_read_b128 v[214:217], v150 offset:21504
	ds_read_b128 v[218:221], v150 offset:22528
	ds_read_b128 v[222:225], v150 offset:23552
	global_load_lds_dwordx4 v[154:155], off
	s_add_i32 m0, s76, 0x2000
	s_add_u32 s76, s48, 0x40000
	v_lshl_add_u64 v[226:227], s[48:49], 0, v[128:129]
	s_addc_u32 s77, s49, 0
	s_add_i32 s78, s67, s54
	global_load_lds_dwordx4 v[226:227], off
	v_lshl_add_u64 v[228:229], s[76:77], 0, v[132:133]
	s_mov_b32 m0, s78
	v_lshl_add_u64 v[230:231], s[50:51], 0, v[130:131]
	global_load_lds_dwordx4 v[228:229], off
	v_lshl_add_u64 v[228:229], s[76:77], 0, v[128:129]
	s_add_i32 m0, s78, 0x2000
	s_nop 0
	global_load_lds_dwordx4 v[228:229], off
	v_lshl_add_u64 v[228:229], s[50:51], 0, v[134:135]
	s_mov_b32 m0, s57
	s_nop 0
	global_load_lds_dwordx4 v[228:229], off
	s_mov_b32 m0, s58
	s_nop 0
	global_load_lds_dwordx4 v[230:231], off
	s_waitcnt vmcnt(8)
	s_waitcnt lgkmcnt(0)
	s_barrier
	s_setprio 1
	s_waitcnt lgkmcnt(0)
	v_mfma_f32_16x16x32_bf16 v[60:63], v[160:163], v[194:197], v[60:63]
	v_mfma_f32_16x16x32_bf16 v[60:63], v[164:167], v[198:201], v[60:63]
	v_mfma_f32_16x16x32_bf16 v[52:55], v[168:171], v[194:197], v[52:55]
	v_mfma_f32_16x16x32_bf16 v[52:55], v[172:175], v[198:201], v[52:55]
	v_mfma_f32_16x16x32_bf16 v[44:47], v[160:163], v[202:205], v[44:47]
	v_mfma_f32_16x16x32_bf16 v[44:47], v[164:167], v[206:209], v[44:47]
	v_mfma_f32_16x16x32_bf16 v[36:39], v[168:171], v[202:205], v[36:39]
	v_mfma_f32_16x16x32_bf16 v[36:39], v[172:175], v[206:209], v[36:39]
	v_mfma_f32_16x16x32_bf16 v[28:31], v[160:163], v[210:213], v[28:31]
	v_mfma_f32_16x16x32_bf16 v[28:31], v[164:167], v[214:217], v[28:31]
	v_mfma_f32_16x16x32_bf16 v[20:23], v[168:171], v[210:213], v[20:23]
	v_mfma_f32_16x16x32_bf16 v[20:23], v[172:175], v[214:217], v[20:23]
	v_mfma_f32_16x16x32_bf16 v[12:15], v[160:163], v[218:221], v[12:15]
	v_mfma_f32_16x16x32_bf16 v[12:15], v[164:167], v[222:225], v[12:15]
	v_mfma_f32_16x16x32_bf16 v[4:7], v[168:171], v[218:221], v[4:7]
	v_mfma_f32_16x16x32_bf16 v[4:7], v[172:175], v[222:225], v[4:7]
	s_setprio 0
	s_setprio 1
	v_mfma_f32_16x16x32_bf16 v[56:59], v[176:179], v[194:197], v[56:59]
	v_mfma_f32_16x16x32_bf16 v[56:59], v[180:183], v[198:201], v[56:59]
	v_mfma_f32_16x16x32_bf16 v[48:51], v[186:189], v[194:197], v[48:51]
	v_mfma_f32_16x16x32_bf16 v[48:51], v[190:193], v[198:201], v[48:51]
	v_mfma_f32_16x16x32_bf16 v[40:43], v[176:179], v[202:205], v[40:43]
	v_mfma_f32_16x16x32_bf16 v[40:43], v[180:183], v[206:209], v[40:43]
	v_mfma_f32_16x16x32_bf16 v[32:35], v[186:189], v[202:205], v[32:35]
	v_mfma_f32_16x16x32_bf16 v[32:35], v[190:193], v[206:209], v[32:35]
	v_mfma_f32_16x16x32_bf16 v[24:27], v[176:179], v[210:213], v[24:27]
	v_mfma_f32_16x16x32_bf16 v[24:27], v[180:183], v[214:217], v[24:27]
	v_mfma_f32_16x16x32_bf16 v[16:19], v[186:189], v[210:213], v[16:19]
	v_mfma_f32_16x16x32_bf16 v[16:19], v[190:193], v[214:217], v[16:19]
	v_mfma_f32_16x16x32_bf16 v[8:11], v[176:179], v[218:221], v[8:11]
	v_mfma_f32_16x16x32_bf16 v[8:11], v[180:183], v[222:225], v[8:11]
	v_mfma_f32_16x16x32_bf16 v[0:3], v[186:189], v[218:221], v[0:3]
	v_mfma_f32_16x16x32_bf16 v[0:3], v[190:193], v[222:225], v[0:3]
	s_setprio 0
	s_barrier
	s_add_i32 s76, 0, 0x18000
	v_add_u32_e32 v153, s76, v147
	s_add_i32 s77, 0, 0x1c000
	ds_read_b128 v[160:163], v153
	ds_read_b128 v[164:167], v153 offset:1024
	ds_read_b128 v[168:171], v153 offset:2048
	ds_read_b128 v[172:175], v153 offset:3072
	v_add_u32_e32 v153, s77, v147
	ds_read_b128 v[176:179], v153
	ds_read_b128 v[180:183], v153 offset:1024
	ds_read_b128 v[186:189], v153 offset:2048
	ds_read_b128 v[190:193], v153 offset:3072
	s_add_u32 s50, s50, 0x40000
	s_addc_u32 s51, s51, 0
	s_mov_b32 m0, s59
	v_lshl_add_u64 v[232:233], s[50:51], 0, v[134:135]
	ds_read_b128 v[194:197], v150 offset:32768
	ds_read_b128 v[198:201], v150 offset:33792
	ds_read_b128 v[202:205], v150 offset:34816
	ds_read_b128 v[206:209], v150 offset:35840
	ds_read_b128 v[210:213], v150 offset:36864
	ds_read_b128 v[214:217], v150 offset:37888
	ds_read_b128 v[218:221], v150 offset:38912
	ds_read_b128 v[222:225], v150 offset:39936
	global_load_lds_dwordx4 v[232:233], off
	v_lshl_add_u64 v[232:233], s[50:51], 0, v[130:131]
	s_mov_b32 m0, s60
	s_nop 0
	global_load_lds_dwordx4 v[232:233], off
	s_waitcnt vmcnt(8)
	s_waitcnt lgkmcnt(0)
	s_barrier
	s_setprio 1
	s_waitcnt lgkmcnt(0)
	v_mfma_f32_16x16x32_bf16 v[124:127], v[160:163], v[194:197], v[124:127]
	v_mfma_f32_16x16x32_bf16 v[124:127], v[164:167], v[198:201], v[124:127]
	v_mfma_f32_16x16x32_bf16 v[116:119], v[168:171], v[194:197], v[116:119]
	v_mfma_f32_16x16x32_bf16 v[116:119], v[172:175], v[198:201], v[116:119]
	v_mfma_f32_16x16x32_bf16 v[108:111], v[160:163], v[202:205], v[108:111]
	v_mfma_f32_16x16x32_bf16 v[108:111], v[164:167], v[206:209], v[108:111]
	v_mfma_f32_16x16x32_bf16 v[100:103], v[168:171], v[202:205], v[100:103]
	v_mfma_f32_16x16x32_bf16 v[100:103], v[172:175], v[206:209], v[100:103]
	v_mfma_f32_16x16x32_bf16 v[92:95], v[160:163], v[210:213], v[92:95]
	v_mfma_f32_16x16x32_bf16 v[92:95], v[164:167], v[214:217], v[92:95]
	v_mfma_f32_16x16x32_bf16 v[84:87], v[168:171], v[210:213], v[84:87]
	v_mfma_f32_16x16x32_bf16 v[84:87], v[172:175], v[214:217], v[84:87]
	v_mfma_f32_16x16x32_bf16 v[76:79], v[160:163], v[218:221], v[76:79]
	v_mfma_f32_16x16x32_bf16 v[76:79], v[164:167], v[222:225], v[76:79]
	v_mfma_f32_16x16x32_bf16 v[68:71], v[168:171], v[218:221], v[68:71]
	v_mfma_f32_16x16x32_bf16 v[68:71], v[172:175], v[222:225], v[68:71]
	s_setprio 0
	s_setprio 1
	v_mfma_f32_16x16x32_bf16 v[120:123], v[176:179], v[194:197], v[120:123]
	v_mfma_f32_16x16x32_bf16 v[120:123], v[180:183], v[198:201], v[120:123]
	v_mfma_f32_16x16x32_bf16 v[112:115], v[186:189], v[194:197], v[112:115]
	v_mfma_f32_16x16x32_bf16 v[112:115], v[190:193], v[198:201], v[112:115]
	v_mfma_f32_16x16x32_bf16 v[104:107], v[176:179], v[202:205], v[104:107]
	v_mfma_f32_16x16x32_bf16 v[104:107], v[180:183], v[206:209], v[104:107]
	v_mfma_f32_16x16x32_bf16 v[96:99], v[186:189], v[202:205], v[96:99]
	v_mfma_f32_16x16x32_bf16 v[96:99], v[190:193], v[206:209], v[96:99]
	v_mfma_f32_16x16x32_bf16 v[88:91], v[176:179], v[210:213], v[88:91]
	v_mfma_f32_16x16x32_bf16 v[88:91], v[180:183], v[214:217], v[88:91]
	v_mfma_f32_16x16x32_bf16 v[80:83], v[186:189], v[210:213], v[80:83]
	v_mfma_f32_16x16x32_bf16 v[80:83], v[190:193], v[214:217], v[80:83]
	v_mfma_f32_16x16x32_bf16 v[72:75], v[176:179], v[218:221], v[72:75]
	v_mfma_f32_16x16x32_bf16 v[72:75], v[180:183], v[222:225], v[72:75]
	v_mfma_f32_16x16x32_bf16 v[64:67], v[186:189], v[218:221], v[64:67]
	v_mfma_f32_16x16x32_bf16 v[64:67], v[190:193], v[222:225], v[64:67]
	s_setprio 0
	s_barrier
	s_add_i32 s50, s76, s54
	v_lshl_add_u64 v[154:155], v[154:155], 0, s[20:21]
	s_mov_b32 m0, s50
	ds_read_b128 v[194:197], v150 offset:49152
	ds_read_b128 v[198:201], v150 offset:50176
	ds_read_b128 v[202:205], v150 offset:51200
	ds_read_b128 v[206:209], v150 offset:52224
	ds_read_b128 v[210:213], v150 offset:53248
	ds_read_b128 v[214:217], v150 offset:54272
	ds_read_b128 v[218:221], v150 offset:55296
	ds_read_b128 v[222:225], v150 offset:56320
	global_load_lds_dwordx4 v[154:155], off
	s_add_i32 m0, s50, 0x2000
	s_add_u32 s48, s48, 0x40080
	v_lshl_add_u64 v[154:155], v[226:227], 0, s[20:21]
	s_addc_u32 s49, s49, 0
	s_add_i32 s50, s77, s54
	global_load_lds_dwordx4 v[154:155], off
	v_lshl_add_u64 v[154:155], s[48:49], 0, v[132:133]
	s_mov_b32 m0, s50
	s_nop 0
	global_load_lds_dwordx4 v[154:155], off
	v_lshl_add_u64 v[154:155], s[48:49], 0, v[128:129]
	s_add_i32 m0, s50, 0x2000
	s_nop 0
	global_load_lds_dwordx4 v[154:155], off
	v_lshl_add_u64 v[154:155], v[228:229], 0, s[20:21]
	s_mov_b32 m0, s62
	s_nop 0
	global_load_lds_dwordx4 v[154:155], off
	v_lshl_add_u64 v[154:155], v[230:231], 0, s[20:21]
	s_mov_b32 m0, s63
	s_nop 0
	global_load_lds_dwordx4 v[154:155], off
	s_waitcnt vmcnt(8)
	s_waitcnt lgkmcnt(0)
	s_barrier
	s_setprio 1
	s_waitcnt lgkmcnt(0)
	v_mfma_f32_16x16x32_bf16 v[60:63], v[160:163], v[194:197], v[60:63]
	v_mfma_f32_16x16x32_bf16 v[60:63], v[164:167], v[198:201], v[60:63]
	v_mfma_f32_16x16x32_bf16 v[52:55], v[168:171], v[194:197], v[52:55]
	v_mfma_f32_16x16x32_bf16 v[52:55], v[172:175], v[198:201], v[52:55]
	v_mfma_f32_16x16x32_bf16 v[44:47], v[160:163], v[202:205], v[44:47]
	v_mfma_f32_16x16x32_bf16 v[44:47], v[164:167], v[206:209], v[44:47]
	v_mfma_f32_16x16x32_bf16 v[36:39], v[168:171], v[202:205], v[36:39]
	v_mfma_f32_16x16x32_bf16 v[36:39], v[172:175], v[206:209], v[36:39]
	v_mfma_f32_16x16x32_bf16 v[28:31], v[160:163], v[210:213], v[28:31]
	v_mfma_f32_16x16x32_bf16 v[28:31], v[164:167], v[214:217], v[28:31]
	v_mfma_f32_16x16x32_bf16 v[20:23], v[168:171], v[210:213], v[20:23]
	v_mfma_f32_16x16x32_bf16 v[20:23], v[172:175], v[214:217], v[20:23]
	v_mfma_f32_16x16x32_bf16 v[12:15], v[160:163], v[218:221], v[12:15]
	v_mfma_f32_16x16x32_bf16 v[12:15], v[164:167], v[222:225], v[12:15]
	v_mfma_f32_16x16x32_bf16 v[4:7], v[168:171], v[218:221], v[4:7]
	v_mfma_f32_16x16x32_bf16 v[4:7], v[172:175], v[222:225], v[4:7]
	s_setprio 0
	s_setprio 1
	v_mfma_f32_16x16x32_bf16 v[56:59], v[176:179], v[194:197], v[56:59]
	v_mfma_f32_16x16x32_bf16 v[56:59], v[180:183], v[198:201], v[56:59]
	v_mfma_f32_16x16x32_bf16 v[48:51], v[186:189], v[194:197], v[48:51]
	v_mfma_f32_16x16x32_bf16 v[48:51], v[190:193], v[198:201], v[48:51]
	v_mfma_f32_16x16x32_bf16 v[40:43], v[176:179], v[202:205], v[40:43]
	v_mfma_f32_16x16x32_bf16 v[40:43], v[180:183], v[206:209], v[40:43]
	v_mfma_f32_16x16x32_bf16 v[32:35], v[186:189], v[202:205], v[32:35]
	v_mfma_f32_16x16x32_bf16 v[32:35], v[190:193], v[206:209], v[32:35]
	v_mfma_f32_16x16x32_bf16 v[24:27], v[176:179], v[210:213], v[24:27]
	v_mfma_f32_16x16x32_bf16 v[24:27], v[180:183], v[214:217], v[24:27]
	v_mfma_f32_16x16x32_bf16 v[16:19], v[186:189], v[210:213], v[16:19]
	v_mfma_f32_16x16x32_bf16 v[16:19], v[190:193], v[214:217], v[16:19]
	v_mfma_f32_16x16x32_bf16 v[8:11], v[176:179], v[218:221], v[8:11]
	v_mfma_f32_16x16x32_bf16 v[8:11], v[180:183], v[222:225], v[8:11]
	v_mfma_f32_16x16x32_bf16 v[0:3], v[186:189], v[218:221], v[0:3]
	v_mfma_f32_16x16x32_bf16 v[0:3], v[190:193], v[222:225], v[0:3]
	s_setprio 0
	s_barrier
	s_add_i32 s75, s75, 2
	s_add_u32 s73, s73, 0x100
	s_addc_u32 s74, s74, 0
	s_add_u32 s46, s46, 0x100
	s_addc_u32 s47, s47, 0
	s_cmp_gt_u32 s75, 13
	s_cbranch_scc1 .LBB0_529

.Llast_4:
	v_add_u32_e32 v153, s66, v147
	ds_read_b128 v[160:163], v153
	ds_read_b128 v[164:167], v153 offset:1024
	ds_read_b128 v[168:171], v153 offset:2048
	ds_read_b128 v[172:175], v153 offset:3072
	v_add_u32_e32 v153, s67, v147
	ds_read_b128 v[176:179], v153
	ds_read_b128 v[180:183], v153 offset:1024
	ds_read_b128 v[186:189], v153 offset:2048
	ds_read_b128 v[190:193], v153 offset:3072
	s_add_u32 s50, s46, 0xfffc0080
	s_addc_u32 s51, s47, -1
	s_and_b64 s[48:49], s[48:49], exec
	s_cselect_b32 s51, s29, s51
	s_cselect_b32 s50, s70, s50
	s_cselect_b32 s49, s71, s74
	s_cselect_b32 s48, s72, s73
	v_lshl_add_u64 v[154:155], s[46:47], 0, v[138:139]
	s_add_i32 m0, s57, 0xc000
	ds_read_b128 v[194:197], v150
	ds_read_b128 v[198:201], v150 offset:1024
	ds_read_b128 v[202:205], v150 offset:2048
	ds_read_b128 v[206:209], v150 offset:3072
	ds_read_b128 v[210:213], v150 offset:4096
	ds_read_b128 v[214:217], v150 offset:5120
	ds_read_b128 v[218:221], v150 offset:6144
	ds_read_b128 v[222:225], v150 offset:7168
	global_load_lds_dwordx4 v[154:155], off
	v_lshl_add_u64 v[154:155], s[46:47], 0, v[136:137]
	s_add_i32 m0, s57, 0xe000
	s_nop 0
	global_load_lds_dwordx4 v[154:155], off
	s_waitcnt vmcnt(8)
	s_waitcnt lgkmcnt(0)
	s_barrier
	s_setprio 1
	s_waitcnt lgkmcnt(0)
	v_mfma_f32_16x16x32_bf16 v[124:127], v[160:163], v[194:197], v[124:127]
	v_mfma_f32_16x16x32_bf16 v[124:127], v[164:167], v[198:201], v[124:127]
	v_mfma_f32_16x16x32_bf16 v[116:119], v[168:171], v[194:197], v[116:119]
	v_mfma_f32_16x16x32_bf16 v[116:119], v[172:175], v[198:201], v[116:119]
	v_mfma_f32_16x16x32_bf16 v[108:111], v[160:163], v[202:205], v[108:111]
	v_mfma_f32_16x16x32_bf16 v[108:111], v[164:167], v[206:209], v[108:111]
	v_mfma_f32_16x16x32_bf16 v[100:103], v[168:171], v[202:205], v[100:103]
	v_mfma_f32_16x16x32_bf16 v[100:103], v[172:175], v[206:209], v[100:103]
	v_mfma_f32_16x16x32_bf16 v[92:95], v[160:163], v[210:213], v[92:95]
	v_mfma_f32_16x16x32_bf16 v[92:95], v[164:167], v[214:217], v[92:95]
	v_mfma_f32_16x16x32_bf16 v[84:87], v[168:171], v[210:213], v[84:87]
	v_mfma_f32_16x16x32_bf16 v[84:87], v[172:175], v[214:217], v[84:87]
	v_mfma_f32_16x16x32_bf16 v[76:79], v[160:163], v[218:221], v[76:79]
	v_mfma_f32_16x16x32_bf16 v[76:79], v[164:167], v[222:225], v[76:79]
	v_mfma_f32_16x16x32_bf16 v[68:71], v[168:171], v[218:221], v[68:71]
	v_mfma_f32_16x16x32_bf16 v[68:71], v[172:175], v[222:225], v[68:71]
	s_setprio 0
	s_setprio 1
	v_mfma_f32_16x16x32_bf16 v[120:123], v[176:179], v[194:197], v[120:123]
	v_mfma_f32_16x16x32_bf16 v[120:123], v[180:183], v[198:201], v[120:123]
	v_mfma_f32_16x16x32_bf16 v[112:115], v[186:189], v[194:197], v[112:115]
	v_mfma_f32_16x16x32_bf16 v[112:115], v[190:193], v[198:201], v[112:115]
	v_mfma_f32_16x16x32_bf16 v[104:107], v[176:179], v[202:205], v[104:107]
	v_mfma_f32_16x16x32_bf16 v[104:107], v[180:183], v[206:209], v[104:107]
	v_mfma_f32_16x16x32_bf16 v[96:99], v[186:189], v[202:205], v[96:99]
	v_mfma_f32_16x16x32_bf16 v[96:99], v[190:193], v[206:209], v[96:99]
	v_mfma_f32_16x16x32_bf16 v[88:91], v[176:179], v[210:213], v[88:91]
	v_mfma_f32_16x16x32_bf16 v[88:91], v[180:183], v[214:217], v[88:91]
	v_mfma_f32_16x16x32_bf16 v[80:83], v[186:189], v[210:213], v[80:83]
	v_mfma_f32_16x16x32_bf16 v[80:83], v[190:193], v[214:217], v[80:83]
	v_mfma_f32_16x16x32_bf16 v[72:75], v[176:179], v[218:221], v[72:75]
	v_mfma_f32_16x16x32_bf16 v[72:75], v[180:183], v[222:225], v[72:75]
	v_mfma_f32_16x16x32_bf16 v[64:67], v[186:189], v[218:221], v[64:67]
	v_mfma_f32_16x16x32_bf16 v[64:67], v[190:193], v[222:225], v[64:67]
	s_setprio 0
	s_barrier
	s_add_i32 s76, s66, s54
	v_lshl_add_u64 v[154:155], s[48:49], 0, v[132:133]
	s_mov_b32 m0, s76
	ds_read_b128 v[194:197], v150 offset:16384
	ds_read_b128 v[198:201], v150 offset:17408
	ds_read_b128 v[202:205], v150 offset:18432
	ds_read_b128 v[206:209], v150 offset:19456
	ds_read_b128 v[210:213], v150 offset:20480
	ds_read_b128 v[214:217], v150 offset:21504
	ds_read_b128 v[218:221], v150 offset:22528
	ds_read_b128 v[222:225], v150 offset:23552
	global_load_lds_dwordx4 v[154:155], off
	s_add_i32 m0, s76, 0x2000
	s_add_u32 s76, s48, 0x40000
	v_lshl_add_u64 v[226:227], s[48:49], 0, v[128:129]
	s_addc_u32 s77, s49, 0
	s_add_i32 s78, s67, s54
	global_load_lds_dwordx4 v[226:227], off
	v_lshl_add_u64 v[228:229], s[76:77], 0, v[132:133]
	s_mov_b32 m0, s78
	v_lshl_add_u64 v[230:231], s[50:51], 0, v[130:131]
	global_load_lds_dwordx4 v[228:229], off
	v_lshl_add_u64 v[228:229], s[76:77], 0, v[128:129]
	s_add_i32 m0, s78, 0x2000
	s_nop 0
	global_load_lds_dwordx4 v[228:229], off
	v_lshl_add_u64 v[228:229], s[50:51], 0, v[134:135]
	s_mov_b32 m0, s57
	s_nop 0
	global_load_lds_dwordx4 v[228:229], off
	s_mov_b32 m0, s58
	s_nop 0
	global_load_lds_dwordx4 v[230:231], off
	s_waitcnt vmcnt(8)
	s_waitcnt lgkmcnt(0)
	s_barrier
	s_setprio 1
	s_waitcnt lgkmcnt(0)
	v_mfma_f32_16x16x32_bf16 v[60:63], v[160:163], v[194:197], v[60:63]
	v_mfma_f32_16x16x32_bf16 v[60:63], v[164:167], v[198:201], v[60:63]
	v_mfma_f32_16x16x32_bf16 v[52:55], v[168:171], v[194:197], v[52:55]
	v_mfma_f32_16x16x32_bf16 v[52:55], v[172:175], v[198:201], v[52:55]
	v_mfma_f32_16x16x32_bf16 v[44:47], v[160:163], v[202:205], v[44:47]
	v_mfma_f32_16x16x32_bf16 v[44:47], v[164:167], v[206:209], v[44:47]
	v_mfma_f32_16x16x32_bf16 v[36:39], v[168:171], v[202:205], v[36:39]
	v_mfma_f32_16x16x32_bf16 v[36:39], v[172:175], v[206:209], v[36:39]
	v_mfma_f32_16x16x32_bf16 v[28:31], v[160:163], v[210:213], v[28:31]
	v_mfma_f32_16x16x32_bf16 v[28:31], v[164:167], v[214:217], v[28:31]
	v_mfma_f32_16x16x32_bf16 v[20:23], v[168:171], v[210:213], v[20:23]
	v_mfma_f32_16x16x32_bf16 v[20:23], v[172:175], v[214:217], v[20:23]
	v_mfma_f32_16x16x32_bf16 v[12:15], v[160:163], v[218:221], v[12:15]
	v_mfma_f32_16x16x32_bf16 v[12:15], v[164:167], v[222:225], v[12:15]
	v_mfma_f32_16x16x32_bf16 v[4:7], v[168:171], v[218:221], v[4:7]
	v_mfma_f32_16x16x32_bf16 v[4:7], v[172:175], v[222:225], v[4:7]
	s_setprio 0
	s_setprio 1
	v_mfma_f32_16x16x32_bf16 v[56:59], v[176:179], v[194:197], v[56:59]
	v_mfma_f32_16x16x32_bf16 v[56:59], v[180:183], v[198:201], v[56:59]
	v_mfma_f32_16x16x32_bf16 v[48:51], v[186:189], v[194:197], v[48:51]
	v_mfma_f32_16x16x32_bf16 v[48:51], v[190:193], v[198:201], v[48:51]
	v_mfma_f32_16x16x32_bf16 v[40:43], v[176:179], v[202:205], v[40:43]
	v_mfma_f32_16x16x32_bf16 v[40:43], v[180:183], v[206:209], v[40:43]
	v_mfma_f32_16x16x32_bf16 v[32:35], v[186:189], v[202:205], v[32:35]
	v_mfma_f32_16x16x32_bf16 v[32:35], v[190:193], v[206:209], v[32:35]
	v_mfma_f32_16x16x32_bf16 v[24:27], v[176:179], v[210:213], v[24:27]
	v_mfma_f32_16x16x32_bf16 v[24:27], v[180:183], v[214:217], v[24:27]
	v_mfma_f32_16x16x32_bf16 v[16:19], v[186:189], v[210:213], v[16:19]
	v_mfma_f32_16x16x32_bf16 v[16:19], v[190:193], v[214:217], v[16:19]
	v_mfma_f32_16x16x32_bf16 v[8:11], v[176:179], v[218:221], v[8:11]
	v_mfma_f32_16x16x32_bf16 v[8:11], v[180:183], v[222:225], v[8:11]
	v_mfma_f32_16x16x32_bf16 v[0:3], v[186:189], v[218:221], v[0:3]
	v_mfma_f32_16x16x32_bf16 v[0:3], v[190:193], v[222:225], v[0:3]
	s_setprio 0
	s_barrier
	s_add_i32 s76, 0, 0x18000
	v_add_u32_e32 v153, s76, v147
	s_add_i32 s77, 0, 0x1c000
	ds_read_b128 v[160:163], v153
	ds_read_b128 v[164:167], v153 offset:1024
	ds_read_b128 v[168:171], v153 offset:2048
	ds_read_b128 v[172:175], v153 offset:3072
	v_add_u32_e32 v153, s77, v147
	ds_read_b128 v[176:179], v153
	ds_read_b128 v[180:183], v153 offset:1024
	ds_read_b128 v[186:189], v153 offset:2048
	ds_read_b128 v[190:193], v153 offset:3072
	s_add_u32 s50, s50, 0x40000
	s_addc_u32 s51, s51, 0
	s_mov_b32 m0, s59
	v_lshl_add_u64 v[232:233], s[50:51], 0, v[134:135]
	ds_read_b128 v[194:197], v150 offset:32768
	ds_read_b128 v[198:201], v150 offset:33792
	ds_read_b128 v[202:205], v150 offset:34816
	ds_read_b128 v[206:209], v150 offset:35840
	ds_read_b128 v[210:213], v150 offset:36864
	ds_read_b128 v[214:217], v150 offset:37888
	ds_read_b128 v[218:221], v150 offset:38912
	ds_read_b128 v[222:225], v150 offset:39936
	global_load_lds_dwordx4 v[232:233], off
	v_lshl_add_u64 v[232:233], s[50:51], 0, v[130:131]
	s_mov_b32 m0, s60
	s_nop 0
	global_load_lds_dwordx4 v[232:233], off
	s_waitcnt vmcnt(8)
	s_waitcnt lgkmcnt(0)
	s_barrier
	s_setprio 1
	s_waitcnt lgkmcnt(0)
	v_mfma_f32_16x16x32_bf16 v[124:127], v[160:163], v[194:197], v[124:127]
	v_mfma_f32_16x16x32_bf16 v[124:127], v[164:167], v[198:201], v[124:127]
	v_mfma_f32_16x16x32_bf16 v[116:119], v[168:171], v[194:197], v[116:119]
	v_mfma_f32_16x16x32_bf16 v[116:119], v[172:175], v[198:201], v[116:119]
	v_mfma_f32_16x16x32_bf16 v[108:111], v[160:163], v[202:205], v[108:111]
	v_mfma_f32_16x16x32_bf16 v[108:111], v[164:167], v[206:209], v[108:111]
	v_mfma_f32_16x16x32_bf16 v[100:103], v[168:171], v[202:205], v[100:103]
	v_mfma_f32_16x16x32_bf16 v[100:103], v[172:175], v[206:209], v[100:103]
	v_mfma_f32_16x16x32_bf16 v[92:95], v[160:163], v[210:213], v[92:95]
	v_mfma_f32_16x16x32_bf16 v[92:95], v[164:167], v[214:217], v[92:95]
	v_mfma_f32_16x16x32_bf16 v[84:87], v[168:171], v[210:213], v[84:87]
	v_mfma_f32_16x16x32_bf16 v[84:87], v[172:175], v[214:217], v[84:87]
	v_mfma_f32_16x16x32_bf16 v[76:79], v[160:163], v[218:221], v[76:79]
	v_mfma_f32_16x16x32_bf16 v[76:79], v[164:167], v[222:225], v[76:79]
	v_mfma_f32_16x16x32_bf16 v[68:71], v[168:171], v[218:221], v[68:71]
	v_mfma_f32_16x16x32_bf16 v[68:71], v[172:175], v[222:225], v[68:71]
	s_setprio 0
	s_setprio 1
	v_mfma_f32_16x16x32_bf16 v[120:123], v[176:179], v[194:197], v[120:123]
	v_mfma_f32_16x16x32_bf16 v[120:123], v[180:183], v[198:201], v[120:123]
	v_mfma_f32_16x16x32_bf16 v[112:115], v[186:189], v[194:197], v[112:115]
	v_mfma_f32_16x16x32_bf16 v[112:115], v[190:193], v[198:201], v[112:115]
	v_mfma_f32_16x16x32_bf16 v[104:107], v[176:179], v[202:205], v[104:107]
	v_mfma_f32_16x16x32_bf16 v[104:107], v[180:183], v[206:209], v[104:107]
	v_mfma_f32_16x16x32_bf16 v[96:99], v[186:189], v[202:205], v[96:99]
	v_mfma_f32_16x16x32_bf16 v[96:99], v[190:193], v[206:209], v[96:99]
	v_mfma_f32_16x16x32_bf16 v[88:91], v[176:179], v[210:213], v[88:91]
	v_mfma_f32_16x16x32_bf16 v[88:91], v[180:183], v[214:217], v[88:91]
	v_mfma_f32_16x16x32_bf16 v[80:83], v[186:189], v[210:213], v[80:83]
	v_mfma_f32_16x16x32_bf16 v[80:83], v[190:193], v[214:217], v[80:83]
	v_mfma_f32_16x16x32_bf16 v[72:75], v[176:179], v[218:221], v[72:75]
	v_mfma_f32_16x16x32_bf16 v[72:75], v[180:183], v[222:225], v[72:75]
	v_mfma_f32_16x16x32_bf16 v[64:67], v[186:189], v[218:221], v[64:67]
	v_mfma_f32_16x16x32_bf16 v[64:67], v[190:193], v[222:225], v[64:67]
	s_setprio 0
	s_barrier
	v_add_u32_e32 v234, 0x21000, v151
	ds_read_b128 v[236:239], v234
	ds_read_b128 v[240:243], v234 offset:256
	ds_read_b128 v[244:247], v234 offset:512
	ds_read_b128 v[248:251], v234 offset:768
	v_add_u32_e32 v235, s27, v146
	v_mul_u32_u24_e32 v235, 0x1600, v235
	v_lshl_or_b32 v234, s69, 7, v149
	v_lshl_add_u32 v235, v234, 1, v235
	s_add_i32 s50, s76, s54
	v_lshl_add_u64 v[154:155], v[154:155], 0, s[20:21]
	s_mov_b32 m0, s50
	ds_read_b128 v[194:197], v150 offset:49152
	ds_read_b128 v[198:201], v150 offset:50176
	ds_read_b128 v[202:205], v150 offset:51200
	ds_read_b128 v[206:209], v150 offset:52224
	ds_read_b128 v[210:213], v150 offset:53248
	ds_read_b128 v[214:217], v150 offset:54272
	ds_read_b128 v[218:221], v150 offset:55296
	ds_read_b128 v[222:225], v150 offset:56320
	global_load_lds_dwordx4 v[154:155], off
	s_add_i32 m0, s50, 0x2000
	s_add_u32 s48, s48, 0x40080
	v_lshl_add_u64 v[154:155], v[226:227], 0, s[20:21]
	s_addc_u32 s49, s49, 0
	s_add_i32 s50, s77, s54
	global_load_lds_dwordx4 v[154:155], off
	v_lshl_add_u64 v[154:155], s[48:49], 0, v[132:133]
	s_mov_b32 m0, s50
	s_nop 0
	global_load_lds_dwordx4 v[154:155], off
	v_lshl_add_u64 v[154:155], s[48:49], 0, v[128:129]
	s_add_i32 m0, s50, 0x2000
	s_nop 0
	global_load_lds_dwordx4 v[154:155], off
	v_lshl_add_u64 v[154:155], v[228:229], 0, s[20:21]
	s_mov_b32 m0, s62
	s_nop 0
	global_load_lds_dwordx4 v[154:155], off
	v_lshl_add_u64 v[154:155], v[230:231], 0, s[20:21]
	s_mov_b32 m0, s63
	s_nop 0
	global_load_lds_dwordx4 v[154:155], off
	s_waitcnt lgkmcnt(8)
	v_add_f32_e32 v236, v236, v237
	v_add_f32_e32 v238, v238, v239
	v_add_f32_e32 v240, v240, v241
	v_add_f32_e32 v242, v242, v243
	v_add_f32_e32 v244, v244, v245
	v_add_f32_e32 v246, v246, v247
	v_add_f32_e32 v248, v248, v249
	v_add_f32_e32 v250, v250, v251
	v_add_f32_e32 v236, v236, v238
	v_add_f32_e32 v240, v240, v242
	v_add_f32_e32 v244, v244, v246
	v_add_f32_e32 v248, v248, v250
	v_fmamk_f32 v236, v236, 0x3a800000, v152
	v_fmamk_f32 v240, v240, 0x3a800000, v152
	v_fmamk_f32 v244, v244, 0x3a800000, v152
	v_fmamk_f32 v248, v248, 0x3a800000, v152
	v_rsq_f32_e32 v236, v236
	v_rsq_f32_e32 v240, v240
	v_rsq_f32_e32 v244, v244
	v_rsq_f32_e32 v248, v248
	v_mul_f32_e32 v252, 0xbfb8aa3b, v236
	v_mul_f32_e32 v254, v236, v236
	v_pk_mul_f32 v[120:121], v[124:125], v[120:121]
	v_pk_mul_f32 v[122:123], v[126:127], v[122:123]
	v_pk_mul_f32 v[112:113], v[116:117], v[112:113]
	v_pk_mul_f32 v[114:115], v[118:119], v[114:115]
	v_pk_mul_f32 v[124:125], v[124:125], v[252:253] op_sel_hi:[1,0]
	v_pk_mul_f32 v[126:127], v[126:127], v[252:253] op_sel_hi:[1,0]
	v_pk_mul_f32 v[116:117], v[116:117], v[252:253] op_sel_hi:[1,0]
	v_pk_mul_f32 v[118:119], v[118:119], v[252:253] op_sel_hi:[1,0]
	v_exp_f32_e32 v124, v124
	v_exp_f32_e32 v125, v125
	v_exp_f32_e32 v126, v126
	v_exp_f32_e32 v127, v127
	v_exp_f32_e32 v116, v116
	v_exp_f32_e32 v117, v117
	v_exp_f32_e32 v118, v118
	v_exp_f32_e32 v119, v119
	v_pk_add_f32 v[124:125], v[124:125], 1.0 op_sel_hi:[1,0]
	v_pk_add_f32 v[126:127], v[126:127], 1.0 op_sel_hi:[1,0]
	v_pk_add_f32 v[116:117], v[116:117], 1.0 op_sel_hi:[1,0]
	v_pk_add_f32 v[118:119], v[118:119], 1.0 op_sel_hi:[1,0]
	v_rcp_f32_e32 v124, v124
	v_rcp_f32_e32 v125, v125
	v_rcp_f32_e32 v126, v126
	v_rcp_f32_e32 v127, v127
	v_rcp_f32_e32 v116, v116
	v_rcp_f32_e32 v117, v117
	v_rcp_f32_e32 v118, v118
	v_rcp_f32_e32 v119, v119
	v_pk_mul_f32 v[120:121], v[120:121], v[254:255] op_sel_hi:[1,0]
	v_pk_mul_f32 v[122:123], v[122:123], v[254:255] op_sel_hi:[1,0]
	v_pk_mul_f32 v[112:113], v[112:113], v[254:255] op_sel_hi:[1,0]
	v_pk_mul_f32 v[114:115], v[114:115], v[254:255] op_sel_hi:[1,0]
	v_pk_mul_f32 v[120:121], v[120:121], v[124:125]
	v_pk_mul_f32 v[122:123], v[122:123], v[126:127]
	v_pk_mul_f32 v[112:113], v[112:113], v[116:117]
	v_pk_mul_f32 v[114:115], v[114:115], v[118:119]
	v_cvt_pk_bf16_f32 v120, v120, v121
	v_cvt_pk_bf16_f32 v121, v122, v123
	v_cvt_pk_bf16_f32 v122, v112, v113
	v_cvt_pk_bf16_f32 v123, v114, v115
	global_store_dwordx4 v235, v[120:123], s[14:15]
	v_add_u32_e32 v234, 0x16000, v235
	v_mul_f32_e32 v252, 0xbfb8aa3b, v240
	v_mul_f32_e32 v254, v240, v240
	v_pk_mul_f32 v[104:105], v[108:109], v[104:105]
	v_pk_mul_f32 v[106:107], v[110:111], v[106:107]
	v_pk_mul_f32 v[96:97], v[100:101], v[96:97]
	v_pk_mul_f32 v[98:99], v[102:103], v[98:99]
	v_pk_mul_f32 v[108:109], v[108:109], v[252:253] op_sel_hi:[1,0]
	v_pk_mul_f32 v[110:111], v[110:111], v[252:253] op_sel_hi:[1,0]
	v_pk_mul_f32 v[100:101], v[100:101], v[252:253] op_sel_hi:[1,0]
	v_pk_mul_f32 v[102:103], v[102:103], v[252:253] op_sel_hi:[1,0]
	v_exp_f32_e32 v108, v108
	v_exp_f32_e32 v109, v109
	v_exp_f32_e32 v110, v110
	v_exp_f32_e32 v111, v111
	v_exp_f32_e32 v100, v100
	v_exp_f32_e32 v101, v101
	v_exp_f32_e32 v102, v102
	v_exp_f32_e32 v103, v103
	v_pk_add_f32 v[108:109], v[108:109], 1.0 op_sel_hi:[1,0]
	v_pk_add_f32 v[110:111], v[110:111], 1.0 op_sel_hi:[1,0]
	v_pk_add_f32 v[100:101], v[100:101], 1.0 op_sel_hi:[1,0]
	v_pk_add_f32 v[102:103], v[102:103], 1.0 op_sel_hi:[1,0]
	v_rcp_f32_e32 v108, v108
	v_rcp_f32_e32 v109, v109
	v_rcp_f32_e32 v110, v110
	v_rcp_f32_e32 v111, v111
	v_rcp_f32_e32 v100, v100
	v_rcp_f32_e32 v101, v101
	v_rcp_f32_e32 v102, v102
	v_rcp_f32_e32 v103, v103
	v_pk_mul_f32 v[104:105], v[104:105], v[254:255] op_sel_hi:[1,0]
	v_pk_mul_f32 v[106:107], v[106:107], v[254:255] op_sel_hi:[1,0]
	v_pk_mul_f32 v[96:97], v[96:97], v[254:255] op_sel_hi:[1,0]
	v_pk_mul_f32 v[98:99], v[98:99], v[254:255] op_sel_hi:[1,0]
	v_pk_mul_f32 v[104:105], v[104:105], v[108:109]
	v_pk_mul_f32 v[106:107], v[106:107], v[110:111]
	v_pk_mul_f32 v[96:97], v[96:97], v[100:101]
	v_pk_mul_f32 v[98:99], v[98:99], v[102:103]
	v_cvt_pk_bf16_f32 v104, v104, v105
	v_cvt_pk_bf16_f32 v105, v106, v107
	v_cvt_pk_bf16_f32 v106, v96, v97
	v_cvt_pk_bf16_f32 v107, v98, v99
	global_store_dwordx4 v234, v[104:107], s[14:15]
	v_add_u32_e32 v235, 0x16000, v234
	v_mul_f32_e32 v252, 0xbfb8aa3b, v244
	v_mul_f32_e32 v254, v244, v244
	v_pk_mul_f32 v[88:89], v[92:93], v[88:89]
	v_pk_mul_f32 v[90:91], v[94:95], v[90:91]
	v_pk_mul_f32 v[80:81], v[84:85], v[80:81]
	v_pk_mul_f32 v[82:83], v[86:87], v[82:83]
	v_pk_mul_f32 v[92:93], v[92:93], v[252:253] op_sel_hi:[1,0]
	v_pk_mul_f32 v[94:95], v[94:95], v[252:253] op_sel_hi:[1,0]
	v_pk_mul_f32 v[84:85], v[84:85], v[252:253] op_sel_hi:[1,0]
	v_pk_mul_f32 v[86:87], v[86:87], v[252:253] op_sel_hi:[1,0]
	v_exp_f32_e32 v92, v92
	v_exp_f32_e32 v93, v93
	v_exp_f32_e32 v94, v94
	v_exp_f32_e32 v95, v95
	v_exp_f32_e32 v84, v84
	v_exp_f32_e32 v85, v85
	v_exp_f32_e32 v86, v86
	v_exp_f32_e32 v87, v87
	v_pk_add_f32 v[92:93], v[92:93], 1.0 op_sel_hi:[1,0]
	v_pk_add_f32 v[94:95], v[94:95], 1.0 op_sel_hi:[1,0]
	v_pk_add_f32 v[84:85], v[84:85], 1.0 op_sel_hi:[1,0]
	v_pk_add_f32 v[86:87], v[86:87], 1.0 op_sel_hi:[1,0]
	v_rcp_f32_e32 v92, v92
	v_rcp_f32_e32 v93, v93
	v_rcp_f32_e32 v94, v94
	v_rcp_f32_e32 v95, v95
	v_rcp_f32_e32 v84, v84
	v_rcp_f32_e32 v85, v85
	v_rcp_f32_e32 v86, v86
	v_rcp_f32_e32 v87, v87
	v_pk_mul_f32 v[88:89], v[88:89], v[254:255] op_sel_hi:[1,0]
	v_pk_mul_f32 v[90:91], v[90:91], v[254:255] op_sel_hi:[1,0]
	v_pk_mul_f32 v[80:81], v[80:81], v[254:255] op_sel_hi:[1,0]
	v_pk_mul_f32 v[82:83], v[82:83], v[254:255] op_sel_hi:[1,0]
	v_pk_mul_f32 v[88:89], v[88:89], v[92:93]
	v_pk_mul_f32 v[90:91], v[90:91], v[94:95]
	v_pk_mul_f32 v[80:81], v[80:81], v[84:85]
	v_pk_mul_f32 v[82:83], v[82:83], v[86:87]
	v_cvt_pk_bf16_f32 v88, v88, v89
	v_cvt_pk_bf16_f32 v89, v90, v91
	v_cvt_pk_bf16_f32 v90, v80, v81
	v_cvt_pk_bf16_f32 v91, v82, v83
	global_store_dwordx4 v235, v[88:91], s[14:15]
	v_add_u32_e32 v234, 0x16000, v235
	v_mul_f32_e32 v252, 0xbfb8aa3b, v248
	v_mul_f32_e32 v254, v248, v248
	v_pk_mul_f32 v[72:73], v[76:77], v[72:73]
	v_pk_mul_f32 v[74:75], v[78:79], v[74:75]
	v_pk_mul_f32 v[64:65], v[68:69], v[64:65]
	v_pk_mul_f32 v[66:67], v[70:71], v[66:67]
	v_pk_mul_f32 v[76:77], v[76:77], v[252:253] op_sel_hi:[1,0]
	v_pk_mul_f32 v[78:79], v[78:79], v[252:253] op_sel_hi:[1,0]
	v_pk_mul_f32 v[68:69], v[68:69], v[252:253] op_sel_hi:[1,0]
	v_pk_mul_f32 v[70:71], v[70:71], v[252:253] op_sel_hi:[1,0]
	v_exp_f32_e32 v76, v76
	v_exp_f32_e32 v77, v77
	v_exp_f32_e32 v78, v78
	v_exp_f32_e32 v79, v79
	v_exp_f32_e32 v68, v68
	v_exp_f32_e32 v69, v69
	v_exp_f32_e32 v70, v70
	v_exp_f32_e32 v71, v71
	v_pk_add_f32 v[76:77], v[76:77], 1.0 op_sel_hi:[1,0]
	v_pk_add_f32 v[78:79], v[78:79], 1.0 op_sel_hi:[1,0]
	v_pk_add_f32 v[68:69], v[68:69], 1.0 op_sel_hi:[1,0]
	v_pk_add_f32 v[70:71], v[70:71], 1.0 op_sel_hi:[1,0]
	v_rcp_f32_e32 v76, v76
	v_rcp_f32_e32 v77, v77
	v_rcp_f32_e32 v78, v78
	v_rcp_f32_e32 v79, v79
	v_rcp_f32_e32 v68, v68
	v_rcp_f32_e32 v69, v69
	v_rcp_f32_e32 v70, v70
	v_rcp_f32_e32 v71, v71
	v_pk_mul_f32 v[72:73], v[72:73], v[254:255] op_sel_hi:[1,0]
	v_pk_mul_f32 v[74:75], v[74:75], v[254:255] op_sel_hi:[1,0]
	v_pk_mul_f32 v[64:65], v[64:65], v[254:255] op_sel_hi:[1,0]
	v_pk_mul_f32 v[66:67], v[66:67], v[254:255] op_sel_hi:[1,0]
	v_pk_mul_f32 v[72:73], v[72:73], v[76:77]
	v_pk_mul_f32 v[74:75], v[74:75], v[78:79]
	v_pk_mul_f32 v[64:65], v[64:65], v[68:69]
	v_pk_mul_f32 v[66:67], v[66:67], v[70:71]
	v_cvt_pk_bf16_f32 v72, v72, v73
	v_cvt_pk_bf16_f32 v73, v74, v75
	v_cvt_pk_bf16_f32 v74, v64, v65
	v_cvt_pk_bf16_f32 v75, v66, v67
	global_store_dwordx4 v234, v[72:75], s[14:15]
	s_waitcnt vmcnt(12)
	s_waitcnt lgkmcnt(0)
	s_barrier
	s_setprio 1
	s_waitcnt lgkmcnt(0)
	v_mfma_f32_16x16x32_bf16 v[60:63], v[160:163], v[194:197], v[60:63]
	v_mfma_f32_16x16x32_bf16 v[60:63], v[164:167], v[198:201], v[60:63]
	v_mfma_f32_16x16x32_bf16 v[52:55], v[168:171], v[194:197], v[52:55]
	v_mfma_f32_16x16x32_bf16 v[52:55], v[172:175], v[198:201], v[52:55]
	v_mfma_f32_16x16x32_bf16 v[44:47], v[160:163], v[202:205], v[44:47]
	v_mfma_f32_16x16x32_bf16 v[44:47], v[164:167], v[206:209], v[44:47]
	v_mfma_f32_16x16x32_bf16 v[36:39], v[168:171], v[202:205], v[36:39]
	v_mfma_f32_16x16x32_bf16 v[36:39], v[172:175], v[206:209], v[36:39]
	v_mfma_f32_16x16x32_bf16 v[28:31], v[160:163], v[210:213], v[28:31]
	v_mfma_f32_16x16x32_bf16 v[28:31], v[164:167], v[214:217], v[28:31]
	v_mfma_f32_16x16x32_bf16 v[20:23], v[168:171], v[210:213], v[20:23]
	v_mfma_f32_16x16x32_bf16 v[20:23], v[172:175], v[214:217], v[20:23]
	v_mfma_f32_16x16x32_bf16 v[12:15], v[160:163], v[218:221], v[12:15]
	v_mfma_f32_16x16x32_bf16 v[12:15], v[164:167], v[222:225], v[12:15]
	v_mfma_f32_16x16x32_bf16 v[4:7], v[168:171], v[218:221], v[4:7]
	v_mfma_f32_16x16x32_bf16 v[4:7], v[172:175], v[222:225], v[4:7]
	s_setprio 0
	s_setprio 1
	v_mfma_f32_16x16x32_bf16 v[56:59], v[176:179], v[194:197], v[56:59]
	v_mfma_f32_16x16x32_bf16 v[56:59], v[180:183], v[198:201], v[56:59]
	v_mfma_f32_16x16x32_bf16 v[48:51], v[186:189], v[194:197], v[48:51]
	v_mfma_f32_16x16x32_bf16 v[48:51], v[190:193], v[198:201], v[48:51]
	v_mfma_f32_16x16x32_bf16 v[40:43], v[176:179], v[202:205], v[40:43]
	v_mfma_f32_16x16x32_bf16 v[40:43], v[180:183], v[206:209], v[40:43]
	v_mfma_f32_16x16x32_bf16 v[32:35], v[186:189], v[202:205], v[32:35]
	v_mfma_f32_16x16x32_bf16 v[32:35], v[190:193], v[206:209], v[32:35]
	v_mfma_f32_16x16x32_bf16 v[24:27], v[176:179], v[210:213], v[24:27]
	v_mfma_f32_16x16x32_bf16 v[24:27], v[180:183], v[214:217], v[24:27]
	v_mfma_f32_16x16x32_bf16 v[16:19], v[186:189], v[210:213], v[16:19]
	v_mfma_f32_16x16x32_bf16 v[16:19], v[190:193], v[214:217], v[16:19]
	v_mfma_f32_16x16x32_bf16 v[8:11], v[176:179], v[218:221], v[8:11]
	v_mfma_f32_16x16x32_bf16 v[8:11], v[180:183], v[222:225], v[8:11]
	v_mfma_f32_16x16x32_bf16 v[0:3], v[186:189], v[218:221], v[0:3]
	v_mfma_f32_16x16x32_bf16 v[0:3], v[190:193], v[222:225], v[0:3]
	s_setprio 0
	s_barrier
	s_add_i32 s75, s75, 2
	s_add_u32 s73, s73, 0x100
	s_addc_u32 s74, s74, 0
	s_add_u32 s46, s46, 0x100
	s_addc_u32 s47, s47, 0

.LBB0_609:
	s_add_u32 s79, s56, 0x100
	s_addc_u32 s80, s57, 0
	s_mov_b32 s81, -2
	s_waitcnt lgkmcnt(0)
	s_cmp_eq_u32 s70, 1
	s_cbranch_scc1 .Lfa_5
	ds_read_b128 v[128:131], v189
	ds_read_b128 v[132:135], v189 offset:1024
	ds_read_b128 v[136:139], v189 offset:2048
	ds_read_b128 v[140:143], v189 offset:3072
	ds_read_b128 v[144:147], v190
	ds_read_b128 v[148:151], v190 offset:1024
	ds_read_b128 v[172:175], v190 offset:2048
	ds_read_b128 v[176:179], v190 offset:3072
	s_add_u32 s56, s54, 0x100
	s_addc_u32 s57, s55, 0
	s_cmp_eq_u32 s81, 40
	s_cselect_b32 s61, s17, s57
	s_cselect_b32 s60, s16, s56
	s_cselect_b32 s59, s53, s80
	s_cselect_b32 s58, s52, s79
	v_lshl_add_u64 v[222:223], s[54:55], 0, v[166:167]
	s_add_i32 m0, s66, 0xc000
	ds_read_b128 v[180:183], v191
	ds_read_b128 v[194:197], v191 offset:1024
	ds_read_b128 v[198:201], v191 offset:2048
	ds_read_b128 v[202:205], v191 offset:3072
	ds_read_b128 v[206:209], v191 offset:4096
	ds_read_b128 v[210:213], v191 offset:5120
	ds_read_b128 v[214:217], v191 offset:6144
	ds_read_b128 v[218:221], v191 offset:7168
	global_load_lds_dwordx4 v[222:223], off
	v_lshl_add_u64 v[222:223], s[54:55], 0, v[164:165]
	s_add_i32 m0, s66, 0xe000
	s_nop 0
	global_load_lds_dwordx4 v[222:223], off
	s_waitcnt vmcnt(24)
	s_waitcnt lgkmcnt(0)
	s_barrier
	s_setprio 1
	s_waitcnt lgkmcnt(0)
	v_mfma_f32_16x16x32_bf16 v[124:127], v[128:131], v[180:183], 0
	v_mfma_f32_16x16x32_bf16 v[120:123], v[136:139], v[180:183], 0
	v_mfma_f32_16x16x32_bf16 v[108:111], v[128:131], v[198:201], 0
	v_mfma_f32_16x16x32_bf16 v[104:107], v[136:139], v[198:201], 0
	v_mfma_f32_16x16x32_bf16 v[92:95], v[128:131], v[206:209], 0
	v_mfma_f32_16x16x32_bf16 v[88:91], v[136:139], v[206:209], 0
	v_mfma_f32_16x16x32_bf16 v[76:79], v[128:131], v[214:217], 0
	v_mfma_f32_16x16x32_bf16 v[72:75], v[136:139], v[214:217], 0
	v_mfma_f32_16x16x32_bf16 v[124:127], v[132:135], v[194:197], v[124:127]
	v_mfma_f32_16x16x32_bf16 v[120:123], v[140:143], v[194:197], v[120:123]
	v_mfma_f32_16x16x32_bf16 v[108:111], v[132:135], v[202:205], v[108:111]
	v_mfma_f32_16x16x32_bf16 v[104:107], v[140:143], v[202:205], v[104:107]
	v_mfma_f32_16x16x32_bf16 v[92:95], v[132:135], v[210:213], v[92:95]
	v_mfma_f32_16x16x32_bf16 v[88:91], v[140:143], v[210:213], v[88:91]
	v_mfma_f32_16x16x32_bf16 v[76:79], v[132:135], v[218:221], v[76:79]
	v_mfma_f32_16x16x32_bf16 v[72:75], v[140:143], v[218:221], v[72:75]
	s_setprio 0
	s_setprio 1
	v_mfma_f32_16x16x32_bf16 v[116:119], v[144:147], v[180:183], 0
	v_mfma_f32_16x16x32_bf16 v[112:115], v[172:175], v[180:183], 0
	v_mfma_f32_16x16x32_bf16 v[100:103], v[144:147], v[198:201], 0
	v_mfma_f32_16x16x32_bf16 v[96:99], v[172:175], v[198:201], 0
	v_mfma_f32_16x16x32_bf16 v[84:87], v[144:147], v[206:209], 0
	v_mfma_f32_16x16x32_bf16 v[80:83], v[172:175], v[206:209], 0
	v_mfma_f32_16x16x32_bf16 v[68:71], v[144:147], v[214:217], 0
	v_mfma_f32_16x16x32_bf16 v[64:67], v[172:175], v[214:217], 0
	v_mfma_f32_16x16x32_bf16 v[116:119], v[148:151], v[194:197], v[116:119]
	v_mfma_f32_16x16x32_bf16 v[112:115], v[176:179], v[194:197], v[112:115]
	v_mfma_f32_16x16x32_bf16 v[100:103], v[148:151], v[202:205], v[100:103]
	v_mfma_f32_16x16x32_bf16 v[96:99], v[176:179], v[202:205], v[96:99]
	v_mfma_f32_16x16x32_bf16 v[84:87], v[148:151], v[210:213], v[84:87]
	v_mfma_f32_16x16x32_bf16 v[80:83], v[176:179], v[210:213], v[80:83]
	v_mfma_f32_16x16x32_bf16 v[68:71], v[148:151], v[218:221], v[68:71]
	v_mfma_f32_16x16x32_bf16 v[64:67], v[176:179], v[218:221], v[64:67]
	s_setprio 0
	s_barrier
	s_add_i32 s54, s75, s65
	v_lshl_add_u64 v[222:223], s[58:59], 0, v[154:155]
	s_mov_b32 m0, s54
	ds_read_b128 v[180:183], v191 offset:16384
	ds_read_b128 v[194:197], v191 offset:17408
	ds_read_b128 v[198:201], v191 offset:18432
	ds_read_b128 v[202:205], v191 offset:19456
	ds_read_b128 v[206:209], v191 offset:20480
	ds_read_b128 v[210:213], v191 offset:21504
	ds_read_b128 v[214:217], v191 offset:22528
	ds_read_b128 v[218:221], v191 offset:23552
	global_load_lds_dwordx4 v[222:223], off
	s_add_i32 m0, s54, 0x2000
	s_add_u32 s54, s58, 0xb0000
	v_lshl_add_u64 v[224:225], s[58:59], 0, v[162:163]
	s_addc_u32 s55, s59, 0
	s_add_i32 s82, s76, s65
	global_load_lds_dwordx4 v[224:225], off
	v_lshl_add_u64 v[226:227], s[54:55], 0, v[154:155]
	s_mov_b32 m0, s82
	v_lshl_add_u64 v[228:229], s[60:61], 0, v[160:161]
	global_load_lds_dwordx4 v[226:227], off
	v_lshl_add_u64 v[226:227], s[54:55], 0, v[162:163]
	s_add_i32 m0, s82, 0x2000
	s_nop 0
	global_load_lds_dwordx4 v[226:227], off
	v_lshl_add_u64 v[226:227], s[60:61], 0, v[152:153]
	s_mov_b32 m0, s66
	s_nop 0
	global_load_lds_dwordx4 v[226:227], off
	s_mov_b32 m0, s67
	s_nop 0
	global_load_lds_dwordx4 v[228:229], off
	s_waitcnt vmcnt(24)
	s_waitcnt lgkmcnt(0)
	s_barrier
	s_setprio 1
	s_waitcnt lgkmcnt(0)
	v_mfma_f32_16x16x32_bf16 v[60:63], v[128:131], v[180:183], 0
	v_mfma_f32_16x16x32_bf16 v[56:59], v[136:139], v[180:183], 0
	v_mfma_f32_16x16x32_bf16 v[44:47], v[128:131], v[198:201], 0
	v_mfma_f32_16x16x32_bf16 v[40:43], v[136:139], v[198:201], 0
	v_mfma_f32_16x16x32_bf16 v[28:31], v[128:131], v[206:209], 0
	v_mfma_f32_16x16x32_bf16 v[24:27], v[136:139], v[206:209], 0
	v_mfma_f32_16x16x32_bf16 v[12:15], v[128:131], v[214:217], 0
	v_mfma_f32_16x16x32_bf16 v[8:11], v[136:139], v[214:217], 0
	v_mfma_f32_16x16x32_bf16 v[60:63], v[132:135], v[194:197], v[60:63]
	v_mfma_f32_16x16x32_bf16 v[56:59], v[140:143], v[194:197], v[56:59]
	v_mfma_f32_16x16x32_bf16 v[44:47], v[132:135], v[202:205], v[44:47]
	v_mfma_f32_16x16x32_bf16 v[40:43], v[140:143], v[202:205], v[40:43]
	v_mfma_f32_16x16x32_bf16 v[28:31], v[132:135], v[210:213], v[28:31]
	v_mfma_f32_16x16x32_bf16 v[24:27], v[140:143], v[210:213], v[24:27]
	v_mfma_f32_16x16x32_bf16 v[12:15], v[132:135], v[218:221], v[12:15]
	v_mfma_f32_16x16x32_bf16 v[8:11], v[140:143], v[218:221], v[8:11]
	s_setprio 0
	s_setprio 1
	v_mfma_f32_16x16x32_bf16 v[52:55], v[144:147], v[180:183], 0
	v_mfma_f32_16x16x32_bf16 v[48:51], v[172:175], v[180:183], 0
	v_mfma_f32_16x16x32_bf16 v[36:39], v[144:147], v[198:201], 0
	v_mfma_f32_16x16x32_bf16 v[32:35], v[172:175], v[198:201], 0
	v_mfma_f32_16x16x32_bf16 v[20:23], v[144:147], v[206:209], 0
	v_mfma_f32_16x16x32_bf16 v[16:19], v[172:175], v[206:209], 0
	v_mfma_f32_16x16x32_bf16 v[4:7], v[144:147], v[214:217], 0
	v_mfma_f32_16x16x32_bf16 v[0:3], v[172:175], v[214:217], 0
	v_mfma_f32_16x16x32_bf16 v[52:55], v[148:151], v[194:197], v[52:55]
	v_mfma_f32_16x16x32_bf16 v[48:51], v[176:179], v[194:197], v[48:51]
	v_mfma_f32_16x16x32_bf16 v[36:39], v[148:151], v[202:205], v[36:39]
	v_mfma_f32_16x16x32_bf16 v[32:35], v[176:179], v[202:205], v[32:35]
	v_mfma_f32_16x16x32_bf16 v[20:23], v[148:151], v[210:213], v[20:23]
	v_mfma_f32_16x16x32_bf16 v[16:19], v[176:179], v[210:213], v[16:19]
	v_mfma_f32_16x16x32_bf16 v[4:7], v[148:151], v[218:221], v[4:7]
	v_mfma_f32_16x16x32_bf16 v[0:3], v[176:179], v[218:221], v[0:3]
	s_setprio 0
	s_barrier
	s_add_i32 s82, 0, 0x18000
	s_add_i32 s83, 0, 0x1c000
	v_add_u32_e32 v140, s82, v186
	v_add_u32_e32 v176, s83, v186
	ds_read_b128 v[128:131], v140
	ds_read_b128 v[132:135], v140 offset:1024
	ds_read_b128 v[136:139], v140 offset:2048
	ds_read_b128 v[140:143], v140 offset:3072
	ds_read_b128 v[144:147], v176
	ds_read_b128 v[148:151], v176 offset:1024
	ds_read_b128 v[172:175], v176 offset:2048
	ds_read_b128 v[176:179], v176 offset:3072
	s_add_u32 s54, s60, 0xb0000
	s_addc_u32 s55, s61, 0
	s_mov_b32 m0, s68
	v_lshl_add_u64 v[230:231], s[54:55], 0, v[152:153]
	ds_read_b128 v[180:183], v191 offset:32768
	ds_read_b128 v[194:197], v191 offset:33792
	ds_read_b128 v[198:201], v191 offset:34816
	ds_read_b128 v[202:205], v191 offset:35840
	ds_read_b128 v[206:209], v191 offset:36864
	ds_read_b128 v[210:213], v191 offset:37888
	ds_read_b128 v[214:217], v191 offset:38912
	ds_read_b128 v[218:221], v191 offset:39936
	global_load_lds_dwordx4 v[230:231], off
	v_lshl_add_u64 v[230:231], s[54:55], 0, v[160:161]
	s_mov_b32 m0, s69
	s_nop 0
	global_load_lds_dwordx4 v[230:231], off
	s_waitcnt vmcnt(8)
	s_waitcnt lgkmcnt(0)
	s_barrier
	s_setprio 1
	s_waitcnt lgkmcnt(0)
	v_mfma_f32_16x16x32_bf16 v[124:127], v[128:131], v[180:183], v[124:127]
	v_mfma_f32_16x16x32_bf16 v[124:127], v[132:135], v[194:197], v[124:127]
	v_mfma_f32_16x16x32_bf16 v[120:123], v[136:139], v[180:183], v[120:123]
	v_mfma_f32_16x16x32_bf16 v[120:123], v[140:143], v[194:197], v[120:123]
	v_mfma_f32_16x16x32_bf16 v[108:111], v[128:131], v[198:201], v[108:111]
	v_mfma_f32_16x16x32_bf16 v[108:111], v[132:135], v[202:205], v[108:111]
	v_mfma_f32_16x16x32_bf16 v[104:107], v[136:139], v[198:201], v[104:107]
	v_mfma_f32_16x16x32_bf16 v[104:107], v[140:143], v[202:205], v[104:107]
	v_mfma_f32_16x16x32_bf16 v[92:95], v[128:131], v[206:209], v[92:95]
	v_mfma_f32_16x16x32_bf16 v[92:95], v[132:135], v[210:213], v[92:95]
	v_mfma_f32_16x16x32_bf16 v[88:91], v[136:139], v[206:209], v[88:91]
	v_mfma_f32_16x16x32_bf16 v[88:91], v[140:143], v[210:213], v[88:91]
	v_mfma_f32_16x16x32_bf16 v[76:79], v[128:131], v[214:217], v[76:79]
	v_mfma_f32_16x16x32_bf16 v[76:79], v[132:135], v[218:221], v[76:79]
	v_mfma_f32_16x16x32_bf16 v[72:75], v[136:139], v[214:217], v[72:75]
	v_mfma_f32_16x16x32_bf16 v[72:75], v[140:143], v[218:221], v[72:75]
	s_setprio 0
	s_setprio 1
	v_mfma_f32_16x16x32_bf16 v[116:119], v[144:147], v[180:183], v[116:119]
	v_mfma_f32_16x16x32_bf16 v[116:119], v[148:151], v[194:197], v[116:119]
	v_mfma_f32_16x16x32_bf16 v[112:115], v[172:175], v[180:183], v[112:115]
	v_mfma_f32_16x16x32_bf16 v[112:115], v[176:179], v[194:197], v[112:115]
	v_mfma_f32_16x16x32_bf16 v[100:103], v[144:147], v[198:201], v[100:103]
	v_mfma_f32_16x16x32_bf16 v[100:103], v[148:151], v[202:205], v[100:103]
	v_mfma_f32_16x16x32_bf16 v[96:99], v[172:175], v[198:201], v[96:99]
	v_mfma_f32_16x16x32_bf16 v[96:99], v[176:179], v[202:205], v[96:99]
	v_mfma_f32_16x16x32_bf16 v[84:87], v[144:147], v[206:209], v[84:87]
	v_mfma_f32_16x16x32_bf16 v[84:87], v[148:151], v[210:213], v[84:87]
	v_mfma_f32_16x16x32_bf16 v[80:83], v[172:175], v[206:209], v[80:83]
	v_mfma_f32_16x16x32_bf16 v[80:83], v[176:179], v[210:213], v[80:83]
	v_mfma_f32_16x16x32_bf16 v[68:71], v[144:147], v[214:217], v[68:71]
	v_mfma_f32_16x16x32_bf16 v[68:71], v[148:151], v[218:221], v[68:71]
	v_mfma_f32_16x16x32_bf16 v[64:67], v[172:175], v[214:217], v[64:67]
	v_mfma_f32_16x16x32_bf16 v[64:67], v[176:179], v[218:221], v[64:67]
	s_setprio 0
	s_barrier
	s_add_i32 s54, s82, s65
	v_lshl_add_u64 v[222:223], v[222:223], 0, s[28:29]
	s_mov_b32 m0, s54
	ds_read_b128 v[180:183], v191 offset:49152
	ds_read_b128 v[194:197], v191 offset:50176
	ds_read_b128 v[198:201], v191 offset:51200
	ds_read_b128 v[202:205], v191 offset:52224
	ds_read_b128 v[206:209], v191 offset:53248
	ds_read_b128 v[210:213], v191 offset:54272
	ds_read_b128 v[214:217], v191 offset:55296
	ds_read_b128 v[218:221], v191 offset:56320
	global_load_lds_dwordx4 v[222:223], off
	s_add_i32 m0, s54, 0x2000
	s_add_u32 s54, s58, 0xb0080
	v_lshl_add_u64 v[222:223], v[224:225], 0, s[28:29]
	s_addc_u32 s55, s59, 0
	s_add_i32 s58, s83, s65
	global_load_lds_dwordx4 v[222:223], off
	v_lshl_add_u64 v[222:223], s[54:55], 0, v[154:155]
	s_mov_b32 m0, s58
	s_nop 0
	global_load_lds_dwordx4 v[222:223], off
	v_lshl_add_u64 v[222:223], s[54:55], 0, v[162:163]
	s_add_i32 m0, s58, 0x2000
	s_nop 0
	global_load_lds_dwordx4 v[222:223], off
	v_lshl_add_u64 v[222:223], v[226:227], 0, s[28:29]
	s_mov_b32 m0, s3
	s_nop 0
	global_load_lds_dwordx4 v[222:223], off
	v_lshl_add_u64 v[222:223], v[228:229], 0, s[28:29]
	s_mov_b32 m0, s71
	s_nop 0
	global_load_lds_dwordx4 v[222:223], off
	s_waitcnt vmcnt(8)
	s_waitcnt lgkmcnt(0)
	s_barrier
	s_setprio 1
	s_waitcnt lgkmcnt(0)
	v_mfma_f32_16x16x32_bf16 v[60:63], v[128:131], v[180:183], v[60:63]
	v_mfma_f32_16x16x32_bf16 v[60:63], v[132:135], v[194:197], v[60:63]
	v_mfma_f32_16x16x32_bf16 v[56:59], v[136:139], v[180:183], v[56:59]
	v_mfma_f32_16x16x32_bf16 v[56:59], v[140:143], v[194:197], v[56:59]
	v_mfma_f32_16x16x32_bf16 v[44:47], v[128:131], v[198:201], v[44:47]
	v_mfma_f32_16x16x32_bf16 v[44:47], v[132:135], v[202:205], v[44:47]
	v_mfma_f32_16x16x32_bf16 v[40:43], v[136:139], v[198:201], v[40:43]
	v_mfma_f32_16x16x32_bf16 v[40:43], v[140:143], v[202:205], v[40:43]
	v_mfma_f32_16x16x32_bf16 v[28:31], v[128:131], v[206:209], v[28:31]
	v_mfma_f32_16x16x32_bf16 v[28:31], v[132:135], v[210:213], v[28:31]
	v_mfma_f32_16x16x32_bf16 v[24:27], v[136:139], v[206:209], v[24:27]
	v_mfma_f32_16x16x32_bf16 v[24:27], v[140:143], v[210:213], v[24:27]
	v_mfma_f32_16x16x32_bf16 v[12:15], v[128:131], v[214:217], v[12:15]
	v_mfma_f32_16x16x32_bf16 v[12:15], v[132:135], v[218:221], v[12:15]
	v_mfma_f32_16x16x32_bf16 v[8:11], v[136:139], v[214:217], v[8:11]
	v_mfma_f32_16x16x32_bf16 v[8:11], v[140:143], v[218:221], v[8:11]
	s_setprio 0
	s_setprio 1
	v_mfma_f32_16x16x32_bf16 v[52:55], v[144:147], v[180:183], v[52:55]
	v_mfma_f32_16x16x32_bf16 v[52:55], v[148:151], v[194:197], v[52:55]
	v_mfma_f32_16x16x32_bf16 v[48:51], v[172:175], v[180:183], v[48:51]
	v_mfma_f32_16x16x32_bf16 v[48:51], v[176:179], v[194:197], v[48:51]
	v_mfma_f32_16x16x32_bf16 v[36:39], v[144:147], v[198:201], v[36:39]
	v_mfma_f32_16x16x32_bf16 v[36:39], v[148:151], v[202:205], v[36:39]
	v_mfma_f32_16x16x32_bf16 v[32:35], v[172:175], v[198:201], v[32:35]
	v_mfma_f32_16x16x32_bf16 v[32:35], v[176:179], v[202:205], v[32:35]
	v_mfma_f32_16x16x32_bf16 v[20:23], v[144:147], v[206:209], v[20:23]
	v_mfma_f32_16x16x32_bf16 v[20:23], v[148:151], v[210:213], v[20:23]
	v_mfma_f32_16x16x32_bf16 v[16:19], v[172:175], v[206:209], v[16:19]
	v_mfma_f32_16x16x32_bf16 v[16:19], v[176:179], v[210:213], v[16:19]
	v_mfma_f32_16x16x32_bf16 v[4:7], v[144:147], v[214:217], v[4:7]
	v_mfma_f32_16x16x32_bf16 v[4:7], v[148:151], v[218:221], v[4:7]
	v_mfma_f32_16x16x32_bf16 v[0:3], v[172:175], v[214:217], v[0:3]
	v_mfma_f32_16x16x32_bf16 v[0:3], v[176:179], v[218:221], v[0:3]
	s_setprio 0
	s_barrier
	s_add_i32 s81, s81, 2
	s_add_u32 s79, s79, 0x100
	s_addc_u32 s80, s80, 0
	s_cmp_gt_u32 s81, 41
	s_mov_b64 s[54:55], s[56:57]
	s_branch .LBB0_610
.Lfa_5:
	ds_read_b128 v[128:131], v189
	ds_read_b128 v[132:135], v189 offset:1024
	ds_read_b128 v[136:139], v189 offset:2048
	ds_read_b128 v[140:143], v189 offset:3072
	ds_read_b128 v[144:147], v190
	ds_read_b128 v[148:151], v190 offset:1024
	ds_read_b128 v[172:175], v190 offset:2048
	ds_read_b128 v[176:179], v190 offset:3072
	s_add_u32 s56, s54, 0x100
	s_addc_u32 s57, s55, 0
	s_cmp_eq_u32 s81, 40
	s_cselect_b32 s61, s17, s57
	s_cselect_b32 s60, s16, s56
	s_cselect_b32 s59, s53, s80
	s_cselect_b32 s58, s52, s79
	v_lshl_add_u64 v[222:223], s[54:55], 0, v[166:167]
	s_add_i32 m0, s66, 0xc000
	ds_read_b128 v[180:183], v191
	ds_read_b128 v[194:197], v191 offset:1024
	ds_read_b128 v[198:201], v191 offset:2048
	ds_read_b128 v[202:205], v191 offset:3072
	ds_read_b128 v[206:209], v191 offset:4096
	ds_read_b128 v[210:213], v191 offset:5120
	ds_read_b128 v[214:217], v191 offset:6144
	ds_read_b128 v[218:221], v191 offset:7168
	global_load_lds_dwordx4 v[222:223], off
	v_lshl_add_u64 v[222:223], s[54:55], 0, v[164:165]
	s_add_i32 m0, s66, 0xe000
	s_nop 0
	global_load_lds_dwordx4 v[222:223], off
	s_waitcnt vmcnt(8)
	s_waitcnt lgkmcnt(0)
	s_barrier
	s_setprio 1
	s_waitcnt lgkmcnt(0)
	v_mfma_f32_16x16x32_bf16 v[124:127], v[128:131], v[180:183], 0
	v_mfma_f32_16x16x32_bf16 v[120:123], v[136:139], v[180:183], 0
	v_mfma_f32_16x16x32_bf16 v[108:111], v[128:131], v[198:201], 0
	v_mfma_f32_16x16x32_bf16 v[104:107], v[136:139], v[198:201], 0
	v_mfma_f32_16x16x32_bf16 v[92:95], v[128:131], v[206:209], 0
	v_mfma_f32_16x16x32_bf16 v[88:91], v[136:139], v[206:209], 0
	v_mfma_f32_16x16x32_bf16 v[76:79], v[128:131], v[214:217], 0
	v_mfma_f32_16x16x32_bf16 v[72:75], v[136:139], v[214:217], 0
	v_mfma_f32_16x16x32_bf16 v[124:127], v[132:135], v[194:197], v[124:127]
	v_mfma_f32_16x16x32_bf16 v[120:123], v[140:143], v[194:197], v[120:123]
	v_mfma_f32_16x16x32_bf16 v[108:111], v[132:135], v[202:205], v[108:111]
	v_mfma_f32_16x16x32_bf16 v[104:107], v[140:143], v[202:205], v[104:107]
	v_mfma_f32_16x16x32_bf16 v[92:95], v[132:135], v[210:213], v[92:95]
	v_mfma_f32_16x16x32_bf16 v[88:91], v[140:143], v[210:213], v[88:91]
	v_mfma_f32_16x16x32_bf16 v[76:79], v[132:135], v[218:221], v[76:79]
	v_mfma_f32_16x16x32_bf16 v[72:75], v[140:143], v[218:221], v[72:75]
	s_setprio 0
	s_setprio 1
	v_mfma_f32_16x16x32_bf16 v[116:119], v[144:147], v[180:183], 0
	v_mfma_f32_16x16x32_bf16 v[112:115], v[172:175], v[180:183], 0
	v_mfma_f32_16x16x32_bf16 v[100:103], v[144:147], v[198:201], 0
	v_mfma_f32_16x16x32_bf16 v[96:99], v[172:175], v[198:201], 0
	v_mfma_f32_16x16x32_bf16 v[84:87], v[144:147], v[206:209], 0
	v_mfma_f32_16x16x32_bf16 v[80:83], v[172:175], v[206:209], 0
	v_mfma_f32_16x16x32_bf16 v[68:71], v[144:147], v[214:217], 0
	v_mfma_f32_16x16x32_bf16 v[64:67], v[172:175], v[214:217], 0
	v_mfma_f32_16x16x32_bf16 v[116:119], v[148:151], v[194:197], v[116:119]
	v_mfma_f32_16x16x32_bf16 v[112:115], v[176:179], v[194:197], v[112:115]
	v_mfma_f32_16x16x32_bf16 v[100:103], v[148:151], v[202:205], v[100:103]
	v_mfma_f32_16x16x32_bf16 v[96:99], v[176:179], v[202:205], v[96:99]
	v_mfma_f32_16x16x32_bf16 v[84:87], v[148:151], v[210:213], v[84:87]
	v_mfma_f32_16x16x32_bf16 v[80:83], v[176:179], v[210:213], v[80:83]
	v_mfma_f32_16x16x32_bf16 v[68:71], v[148:151], v[218:221], v[68:71]
	v_mfma_f32_16x16x32_bf16 v[64:67], v[176:179], v[218:221], v[64:67]
	s_setprio 0
	s_barrier
	s_add_i32 s54, s75, s65
	v_lshl_add_u64 v[222:223], s[58:59], 0, v[154:155]
	s_mov_b32 m0, s54
	ds_read_b128 v[180:183], v191 offset:16384
	ds_read_b128 v[194:197], v191 offset:17408
	ds_read_b128 v[198:201], v191 offset:18432
	ds_read_b128 v[202:205], v191 offset:19456
	ds_read_b128 v[206:209], v191 offset:20480
	ds_read_b128 v[210:213], v191 offset:21504
	ds_read_b128 v[214:217], v191 offset:22528
	ds_read_b128 v[218:221], v191 offset:23552
	global_load_lds_dwordx4 v[222:223], off
	s_add_i32 m0, s54, 0x2000
	s_add_u32 s54, s58, 0xb0000
	v_lshl_add_u64 v[224:225], s[58:59], 0, v[162:163]
	s_addc_u32 s55, s59, 0
	s_add_i32 s82, s76, s65
	global_load_lds_dwordx4 v[224:225], off
	v_lshl_add_u64 v[226:227], s[54:55], 0, v[154:155]
	s_mov_b32 m0, s82
	v_lshl_add_u64 v[228:229], s[60:61], 0, v[160:161]
	global_load_lds_dwordx4 v[226:227], off
	v_lshl_add_u64 v[226:227], s[54:55], 0, v[162:163]
	s_add_i32 m0, s82, 0x2000
	s_nop 0
	global_load_lds_dwordx4 v[226:227], off
	v_lshl_add_u64 v[226:227], s[60:61], 0, v[152:153]
	s_mov_b32 m0, s66
	s_nop 0
	global_load_lds_dwordx4 v[226:227], off
	s_mov_b32 m0, s67
	s_nop 0
	global_load_lds_dwordx4 v[228:229], off
	s_waitcnt vmcnt(8)
	s_waitcnt lgkmcnt(0)
	s_barrier
	s_setprio 1
	s_waitcnt lgkmcnt(0)
	v_mfma_f32_16x16x32_bf16 v[60:63], v[128:131], v[180:183], 0
	v_mfma_f32_16x16x32_bf16 v[56:59], v[136:139], v[180:183], 0
	v_mfma_f32_16x16x32_bf16 v[44:47], v[128:131], v[198:201], 0
	v_mfma_f32_16x16x32_bf16 v[40:43], v[136:139], v[198:201], 0
	v_mfma_f32_16x16x32_bf16 v[28:31], v[128:131], v[206:209], 0
	v_mfma_f32_16x16x32_bf16 v[24:27], v[136:139], v[206:209], 0
	v_mfma_f32_16x16x32_bf16 v[12:15], v[128:131], v[214:217], 0
	v_mfma_f32_16x16x32_bf16 v[8:11], v[136:139], v[214:217], 0
	v_mfma_f32_16x16x32_bf16 v[60:63], v[132:135], v[194:197], v[60:63]
	v_mfma_f32_16x16x32_bf16 v[56:59], v[140:143], v[194:197], v[56:59]
	v_mfma_f32_16x16x32_bf16 v[44:47], v[132:135], v[202:205], v[44:47]
	v_mfma_f32_16x16x32_bf16 v[40:43], v[140:143], v[202:205], v[40:43]
	v_mfma_f32_16x16x32_bf16 v[28:31], v[132:135], v[210:213], v[28:31]
	v_mfma_f32_16x16x32_bf16 v[24:27], v[140:143], v[210:213], v[24:27]
	v_mfma_f32_16x16x32_bf16 v[12:15], v[132:135], v[218:221], v[12:15]
	v_mfma_f32_16x16x32_bf16 v[8:11], v[140:143], v[218:221], v[8:11]
	s_setprio 0
	s_setprio 1
	v_mfma_f32_16x16x32_bf16 v[52:55], v[144:147], v[180:183], 0
	v_mfma_f32_16x16x32_bf16 v[48:51], v[172:175], v[180:183], 0
	v_mfma_f32_16x16x32_bf16 v[36:39], v[144:147], v[198:201], 0
	v_mfma_f32_16x16x32_bf16 v[32:35], v[172:175], v[198:201], 0
	v_mfma_f32_16x16x32_bf16 v[20:23], v[144:147], v[206:209], 0
	v_mfma_f32_16x16x32_bf16 v[16:19], v[172:175], v[206:209], 0
	v_mfma_f32_16x16x32_bf16 v[4:7], v[144:147], v[214:217], 0
	v_mfma_f32_16x16x32_bf16 v[0:3], v[172:175], v[214:217], 0
	v_mfma_f32_16x16x32_bf16 v[52:55], v[148:151], v[194:197], v[52:55]
	v_mfma_f32_16x16x32_bf16 v[48:51], v[176:179], v[194:197], v[48:51]
	v_mfma_f32_16x16x32_bf16 v[36:39], v[148:151], v[202:205], v[36:39]
	v_mfma_f32_16x16x32_bf16 v[32:35], v[176:179], v[202:205], v[32:35]
	v_mfma_f32_16x16x32_bf16 v[20:23], v[148:151], v[210:213], v[20:23]
	v_mfma_f32_16x16x32_bf16 v[16:19], v[176:179], v[210:213], v[16:19]
	v_mfma_f32_16x16x32_bf16 v[4:7], v[148:151], v[218:221], v[4:7]
	v_mfma_f32_16x16x32_bf16 v[0:3], v[176:179], v[218:221], v[0:3]
	s_setprio 0
	s_barrier
	s_add_i32 s82, 0, 0x18000
	s_add_i32 s83, 0, 0x1c000
	v_add_u32_e32 v140, s82, v186
	v_add_u32_e32 v176, s83, v186
	ds_read_b128 v[128:131], v140
	ds_read_b128 v[132:135], v140 offset:1024
	ds_read_b128 v[136:139], v140 offset:2048
	ds_read_b128 v[140:143], v140 offset:3072
	ds_read_b128 v[144:147], v176
	ds_read_b128 v[148:151], v176 offset:1024
	ds_read_b128 v[172:175], v176 offset:2048
	ds_read_b128 v[176:179], v176 offset:3072
	s_add_u32 s54, s60, 0xb0000
	s_addc_u32 s55, s61, 0
	s_mov_b32 m0, s68
	v_lshl_add_u64 v[230:231], s[54:55], 0, v[152:153]
	ds_read_b128 v[180:183], v191 offset:32768
	ds_read_b128 v[194:197], v191 offset:33792
	ds_read_b128 v[198:201], v191 offset:34816
	ds_read_b128 v[202:205], v191 offset:35840
	ds_read_b128 v[206:209], v191 offset:36864
	ds_read_b128 v[210:213], v191 offset:37888
	ds_read_b128 v[214:217], v191 offset:38912
	ds_read_b128 v[218:221], v191 offset:39936
	global_load_lds_dwordx4 v[230:231], off
	v_lshl_add_u64 v[230:231], s[54:55], 0, v[160:161]
	s_mov_b32 m0, s69
	s_nop 0
	global_load_lds_dwordx4 v[230:231], off
	s_waitcnt vmcnt(8)
	s_waitcnt lgkmcnt(0)
	s_barrier
	s_setprio 1
	s_waitcnt lgkmcnt(0)
	v_mfma_f32_16x16x32_bf16 v[124:127], v[128:131], v[180:183], v[124:127]
	v_mfma_f32_16x16x32_bf16 v[124:127], v[132:135], v[194:197], v[124:127]
	v_mfma_f32_16x16x32_bf16 v[120:123], v[136:139], v[180:183], v[120:123]
	v_mfma_f32_16x16x32_bf16 v[120:123], v[140:143], v[194:197], v[120:123]
	v_mfma_f32_16x16x32_bf16 v[108:111], v[128:131], v[198:201], v[108:111]
	v_mfma_f32_16x16x32_bf16 v[108:111], v[132:135], v[202:205], v[108:111]
	v_mfma_f32_16x16x32_bf16 v[104:107], v[136:139], v[198:201], v[104:107]
	v_mfma_f32_16x16x32_bf16 v[104:107], v[140:143], v[202:205], v[104:107]
	v_mfma_f32_16x16x32_bf16 v[92:95], v[128:131], v[206:209], v[92:95]
	v_mfma_f32_16x16x32_bf16 v[92:95], v[132:135], v[210:213], v[92:95]
	v_mfma_f32_16x16x32_bf16 v[88:91], v[136:139], v[206:209], v[88:91]
	v_mfma_f32_16x16x32_bf16 v[88:91], v[140:143], v[210:213], v[88:91]
	v_mfma_f32_16x16x32_bf16 v[76:79], v[128:131], v[214:217], v[76:79]
	v_mfma_f32_16x16x32_bf16 v[76:79], v[132:135], v[218:221], v[76:79]
	v_mfma_f32_16x16x32_bf16 v[72:75], v[136:139], v[214:217], v[72:75]
	v_mfma_f32_16x16x32_bf16 v[72:75], v[140:143], v[218:221], v[72:75]
	s_setprio 0
	s_setprio 1
	v_mfma_f32_16x16x32_bf16 v[116:119], v[144:147], v[180:183], v[116:119]
	v_mfma_f32_16x16x32_bf16 v[116:119], v[148:151], v[194:197], v[116:119]
	v_mfma_f32_16x16x32_bf16 v[112:115], v[172:175], v[180:183], v[112:115]
	v_mfma_f32_16x16x32_bf16 v[112:115], v[176:179], v[194:197], v[112:115]
	v_mfma_f32_16x16x32_bf16 v[100:103], v[144:147], v[198:201], v[100:103]
	v_mfma_f32_16x16x32_bf16 v[100:103], v[148:151], v[202:205], v[100:103]
	v_mfma_f32_16x16x32_bf16 v[96:99], v[172:175], v[198:201], v[96:99]
	v_mfma_f32_16x16x32_bf16 v[96:99], v[176:179], v[202:205], v[96:99]
	v_mfma_f32_16x16x32_bf16 v[84:87], v[144:147], v[206:209], v[84:87]
	v_mfma_f32_16x16x32_bf16 v[84:87], v[148:151], v[210:213], v[84:87]
	v_mfma_f32_16x16x32_bf16 v[80:83], v[172:175], v[206:209], v[80:83]
	v_mfma_f32_16x16x32_bf16 v[80:83], v[176:179], v[210:213], v[80:83]
	v_mfma_f32_16x16x32_bf16 v[68:71], v[144:147], v[214:217], v[68:71]
	v_mfma_f32_16x16x32_bf16 v[68:71], v[148:151], v[218:221], v[68:71]
	v_mfma_f32_16x16x32_bf16 v[64:67], v[172:175], v[214:217], v[64:67]
	v_mfma_f32_16x16x32_bf16 v[64:67], v[176:179], v[218:221], v[64:67]
	s_setprio 0
	s_barrier
	s_add_i32 s54, s82, s65
	v_lshl_add_u64 v[222:223], v[222:223], 0, s[28:29]
	s_mov_b32 m0, s54
	ds_read_b128 v[180:183], v191 offset:49152
	ds_read_b128 v[194:197], v191 offset:50176
	ds_read_b128 v[198:201], v191 offset:51200
	ds_read_b128 v[202:205], v191 offset:52224
	ds_read_b128 v[206:209], v191 offset:53248
	ds_read_b128 v[210:213], v191 offset:54272
	ds_read_b128 v[214:217], v191 offset:55296
	ds_read_b128 v[218:221], v191 offset:56320
	global_load_lds_dwordx4 v[222:223], off
	s_add_i32 m0, s54, 0x2000
	s_add_u32 s54, s58, 0xb0080
	v_lshl_add_u64 v[222:223], v[224:225], 0, s[28:29]
	s_addc_u32 s55, s59, 0
	s_add_i32 s58, s83, s65
	global_load_lds_dwordx4 v[222:223], off
	v_lshl_add_u64 v[222:223], s[54:55], 0, v[154:155]
	s_mov_b32 m0, s58
	s_nop 0
	global_load_lds_dwordx4 v[222:223], off
	v_lshl_add_u64 v[222:223], s[54:55], 0, v[162:163]
	s_add_i32 m0, s58, 0x2000
	s_nop 0
	global_load_lds_dwordx4 v[222:223], off
	v_lshl_add_u64 v[222:223], v[226:227], 0, s[28:29]
	s_mov_b32 m0, s3
	s_nop 0
	global_load_lds_dwordx4 v[222:223], off
	v_lshl_add_u64 v[222:223], v[228:229], 0, s[28:29]
	s_mov_b32 m0, s71
	s_nop 0
	global_load_lds_dwordx4 v[222:223], off
	s_waitcnt vmcnt(8)
	s_waitcnt lgkmcnt(0)
	s_barrier
	s_setprio 1
	s_waitcnt lgkmcnt(0)
	v_mfma_f32_16x16x32_bf16 v[60:63], v[128:131], v[180:183], v[60:63]
	v_mfma_f32_16x16x32_bf16 v[60:63], v[132:135], v[194:197], v[60:63]
	v_mfma_f32_16x16x32_bf16 v[56:59], v[136:139], v[180:183], v[56:59]
	v_mfma_f32_16x16x32_bf16 v[56:59], v[140:143], v[194:197], v[56:59]
	v_mfma_f32_16x16x32_bf16 v[44:47], v[128:131], v[198:201], v[44:47]
	v_mfma_f32_16x16x32_bf16 v[44:47], v[132:135], v[202:205], v[44:47]
	v_mfma_f32_16x16x32_bf16 v[40:43], v[136:139], v[198:201], v[40:43]
	v_mfma_f32_16x16x32_bf16 v[40:43], v[140:143], v[202:205], v[40:43]
	v_mfma_f32_16x16x32_bf16 v[28:31], v[128:131], v[206:209], v[28:31]
	v_mfma_f32_16x16x32_bf16 v[28:31], v[132:135], v[210:213], v[28:31]
	v_mfma_f32_16x16x32_bf16 v[24:27], v[136:139], v[206:209], v[24:27]
	v_mfma_f32_16x16x32_bf16 v[24:27], v[140:143], v[210:213], v[24:27]
	v_mfma_f32_16x16x32_bf16 v[12:15], v[128:131], v[214:217], v[12:15]
	v_mfma_f32_16x16x32_bf16 v[12:15], v[132:135], v[218:221], v[12:15]
	v_mfma_f32_16x16x32_bf16 v[8:11], v[136:139], v[214:217], v[8:11]
	v_mfma_f32_16x16x32_bf16 v[8:11], v[140:143], v[218:221], v[8:11]
	s_setprio 0
	s_setprio 1
	v_mfma_f32_16x16x32_bf16 v[52:55], v[144:147], v[180:183], v[52:55]
	v_mfma_f32_16x16x32_bf16 v[52:55], v[148:151], v[194:197], v[52:55]
	v_mfma_f32_16x16x32_bf16 v[48:51], v[172:175], v[180:183], v[48:51]
	v_mfma_f32_16x16x32_bf16 v[48:51], v[176:179], v[194:197], v[48:51]
	v_mfma_f32_16x16x32_bf16 v[36:39], v[144:147], v[198:201], v[36:39]
	v_mfma_f32_16x16x32_bf16 v[36:39], v[148:151], v[202:205], v[36:39]
	v_mfma_f32_16x16x32_bf16 v[32:35], v[172:175], v[198:201], v[32:35]
	v_mfma_f32_16x16x32_bf16 v[32:35], v[176:179], v[202:205], v[32:35]
	v_mfma_f32_16x16x32_bf16 v[20:23], v[144:147], v[206:209], v[20:23]
	v_mfma_f32_16x16x32_bf16 v[20:23], v[148:151], v[210:213], v[20:23]
	v_mfma_f32_16x16x32_bf16 v[16:19], v[172:175], v[206:209], v[16:19]
	v_mfma_f32_16x16x32_bf16 v[16:19], v[176:179], v[210:213], v[16:19]
	v_mfma_f32_16x16x32_bf16 v[4:7], v[144:147], v[214:217], v[4:7]
	v_mfma_f32_16x16x32_bf16 v[4:7], v[148:151], v[218:221], v[4:7]
	v_mfma_f32_16x16x32_bf16 v[0:3], v[172:175], v[214:217], v[0:3]
	v_mfma_f32_16x16x32_bf16 v[0:3], v[176:179], v[218:221], v[0:3]
	s_setprio 0
	s_barrier
	s_add_i32 s81, s81, 2
	s_add_u32 s79, s79, 0x100
	s_addc_u32 s80, s80, 0
	s_cmp_gt_u32 s81, 41
	s_mov_b64 s[54:55], s[56:57]
.LBB0_610:
	ds_read_b128 v[128:131], v189
	ds_read_b128 v[132:135], v189 offset:1024
	ds_read_b128 v[136:139], v189 offset:2048
	ds_read_b128 v[140:143], v189 offset:3072
	ds_read_b128 v[144:147], v190
	ds_read_b128 v[148:151], v190 offset:1024
	ds_read_b128 v[172:175], v190 offset:2048
	ds_read_b128 v[176:179], v190 offset:3072
	s_add_u32 s56, s54, 0x100
	s_addc_u32 s57, s55, 0
	s_cmp_eq_u32 s81, 40
	s_cselect_b32 s61, s17, s57
	s_cselect_b32 s60, s16, s56
	s_cselect_b32 s59, s53, s80
	s_cselect_b32 s58, s52, s79
	v_lshl_add_u64 v[222:223], s[54:55], 0, v[166:167]
	s_add_i32 m0, s66, 0xc000
	ds_read_b128 v[180:183], v191
	ds_read_b128 v[194:197], v191 offset:1024
	ds_read_b128 v[198:201], v191 offset:2048
	ds_read_b128 v[202:205], v191 offset:3072
	ds_read_b128 v[206:209], v191 offset:4096
	ds_read_b128 v[210:213], v191 offset:5120
	ds_read_b128 v[214:217], v191 offset:6144
	ds_read_b128 v[218:221], v191 offset:7168
	global_load_lds_dwordx4 v[222:223], off
	v_lshl_add_u64 v[222:223], s[54:55], 0, v[164:165]
	s_add_i32 m0, s66, 0xe000
	s_nop 0
	global_load_lds_dwordx4 v[222:223], off
	s_waitcnt vmcnt(8)
	s_waitcnt lgkmcnt(0)
	s_barrier
	s_setprio 1
	s_waitcnt lgkmcnt(0)
	v_mfma_f32_16x16x32_bf16 v[124:127], v[128:131], v[180:183], v[124:127]
	v_mfma_f32_16x16x32_bf16 v[124:127], v[132:135], v[194:197], v[124:127]
	v_mfma_f32_16x16x32_bf16 v[120:123], v[136:139], v[180:183], v[120:123]
	v_mfma_f32_16x16x32_bf16 v[120:123], v[140:143], v[194:197], v[120:123]
	v_mfma_f32_16x16x32_bf16 v[108:111], v[128:131], v[198:201], v[108:111]
	v_mfma_f32_16x16x32_bf16 v[108:111], v[132:135], v[202:205], v[108:111]
	v_mfma_f32_16x16x32_bf16 v[104:107], v[136:139], v[198:201], v[104:107]
	v_mfma_f32_16x16x32_bf16 v[104:107], v[140:143], v[202:205], v[104:107]
	v_mfma_f32_16x16x32_bf16 v[92:95], v[128:131], v[206:209], v[92:95]
	v_mfma_f32_16x16x32_bf16 v[92:95], v[132:135], v[210:213], v[92:95]
	v_mfma_f32_16x16x32_bf16 v[88:91], v[136:139], v[206:209], v[88:91]
	v_mfma_f32_16x16x32_bf16 v[88:91], v[140:143], v[210:213], v[88:91]
	v_mfma_f32_16x16x32_bf16 v[76:79], v[128:131], v[214:217], v[76:79]
	v_mfma_f32_16x16x32_bf16 v[76:79], v[132:135], v[218:221], v[76:79]
	v_mfma_f32_16x16x32_bf16 v[72:75], v[136:139], v[214:217], v[72:75]
	v_mfma_f32_16x16x32_bf16 v[72:75], v[140:143], v[218:221], v[72:75]
	s_setprio 0
	s_setprio 1
	v_mfma_f32_16x16x32_bf16 v[116:119], v[144:147], v[180:183], v[116:119]
	v_mfma_f32_16x16x32_bf16 v[116:119], v[148:151], v[194:197], v[116:119]
	v_mfma_f32_16x16x32_bf16 v[112:115], v[172:175], v[180:183], v[112:115]
	v_mfma_f32_16x16x32_bf16 v[112:115], v[176:179], v[194:197], v[112:115]
	v_mfma_f32_16x16x32_bf16 v[100:103], v[144:147], v[198:201], v[100:103]
	v_mfma_f32_16x16x32_bf16 v[100:103], v[148:151], v[202:205], v[100:103]
	v_mfma_f32_16x16x32_bf16 v[96:99], v[172:175], v[198:201], v[96:99]
	v_mfma_f32_16x16x32_bf16 v[96:99], v[176:179], v[202:205], v[96:99]
	v_mfma_f32_16x16x32_bf16 v[84:87], v[144:147], v[206:209], v[84:87]
	v_mfma_f32_16x16x32_bf16 v[84:87], v[148:151], v[210:213], v[84:87]
	v_mfma_f32_16x16x32_bf16 v[80:83], v[172:175], v[206:209], v[80:83]
	v_mfma_f32_16x16x32_bf16 v[80:83], v[176:179], v[210:213], v[80:83]
	v_mfma_f32_16x16x32_bf16 v[68:71], v[144:147], v[214:217], v[68:71]
	v_mfma_f32_16x16x32_bf16 v[68:71], v[148:151], v[218:221], v[68:71]
	v_mfma_f32_16x16x32_bf16 v[64:67], v[172:175], v[214:217], v[64:67]
	v_mfma_f32_16x16x32_bf16 v[64:67], v[176:179], v[218:221], v[64:67]
	s_setprio 0
	s_barrier
	s_add_i32 s54, s75, s65
	v_lshl_add_u64 v[222:223], s[58:59], 0, v[154:155]
	s_mov_b32 m0, s54
	ds_read_b128 v[180:183], v191 offset:16384
	ds_read_b128 v[194:197], v191 offset:17408
	ds_read_b128 v[198:201], v191 offset:18432
	ds_read_b128 v[202:205], v191 offset:19456
	ds_read_b128 v[206:209], v191 offset:20480
	ds_read_b128 v[210:213], v191 offset:21504
	ds_read_b128 v[214:217], v191 offset:22528
	ds_read_b128 v[218:221], v191 offset:23552
	global_load_lds_dwordx4 v[222:223], off
	s_add_i32 m0, s54, 0x2000
	s_add_u32 s54, s58, 0xb0000
	v_lshl_add_u64 v[224:225], s[58:59], 0, v[162:163]
	s_addc_u32 s55, s59, 0
	s_add_i32 s82, s76, s65
	global_load_lds_dwordx4 v[224:225], off
	v_lshl_add_u64 v[226:227], s[54:55], 0, v[154:155]
	s_mov_b32 m0, s82
	v_lshl_add_u64 v[228:229], s[60:61], 0, v[160:161]
	global_load_lds_dwordx4 v[226:227], off
	v_lshl_add_u64 v[226:227], s[54:55], 0, v[162:163]
	s_add_i32 m0, s82, 0x2000
	s_nop 0
	global_load_lds_dwordx4 v[226:227], off
	v_lshl_add_u64 v[226:227], s[60:61], 0, v[152:153]
	s_mov_b32 m0, s66
	s_nop 0
	global_load_lds_dwordx4 v[226:227], off
	s_mov_b32 m0, s67
	s_nop 0
	global_load_lds_dwordx4 v[228:229], off
	s_waitcnt vmcnt(8)
	s_waitcnt lgkmcnt(0)
	s_barrier
	s_setprio 1
	s_waitcnt lgkmcnt(0)
	v_mfma_f32_16x16x32_bf16 v[60:63], v[128:131], v[180:183], v[60:63]
	v_mfma_f32_16x16x32_bf16 v[60:63], v[132:135], v[194:197], v[60:63]
	v_mfma_f32_16x16x32_bf16 v[56:59], v[136:139], v[180:183], v[56:59]
	v_mfma_f32_16x16x32_bf16 v[56:59], v[140:143], v[194:197], v[56:59]
	v_mfma_f32_16x16x32_bf16 v[44:47], v[128:131], v[198:201], v[44:47]
	v_mfma_f32_16x16x32_bf16 v[44:47], v[132:135], v[202:205], v[44:47]
	v_mfma_f32_16x16x32_bf16 v[40:43], v[136:139], v[198:201], v[40:43]
	v_mfma_f32_16x16x32_bf16 v[40:43], v[140:143], v[202:205], v[40:43]
	v_mfma_f32_16x16x32_bf16 v[28:31], v[128:131], v[206:209], v[28:31]
	v_mfma_f32_16x16x32_bf16 v[28:31], v[132:135], v[210:213], v[28:31]
	v_mfma_f32_16x16x32_bf16 v[24:27], v[136:139], v[206:209], v[24:27]
	v_mfma_f32_16x16x32_bf16 v[24:27], v[140:143], v[210:213], v[24:27]
	v_mfma_f32_16x16x32_bf16 v[12:15], v[128:131], v[214:217], v[12:15]
	v_mfma_f32_16x16x32_bf16 v[12:15], v[132:135], v[218:221], v[12:15]
	v_mfma_f32_16x16x32_bf16 v[8:11], v[136:139], v[214:217], v[8:11]
	v_mfma_f32_16x16x32_bf16 v[8:11], v[140:143], v[218:221], v[8:11]
	s_setprio 0
	s_setprio 1
	v_mfma_f32_16x16x32_bf16 v[52:55], v[144:147], v[180:183], v[52:55]
	v_mfma_f32_16x16x32_bf16 v[52:55], v[148:151], v[194:197], v[52:55]
	v_mfma_f32_16x16x32_bf16 v[48:51], v[172:175], v[180:183], v[48:51]
	v_mfma_f32_16x16x32_bf16 v[48:51], v[176:179], v[194:197], v[48:51]
	v_mfma_f32_16x16x32_bf16 v[36:39], v[144:147], v[198:201], v[36:39]
	v_mfma_f32_16x16x32_bf16 v[36:39], v[148:151], v[202:205], v[36:39]
	v_mfma_f32_16x16x32_bf16 v[32:35], v[172:175], v[198:201], v[32:35]
	v_mfma_f32_16x16x32_bf16 v[32:35], v[176:179], v[202:205], v[32:35]
	v_mfma_f32_16x16x32_bf16 v[20:23], v[144:147], v[206:209], v[20:23]
	v_mfma_f32_16x16x32_bf16 v[20:23], v[148:151], v[210:213], v[20:23]
	v_mfma_f32_16x16x32_bf16 v[16:19], v[172:175], v[206:209], v[16:19]
	v_mfma_f32_16x16x32_bf16 v[16:19], v[176:179], v[210:213], v[16:19]
	v_mfma_f32_16x16x32_bf16 v[4:7], v[144:147], v[214:217], v[4:7]
	v_mfma_f32_16x16x32_bf16 v[4:7], v[148:151], v[218:221], v[4:7]
	v_mfma_f32_16x16x32_bf16 v[0:3], v[172:175], v[214:217], v[0:3]
	v_mfma_f32_16x16x32_bf16 v[0:3], v[176:179], v[218:221], v[0:3]
	s_setprio 0
	s_barrier
	s_add_i32 s82, 0, 0x18000
	s_add_i32 s83, 0, 0x1c000
	v_add_u32_e32 v140, s82, v186
	v_add_u32_e32 v176, s83, v186
	ds_read_b128 v[128:131], v140
	ds_read_b128 v[132:135], v140 offset:1024
	ds_read_b128 v[136:139], v140 offset:2048
	ds_read_b128 v[140:143], v140 offset:3072
	ds_read_b128 v[144:147], v176
	ds_read_b128 v[148:151], v176 offset:1024
	ds_read_b128 v[172:175], v176 offset:2048
	ds_read_b128 v[176:179], v176 offset:3072
	s_add_u32 s54, s60, 0xb0000
	s_addc_u32 s55, s61, 0
	s_mov_b32 m0, s68
	v_lshl_add_u64 v[230:231], s[54:55], 0, v[152:153]
	ds_read_b128 v[180:183], v191 offset:32768
	ds_read_b128 v[194:197], v191 offset:33792
	ds_read_b128 v[198:201], v191 offset:34816
	ds_read_b128 v[202:205], v191 offset:35840
	ds_read_b128 v[206:209], v191 offset:36864
	ds_read_b128 v[210:213], v191 offset:37888
	ds_read_b128 v[214:217], v191 offset:38912
	ds_read_b128 v[218:221], v191 offset:39936
	global_load_lds_dwordx4 v[230:231], off
	v_lshl_add_u64 v[230:231], s[54:55], 0, v[160:161]
	s_mov_b32 m0, s69
	s_nop 0
	global_load_lds_dwordx4 v[230:231], off
	s_waitcnt vmcnt(8)
	s_waitcnt lgkmcnt(0)
	s_barrier
	s_setprio 1
	s_waitcnt lgkmcnt(0)
	v_mfma_f32_16x16x32_bf16 v[124:127], v[128:131], v[180:183], v[124:127]
	v_mfma_f32_16x16x32_bf16 v[124:127], v[132:135], v[194:197], v[124:127]
	v_mfma_f32_16x16x32_bf16 v[120:123], v[136:139], v[180:183], v[120:123]
	v_mfma_f32_16x16x32_bf16 v[120:123], v[140:143], v[194:197], v[120:123]
	v_mfma_f32_16x16x32_bf16 v[108:111], v[128:131], v[198:201], v[108:111]
	v_mfma_f32_16x16x32_bf16 v[108:111], v[132:135], v[202:205], v[108:111]
	v_mfma_f32_16x16x32_bf16 v[104:107], v[136:139], v[198:201], v[104:107]
	v_mfma_f32_16x16x32_bf16 v[104:107], v[140:143], v[202:205], v[104:107]
	v_mfma_f32_16x16x32_bf16 v[92:95], v[128:131], v[206:209], v[92:95]
	v_mfma_f32_16x16x32_bf16 v[92:95], v[132:135], v[210:213], v[92:95]
	v_mfma_f32_16x16x32_bf16 v[88:91], v[136:139], v[206:209], v[88:91]
	v_mfma_f32_16x16x32_bf16 v[88:91], v[140:143], v[210:213], v[88:91]
	v_mfma_f32_16x16x32_bf16 v[76:79], v[128:131], v[214:217], v[76:79]
	v_mfma_f32_16x16x32_bf16 v[76:79], v[132:135], v[218:221], v[76:79]
	v_mfma_f32_16x16x32_bf16 v[72:75], v[136:139], v[214:217], v[72:75]
	v_mfma_f32_16x16x32_bf16 v[72:75], v[140:143], v[218:221], v[72:75]
	s_setprio 0
	s_setprio 1
	v_mfma_f32_16x16x32_bf16 v[116:119], v[144:147], v[180:183], v[116:119]
	v_mfma_f32_16x16x32_bf16 v[116:119], v[148:151], v[194:197], v[116:119]
	v_mfma_f32_16x16x32_bf16 v[112:115], v[172:175], v[180:183], v[112:115]
	v_mfma_f32_16x16x32_bf16 v[112:115], v[176:179], v[194:197], v[112:115]
	v_mfma_f32_16x16x32_bf16 v[100:103], v[144:147], v[198:201], v[100:103]
	v_mfma_f32_16x16x32_bf16 v[100:103], v[148:151], v[202:205], v[100:103]
	v_mfma_f32_16x16x32_bf16 v[96:99], v[172:175], v[198:201], v[96:99]
	v_mfma_f32_16x16x32_bf16 v[96:99], v[176:179], v[202:205], v[96:99]
	v_mfma_f32_16x16x32_bf16 v[84:87], v[144:147], v[206:209], v[84:87]
	v_mfma_f32_16x16x32_bf16 v[84:87], v[148:151], v[210:213], v[84:87]
	v_mfma_f32_16x16x32_bf16 v[80:83], v[172:175], v[206:209], v[80:83]
	v_mfma_f32_16x16x32_bf16 v[80:83], v[176:179], v[210:213], v[80:83]
	v_mfma_f32_16x16x32_bf16 v[68:71], v[144:147], v[214:217], v[68:71]
	v_mfma_f32_16x16x32_bf16 v[68:71], v[148:151], v[218:221], v[68:71]
	v_mfma_f32_16x16x32_bf16 v[64:67], v[172:175], v[214:217], v[64:67]
	v_mfma_f32_16x16x32_bf16 v[64:67], v[176:179], v[218:221], v[64:67]
	s_setprio 0
	s_barrier
	s_add_i32 s54, s82, s65
	v_lshl_add_u64 v[222:223], v[222:223], 0, s[28:29]
	s_mov_b32 m0, s54
	ds_read_b128 v[180:183], v191 offset:49152
	ds_read_b128 v[194:197], v191 offset:50176
	ds_read_b128 v[198:201], v191 offset:51200
	ds_read_b128 v[202:205], v191 offset:52224
	ds_read_b128 v[206:209], v191 offset:53248
	ds_read_b128 v[210:213], v191 offset:54272
	ds_read_b128 v[214:217], v191 offset:55296
	ds_read_b128 v[218:221], v191 offset:56320
	global_load_lds_dwordx4 v[222:223], off
	s_add_i32 m0, s54, 0x2000
	s_add_u32 s54, s58, 0xb0080
	v_lshl_add_u64 v[222:223], v[224:225], 0, s[28:29]
	s_addc_u32 s55, s59, 0
	s_add_i32 s58, s83, s65
	global_load_lds_dwordx4 v[222:223], off
	v_lshl_add_u64 v[222:223], s[54:55], 0, v[154:155]
	s_mov_b32 m0, s58
	s_nop 0
	global_load_lds_dwordx4 v[222:223], off
	v_lshl_add_u64 v[222:223], s[54:55], 0, v[162:163]
	s_add_i32 m0, s58, 0x2000
	s_nop 0
	global_load_lds_dwordx4 v[222:223], off
	v_lshl_add_u64 v[222:223], v[226:227], 0, s[28:29]
	s_mov_b32 m0, s3
	s_nop 0
	global_load_lds_dwordx4 v[222:223], off
	v_lshl_add_u64 v[222:223], v[228:229], 0, s[28:29]
	s_mov_b32 m0, s71
	s_nop 0
	global_load_lds_dwordx4 v[222:223], off
	s_waitcnt vmcnt(8)
	s_waitcnt lgkmcnt(0)
	s_barrier
	s_setprio 1
	s_waitcnt lgkmcnt(0)
	v_mfma_f32_16x16x32_bf16 v[60:63], v[128:131], v[180:183], v[60:63]
	v_mfma_f32_16x16x32_bf16 v[60:63], v[132:135], v[194:197], v[60:63]
	v_mfma_f32_16x16x32_bf16 v[56:59], v[136:139], v[180:183], v[56:59]
	v_mfma_f32_16x16x32_bf16 v[56:59], v[140:143], v[194:197], v[56:59]
	v_mfma_f32_16x16x32_bf16 v[44:47], v[128:131], v[198:201], v[44:47]
	v_mfma_f32_16x16x32_bf16 v[44:47], v[132:135], v[202:205], v[44:47]
	v_mfma_f32_16x16x32_bf16 v[40:43], v[136:139], v[198:201], v[40:43]
	v_mfma_f32_16x16x32_bf16 v[40:43], v[140:143], v[202:205], v[40:43]
	v_mfma_f32_16x16x32_bf16 v[28:31], v[128:131], v[206:209], v[28:31]
	v_mfma_f32_16x16x32_bf16 v[28:31], v[132:135], v[210:213], v[28:31]
	v_mfma_f32_16x16x32_bf16 v[24:27], v[136:139], v[206:209], v[24:27]
	v_mfma_f32_16x16x32_bf16 v[24:27], v[140:143], v[210:213], v[24:27]
	v_mfma_f32_16x16x32_bf16 v[12:15], v[128:131], v[214:217], v[12:15]
	v_mfma_f32_16x16x32_bf16 v[12:15], v[132:135], v[218:221], v[12:15]
	v_mfma_f32_16x16x32_bf16 v[8:11], v[136:139], v[214:217], v[8:11]
	v_mfma_f32_16x16x32_bf16 v[8:11], v[140:143], v[218:221], v[8:11]
	s_setprio 0
	s_setprio 1
	v_mfma_f32_16x16x32_bf16 v[52:55], v[144:147], v[180:183], v[52:55]
	v_mfma_f32_16x16x32_bf16 v[52:55], v[148:151], v[194:197], v[52:55]
	v_mfma_f32_16x16x32_bf16 v[48:51], v[172:175], v[180:183], v[48:51]
	v_mfma_f32_16x16x32_bf16 v[48:51], v[176:179], v[194:197], v[48:51]
	v_mfma_f32_16x16x32_bf16 v[36:39], v[144:147], v[198:201], v[36:39]
	v_mfma_f32_16x16x32_bf16 v[36:39], v[148:151], v[202:205], v[36:39]
	v_mfma_f32_16x16x32_bf16 v[32:35], v[172:175], v[198:201], v[32:35]
	v_mfma_f32_16x16x32_bf16 v[32:35], v[176:179], v[202:205], v[32:35]
	v_mfma_f32_16x16x32_bf16 v[20:23], v[144:147], v[206:209], v[20:23]
	v_mfma_f32_16x16x32_bf16 v[20:23], v[148:151], v[210:213], v[20:23]
	v_mfma_f32_16x16x32_bf16 v[16:19], v[172:175], v[206:209], v[16:19]
	v_mfma_f32_16x16x32_bf16 v[16:19], v[176:179], v[210:213], v[16:19]
	v_mfma_f32_16x16x32_bf16 v[4:7], v[144:147], v[214:217], v[4:7]
	v_mfma_f32_16x16x32_bf16 v[4:7], v[148:151], v[218:221], v[4:7]
	v_mfma_f32_16x16x32_bf16 v[0:3], v[172:175], v[214:217], v[0:3]
	v_mfma_f32_16x16x32_bf16 v[0:3], v[176:179], v[218:221], v[0:3]
	s_setprio 0
	s_barrier
	s_add_i32 s81, s81, 2
	s_add_u32 s79, s79, 0x100
	s_addc_u32 s80, s80, 0
	s_cmp_gt_u32 s81, 41
	s_mov_b64 s[54:55], s[56:57]
	s_cbranch_scc0 .LBB0_610
	s_and_b64 vcc, exec, s[30:31]
	s_cbranch_vccz .LBB0_613
	s_barrier

.LBB0_873:
	s_ashr_i32 s49, s48, 31
	s_lshl_b64 s[50:51], s[48:49], 19
	s_add_u32 s50, s35, s50
	s_addc_u32 s51, s60, s51
	s_and_b64 s[52:53], s[10:11], exec
	s_cselect_b32 s49, s51, s59
	s_cselect_b32 s80, s50, s58
	s_ashr_i32 s47, s46, 31
	s_lshl_b64 s[52:53], s[46:47], 19
	s_add_u32 s52, s61, s52
	s_addc_u32 s53, s62, s53
	s_and_b64 s[82:83], s[10:11], exec
	s_cselect_b32 s81, s53, s57
	s_cselect_b32 s82, s52, s56
	s_lshl_b32 s47, s54, 8
	v_add_u32_e32 v0, s47, v151
	s_add_u32 s83, s56, 0x100
	v_ashrrev_i32_e32 v1, 31, v0
	s_addc_u32 s84, s57, 0
	v_lshl_add_u64 v[144:145], v[0:1], 4, s[20:21]
	s_add_u32 s54, s58, 0x40080
	s_addc_u32 s55, s59, 0
	s_mov_b32 s85, -2
	s_mov_b64 s[56:57], 0
	s_cmp_eq_u32 s68, 1
	s_cbranch_scc1 .Lfa_8
	v_add_u32_e32 v146, s73, v149
	ds_read_b128 v[162:165], v146
	ds_read_b128 v[166:169], v146 offset:1024
	ds_read_b128 v[170:173], v146 offset:2048
	ds_read_b128 v[174:177], v146 offset:3072
	v_add_u32_e32 v146, s74, v149
	ds_read_b128 v[178:181], v146
	ds_read_b128 v[186:189], v146 offset:1024
	ds_read_b128 v[190:193], v146 offset:2048
	ds_read_b128 v[194:197], v146 offset:3072
	s_add_u32 s58, s54, 0xfffc0080
	s_addc_u32 s59, s55, -1
	s_and_b64 s[56:57], s[56:57], exec
	s_cselect_b32 s59, s49, s59
	s_cselect_b32 s58, s80, s58
	s_cselect_b32 s57, s81, s84
	s_cselect_b32 s56, s82, s83
	v_lshl_add_u64 v[182:183], s[54:55], 0, v[138:139]
	s_add_i32 m0, s64, 0xc000
	ds_read_b128 v[198:201], v154
	ds_read_b128 v[202:205], v154 offset:1024
	ds_read_b128 v[206:209], v154 offset:2048
	ds_read_b128 v[210:213], v154 offset:3072
	ds_read_b128 v[214:217], v154 offset:4096
	ds_read_b128 v[218:221], v154 offset:5120
	ds_read_b128 v[222:225], v154 offset:6144
	ds_read_b128 v[226:229], v154 offset:7168
	global_load_lds_dwordx4 v[182:183], off
	v_lshl_add_u64 v[182:183], s[54:55], 0, v[136:137]
	s_add_i32 m0, s64, 0xe000
	s_nop 0
	global_load_lds_dwordx4 v[182:183], off
	s_waitcnt vmcnt(24)
	s_waitcnt lgkmcnt(0)
	s_barrier
	s_setprio 1
	s_waitcnt lgkmcnt(0)
	v_mfma_f32_16x16x32_bf16 v[124:127], v[162:165], v[198:201], 0
	v_mfma_f32_16x16x32_bf16 v[120:123], v[170:173], v[198:201], 0
	v_mfma_f32_16x16x32_bf16 v[112:115], v[162:165], v[206:209], 0
	v_mfma_f32_16x16x32_bf16 v[104:107], v[170:173], v[206:209], 0
	v_mfma_f32_16x16x32_bf16 v[96:99], v[162:165], v[214:217], 0
	v_mfma_f32_16x16x32_bf16 v[88:91], v[170:173], v[214:217], 0
	v_mfma_f32_16x16x32_bf16 v[80:83], v[162:165], v[222:225], 0
	v_mfma_f32_16x16x32_bf16 v[72:75], v[170:173], v[222:225], 0
	v_mfma_f32_16x16x32_bf16 v[124:127], v[166:169], v[202:205], v[124:127]
	v_mfma_f32_16x16x32_bf16 v[120:123], v[174:177], v[202:205], v[120:123]
	v_mfma_f32_16x16x32_bf16 v[112:115], v[166:169], v[210:213], v[112:115]
	v_mfma_f32_16x16x32_bf16 v[104:107], v[174:177], v[210:213], v[104:107]
	v_mfma_f32_16x16x32_bf16 v[96:99], v[166:169], v[218:221], v[96:99]
	v_mfma_f32_16x16x32_bf16 v[88:91], v[174:177], v[218:221], v[88:91]
	v_mfma_f32_16x16x32_bf16 v[80:83], v[166:169], v[226:229], v[80:83]
	v_mfma_f32_16x16x32_bf16 v[72:75], v[174:177], v[226:229], v[72:75]
	s_setprio 0
	s_setprio 1
	v_mfma_f32_16x16x32_bf16 v[116:119], v[178:181], v[198:201], 0
	v_mfma_f32_16x16x32_bf16 v[108:111], v[190:193], v[198:201], 0
	v_mfma_f32_16x16x32_bf16 v[100:103], v[178:181], v[206:209], 0
	v_mfma_f32_16x16x32_bf16 v[92:95], v[190:193], v[206:209], 0
	v_mfma_f32_16x16x32_bf16 v[84:87], v[178:181], v[214:217], 0
	v_mfma_f32_16x16x32_bf16 v[76:79], v[190:193], v[214:217], 0
	v_mfma_f32_16x16x32_bf16 v[68:71], v[178:181], v[222:225], 0
	v_mfma_f32_16x16x32_bf16 v[64:67], v[190:193], v[222:225], 0
	v_mfma_f32_16x16x32_bf16 v[116:119], v[186:189], v[202:205], v[116:119]
	v_mfma_f32_16x16x32_bf16 v[108:111], v[194:197], v[202:205], v[108:111]
	v_mfma_f32_16x16x32_bf16 v[100:103], v[186:189], v[210:213], v[100:103]
	v_mfma_f32_16x16x32_bf16 v[92:95], v[194:197], v[210:213], v[92:95]
	v_mfma_f32_16x16x32_bf16 v[84:87], v[186:189], v[218:221], v[84:87]
	v_mfma_f32_16x16x32_bf16 v[76:79], v[194:197], v[218:221], v[76:79]
	v_mfma_f32_16x16x32_bf16 v[68:71], v[186:189], v[226:229], v[68:71]
	v_mfma_f32_16x16x32_bf16 v[64:67], v[194:197], v[226:229], v[64:67]
	s_setprio 0
	s_barrier
	s_add_i32 s86, s73, s63
	v_lshl_add_u64 v[182:183], s[56:57], 0, v[130:131]
	s_mov_b32 m0, s86
	ds_read_b128 v[198:201], v154 offset:16384
	ds_read_b128 v[202:205], v154 offset:17408
	ds_read_b128 v[206:209], v154 offset:18432
	ds_read_b128 v[210:213], v154 offset:19456
	ds_read_b128 v[214:217], v154 offset:20480
	ds_read_b128 v[218:221], v154 offset:21504
	ds_read_b128 v[222:225], v154 offset:22528
	ds_read_b128 v[226:229], v154 offset:23552
	global_load_lds_dwordx4 v[182:183], off
	s_add_i32 m0, s86, 0x2000
	s_add_u32 s86, s56, 0x40000
	v_lshl_add_u64 v[230:231], s[56:57], 0, v[134:135]
	s_addc_u32 s87, s57, 0
	s_add_i32 s88, s74, s63
	global_load_lds_dwordx4 v[230:231], off
	v_lshl_add_u64 v[232:233], s[86:87], 0, v[130:131]
	s_mov_b32 m0, s88
	v_lshl_add_u64 v[234:235], s[58:59], 0, v[132:133]
	global_load_lds_dwordx4 v[232:233], off
	v_lshl_add_u64 v[232:233], s[86:87], 0, v[134:135]
	s_add_i32 m0, s88, 0x2000
	s_nop 0
	global_load_lds_dwordx4 v[232:233], off
	v_lshl_add_u64 v[232:233], s[58:59], 0, v[128:129]
	s_mov_b32 m0, s64
	s_nop 0
	global_load_lds_dwordx4 v[232:233], off
	s_mov_b32 m0, s65
	s_nop 0
	global_load_lds_dwordx4 v[234:235], off
	s_waitcnt vmcnt(24)
	s_waitcnt lgkmcnt(0)
	s_barrier
	s_setprio 1
	s_waitcnt lgkmcnt(0)
	v_mfma_f32_16x16x32_bf16 v[60:63], v[162:165], v[198:201], 0
	v_mfma_f32_16x16x32_bf16 v[56:59], v[170:173], v[198:201], 0
	v_mfma_f32_16x16x32_bf16 v[48:51], v[162:165], v[206:209], 0
	v_mfma_f32_16x16x32_bf16 v[40:43], v[170:173], v[206:209], 0
	v_mfma_f32_16x16x32_bf16 v[32:35], v[162:165], v[214:217], 0
	v_mfma_f32_16x16x32_bf16 v[24:27], v[170:173], v[214:217], 0
	v_mfma_f32_16x16x32_bf16 v[16:19], v[162:165], v[222:225], 0
	v_mfma_f32_16x16x32_bf16 v[8:11], v[170:173], v[222:225], 0
	v_mfma_f32_16x16x32_bf16 v[60:63], v[166:169], v[202:205], v[60:63]
	v_mfma_f32_16x16x32_bf16 v[56:59], v[174:177], v[202:205], v[56:59]
	v_mfma_f32_16x16x32_bf16 v[48:51], v[166:169], v[210:213], v[48:51]
	v_mfma_f32_16x16x32_bf16 v[40:43], v[174:177], v[210:213], v[40:43]
	v_mfma_f32_16x16x32_bf16 v[32:35], v[166:169], v[218:221], v[32:35]
	v_mfma_f32_16x16x32_bf16 v[24:27], v[174:177], v[218:221], v[24:27]
	v_mfma_f32_16x16x32_bf16 v[16:19], v[166:169], v[226:229], v[16:19]
	v_mfma_f32_16x16x32_bf16 v[8:11], v[174:177], v[226:229], v[8:11]
	s_setprio 0
	s_setprio 1
	v_mfma_f32_16x16x32_bf16 v[52:55], v[178:181], v[198:201], 0
	v_mfma_f32_16x16x32_bf16 v[44:47], v[190:193], v[198:201], 0
	v_mfma_f32_16x16x32_bf16 v[36:39], v[178:181], v[206:209], 0
	v_mfma_f32_16x16x32_bf16 v[28:31], v[190:193], v[206:209], 0
	v_mfma_f32_16x16x32_bf16 v[20:23], v[178:181], v[214:217], 0
	v_mfma_f32_16x16x32_bf16 v[12:15], v[190:193], v[214:217], 0
	v_mfma_f32_16x16x32_bf16 v[4:7], v[178:181], v[222:225], 0
	v_mfma_f32_16x16x32_bf16 v[0:3], v[190:193], v[222:225], 0
	v_mfma_f32_16x16x32_bf16 v[52:55], v[186:189], v[202:205], v[52:55]
	v_mfma_f32_16x16x32_bf16 v[44:47], v[194:197], v[202:205], v[44:47]
	v_mfma_f32_16x16x32_bf16 v[36:39], v[186:189], v[210:213], v[36:39]
	v_mfma_f32_16x16x32_bf16 v[28:31], v[194:197], v[210:213], v[28:31]
	v_mfma_f32_16x16x32_bf16 v[20:23], v[186:189], v[218:221], v[20:23]
	v_mfma_f32_16x16x32_bf16 v[12:15], v[194:197], v[218:221], v[12:15]
	v_mfma_f32_16x16x32_bf16 v[4:7], v[186:189], v[226:229], v[4:7]
	v_mfma_f32_16x16x32_bf16 v[0:3], v[194:197], v[226:229], v[0:3]
	s_setprio 0
	s_barrier
	s_add_i32 s86, 0, 0x18000
	v_add_u32_e32 v146, s86, v149
	s_add_i32 s87, 0, 0x1c000
	ds_read_b128 v[162:165], v146
	ds_read_b128 v[166:169], v146 offset:1024
	ds_read_b128 v[170:173], v146 offset:2048
	ds_read_b128 v[174:177], v146 offset:3072
	v_add_u32_e32 v146, s87, v149
	ds_read_b128 v[178:181], v146
	ds_read_b128 v[186:189], v146 offset:1024
	ds_read_b128 v[190:193], v146 offset:2048
	ds_read_b128 v[194:197], v146 offset:3072
	s_add_u32 s58, s58, 0x40000
	s_addc_u32 s59, s59, 0
	s_mov_b32 m0, s66
	v_lshl_add_u64 v[236:237], s[58:59], 0, v[128:129]
	ds_read_b128 v[198:201], v154 offset:32768
	ds_read_b128 v[202:205], v154 offset:33792
	ds_read_b128 v[206:209], v154 offset:34816
	ds_read_b128 v[210:213], v154 offset:35840
	ds_read_b128 v[214:217], v154 offset:36864
	ds_read_b128 v[218:221], v154 offset:37888
	ds_read_b128 v[222:225], v154 offset:38912
	ds_read_b128 v[226:229], v154 offset:39936
	global_load_lds_dwordx4 v[236:237], off
	v_lshl_add_u64 v[236:237], s[58:59], 0, v[132:133]
	s_mov_b32 m0, s67
	s_nop 0
	global_load_lds_dwordx4 v[236:237], off
	s_waitcnt vmcnt(8)
	s_waitcnt lgkmcnt(0)
	s_barrier
	s_setprio 1
	s_waitcnt lgkmcnt(0)
	v_mfma_f32_16x16x32_bf16 v[124:127], v[162:165], v[198:201], v[124:127]
	v_mfma_f32_16x16x32_bf16 v[124:127], v[166:169], v[202:205], v[124:127]
	v_mfma_f32_16x16x32_bf16 v[120:123], v[170:173], v[198:201], v[120:123]
	v_mfma_f32_16x16x32_bf16 v[120:123], v[174:177], v[202:205], v[120:123]
	v_mfma_f32_16x16x32_bf16 v[112:115], v[162:165], v[206:209], v[112:115]
	v_mfma_f32_16x16x32_bf16 v[112:115], v[166:169], v[210:213], v[112:115]
	v_mfma_f32_16x16x32_bf16 v[104:107], v[170:173], v[206:209], v[104:107]
	v_mfma_f32_16x16x32_bf16 v[104:107], v[174:177], v[210:213], v[104:107]
	v_mfma_f32_16x16x32_bf16 v[96:99], v[162:165], v[214:217], v[96:99]
	v_mfma_f32_16x16x32_bf16 v[96:99], v[166:169], v[218:221], v[96:99]
	v_mfma_f32_16x16x32_bf16 v[88:91], v[170:173], v[214:217], v[88:91]
	v_mfma_f32_16x16x32_bf16 v[88:91], v[174:177], v[218:221], v[88:91]
	v_mfma_f32_16x16x32_bf16 v[80:83], v[162:165], v[222:225], v[80:83]
	v_mfma_f32_16x16x32_bf16 v[80:83], v[166:169], v[226:229], v[80:83]
	v_mfma_f32_16x16x32_bf16 v[72:75], v[170:173], v[222:225], v[72:75]
	v_mfma_f32_16x16x32_bf16 v[72:75], v[174:177], v[226:229], v[72:75]
	s_setprio 0
	s_setprio 1
	v_mfma_f32_16x16x32_bf16 v[116:119], v[178:181], v[198:201], v[116:119]
	v_mfma_f32_16x16x32_bf16 v[116:119], v[186:189], v[202:205], v[116:119]
	v_mfma_f32_16x16x32_bf16 v[108:111], v[190:193], v[198:201], v[108:111]
	v_mfma_f32_16x16x32_bf16 v[108:111], v[194:197], v[202:205], v[108:111]
	v_mfma_f32_16x16x32_bf16 v[100:103], v[178:181], v[206:209], v[100:103]
	v_mfma_f32_16x16x32_bf16 v[100:103], v[186:189], v[210:213], v[100:103]
	v_mfma_f32_16x16x32_bf16 v[92:95], v[190:193], v[206:209], v[92:95]
	v_mfma_f32_16x16x32_bf16 v[92:95], v[194:197], v[210:213], v[92:95]
	v_mfma_f32_16x16x32_bf16 v[84:87], v[178:181], v[214:217], v[84:87]
	v_mfma_f32_16x16x32_bf16 v[84:87], v[186:189], v[218:221], v[84:87]
	v_mfma_f32_16x16x32_bf16 v[76:79], v[190:193], v[214:217], v[76:79]
	v_mfma_f32_16x16x32_bf16 v[76:79], v[194:197], v[218:221], v[76:79]
	v_mfma_f32_16x16x32_bf16 v[68:71], v[178:181], v[222:225], v[68:71]
	v_mfma_f32_16x16x32_bf16 v[68:71], v[186:189], v[226:229], v[68:71]
	v_mfma_f32_16x16x32_bf16 v[64:67], v[190:193], v[222:225], v[64:67]
	v_mfma_f32_16x16x32_bf16 v[64:67], v[194:197], v[226:229], v[64:67]
	s_setprio 0
	s_barrier
	s_add_i32 s58, s86, s63
	v_lshl_add_u64 v[182:183], v[182:183], 0, s[22:23]
	s_mov_b32 m0, s58
	ds_read_b128 v[198:201], v154 offset:49152
	ds_read_b128 v[202:205], v154 offset:50176
	ds_read_b128 v[206:209], v154 offset:51200
	ds_read_b128 v[210:213], v154 offset:52224
	ds_read_b128 v[214:217], v154 offset:53248
	ds_read_b128 v[218:221], v154 offset:54272
	ds_read_b128 v[222:225], v154 offset:55296
	ds_read_b128 v[226:229], v154 offset:56320
	global_load_lds_dwordx4 v[182:183], off
	s_add_i32 m0, s58, 0x2000
	s_add_u32 s56, s56, 0x40080
	v_lshl_add_u64 v[182:183], v[230:231], 0, s[22:23]
	s_addc_u32 s57, s57, 0
	s_add_i32 s58, s87, s63
	global_load_lds_dwordx4 v[182:183], off
	v_lshl_add_u64 v[182:183], s[56:57], 0, v[130:131]
	s_mov_b32 m0, s58
	s_nop 0
	global_load_lds_dwordx4 v[182:183], off
	v_lshl_add_u64 v[182:183], s[56:57], 0, v[134:135]
	s_add_i32 m0, s58, 0x2000
	s_nop 0
	global_load_lds_dwordx4 v[182:183], off
	v_lshl_add_u64 v[182:183], v[232:233], 0, s[22:23]
	s_mov_b32 m0, s69
	s_nop 0
	global_load_lds_dwordx4 v[182:183], off
	v_lshl_add_u64 v[182:183], v[234:235], 0, s[22:23]
	s_mov_b32 m0, s70
	s_nop 0
	global_load_lds_dwordx4 v[182:183], off
	s_waitcnt vmcnt(8)
	s_waitcnt lgkmcnt(0)
	s_barrier
	s_setprio 1
	s_waitcnt lgkmcnt(0)
	v_mfma_f32_16x16x32_bf16 v[60:63], v[162:165], v[198:201], v[60:63]
	v_mfma_f32_16x16x32_bf16 v[60:63], v[166:169], v[202:205], v[60:63]
	v_mfma_f32_16x16x32_bf16 v[56:59], v[170:173], v[198:201], v[56:59]
	v_mfma_f32_16x16x32_bf16 v[56:59], v[174:177], v[202:205], v[56:59]
	v_mfma_f32_16x16x32_bf16 v[48:51], v[162:165], v[206:209], v[48:51]
	v_mfma_f32_16x16x32_bf16 v[48:51], v[166:169], v[210:213], v[48:51]
	v_mfma_f32_16x16x32_bf16 v[40:43], v[170:173], v[206:209], v[40:43]
	v_mfma_f32_16x16x32_bf16 v[40:43], v[174:177], v[210:213], v[40:43]
	v_mfma_f32_16x16x32_bf16 v[32:35], v[162:165], v[214:217], v[32:35]
	v_mfma_f32_16x16x32_bf16 v[32:35], v[166:169], v[218:221], v[32:35]
	v_mfma_f32_16x16x32_bf16 v[24:27], v[170:173], v[214:217], v[24:27]
	v_mfma_f32_16x16x32_bf16 v[24:27], v[174:177], v[218:221], v[24:27]
	v_mfma_f32_16x16x32_bf16 v[16:19], v[162:165], v[222:225], v[16:19]
	v_mfma_f32_16x16x32_bf16 v[16:19], v[166:169], v[226:229], v[16:19]
	v_mfma_f32_16x16x32_bf16 v[8:11], v[170:173], v[222:225], v[8:11]
	v_mfma_f32_16x16x32_bf16 v[8:11], v[174:177], v[226:229], v[8:11]
	s_setprio 0
	s_setprio 1
	v_mfma_f32_16x16x32_bf16 v[52:55], v[178:181], v[198:201], v[52:55]
	v_mfma_f32_16x16x32_bf16 v[52:55], v[186:189], v[202:205], v[52:55]
	v_mfma_f32_16x16x32_bf16 v[44:47], v[190:193], v[198:201], v[44:47]
	v_mfma_f32_16x16x32_bf16 v[44:47], v[194:197], v[202:205], v[44:47]
	v_mfma_f32_16x16x32_bf16 v[36:39], v[178:181], v[206:209], v[36:39]
	v_mfma_f32_16x16x32_bf16 v[36:39], v[186:189], v[210:213], v[36:39]
	v_mfma_f32_16x16x32_bf16 v[28:31], v[190:193], v[206:209], v[28:31]
	v_mfma_f32_16x16x32_bf16 v[28:31], v[194:197], v[210:213], v[28:31]
	v_mfma_f32_16x16x32_bf16 v[20:23], v[178:181], v[214:217], v[20:23]
	v_mfma_f32_16x16x32_bf16 v[20:23], v[186:189], v[218:221], v[20:23]
	v_mfma_f32_16x16x32_bf16 v[12:15], v[190:193], v[214:217], v[12:15]
	v_mfma_f32_16x16x32_bf16 v[12:15], v[194:197], v[218:221], v[12:15]
	v_mfma_f32_16x16x32_bf16 v[4:7], v[178:181], v[222:225], v[4:7]
	v_mfma_f32_16x16x32_bf16 v[4:7], v[186:189], v[226:229], v[4:7]
	v_mfma_f32_16x16x32_bf16 v[0:3], v[190:193], v[222:225], v[0:3]
	v_mfma_f32_16x16x32_bf16 v[0:3], v[194:197], v[226:229], v[0:3]
	s_setprio 0
	s_barrier
	s_add_i32 s85, s85, 2
	s_add_u32 s83, s83, 0x100
	s_addc_u32 s84, s84, 0
	s_add_u32 s54, s54, 0x100
	s_addc_u32 s55, s55, 0
	s_branch .LBB0_875
.Lfa_8:
	v_add_u32_e32 v146, s73, v149
	ds_read_b128 v[162:165], v146
	ds_read_b128 v[166:169], v146 offset:1024
	ds_read_b128 v[170:173], v146 offset:2048
	ds_read_b128 v[174:177], v146 offset:3072
	v_add_u32_e32 v146, s74, v149
	ds_read_b128 v[178:181], v146
	ds_read_b128 v[186:189], v146 offset:1024
	ds_read_b128 v[190:193], v146 offset:2048
	ds_read_b128 v[194:197], v146 offset:3072
	s_add_u32 s58, s54, 0xfffc0080
	s_addc_u32 s59, s55, -1
	s_and_b64 s[56:57], s[56:57], exec
	s_cselect_b32 s59, s49, s59
	s_cselect_b32 s58, s80, s58
	s_cselect_b32 s57, s81, s84
	s_cselect_b32 s56, s82, s83
	v_lshl_add_u64 v[182:183], s[54:55], 0, v[138:139]
	s_add_i32 m0, s64, 0xc000
	ds_read_b128 v[198:201], v154
	ds_read_b128 v[202:205], v154 offset:1024
	ds_read_b128 v[206:209], v154 offset:2048
	ds_read_b128 v[210:213], v154 offset:3072
	ds_read_b128 v[214:217], v154 offset:4096
	ds_read_b128 v[218:221], v154 offset:5120
	ds_read_b128 v[222:225], v154 offset:6144
	ds_read_b128 v[226:229], v154 offset:7168
	global_load_lds_dwordx4 v[182:183], off
	v_lshl_add_u64 v[182:183], s[54:55], 0, v[136:137]
	s_add_i32 m0, s64, 0xe000
	s_nop 0
	global_load_lds_dwordx4 v[182:183], off
	s_waitcnt vmcnt(8)
	s_waitcnt lgkmcnt(0)
	s_barrier
	s_setprio 1
	s_waitcnt lgkmcnt(0)
	v_mfma_f32_16x16x32_bf16 v[124:127], v[162:165], v[198:201], 0
	v_mfma_f32_16x16x32_bf16 v[120:123], v[170:173], v[198:201], 0
	v_mfma_f32_16x16x32_bf16 v[112:115], v[162:165], v[206:209], 0
	v_mfma_f32_16x16x32_bf16 v[104:107], v[170:173], v[206:209], 0
	v_mfma_f32_16x16x32_bf16 v[96:99], v[162:165], v[214:217], 0
	v_mfma_f32_16x16x32_bf16 v[88:91], v[170:173], v[214:217], 0
	v_mfma_f32_16x16x32_bf16 v[80:83], v[162:165], v[222:225], 0
	v_mfma_f32_16x16x32_bf16 v[72:75], v[170:173], v[222:225], 0
	v_mfma_f32_16x16x32_bf16 v[124:127], v[166:169], v[202:205], v[124:127]
	v_mfma_f32_16x16x32_bf16 v[120:123], v[174:177], v[202:205], v[120:123]
	v_mfma_f32_16x16x32_bf16 v[112:115], v[166:169], v[210:213], v[112:115]
	v_mfma_f32_16x16x32_bf16 v[104:107], v[174:177], v[210:213], v[104:107]
	v_mfma_f32_16x16x32_bf16 v[96:99], v[166:169], v[218:221], v[96:99]
	v_mfma_f32_16x16x32_bf16 v[88:91], v[174:177], v[218:221], v[88:91]
	v_mfma_f32_16x16x32_bf16 v[80:83], v[166:169], v[226:229], v[80:83]
	v_mfma_f32_16x16x32_bf16 v[72:75], v[174:177], v[226:229], v[72:75]
	s_setprio 0
	s_setprio 1
	v_mfma_f32_16x16x32_bf16 v[116:119], v[178:181], v[198:201], 0
	v_mfma_f32_16x16x32_bf16 v[108:111], v[190:193], v[198:201], 0
	v_mfma_f32_16x16x32_bf16 v[100:103], v[178:181], v[206:209], 0
	v_mfma_f32_16x16x32_bf16 v[92:95], v[190:193], v[206:209], 0
	v_mfma_f32_16x16x32_bf16 v[84:87], v[178:181], v[214:217], 0
	v_mfma_f32_16x16x32_bf16 v[76:79], v[190:193], v[214:217], 0
	v_mfma_f32_16x16x32_bf16 v[68:71], v[178:181], v[222:225], 0
	v_mfma_f32_16x16x32_bf16 v[64:67], v[190:193], v[222:225], 0
	v_mfma_f32_16x16x32_bf16 v[116:119], v[186:189], v[202:205], v[116:119]
	v_mfma_f32_16x16x32_bf16 v[108:111], v[194:197], v[202:205], v[108:111]
	v_mfma_f32_16x16x32_bf16 v[100:103], v[186:189], v[210:213], v[100:103]
	v_mfma_f32_16x16x32_bf16 v[92:95], v[194:197], v[210:213], v[92:95]
	v_mfma_f32_16x16x32_bf16 v[84:87], v[186:189], v[218:221], v[84:87]
	v_mfma_f32_16x16x32_bf16 v[76:79], v[194:197], v[218:221], v[76:79]
	v_mfma_f32_16x16x32_bf16 v[68:71], v[186:189], v[226:229], v[68:71]
	v_mfma_f32_16x16x32_bf16 v[64:67], v[194:197], v[226:229], v[64:67]
	s_setprio 0
	s_barrier
	s_add_i32 s86, s73, s63
	v_lshl_add_u64 v[182:183], s[56:57], 0, v[130:131]
	s_mov_b32 m0, s86
	ds_read_b128 v[198:201], v154 offset:16384
	ds_read_b128 v[202:205], v154 offset:17408
	ds_read_b128 v[206:209], v154 offset:18432
	ds_read_b128 v[210:213], v154 offset:19456
	ds_read_b128 v[214:217], v154 offset:20480
	ds_read_b128 v[218:221], v154 offset:21504
	ds_read_b128 v[222:225], v154 offset:22528
	ds_read_b128 v[226:229], v154 offset:23552
	global_load_lds_dwordx4 v[182:183], off
	s_add_i32 m0, s86, 0x2000
	s_add_u32 s86, s56, 0x40000
	v_lshl_add_u64 v[230:231], s[56:57], 0, v[134:135]
	s_addc_u32 s87, s57, 0
	s_add_i32 s88, s74, s63
	global_load_lds_dwordx4 v[230:231], off
	v_lshl_add_u64 v[232:233], s[86:87], 0, v[130:131]
	s_mov_b32 m0, s88
	v_lshl_add_u64 v[234:235], s[58:59], 0, v[132:133]
	global_load_lds_dwordx4 v[232:233], off
	v_lshl_add_u64 v[232:233], s[86:87], 0, v[134:135]
	s_add_i32 m0, s88, 0x2000
	s_nop 0
	global_load_lds_dwordx4 v[232:233], off
	v_lshl_add_u64 v[232:233], s[58:59], 0, v[128:129]
	s_mov_b32 m0, s64
	s_nop 0
	global_load_lds_dwordx4 v[232:233], off
	s_mov_b32 m0, s65
	s_nop 0
	global_load_lds_dwordx4 v[234:235], off
	s_waitcnt vmcnt(8)
	s_waitcnt lgkmcnt(0)
	s_barrier
	s_setprio 1
	s_waitcnt lgkmcnt(0)
	v_mfma_f32_16x16x32_bf16 v[60:63], v[162:165], v[198:201], 0
	v_mfma_f32_16x16x32_bf16 v[56:59], v[170:173], v[198:201], 0
	v_mfma_f32_16x16x32_bf16 v[48:51], v[162:165], v[206:209], 0
	v_mfma_f32_16x16x32_bf16 v[40:43], v[170:173], v[206:209], 0
	v_mfma_f32_16x16x32_bf16 v[32:35], v[162:165], v[214:217], 0
	v_mfma_f32_16x16x32_bf16 v[24:27], v[170:173], v[214:217], 0
	v_mfma_f32_16x16x32_bf16 v[16:19], v[162:165], v[222:225], 0
	v_mfma_f32_16x16x32_bf16 v[8:11], v[170:173], v[222:225], 0
	v_mfma_f32_16x16x32_bf16 v[60:63], v[166:169], v[202:205], v[60:63]
	v_mfma_f32_16x16x32_bf16 v[56:59], v[174:177], v[202:205], v[56:59]
	v_mfma_f32_16x16x32_bf16 v[48:51], v[166:169], v[210:213], v[48:51]
	v_mfma_f32_16x16x32_bf16 v[40:43], v[174:177], v[210:213], v[40:43]
	v_mfma_f32_16x16x32_bf16 v[32:35], v[166:169], v[218:221], v[32:35]
	v_mfma_f32_16x16x32_bf16 v[24:27], v[174:177], v[218:221], v[24:27]
	v_mfma_f32_16x16x32_bf16 v[16:19], v[166:169], v[226:229], v[16:19]
	v_mfma_f32_16x16x32_bf16 v[8:11], v[174:177], v[226:229], v[8:11]
	s_setprio 0
	s_setprio 1
	v_mfma_f32_16x16x32_bf16 v[52:55], v[178:181], v[198:201], 0
	v_mfma_f32_16x16x32_bf16 v[44:47], v[190:193], v[198:201], 0
	v_mfma_f32_16x16x32_bf16 v[36:39], v[178:181], v[206:209], 0
	v_mfma_f32_16x16x32_bf16 v[28:31], v[190:193], v[206:209], 0
	v_mfma_f32_16x16x32_bf16 v[20:23], v[178:181], v[214:217], 0
	v_mfma_f32_16x16x32_bf16 v[12:15], v[190:193], v[214:217], 0
	v_mfma_f32_16x16x32_bf16 v[4:7], v[178:181], v[222:225], 0
	v_mfma_f32_16x16x32_bf16 v[0:3], v[190:193], v[222:225], 0
	v_mfma_f32_16x16x32_bf16 v[52:55], v[186:189], v[202:205], v[52:55]
	v_mfma_f32_16x16x32_bf16 v[44:47], v[194:197], v[202:205], v[44:47]
	v_mfma_f32_16x16x32_bf16 v[36:39], v[186:189], v[210:213], v[36:39]
	v_mfma_f32_16x16x32_bf16 v[28:31], v[194:197], v[210:213], v[28:31]
	v_mfma_f32_16x16x32_bf16 v[20:23], v[186:189], v[218:221], v[20:23]
	v_mfma_f32_16x16x32_bf16 v[12:15], v[194:197], v[218:221], v[12:15]
	v_mfma_f32_16x16x32_bf16 v[4:7], v[186:189], v[226:229], v[4:7]
	v_mfma_f32_16x16x32_bf16 v[0:3], v[194:197], v[226:229], v[0:3]
	s_setprio 0
	s_barrier
	s_add_i32 s86, 0, 0x18000
	v_add_u32_e32 v146, s86, v149
	s_add_i32 s87, 0, 0x1c000
	ds_read_b128 v[162:165], v146
	ds_read_b128 v[166:169], v146 offset:1024
	ds_read_b128 v[170:173], v146 offset:2048
	ds_read_b128 v[174:177], v146 offset:3072
	v_add_u32_e32 v146, s87, v149
	ds_read_b128 v[178:181], v146
	ds_read_b128 v[186:189], v146 offset:1024
	ds_read_b128 v[190:193], v146 offset:2048
	ds_read_b128 v[194:197], v146 offset:3072
	s_add_u32 s58, s58, 0x40000
	s_addc_u32 s59, s59, 0
	s_mov_b32 m0, s66
	v_lshl_add_u64 v[236:237], s[58:59], 0, v[128:129]
	ds_read_b128 v[198:201], v154 offset:32768
	ds_read_b128 v[202:205], v154 offset:33792
	ds_read_b128 v[206:209], v154 offset:34816
	ds_read_b128 v[210:213], v154 offset:35840
	ds_read_b128 v[214:217], v154 offset:36864
	ds_read_b128 v[218:221], v154 offset:37888
	ds_read_b128 v[222:225], v154 offset:38912
	ds_read_b128 v[226:229], v154 offset:39936
	global_load_lds_dwordx4 v[236:237], off
	v_lshl_add_u64 v[236:237], s[58:59], 0, v[132:133]
	s_mov_b32 m0, s67
	s_nop 0
	global_load_lds_dwordx4 v[236:237], off
	s_waitcnt vmcnt(8)
	s_waitcnt lgkmcnt(0)
	s_barrier
	s_setprio 1
	s_waitcnt lgkmcnt(0)
	v_mfma_f32_16x16x32_bf16 v[124:127], v[162:165], v[198:201], v[124:127]
	v_mfma_f32_16x16x32_bf16 v[124:127], v[166:169], v[202:205], v[124:127]
	v_mfma_f32_16x16x32_bf16 v[120:123], v[170:173], v[198:201], v[120:123]
	v_mfma_f32_16x16x32_bf16 v[120:123], v[174:177], v[202:205], v[120:123]
	v_mfma_f32_16x16x32_bf16 v[112:115], v[162:165], v[206:209], v[112:115]
	v_mfma_f32_16x16x32_bf16 v[112:115], v[166:169], v[210:213], v[112:115]
	v_mfma_f32_16x16x32_bf16 v[104:107], v[170:173], v[206:209], v[104:107]
	v_mfma_f32_16x16x32_bf16 v[104:107], v[174:177], v[210:213], v[104:107]
	v_mfma_f32_16x16x32_bf16 v[96:99], v[162:165], v[214:217], v[96:99]
	v_mfma_f32_16x16x32_bf16 v[96:99], v[166:169], v[218:221], v[96:99]
	v_mfma_f32_16x16x32_bf16 v[88:91], v[170:173], v[214:217], v[88:91]
	v_mfma_f32_16x16x32_bf16 v[88:91], v[174:177], v[218:221], v[88:91]
	v_mfma_f32_16x16x32_bf16 v[80:83], v[162:165], v[222:225], v[80:83]
	v_mfma_f32_16x16x32_bf16 v[80:83], v[166:169], v[226:229], v[80:83]
	v_mfma_f32_16x16x32_bf16 v[72:75], v[170:173], v[222:225], v[72:75]
	v_mfma_f32_16x16x32_bf16 v[72:75], v[174:177], v[226:229], v[72:75]
	s_setprio 0
	s_setprio 1
	v_mfma_f32_16x16x32_bf16 v[116:119], v[178:181], v[198:201], v[116:119]
	v_mfma_f32_16x16x32_bf16 v[116:119], v[186:189], v[202:205], v[116:119]
	v_mfma_f32_16x16x32_bf16 v[108:111], v[190:193], v[198:201], v[108:111]
	v_mfma_f32_16x16x32_bf16 v[108:111], v[194:197], v[202:205], v[108:111]
	v_mfma_f32_16x16x32_bf16 v[100:103], v[178:181], v[206:209], v[100:103]
	v_mfma_f32_16x16x32_bf16 v[100:103], v[186:189], v[210:213], v[100:103]
	v_mfma_f32_16x16x32_bf16 v[92:95], v[190:193], v[206:209], v[92:95]
	v_mfma_f32_16x16x32_bf16 v[92:95], v[194:197], v[210:213], v[92:95]
	v_mfma_f32_16x16x32_bf16 v[84:87], v[178:181], v[214:217], v[84:87]
	v_mfma_f32_16x16x32_bf16 v[84:87], v[186:189], v[218:221], v[84:87]
	v_mfma_f32_16x16x32_bf16 v[76:79], v[190:193], v[214:217], v[76:79]
	v_mfma_f32_16x16x32_bf16 v[76:79], v[194:197], v[218:221], v[76:79]
	v_mfma_f32_16x16x32_bf16 v[68:71], v[178:181], v[222:225], v[68:71]
	v_mfma_f32_16x16x32_bf16 v[68:71], v[186:189], v[226:229], v[68:71]
	v_mfma_f32_16x16x32_bf16 v[64:67], v[190:193], v[222:225], v[64:67]
	v_mfma_f32_16x16x32_bf16 v[64:67], v[194:197], v[226:229], v[64:67]
	s_setprio 0
	s_barrier
	s_add_i32 s58, s86, s63
	v_lshl_add_u64 v[182:183], v[182:183], 0, s[22:23]
	s_mov_b32 m0, s58
	ds_read_b128 v[198:201], v154 offset:49152
	ds_read_b128 v[202:205], v154 offset:50176
	ds_read_b128 v[206:209], v154 offset:51200
	ds_read_b128 v[210:213], v154 offset:52224
	ds_read_b128 v[214:217], v154 offset:53248
	ds_read_b128 v[218:221], v154 offset:54272
	ds_read_b128 v[222:225], v154 offset:55296
	ds_read_b128 v[226:229], v154 offset:56320
	global_load_lds_dwordx4 v[182:183], off
	s_add_i32 m0, s58, 0x2000
	s_add_u32 s56, s56, 0x40080
	v_lshl_add_u64 v[182:183], v[230:231], 0, s[22:23]
	s_addc_u32 s57, s57, 0
	s_add_i32 s58, s87, s63
	global_load_lds_dwordx4 v[182:183], off
	v_lshl_add_u64 v[182:183], s[56:57], 0, v[130:131]
	s_mov_b32 m0, s58
	s_nop 0
	global_load_lds_dwordx4 v[182:183], off
	v_lshl_add_u64 v[182:183], s[56:57], 0, v[134:135]
	s_add_i32 m0, s58, 0x2000
	s_nop 0
	global_load_lds_dwordx4 v[182:183], off
	v_lshl_add_u64 v[182:183], v[232:233], 0, s[22:23]
	s_mov_b32 m0, s69
	s_nop 0
	global_load_lds_dwordx4 v[182:183], off
	v_lshl_add_u64 v[182:183], v[234:235], 0, s[22:23]
	s_mov_b32 m0, s70
	s_nop 0
	global_load_lds_dwordx4 v[182:183], off
	s_waitcnt vmcnt(8)
	s_waitcnt lgkmcnt(0)
	s_barrier
	s_setprio 1
	s_waitcnt lgkmcnt(0)
	v_mfma_f32_16x16x32_bf16 v[60:63], v[162:165], v[198:201], v[60:63]
	v_mfma_f32_16x16x32_bf16 v[60:63], v[166:169], v[202:205], v[60:63]
	v_mfma_f32_16x16x32_bf16 v[56:59], v[170:173], v[198:201], v[56:59]
	v_mfma_f32_16x16x32_bf16 v[56:59], v[174:177], v[202:205], v[56:59]
	v_mfma_f32_16x16x32_bf16 v[48:51], v[162:165], v[206:209], v[48:51]
	v_mfma_f32_16x16x32_bf16 v[48:51], v[166:169], v[210:213], v[48:51]
	v_mfma_f32_16x16x32_bf16 v[40:43], v[170:173], v[206:209], v[40:43]
	v_mfma_f32_16x16x32_bf16 v[40:43], v[174:177], v[210:213], v[40:43]
	v_mfma_f32_16x16x32_bf16 v[32:35], v[162:165], v[214:217], v[32:35]
	v_mfma_f32_16x16x32_bf16 v[32:35], v[166:169], v[218:221], v[32:35]
	v_mfma_f32_16x16x32_bf16 v[24:27], v[170:173], v[214:217], v[24:27]
	v_mfma_f32_16x16x32_bf16 v[24:27], v[174:177], v[218:221], v[24:27]
	v_mfma_f32_16x16x32_bf16 v[16:19], v[162:165], v[222:225], v[16:19]
	v_mfma_f32_16x16x32_bf16 v[16:19], v[166:169], v[226:229], v[16:19]
	v_mfma_f32_16x16x32_bf16 v[8:11], v[170:173], v[222:225], v[8:11]
	v_mfma_f32_16x16x32_bf16 v[8:11], v[174:177], v[226:229], v[8:11]
	s_setprio 0
	s_setprio 1
	v_mfma_f32_16x16x32_bf16 v[52:55], v[178:181], v[198:201], v[52:55]
	v_mfma_f32_16x16x32_bf16 v[52:55], v[186:189], v[202:205], v[52:55]
	v_mfma_f32_16x16x32_bf16 v[44:47], v[190:193], v[198:201], v[44:47]
	v_mfma_f32_16x16x32_bf16 v[44:47], v[194:197], v[202:205], v[44:47]
	v_mfma_f32_16x16x32_bf16 v[36:39], v[178:181], v[206:209], v[36:39]
	v_mfma_f32_16x16x32_bf16 v[36:39], v[186:189], v[210:213], v[36:39]
	v_mfma_f32_16x16x32_bf16 v[28:31], v[190:193], v[206:209], v[28:31]
	v_mfma_f32_16x16x32_bf16 v[28:31], v[194:197], v[210:213], v[28:31]
	v_mfma_f32_16x16x32_bf16 v[20:23], v[178:181], v[214:217], v[20:23]
	v_mfma_f32_16x16x32_bf16 v[20:23], v[186:189], v[218:221], v[20:23]
	v_mfma_f32_16x16x32_bf16 v[12:15], v[190:193], v[214:217], v[12:15]
	v_mfma_f32_16x16x32_bf16 v[12:15], v[194:197], v[218:221], v[12:15]
	v_mfma_f32_16x16x32_bf16 v[4:7], v[178:181], v[222:225], v[4:7]
	v_mfma_f32_16x16x32_bf16 v[4:7], v[186:189], v[226:229], v[4:7]
	v_mfma_f32_16x16x32_bf16 v[0:3], v[190:193], v[222:225], v[0:3]
	v_mfma_f32_16x16x32_bf16 v[0:3], v[194:197], v[226:229], v[0:3]
	s_setprio 0
	s_barrier
	s_add_i32 s85, s85, 2
	s_add_u32 s83, s83, 0x100
	s_addc_u32 s84, s84, 0
	s_add_u32 s54, s54, 0x100
	s_addc_u32 s55, s55, 0
	s_branch .LBB0_875
.LBB0_874:
	v_add_u32_e32 v146, s73, v149
	ds_read_b128 v[162:165], v146
	ds_read_b128 v[166:169], v146 offset:1024
	ds_read_b128 v[170:173], v146 offset:2048
	ds_read_b128 v[174:177], v146 offset:3072
	v_add_u32_e32 v146, s74, v149
	ds_read_b128 v[178:181], v146
	ds_read_b128 v[186:189], v146 offset:1024
	ds_read_b128 v[190:193], v146 offset:2048
	ds_read_b128 v[194:197], v146 offset:3072
	s_add_u32 s58, s54, 0xfffc0080
	s_addc_u32 s59, s55, -1
	s_and_b64 s[56:57], s[56:57], exec
	s_cselect_b32 s59, s49, s59
	s_cselect_b32 s58, s80, s58
	s_cselect_b32 s57, s81, s84
	s_cselect_b32 s56, s82, s83
	v_lshl_add_u64 v[182:183], s[54:55], 0, v[138:139]
	s_add_i32 m0, s64, 0xc000
	ds_read_b128 v[198:201], v154
	ds_read_b128 v[202:205], v154 offset:1024
	ds_read_b128 v[206:209], v154 offset:2048
	ds_read_b128 v[210:213], v154 offset:3072
	ds_read_b128 v[214:217], v154 offset:4096
	ds_read_b128 v[218:221], v154 offset:5120
	ds_read_b128 v[222:225], v154 offset:6144
	ds_read_b128 v[226:229], v154 offset:7168
	global_load_lds_dwordx4 v[182:183], off
	v_lshl_add_u64 v[182:183], s[54:55], 0, v[136:137]
	s_add_i32 m0, s64, 0xe000
	s_nop 0
	global_load_lds_dwordx4 v[182:183], off
	s_waitcnt vmcnt(8)
	s_waitcnt lgkmcnt(0)
	s_barrier
	s_setprio 1
	s_waitcnt lgkmcnt(0)
	v_mfma_f32_16x16x32_bf16 v[124:127], v[162:165], v[198:201], v[124:127]
	v_mfma_f32_16x16x32_bf16 v[124:127], v[166:169], v[202:205], v[124:127]
	v_mfma_f32_16x16x32_bf16 v[120:123], v[170:173], v[198:201], v[120:123]
	v_mfma_f32_16x16x32_bf16 v[120:123], v[174:177], v[202:205], v[120:123]
	v_mfma_f32_16x16x32_bf16 v[112:115], v[162:165], v[206:209], v[112:115]
	v_mfma_f32_16x16x32_bf16 v[112:115], v[166:169], v[210:213], v[112:115]
	v_mfma_f32_16x16x32_bf16 v[104:107], v[170:173], v[206:209], v[104:107]
	v_mfma_f32_16x16x32_bf16 v[104:107], v[174:177], v[210:213], v[104:107]
	v_mfma_f32_16x16x32_bf16 v[96:99], v[162:165], v[214:217], v[96:99]
	v_mfma_f32_16x16x32_bf16 v[96:99], v[166:169], v[218:221], v[96:99]
	v_mfma_f32_16x16x32_bf16 v[88:91], v[170:173], v[214:217], v[88:91]
	v_mfma_f32_16x16x32_bf16 v[88:91], v[174:177], v[218:221], v[88:91]
	v_mfma_f32_16x16x32_bf16 v[80:83], v[162:165], v[222:225], v[80:83]
	v_mfma_f32_16x16x32_bf16 v[80:83], v[166:169], v[226:229], v[80:83]
	v_mfma_f32_16x16x32_bf16 v[72:75], v[170:173], v[222:225], v[72:75]
	v_mfma_f32_16x16x32_bf16 v[72:75], v[174:177], v[226:229], v[72:75]
	s_setprio 0
	s_setprio 1
	v_mfma_f32_16x16x32_bf16 v[116:119], v[178:181], v[198:201], v[116:119]
	v_mfma_f32_16x16x32_bf16 v[116:119], v[186:189], v[202:205], v[116:119]
	v_mfma_f32_16x16x32_bf16 v[108:111], v[190:193], v[198:201], v[108:111]
	v_mfma_f32_16x16x32_bf16 v[108:111], v[194:197], v[202:205], v[108:111]
	v_mfma_f32_16x16x32_bf16 v[100:103], v[178:181], v[206:209], v[100:103]
	v_mfma_f32_16x16x32_bf16 v[100:103], v[186:189], v[210:213], v[100:103]
	v_mfma_f32_16x16x32_bf16 v[92:95], v[190:193], v[206:209], v[92:95]
	v_mfma_f32_16x16x32_bf16 v[92:95], v[194:197], v[210:213], v[92:95]
	v_mfma_f32_16x16x32_bf16 v[84:87], v[178:181], v[214:217], v[84:87]
	v_mfma_f32_16x16x32_bf16 v[84:87], v[186:189], v[218:221], v[84:87]
	v_mfma_f32_16x16x32_bf16 v[76:79], v[190:193], v[214:217], v[76:79]
	v_mfma_f32_16x16x32_bf16 v[76:79], v[194:197], v[218:221], v[76:79]
	v_mfma_f32_16x16x32_bf16 v[68:71], v[178:181], v[222:225], v[68:71]
	v_mfma_f32_16x16x32_bf16 v[68:71], v[186:189], v[226:229], v[68:71]
	v_mfma_f32_16x16x32_bf16 v[64:67], v[190:193], v[222:225], v[64:67]
	v_mfma_f32_16x16x32_bf16 v[64:67], v[194:197], v[226:229], v[64:67]
	s_setprio 0
	s_barrier
	s_add_i32 s86, s73, s63
	v_lshl_add_u64 v[182:183], s[56:57], 0, v[130:131]
	s_mov_b32 m0, s86
	ds_read_b128 v[198:201], v154 offset:16384
	ds_read_b128 v[202:205], v154 offset:17408
	ds_read_b128 v[206:209], v154 offset:18432
	ds_read_b128 v[210:213], v154 offset:19456
	ds_read_b128 v[214:217], v154 offset:20480
	ds_read_b128 v[218:221], v154 offset:21504
	ds_read_b128 v[222:225], v154 offset:22528
	ds_read_b128 v[226:229], v154 offset:23552
	global_load_lds_dwordx4 v[182:183], off
	s_add_i32 m0, s86, 0x2000
	s_add_u32 s86, s56, 0x40000
	v_lshl_add_u64 v[230:231], s[56:57], 0, v[134:135]
	s_addc_u32 s87, s57, 0
	s_add_i32 s88, s74, s63
	global_load_lds_dwordx4 v[230:231], off
	v_lshl_add_u64 v[232:233], s[86:87], 0, v[130:131]
	s_mov_b32 m0, s88
	v_lshl_add_u64 v[234:235], s[58:59], 0, v[132:133]
	global_load_lds_dwordx4 v[232:233], off
	v_lshl_add_u64 v[232:233], s[86:87], 0, v[134:135]
	s_add_i32 m0, s88, 0x2000
	s_nop 0
	global_load_lds_dwordx4 v[232:233], off
	v_lshl_add_u64 v[232:233], s[58:59], 0, v[128:129]
	s_mov_b32 m0, s64
	s_nop 0
	global_load_lds_dwordx4 v[232:233], off
	s_mov_b32 m0, s65
	s_nop 0
	global_load_lds_dwordx4 v[234:235], off
	s_waitcnt vmcnt(8)
	s_waitcnt lgkmcnt(0)
	s_barrier
	s_setprio 1
	s_waitcnt lgkmcnt(0)
	v_mfma_f32_16x16x32_bf16 v[60:63], v[162:165], v[198:201], v[60:63]
	v_mfma_f32_16x16x32_bf16 v[60:63], v[166:169], v[202:205], v[60:63]
	v_mfma_f32_16x16x32_bf16 v[56:59], v[170:173], v[198:201], v[56:59]
	v_mfma_f32_16x16x32_bf16 v[56:59], v[174:177], v[202:205], v[56:59]
	v_mfma_f32_16x16x32_bf16 v[48:51], v[162:165], v[206:209], v[48:51]
	v_mfma_f32_16x16x32_bf16 v[48:51], v[166:169], v[210:213], v[48:51]
	v_mfma_f32_16x16x32_bf16 v[40:43], v[170:173], v[206:209], v[40:43]
	v_mfma_f32_16x16x32_bf16 v[40:43], v[174:177], v[210:213], v[40:43]
	v_mfma_f32_16x16x32_bf16 v[32:35], v[162:165], v[214:217], v[32:35]
	v_mfma_f32_16x16x32_bf16 v[32:35], v[166:169], v[218:221], v[32:35]
	v_mfma_f32_16x16x32_bf16 v[24:27], v[170:173], v[214:217], v[24:27]
	v_mfma_f32_16x16x32_bf16 v[24:27], v[174:177], v[218:221], v[24:27]
	v_mfma_f32_16x16x32_bf16 v[16:19], v[162:165], v[222:225], v[16:19]
	v_mfma_f32_16x16x32_bf16 v[16:19], v[166:169], v[226:229], v[16:19]
	v_mfma_f32_16x16x32_bf16 v[8:11], v[170:173], v[222:225], v[8:11]
	v_mfma_f32_16x16x32_bf16 v[8:11], v[174:177], v[226:229], v[8:11]
	s_setprio 0
	s_setprio 1
	v_mfma_f32_16x16x32_bf16 v[52:55], v[178:181], v[198:201], v[52:55]
	v_mfma_f32_16x16x32_bf16 v[52:55], v[186:189], v[202:205], v[52:55]
	v_mfma_f32_16x16x32_bf16 v[44:47], v[190:193], v[198:201], v[44:47]
	v_mfma_f32_16x16x32_bf16 v[44:47], v[194:197], v[202:205], v[44:47]
	v_mfma_f32_16x16x32_bf16 v[36:39], v[178:181], v[206:209], v[36:39]
	v_mfma_f32_16x16x32_bf16 v[36:39], v[186:189], v[210:213], v[36:39]
	v_mfma_f32_16x16x32_bf16 v[28:31], v[190:193], v[206:209], v[28:31]
	v_mfma_f32_16x16x32_bf16 v[28:31], v[194:197], v[210:213], v[28:31]
	v_mfma_f32_16x16x32_bf16 v[20:23], v[178:181], v[214:217], v[20:23]
	v_mfma_f32_16x16x32_bf16 v[20:23], v[186:189], v[218:221], v[20:23]
	v_mfma_f32_16x16x32_bf16 v[12:15], v[190:193], v[214:217], v[12:15]
	v_mfma_f32_16x16x32_bf16 v[12:15], v[194:197], v[218:221], v[12:15]
	v_mfma_f32_16x16x32_bf16 v[4:7], v[178:181], v[222:225], v[4:7]
	v_mfma_f32_16x16x32_bf16 v[4:7], v[186:189], v[226:229], v[4:7]
	v_mfma_f32_16x16x32_bf16 v[0:3], v[190:193], v[222:225], v[0:3]
	v_mfma_f32_16x16x32_bf16 v[0:3], v[194:197], v[226:229], v[0:3]
	s_setprio 0
	s_barrier
	s_add_i32 s86, 0, 0x18000
	v_add_u32_e32 v146, s86, v149
	s_add_i32 s87, 0, 0x1c000
	ds_read_b128 v[162:165], v146
	ds_read_b128 v[166:169], v146 offset:1024
	ds_read_b128 v[170:173], v146 offset:2048
	ds_read_b128 v[174:177], v146 offset:3072
	v_add_u32_e32 v146, s87, v149
	ds_read_b128 v[178:181], v146
	ds_read_b128 v[186:189], v146 offset:1024
	ds_read_b128 v[190:193], v146 offset:2048
	ds_read_b128 v[194:197], v146 offset:3072
	s_add_u32 s58, s58, 0x40000
	s_addc_u32 s59, s59, 0
	s_mov_b32 m0, s66
	v_lshl_add_u64 v[236:237], s[58:59], 0, v[128:129]
	ds_read_b128 v[198:201], v154 offset:32768
	ds_read_b128 v[202:205], v154 offset:33792
	ds_read_b128 v[206:209], v154 offset:34816
	ds_read_b128 v[210:213], v154 offset:35840
	ds_read_b128 v[214:217], v154 offset:36864
	ds_read_b128 v[218:221], v154 offset:37888
	ds_read_b128 v[222:225], v154 offset:38912
	ds_read_b128 v[226:229], v154 offset:39936
	global_load_lds_dwordx4 v[236:237], off
	v_lshl_add_u64 v[236:237], s[58:59], 0, v[132:133]
	s_mov_b32 m0, s67
	s_nop 0
	global_load_lds_dwordx4 v[236:237], off
	s_waitcnt vmcnt(8)
	s_waitcnt lgkmcnt(0)
	s_barrier
	s_setprio 1
	s_waitcnt lgkmcnt(0)
	v_mfma_f32_16x16x32_bf16 v[124:127], v[162:165], v[198:201], v[124:127]
	v_mfma_f32_16x16x32_bf16 v[124:127], v[166:169], v[202:205], v[124:127]
	v_mfma_f32_16x16x32_bf16 v[120:123], v[170:173], v[198:201], v[120:123]
	v_mfma_f32_16x16x32_bf16 v[120:123], v[174:177], v[202:205], v[120:123]
	v_mfma_f32_16x16x32_bf16 v[112:115], v[162:165], v[206:209], v[112:115]
	v_mfma_f32_16x16x32_bf16 v[112:115], v[166:169], v[210:213], v[112:115]
	v_mfma_f32_16x16x32_bf16 v[104:107], v[170:173], v[206:209], v[104:107]
	v_mfma_f32_16x16x32_bf16 v[104:107], v[174:177], v[210:213], v[104:107]
	v_mfma_f32_16x16x32_bf16 v[96:99], v[162:165], v[214:217], v[96:99]
	v_mfma_f32_16x16x32_bf16 v[96:99], v[166:169], v[218:221], v[96:99]
	v_mfma_f32_16x16x32_bf16 v[88:91], v[170:173], v[214:217], v[88:91]
	v_mfma_f32_16x16x32_bf16 v[88:91], v[174:177], v[218:221], v[88:91]
	v_mfma_f32_16x16x32_bf16 v[80:83], v[162:165], v[222:225], v[80:83]
	v_mfma_f32_16x16x32_bf16 v[80:83], v[166:169], v[226:229], v[80:83]
	v_mfma_f32_16x16x32_bf16 v[72:75], v[170:173], v[222:225], v[72:75]
	v_mfma_f32_16x16x32_bf16 v[72:75], v[174:177], v[226:229], v[72:75]
	s_setprio 0
	s_setprio 1
	v_mfma_f32_16x16x32_bf16 v[116:119], v[178:181], v[198:201], v[116:119]
	v_mfma_f32_16x16x32_bf16 v[116:119], v[186:189], v[202:205], v[116:119]
	v_mfma_f32_16x16x32_bf16 v[108:111], v[190:193], v[198:201], v[108:111]
	v_mfma_f32_16x16x32_bf16 v[108:111], v[194:197], v[202:205], v[108:111]
	v_mfma_f32_16x16x32_bf16 v[100:103], v[178:181], v[206:209], v[100:103]
	v_mfma_f32_16x16x32_bf16 v[100:103], v[186:189], v[210:213], v[100:103]
	v_mfma_f32_16x16x32_bf16 v[92:95], v[190:193], v[206:209], v[92:95]
	v_mfma_f32_16x16x32_bf16 v[92:95], v[194:197], v[210:213], v[92:95]
	v_mfma_f32_16x16x32_bf16 v[84:87], v[178:181], v[214:217], v[84:87]
	v_mfma_f32_16x16x32_bf16 v[84:87], v[186:189], v[218:221], v[84:87]
	v_mfma_f32_16x16x32_bf16 v[76:79], v[190:193], v[214:217], v[76:79]
	v_mfma_f32_16x16x32_bf16 v[76:79], v[194:197], v[218:221], v[76:79]
	v_mfma_f32_16x16x32_bf16 v[68:71], v[178:181], v[222:225], v[68:71]
	v_mfma_f32_16x16x32_bf16 v[68:71], v[186:189], v[226:229], v[68:71]
	v_mfma_f32_16x16x32_bf16 v[64:67], v[190:193], v[222:225], v[64:67]
	v_mfma_f32_16x16x32_bf16 v[64:67], v[194:197], v[226:229], v[64:67]
	s_setprio 0
	s_barrier
	s_add_i32 s58, s86, s63
	v_lshl_add_u64 v[182:183], v[182:183], 0, s[22:23]
	s_mov_b32 m0, s58
	ds_read_b128 v[198:201], v154 offset:49152
	ds_read_b128 v[202:205], v154 offset:50176
	ds_read_b128 v[206:209], v154 offset:51200
	ds_read_b128 v[210:213], v154 offset:52224
	ds_read_b128 v[214:217], v154 offset:53248
	ds_read_b128 v[218:221], v154 offset:54272
	ds_read_b128 v[222:225], v154 offset:55296
	ds_read_b128 v[226:229], v154 offset:56320
	global_load_lds_dwordx4 v[182:183], off
	s_add_i32 m0, s58, 0x2000
	s_add_u32 s56, s56, 0x40080
	v_lshl_add_u64 v[182:183], v[230:231], 0, s[22:23]
	s_addc_u32 s57, s57, 0
	s_add_i32 s58, s87, s63
	global_load_lds_dwordx4 v[182:183], off
	v_lshl_add_u64 v[182:183], s[56:57], 0, v[130:131]
	s_mov_b32 m0, s58
	s_nop 0
	global_load_lds_dwordx4 v[182:183], off
	v_lshl_add_u64 v[182:183], s[56:57], 0, v[134:135]
	s_add_i32 m0, s58, 0x2000
	s_nop 0
	global_load_lds_dwordx4 v[182:183], off
	v_lshl_add_u64 v[182:183], v[232:233], 0, s[22:23]
	s_mov_b32 m0, s69
	s_nop 0
	global_load_lds_dwordx4 v[182:183], off
	v_lshl_add_u64 v[182:183], v[234:235], 0, s[22:23]
	s_mov_b32 m0, s70
	s_nop 0
	global_load_lds_dwordx4 v[182:183], off
	s_waitcnt vmcnt(8)
	s_waitcnt lgkmcnt(0)
	s_barrier
	s_setprio 1
	s_waitcnt lgkmcnt(0)
	v_mfma_f32_16x16x32_bf16 v[60:63], v[162:165], v[198:201], v[60:63]
	v_mfma_f32_16x16x32_bf16 v[60:63], v[166:169], v[202:205], v[60:63]
	v_mfma_f32_16x16x32_bf16 v[56:59], v[170:173], v[198:201], v[56:59]
	v_mfma_f32_16x16x32_bf16 v[56:59], v[174:177], v[202:205], v[56:59]
	v_mfma_f32_16x16x32_bf16 v[48:51], v[162:165], v[206:209], v[48:51]
	v_mfma_f32_16x16x32_bf16 v[48:51], v[166:169], v[210:213], v[48:51]
	v_mfma_f32_16x16x32_bf16 v[40:43], v[170:173], v[206:209], v[40:43]
	v_mfma_f32_16x16x32_bf16 v[40:43], v[174:177], v[210:213], v[40:43]
	v_mfma_f32_16x16x32_bf16 v[32:35], v[162:165], v[214:217], v[32:35]
	v_mfma_f32_16x16x32_bf16 v[32:35], v[166:169], v[218:221], v[32:35]
	v_mfma_f32_16x16x32_bf16 v[24:27], v[170:173], v[214:217], v[24:27]
	v_mfma_f32_16x16x32_bf16 v[24:27], v[174:177], v[218:221], v[24:27]
	v_mfma_f32_16x16x32_bf16 v[16:19], v[162:165], v[222:225], v[16:19]
	v_mfma_f32_16x16x32_bf16 v[16:19], v[166:169], v[226:229], v[16:19]
	v_mfma_f32_16x16x32_bf16 v[8:11], v[170:173], v[222:225], v[8:11]
	v_mfma_f32_16x16x32_bf16 v[8:11], v[174:177], v[226:229], v[8:11]
	s_setprio 0
	s_setprio 1
	v_mfma_f32_16x16x32_bf16 v[52:55], v[178:181], v[198:201], v[52:55]
	v_mfma_f32_16x16x32_bf16 v[52:55], v[186:189], v[202:205], v[52:55]
	v_mfma_f32_16x16x32_bf16 v[44:47], v[190:193], v[198:201], v[44:47]
	v_mfma_f32_16x16x32_bf16 v[44:47], v[194:197], v[202:205], v[44:47]
	v_mfma_f32_16x16x32_bf16 v[36:39], v[178:181], v[206:209], v[36:39]
	v_mfma_f32_16x16x32_bf16 v[36:39], v[186:189], v[210:213], v[36:39]
	v_mfma_f32_16x16x32_bf16 v[28:31], v[190:193], v[206:209], v[28:31]
	v_mfma_f32_16x16x32_bf16 v[28:31], v[194:197], v[210:213], v[28:31]
	v_mfma_f32_16x16x32_bf16 v[20:23], v[178:181], v[214:217], v[20:23]
	v_mfma_f32_16x16x32_bf16 v[20:23], v[186:189], v[218:221], v[20:23]
	v_mfma_f32_16x16x32_bf16 v[12:15], v[190:193], v[214:217], v[12:15]
	v_mfma_f32_16x16x32_bf16 v[12:15], v[194:197], v[218:221], v[12:15]
	v_mfma_f32_16x16x32_bf16 v[4:7], v[178:181], v[222:225], v[4:7]
	v_mfma_f32_16x16x32_bf16 v[4:7], v[186:189], v[226:229], v[4:7]
	v_mfma_f32_16x16x32_bf16 v[0:3], v[190:193], v[222:225], v[0:3]
	v_mfma_f32_16x16x32_bf16 v[0:3], v[194:197], v[226:229], v[0:3]
	s_setprio 0
	s_barrier
	s_add_i32 s85, s85, 2
	s_add_u32 s83, s83, 0x100
	s_addc_u32 s84, s84, 0
	s_add_u32 s54, s54, 0x100
	s_addc_u32 s55, s55, 0
	s_cmp_gt_u32 s85, 13
	s_cbranch_scc1 .LBB0_877

.LBB0_1010:
	s_ashr_i32 s51, s50, 31
	s_lshl_b64 s[52:53], s[50:51], 19
	s_add_u32 s52, s33, s52
	s_addc_u32 s53, s35, s53
	s_and_b64 s[54:55], s[12:13], exec
	s_cselect_b32 s15, s53, s61
	s_cselect_b32 s51, s52, s60
	s_ashr_i32 s49, s48, 31
	s_lshl_b64 s[54:55], s[48:49], 19
	s_add_u32 s54, s64, s54
	s_addc_u32 s55, s65, s55
	s_and_b64 s[62:63], s[12:13], exec
	s_cselect_b32 s49, s55, s59
	s_cselect_b32 s57, s54, s58
	s_add_u32 s78, s58, 0x100
	s_addc_u32 s79, s59, 0
	s_add_u32 s58, s60, 0x40080
	s_addc_u32 s59, s61, 0
	s_mov_b32 s80, -2
	s_waitcnt lgkmcnt(0)
	s_cmp_eq_u32 s71, 1
	s_cbranch_scc1 .Lfa_9
	ds_read_b128 v[128:131], v188
	ds_read_b128 v[132:135], v188 offset:1024
	ds_read_b128 v[136:139], v188 offset:2048
	ds_read_b128 v[140:143], v188 offset:3072
	ds_read_b128 v[144:147], v189
	ds_read_b128 v[148:151], v189 offset:1024
	ds_read_b128 v[172:175], v189 offset:2048
	ds_read_b128 v[176:179], v189 offset:3072
	s_add_u32 s60, s58, 0xfffc0080
	s_addc_u32 s61, s59, -1
	s_cmp_eq_u32 s80, 12
	s_cselect_b32 s63, s15, s61
	s_cselect_b32 s62, s51, s60
	s_cselect_b32 s61, s49, s79
	s_cselect_b32 s60, s57, s78
	v_lshl_add_u64 v[220:221], s[58:59], 0, v[166:167]
	s_add_i32 m0, s67, 0xc000
	ds_read_b128 v[180:183], v190
	ds_read_b128 v[192:195], v190 offset:1024
	ds_read_b128 v[196:199], v190 offset:2048
	ds_read_b128 v[200:203], v190 offset:3072
	ds_read_b128 v[204:207], v190 offset:4096
	ds_read_b128 v[208:211], v190 offset:5120
	ds_read_b128 v[212:215], v190 offset:6144
	ds_read_b128 v[216:219], v190 offset:7168
	global_load_lds_dwordx4 v[220:221], off
	v_lshl_add_u64 v[220:221], s[58:59], 0, v[164:165]
	s_add_i32 m0, s67, 0xe000
	s_nop 0
	global_load_lds_dwordx4 v[220:221], off
	s_waitcnt vmcnt(24)
	s_waitcnt lgkmcnt(0)
	s_barrier
	s_setprio 1
	s_waitcnt lgkmcnt(0)
	v_mfma_f32_16x16x32_bf16 v[124:127], v[128:131], v[180:183], 0
	v_mfma_f32_16x16x32_bf16 v[120:123], v[136:139], v[180:183], 0
	v_mfma_f32_16x16x32_bf16 v[108:111], v[128:131], v[196:199], 0
	v_mfma_f32_16x16x32_bf16 v[104:107], v[136:139], v[196:199], 0
	v_mfma_f32_16x16x32_bf16 v[92:95], v[128:131], v[204:207], 0
	v_mfma_f32_16x16x32_bf16 v[88:91], v[136:139], v[204:207], 0
	v_mfma_f32_16x16x32_bf16 v[76:79], v[128:131], v[212:215], 0
	v_mfma_f32_16x16x32_bf16 v[72:75], v[136:139], v[212:215], 0
	v_mfma_f32_16x16x32_bf16 v[124:127], v[132:135], v[192:195], v[124:127]
	v_mfma_f32_16x16x32_bf16 v[120:123], v[140:143], v[192:195], v[120:123]
	v_mfma_f32_16x16x32_bf16 v[108:111], v[132:135], v[200:203], v[108:111]
	v_mfma_f32_16x16x32_bf16 v[104:107], v[140:143], v[200:203], v[104:107]
	v_mfma_f32_16x16x32_bf16 v[92:95], v[132:135], v[208:211], v[92:95]
	v_mfma_f32_16x16x32_bf16 v[88:91], v[140:143], v[208:211], v[88:91]
	v_mfma_f32_16x16x32_bf16 v[76:79], v[132:135], v[216:219], v[76:79]
	v_mfma_f32_16x16x32_bf16 v[72:75], v[140:143], v[216:219], v[72:75]
	s_setprio 0
	s_setprio 1
	v_mfma_f32_16x16x32_bf16 v[116:119], v[144:147], v[180:183], 0
	v_mfma_f32_16x16x32_bf16 v[112:115], v[172:175], v[180:183], 0
	v_mfma_f32_16x16x32_bf16 v[100:103], v[144:147], v[196:199], 0
	v_mfma_f32_16x16x32_bf16 v[96:99], v[172:175], v[196:199], 0
	v_mfma_f32_16x16x32_bf16 v[84:87], v[144:147], v[204:207], 0
	v_mfma_f32_16x16x32_bf16 v[80:83], v[172:175], v[204:207], 0
	v_mfma_f32_16x16x32_bf16 v[68:71], v[144:147], v[212:215], 0
	v_mfma_f32_16x16x32_bf16 v[64:67], v[172:175], v[212:215], 0
	v_mfma_f32_16x16x32_bf16 v[116:119], v[148:151], v[192:195], v[116:119]
	v_mfma_f32_16x16x32_bf16 v[112:115], v[176:179], v[192:195], v[112:115]
	v_mfma_f32_16x16x32_bf16 v[100:103], v[148:151], v[200:203], v[100:103]
	v_mfma_f32_16x16x32_bf16 v[96:99], v[176:179], v[200:203], v[96:99]
	v_mfma_f32_16x16x32_bf16 v[84:87], v[148:151], v[208:211], v[84:87]
	v_mfma_f32_16x16x32_bf16 v[80:83], v[176:179], v[208:211], v[80:83]
	v_mfma_f32_16x16x32_bf16 v[68:71], v[148:151], v[216:219], v[68:71]
	v_mfma_f32_16x16x32_bf16 v[64:67], v[176:179], v[216:219], v[64:67]
	s_setprio 0
	s_barrier
	s_add_i32 s81, s76, s66
	v_lshl_add_u64 v[220:221], s[60:61], 0, v[154:155]
	s_mov_b32 m0, s81
	ds_read_b128 v[180:183], v190 offset:16384
	ds_read_b128 v[192:195], v190 offset:17408
	ds_read_b128 v[196:199], v190 offset:18432
	ds_read_b128 v[200:203], v190 offset:19456
	ds_read_b128 v[204:207], v190 offset:20480
	ds_read_b128 v[208:211], v190 offset:21504
	ds_read_b128 v[212:215], v190 offset:22528
	ds_read_b128 v[216:219], v190 offset:23552
	global_load_lds_dwordx4 v[220:221], off
	s_add_i32 m0, s81, 0x2000
	s_add_u32 s82, s60, 0x40000
	v_lshl_add_u64 v[222:223], s[60:61], 0, v[162:163]
	s_addc_u32 s83, s61, 0
	s_add_i32 s81, s77, s66
	global_load_lds_dwordx4 v[222:223], off
	v_lshl_add_u64 v[224:225], s[82:83], 0, v[154:155]
	s_mov_b32 m0, s81
	v_lshl_add_u64 v[226:227], s[62:63], 0, v[160:161]
	global_load_lds_dwordx4 v[224:225], off
	v_lshl_add_u64 v[224:225], s[82:83], 0, v[162:163]
	s_add_i32 m0, s81, 0x2000
	s_nop 0
	global_load_lds_dwordx4 v[224:225], off
	v_lshl_add_u64 v[224:225], s[62:63], 0, v[152:153]
	s_mov_b32 m0, s67
	s_nop 0
	global_load_lds_dwordx4 v[224:225], off
	s_mov_b32 m0, s68
	s_nop 0
	global_load_lds_dwordx4 v[226:227], off
	s_waitcnt vmcnt(24)
	s_waitcnt lgkmcnt(0)
	s_barrier
	s_setprio 1
	s_waitcnt lgkmcnt(0)
	v_mfma_f32_16x16x32_bf16 v[60:63], v[128:131], v[180:183], 0
	v_mfma_f32_16x16x32_bf16 v[56:59], v[136:139], v[180:183], 0
	v_mfma_f32_16x16x32_bf16 v[44:47], v[128:131], v[196:199], 0
	v_mfma_f32_16x16x32_bf16 v[40:43], v[136:139], v[196:199], 0
	v_mfma_f32_16x16x32_bf16 v[28:31], v[128:131], v[204:207], 0
	v_mfma_f32_16x16x32_bf16 v[24:27], v[136:139], v[204:207], 0
	v_mfma_f32_16x16x32_bf16 v[12:15], v[128:131], v[212:215], 0
	v_mfma_f32_16x16x32_bf16 v[8:11], v[136:139], v[212:215], 0
	v_mfma_f32_16x16x32_bf16 v[60:63], v[132:135], v[192:195], v[60:63]
	v_mfma_f32_16x16x32_bf16 v[56:59], v[140:143], v[192:195], v[56:59]
	v_mfma_f32_16x16x32_bf16 v[44:47], v[132:135], v[200:203], v[44:47]
	v_mfma_f32_16x16x32_bf16 v[40:43], v[140:143], v[200:203], v[40:43]
	v_mfma_f32_16x16x32_bf16 v[28:31], v[132:135], v[208:211], v[28:31]
	v_mfma_f32_16x16x32_bf16 v[24:27], v[140:143], v[208:211], v[24:27]
	v_mfma_f32_16x16x32_bf16 v[12:15], v[132:135], v[216:219], v[12:15]
	v_mfma_f32_16x16x32_bf16 v[8:11], v[140:143], v[216:219], v[8:11]
	s_setprio 0
	s_setprio 1
	v_mfma_f32_16x16x32_bf16 v[52:55], v[144:147], v[180:183], 0
	v_mfma_f32_16x16x32_bf16 v[48:51], v[172:175], v[180:183], 0
	v_mfma_f32_16x16x32_bf16 v[36:39], v[144:147], v[196:199], 0
	v_mfma_f32_16x16x32_bf16 v[32:35], v[172:175], v[196:199], 0
	v_mfma_f32_16x16x32_bf16 v[20:23], v[144:147], v[204:207], 0
	v_mfma_f32_16x16x32_bf16 v[16:19], v[172:175], v[204:207], 0
	v_mfma_f32_16x16x32_bf16 v[4:7], v[144:147], v[212:215], 0
	v_mfma_f32_16x16x32_bf16 v[0:3], v[172:175], v[212:215], 0
	v_mfma_f32_16x16x32_bf16 v[52:55], v[148:151], v[192:195], v[52:55]
	v_mfma_f32_16x16x32_bf16 v[48:51], v[176:179], v[192:195], v[48:51]
	v_mfma_f32_16x16x32_bf16 v[36:39], v[148:151], v[200:203], v[36:39]
	v_mfma_f32_16x16x32_bf16 v[32:35], v[176:179], v[200:203], v[32:35]
	v_mfma_f32_16x16x32_bf16 v[20:23], v[148:151], v[208:211], v[20:23]
	v_mfma_f32_16x16x32_bf16 v[16:19], v[176:179], v[208:211], v[16:19]
	v_mfma_f32_16x16x32_bf16 v[4:7], v[148:151], v[216:219], v[4:7]
	v_mfma_f32_16x16x32_bf16 v[0:3], v[176:179], v[216:219], v[0:3]
	s_setprio 0
	s_barrier
	s_add_i32 s81, 0, 0x18000
	s_add_i32 s82, 0, 0x1c000
	v_add_u32_e32 v140, s81, v185
	v_add_u32_e32 v176, s82, v185
	ds_read_b128 v[128:131], v140
	ds_read_b128 v[132:135], v140 offset:1024
	ds_read_b128 v[136:139], v140 offset:2048
	ds_read_b128 v[140:143], v140 offset:3072
	ds_read_b128 v[144:147], v176
	ds_read_b128 v[148:151], v176 offset:1024
	ds_read_b128 v[172:175], v176 offset:2048
	ds_read_b128 v[176:179], v176 offset:3072
	s_add_u32 s62, s62, 0x40000
	s_addc_u32 s63, s63, 0
	s_mov_b32 m0, s69
	v_lshl_add_u64 v[228:229], s[62:63], 0, v[152:153]
	ds_read_b128 v[180:183], v190 offset:32768
	ds_read_b128 v[192:195], v190 offset:33792
	ds_read_b128 v[196:199], v190 offset:34816
	ds_read_b128 v[200:203], v190 offset:35840
	ds_read_b128 v[204:207], v190 offset:36864
	ds_read_b128 v[208:211], v190 offset:37888
	ds_read_b128 v[212:215], v190 offset:38912
	ds_read_b128 v[216:219], v190 offset:39936
	global_load_lds_dwordx4 v[228:229], off
	v_lshl_add_u64 v[228:229], s[62:63], 0, v[160:161]
	s_mov_b32 m0, s70
	s_nop 0
	global_load_lds_dwordx4 v[228:229], off
	s_waitcnt vmcnt(8)
	s_waitcnt lgkmcnt(0)
	s_barrier
	s_setprio 1
	s_waitcnt lgkmcnt(0)
	v_mfma_f32_16x16x32_bf16 v[124:127], v[128:131], v[180:183], v[124:127]
	v_mfma_f32_16x16x32_bf16 v[124:127], v[132:135], v[192:195], v[124:127]
	v_mfma_f32_16x16x32_bf16 v[120:123], v[136:139], v[180:183], v[120:123]
	v_mfma_f32_16x16x32_bf16 v[120:123], v[140:143], v[192:195], v[120:123]
	v_mfma_f32_16x16x32_bf16 v[108:111], v[128:131], v[196:199], v[108:111]
	v_mfma_f32_16x16x32_bf16 v[108:111], v[132:135], v[200:203], v[108:111]
	v_mfma_f32_16x16x32_bf16 v[104:107], v[136:139], v[196:199], v[104:107]
	v_mfma_f32_16x16x32_bf16 v[104:107], v[140:143], v[200:203], v[104:107]
	v_mfma_f32_16x16x32_bf16 v[92:95], v[128:131], v[204:207], v[92:95]
	v_mfma_f32_16x16x32_bf16 v[92:95], v[132:135], v[208:211], v[92:95]
	v_mfma_f32_16x16x32_bf16 v[88:91], v[136:139], v[204:207], v[88:91]
	v_mfma_f32_16x16x32_bf16 v[88:91], v[140:143], v[208:211], v[88:91]
	v_mfma_f32_16x16x32_bf16 v[76:79], v[128:131], v[212:215], v[76:79]
	v_mfma_f32_16x16x32_bf16 v[76:79], v[132:135], v[216:219], v[76:79]
	v_mfma_f32_16x16x32_bf16 v[72:75], v[136:139], v[212:215], v[72:75]
	v_mfma_f32_16x16x32_bf16 v[72:75], v[140:143], v[216:219], v[72:75]
	s_setprio 0
	s_setprio 1
	v_mfma_f32_16x16x32_bf16 v[116:119], v[144:147], v[180:183], v[116:119]
	v_mfma_f32_16x16x32_bf16 v[116:119], v[148:151], v[192:195], v[116:119]
	v_mfma_f32_16x16x32_bf16 v[112:115], v[172:175], v[180:183], v[112:115]
	v_mfma_f32_16x16x32_bf16 v[112:115], v[176:179], v[192:195], v[112:115]
	v_mfma_f32_16x16x32_bf16 v[100:103], v[144:147], v[196:199], v[100:103]
	v_mfma_f32_16x16x32_bf16 v[100:103], v[148:151], v[200:203], v[100:103]
	v_mfma_f32_16x16x32_bf16 v[96:99], v[172:175], v[196:199], v[96:99]
	v_mfma_f32_16x16x32_bf16 v[96:99], v[176:179], v[200:203], v[96:99]
	v_mfma_f32_16x16x32_bf16 v[84:87], v[144:147], v[204:207], v[84:87]
	v_mfma_f32_16x16x32_bf16 v[84:87], v[148:151], v[208:211], v[84:87]
	v_mfma_f32_16x16x32_bf16 v[80:83], v[172:175], v[204:207], v[80:83]
	v_mfma_f32_16x16x32_bf16 v[80:83], v[176:179], v[208:211], v[80:83]
	v_mfma_f32_16x16x32_bf16 v[68:71], v[144:147], v[212:215], v[68:71]
	v_mfma_f32_16x16x32_bf16 v[68:71], v[148:151], v[216:219], v[68:71]
	v_mfma_f32_16x16x32_bf16 v[64:67], v[172:175], v[212:215], v[64:67]
	v_mfma_f32_16x16x32_bf16 v[64:67], v[176:179], v[216:219], v[64:67]
	s_setprio 0
	s_barrier
	s_add_i32 s62, s81, s66
	v_lshl_add_u64 v[220:221], v[220:221], 0, s[26:27]
	s_mov_b32 m0, s62
	ds_read_b128 v[180:183], v190 offset:49152
	ds_read_b128 v[192:195], v190 offset:50176
	ds_read_b128 v[196:199], v190 offset:51200
	ds_read_b128 v[200:203], v190 offset:52224
	ds_read_b128 v[204:207], v190 offset:53248
	ds_read_b128 v[208:211], v190 offset:54272
	ds_read_b128 v[212:215], v190 offset:55296
	ds_read_b128 v[216:219], v190 offset:56320
	global_load_lds_dwordx4 v[220:221], off
	s_add_i32 m0, s62, 0x2000
	s_add_u32 s60, s60, 0x40080
	v_lshl_add_u64 v[220:221], v[222:223], 0, s[26:27]
	s_addc_u32 s61, s61, 0
	s_add_i32 s62, s82, s66
	global_load_lds_dwordx4 v[220:221], off
	v_lshl_add_u64 v[220:221], s[60:61], 0, v[154:155]
	s_mov_b32 m0, s62
	s_nop 0
	global_load_lds_dwordx4 v[220:221], off
	v_lshl_add_u64 v[220:221], s[60:61], 0, v[162:163]
	s_add_i32 m0, s62, 0x2000
	s_nop 0
	global_load_lds_dwordx4 v[220:221], off
	v_lshl_add_u64 v[220:221], v[224:225], 0, s[26:27]
	s_mov_b32 m0, s3
	s_nop 0
	global_load_lds_dwordx4 v[220:221], off
	v_lshl_add_u64 v[220:221], v[226:227], 0, s[26:27]
	s_mov_b32 m0, s72
	s_nop 0
	global_load_lds_dwordx4 v[220:221], off
	s_waitcnt vmcnt(8)
	s_waitcnt lgkmcnt(0)
	s_barrier
	s_setprio 1
	s_waitcnt lgkmcnt(0)
	v_mfma_f32_16x16x32_bf16 v[60:63], v[128:131], v[180:183], v[60:63]
	v_mfma_f32_16x16x32_bf16 v[60:63], v[132:135], v[192:195], v[60:63]
	v_mfma_f32_16x16x32_bf16 v[56:59], v[136:139], v[180:183], v[56:59]
	v_mfma_f32_16x16x32_bf16 v[56:59], v[140:143], v[192:195], v[56:59]
	v_mfma_f32_16x16x32_bf16 v[44:47], v[128:131], v[196:199], v[44:47]
	v_mfma_f32_16x16x32_bf16 v[44:47], v[132:135], v[200:203], v[44:47]
	v_mfma_f32_16x16x32_bf16 v[40:43], v[136:139], v[196:199], v[40:43]
	v_mfma_f32_16x16x32_bf16 v[40:43], v[140:143], v[200:203], v[40:43]
	v_mfma_f32_16x16x32_bf16 v[28:31], v[128:131], v[204:207], v[28:31]
	v_mfma_f32_16x16x32_bf16 v[28:31], v[132:135], v[208:211], v[28:31]
	v_mfma_f32_16x16x32_bf16 v[24:27], v[136:139], v[204:207], v[24:27]
	v_mfma_f32_16x16x32_bf16 v[24:27], v[140:143], v[208:211], v[24:27]
	v_mfma_f32_16x16x32_bf16 v[12:15], v[128:131], v[212:215], v[12:15]
	v_mfma_f32_16x16x32_bf16 v[12:15], v[132:135], v[216:219], v[12:15]
	v_mfma_f32_16x16x32_bf16 v[8:11], v[136:139], v[212:215], v[8:11]
	v_mfma_f32_16x16x32_bf16 v[8:11], v[140:143], v[216:219], v[8:11]
	s_setprio 0
	s_setprio 1
	v_mfma_f32_16x16x32_bf16 v[52:55], v[144:147], v[180:183], v[52:55]
	v_mfma_f32_16x16x32_bf16 v[52:55], v[148:151], v[192:195], v[52:55]
	v_mfma_f32_16x16x32_bf16 v[48:51], v[172:175], v[180:183], v[48:51]
	v_mfma_f32_16x16x32_bf16 v[48:51], v[176:179], v[192:195], v[48:51]
	v_mfma_f32_16x16x32_bf16 v[36:39], v[144:147], v[196:199], v[36:39]
	v_mfma_f32_16x16x32_bf16 v[36:39], v[148:151], v[200:203], v[36:39]
	v_mfma_f32_16x16x32_bf16 v[32:35], v[172:175], v[196:199], v[32:35]
	v_mfma_f32_16x16x32_bf16 v[32:35], v[176:179], v[200:203], v[32:35]
	v_mfma_f32_16x16x32_bf16 v[20:23], v[144:147], v[204:207], v[20:23]
	v_mfma_f32_16x16x32_bf16 v[20:23], v[148:151], v[208:211], v[20:23]
	v_mfma_f32_16x16x32_bf16 v[16:19], v[172:175], v[204:207], v[16:19]
	v_mfma_f32_16x16x32_bf16 v[16:19], v[176:179], v[208:211], v[16:19]
	v_mfma_f32_16x16x32_bf16 v[4:7], v[144:147], v[212:215], v[4:7]
	v_mfma_f32_16x16x32_bf16 v[4:7], v[148:151], v[216:219], v[4:7]
	v_mfma_f32_16x16x32_bf16 v[0:3], v[172:175], v[212:215], v[0:3]
	v_mfma_f32_16x16x32_bf16 v[0:3], v[176:179], v[216:219], v[0:3]
	s_setprio 0
	s_barrier
	s_add_i32 s80, s80, 2
	s_add_u32 s78, s78, 0x100
	s_addc_u32 s79, s79, 0
	s_add_u32 s58, s58, 0x100
	s_addc_u32 s59, s59, 0
	s_cmp_gt_u32 s80, 13
	s_branch .LBB0_1011
.Lfa_9:
	ds_read_b128 v[128:131], v188
	ds_read_b128 v[132:135], v188 offset:1024
	ds_read_b128 v[136:139], v188 offset:2048
	ds_read_b128 v[140:143], v188 offset:3072
	ds_read_b128 v[144:147], v189
	ds_read_b128 v[148:151], v189 offset:1024
	ds_read_b128 v[172:175], v189 offset:2048
	ds_read_b128 v[176:179], v189 offset:3072
	s_add_u32 s60, s58, 0xfffc0080
	s_addc_u32 s61, s59, -1
	s_cmp_eq_u32 s80, 12
	s_cselect_b32 s63, s15, s61
	s_cselect_b32 s62, s51, s60
	s_cselect_b32 s61, s49, s79
	s_cselect_b32 s60, s57, s78
	v_lshl_add_u64 v[220:221], s[58:59], 0, v[166:167]
	s_add_i32 m0, s67, 0xc000
	ds_read_b128 v[180:183], v190
	ds_read_b128 v[192:195], v190 offset:1024
	ds_read_b128 v[196:199], v190 offset:2048
	ds_read_b128 v[200:203], v190 offset:3072
	ds_read_b128 v[204:207], v190 offset:4096
	ds_read_b128 v[208:211], v190 offset:5120
	ds_read_b128 v[212:215], v190 offset:6144
	ds_read_b128 v[216:219], v190 offset:7168
	global_load_lds_dwordx4 v[220:221], off
	v_lshl_add_u64 v[220:221], s[58:59], 0, v[164:165]
	s_add_i32 m0, s67, 0xe000
	s_nop 0
	global_load_lds_dwordx4 v[220:221], off
	s_waitcnt vmcnt(8)
	s_waitcnt lgkmcnt(0)
	s_barrier
	s_setprio 1
	s_waitcnt lgkmcnt(0)
	v_mfma_f32_16x16x32_bf16 v[124:127], v[128:131], v[180:183], 0
	v_mfma_f32_16x16x32_bf16 v[120:123], v[136:139], v[180:183], 0
	v_mfma_f32_16x16x32_bf16 v[108:111], v[128:131], v[196:199], 0
	v_mfma_f32_16x16x32_bf16 v[104:107], v[136:139], v[196:199], 0
	v_mfma_f32_16x16x32_bf16 v[92:95], v[128:131], v[204:207], 0
	v_mfma_f32_16x16x32_bf16 v[88:91], v[136:139], v[204:207], 0
	v_mfma_f32_16x16x32_bf16 v[76:79], v[128:131], v[212:215], 0
	v_mfma_f32_16x16x32_bf16 v[72:75], v[136:139], v[212:215], 0
	v_mfma_f32_16x16x32_bf16 v[124:127], v[132:135], v[192:195], v[124:127]
	v_mfma_f32_16x16x32_bf16 v[120:123], v[140:143], v[192:195], v[120:123]
	v_mfma_f32_16x16x32_bf16 v[108:111], v[132:135], v[200:203], v[108:111]
	v_mfma_f32_16x16x32_bf16 v[104:107], v[140:143], v[200:203], v[104:107]
	v_mfma_f32_16x16x32_bf16 v[92:95], v[132:135], v[208:211], v[92:95]
	v_mfma_f32_16x16x32_bf16 v[88:91], v[140:143], v[208:211], v[88:91]
	v_mfma_f32_16x16x32_bf16 v[76:79], v[132:135], v[216:219], v[76:79]
	v_mfma_f32_16x16x32_bf16 v[72:75], v[140:143], v[216:219], v[72:75]
	s_setprio 0
	s_setprio 1
	v_mfma_f32_16x16x32_bf16 v[116:119], v[144:147], v[180:183], 0
	v_mfma_f32_16x16x32_bf16 v[112:115], v[172:175], v[180:183], 0
	v_mfma_f32_16x16x32_bf16 v[100:103], v[144:147], v[196:199], 0
	v_mfma_f32_16x16x32_bf16 v[96:99], v[172:175], v[196:199], 0
	v_mfma_f32_16x16x32_bf16 v[84:87], v[144:147], v[204:207], 0
	v_mfma_f32_16x16x32_bf16 v[80:83], v[172:175], v[204:207], 0
	v_mfma_f32_16x16x32_bf16 v[68:71], v[144:147], v[212:215], 0
	v_mfma_f32_16x16x32_bf16 v[64:67], v[172:175], v[212:215], 0
	v_mfma_f32_16x16x32_bf16 v[116:119], v[148:151], v[192:195], v[116:119]
	v_mfma_f32_16x16x32_bf16 v[112:115], v[176:179], v[192:195], v[112:115]
	v_mfma_f32_16x16x32_bf16 v[100:103], v[148:151], v[200:203], v[100:103]
	v_mfma_f32_16x16x32_bf16 v[96:99], v[176:179], v[200:203], v[96:99]
	v_mfma_f32_16x16x32_bf16 v[84:87], v[148:151], v[208:211], v[84:87]
	v_mfma_f32_16x16x32_bf16 v[80:83], v[176:179], v[208:211], v[80:83]
	v_mfma_f32_16x16x32_bf16 v[68:71], v[148:151], v[216:219], v[68:71]
	v_mfma_f32_16x16x32_bf16 v[64:67], v[176:179], v[216:219], v[64:67]
	s_setprio 0
	s_barrier
	s_add_i32 s81, s76, s66
	v_lshl_add_u64 v[220:221], s[60:61], 0, v[154:155]
	s_mov_b32 m0, s81
	ds_read_b128 v[180:183], v190 offset:16384
	ds_read_b128 v[192:195], v190 offset:17408
	ds_read_b128 v[196:199], v190 offset:18432
	ds_read_b128 v[200:203], v190 offset:19456
	ds_read_b128 v[204:207], v190 offset:20480
	ds_read_b128 v[208:211], v190 offset:21504
	ds_read_b128 v[212:215], v190 offset:22528
	ds_read_b128 v[216:219], v190 offset:23552
	global_load_lds_dwordx4 v[220:221], off
	s_add_i32 m0, s81, 0x2000
	s_add_u32 s82, s60, 0x40000
	v_lshl_add_u64 v[222:223], s[60:61], 0, v[162:163]
	s_addc_u32 s83, s61, 0
	s_add_i32 s81, s77, s66
	global_load_lds_dwordx4 v[222:223], off
	v_lshl_add_u64 v[224:225], s[82:83], 0, v[154:155]
	s_mov_b32 m0, s81
	v_lshl_add_u64 v[226:227], s[62:63], 0, v[160:161]
	global_load_lds_dwordx4 v[224:225], off
	v_lshl_add_u64 v[224:225], s[82:83], 0, v[162:163]
	s_add_i32 m0, s81, 0x2000
	s_nop 0
	global_load_lds_dwordx4 v[224:225], off
	v_lshl_add_u64 v[224:225], s[62:63], 0, v[152:153]
	s_mov_b32 m0, s67
	s_nop 0
	global_load_lds_dwordx4 v[224:225], off
	s_mov_b32 m0, s68
	s_nop 0
	global_load_lds_dwordx4 v[226:227], off
	s_waitcnt vmcnt(8)
	s_waitcnt lgkmcnt(0)
	s_barrier
	s_setprio 1
	s_waitcnt lgkmcnt(0)
	v_mfma_f32_16x16x32_bf16 v[60:63], v[128:131], v[180:183], 0
	v_mfma_f32_16x16x32_bf16 v[56:59], v[136:139], v[180:183], 0
	v_mfma_f32_16x16x32_bf16 v[44:47], v[128:131], v[196:199], 0
	v_mfma_f32_16x16x32_bf16 v[40:43], v[136:139], v[196:199], 0
	v_mfma_f32_16x16x32_bf16 v[28:31], v[128:131], v[204:207], 0
	v_mfma_f32_16x16x32_bf16 v[24:27], v[136:139], v[204:207], 0
	v_mfma_f32_16x16x32_bf16 v[12:15], v[128:131], v[212:215], 0
	v_mfma_f32_16x16x32_bf16 v[8:11], v[136:139], v[212:215], 0
	v_mfma_f32_16x16x32_bf16 v[60:63], v[132:135], v[192:195], v[60:63]
	v_mfma_f32_16x16x32_bf16 v[56:59], v[140:143], v[192:195], v[56:59]
	v_mfma_f32_16x16x32_bf16 v[44:47], v[132:135], v[200:203], v[44:47]
	v_mfma_f32_16x16x32_bf16 v[40:43], v[140:143], v[200:203], v[40:43]
	v_mfma_f32_16x16x32_bf16 v[28:31], v[132:135], v[208:211], v[28:31]
	v_mfma_f32_16x16x32_bf16 v[24:27], v[140:143], v[208:211], v[24:27]
	v_mfma_f32_16x16x32_bf16 v[12:15], v[132:135], v[216:219], v[12:15]
	v_mfma_f32_16x16x32_bf16 v[8:11], v[140:143], v[216:219], v[8:11]
	s_setprio 0
	s_setprio 1
	v_mfma_f32_16x16x32_bf16 v[52:55], v[144:147], v[180:183], 0
	v_mfma_f32_16x16x32_bf16 v[48:51], v[172:175], v[180:183], 0
	v_mfma_f32_16x16x32_bf16 v[36:39], v[144:147], v[196:199], 0
	v_mfma_f32_16x16x32_bf16 v[32:35], v[172:175], v[196:199], 0
	v_mfma_f32_16x16x32_bf16 v[20:23], v[144:147], v[204:207], 0
	v_mfma_f32_16x16x32_bf16 v[16:19], v[172:175], v[204:207], 0
	v_mfma_f32_16x16x32_bf16 v[4:7], v[144:147], v[212:215], 0
	v_mfma_f32_16x16x32_bf16 v[0:3], v[172:175], v[212:215], 0
	v_mfma_f32_16x16x32_bf16 v[52:55], v[148:151], v[192:195], v[52:55]
	v_mfma_f32_16x16x32_bf16 v[48:51], v[176:179], v[192:195], v[48:51]
	v_mfma_f32_16x16x32_bf16 v[36:39], v[148:151], v[200:203], v[36:39]
	v_mfma_f32_16x16x32_bf16 v[32:35], v[176:179], v[200:203], v[32:35]
	v_mfma_f32_16x16x32_bf16 v[20:23], v[148:151], v[208:211], v[20:23]
	v_mfma_f32_16x16x32_bf16 v[16:19], v[176:179], v[208:211], v[16:19]
	v_mfma_f32_16x16x32_bf16 v[4:7], v[148:151], v[216:219], v[4:7]
	v_mfma_f32_16x16x32_bf16 v[0:3], v[176:179], v[216:219], v[0:3]
	s_setprio 0
	s_barrier
	s_add_i32 s81, 0, 0x18000
	s_add_i32 s82, 0, 0x1c000
	v_add_u32_e32 v140, s81, v185
	v_add_u32_e32 v176, s82, v185
	ds_read_b128 v[128:131], v140
	ds_read_b128 v[132:135], v140 offset:1024
	ds_read_b128 v[136:139], v140 offset:2048
	ds_read_b128 v[140:143], v140 offset:3072
	ds_read_b128 v[144:147], v176
	ds_read_b128 v[148:151], v176 offset:1024
	ds_read_b128 v[172:175], v176 offset:2048
	ds_read_b128 v[176:179], v176 offset:3072
	s_add_u32 s62, s62, 0x40000
	s_addc_u32 s63, s63, 0
	s_mov_b32 m0, s69
	v_lshl_add_u64 v[228:229], s[62:63], 0, v[152:153]
	ds_read_b128 v[180:183], v190 offset:32768
	ds_read_b128 v[192:195], v190 offset:33792
	ds_read_b128 v[196:199], v190 offset:34816
	ds_read_b128 v[200:203], v190 offset:35840
	ds_read_b128 v[204:207], v190 offset:36864
	ds_read_b128 v[208:211], v190 offset:37888
	ds_read_b128 v[212:215], v190 offset:38912
	ds_read_b128 v[216:219], v190 offset:39936
	global_load_lds_dwordx4 v[228:229], off
	v_lshl_add_u64 v[228:229], s[62:63], 0, v[160:161]
	s_mov_b32 m0, s70
	s_nop 0
	global_load_lds_dwordx4 v[228:229], off
	s_waitcnt vmcnt(8)
	s_waitcnt lgkmcnt(0)
	s_barrier
	s_setprio 1
	s_waitcnt lgkmcnt(0)
	v_mfma_f32_16x16x32_bf16 v[124:127], v[128:131], v[180:183], v[124:127]
	v_mfma_f32_16x16x32_bf16 v[124:127], v[132:135], v[192:195], v[124:127]
	v_mfma_f32_16x16x32_bf16 v[120:123], v[136:139], v[180:183], v[120:123]
	v_mfma_f32_16x16x32_bf16 v[120:123], v[140:143], v[192:195], v[120:123]
	v_mfma_f32_16x16x32_bf16 v[108:111], v[128:131], v[196:199], v[108:111]
	v_mfma_f32_16x16x32_bf16 v[108:111], v[132:135], v[200:203], v[108:111]
	v_mfma_f32_16x16x32_bf16 v[104:107], v[136:139], v[196:199], v[104:107]
	v_mfma_f32_16x16x32_bf16 v[104:107], v[140:143], v[200:203], v[104:107]
	v_mfma_f32_16x16x32_bf16 v[92:95], v[128:131], v[204:207], v[92:95]
	v_mfma_f32_16x16x32_bf16 v[92:95], v[132:135], v[208:211], v[92:95]
	v_mfma_f32_16x16x32_bf16 v[88:91], v[136:139], v[204:207], v[88:91]
	v_mfma_f32_16x16x32_bf16 v[88:91], v[140:143], v[208:211], v[88:91]
	v_mfma_f32_16x16x32_bf16 v[76:79], v[128:131], v[212:215], v[76:79]
	v_mfma_f32_16x16x32_bf16 v[76:79], v[132:135], v[216:219], v[76:79]
	v_mfma_f32_16x16x32_bf16 v[72:75], v[136:139], v[212:215], v[72:75]
	v_mfma_f32_16x16x32_bf16 v[72:75], v[140:143], v[216:219], v[72:75]
	s_setprio 0
	s_setprio 1
	v_mfma_f32_16x16x32_bf16 v[116:119], v[144:147], v[180:183], v[116:119]
	v_mfma_f32_16x16x32_bf16 v[116:119], v[148:151], v[192:195], v[116:119]
	v_mfma_f32_16x16x32_bf16 v[112:115], v[172:175], v[180:183], v[112:115]
	v_mfma_f32_16x16x32_bf16 v[112:115], v[176:179], v[192:195], v[112:115]
	v_mfma_f32_16x16x32_bf16 v[100:103], v[144:147], v[196:199], v[100:103]
	v_mfma_f32_16x16x32_bf16 v[100:103], v[148:151], v[200:203], v[100:103]
	v_mfma_f32_16x16x32_bf16 v[96:99], v[172:175], v[196:199], v[96:99]
	v_mfma_f32_16x16x32_bf16 v[96:99], v[176:179], v[200:203], v[96:99]
	v_mfma_f32_16x16x32_bf16 v[84:87], v[144:147], v[204:207], v[84:87]
	v_mfma_f32_16x16x32_bf16 v[84:87], v[148:151], v[208:211], v[84:87]
	v_mfma_f32_16x16x32_bf16 v[80:83], v[172:175], v[204:207], v[80:83]
	v_mfma_f32_16x16x32_bf16 v[80:83], v[176:179], v[208:211], v[80:83]
	v_mfma_f32_16x16x32_bf16 v[68:71], v[144:147], v[212:215], v[68:71]
	v_mfma_f32_16x16x32_bf16 v[68:71], v[148:151], v[216:219], v[68:71]
	v_mfma_f32_16x16x32_bf16 v[64:67], v[172:175], v[212:215], v[64:67]
	v_mfma_f32_16x16x32_bf16 v[64:67], v[176:179], v[216:219], v[64:67]
	s_setprio 0
	s_barrier
	s_add_i32 s62, s81, s66
	v_lshl_add_u64 v[220:221], v[220:221], 0, s[26:27]
	s_mov_b32 m0, s62
	ds_read_b128 v[180:183], v190 offset:49152
	ds_read_b128 v[192:195], v190 offset:50176
	ds_read_b128 v[196:199], v190 offset:51200
	ds_read_b128 v[200:203], v190 offset:52224
	ds_read_b128 v[204:207], v190 offset:53248
	ds_read_b128 v[208:211], v190 offset:54272
	ds_read_b128 v[212:215], v190 offset:55296
	ds_read_b128 v[216:219], v190 offset:56320
	global_load_lds_dwordx4 v[220:221], off
	s_add_i32 m0, s62, 0x2000
	s_add_u32 s60, s60, 0x40080
	v_lshl_add_u64 v[220:221], v[222:223], 0, s[26:27]
	s_addc_u32 s61, s61, 0
	s_add_i32 s62, s82, s66
	global_load_lds_dwordx4 v[220:221], off
	v_lshl_add_u64 v[220:221], s[60:61], 0, v[154:155]
	s_mov_b32 m0, s62
	s_nop 0
	global_load_lds_dwordx4 v[220:221], off
	v_lshl_add_u64 v[220:221], s[60:61], 0, v[162:163]
	s_add_i32 m0, s62, 0x2000
	s_nop 0
	global_load_lds_dwordx4 v[220:221], off
	v_lshl_add_u64 v[220:221], v[224:225], 0, s[26:27]
	s_mov_b32 m0, s3
	s_nop 0
	global_load_lds_dwordx4 v[220:221], off
	v_lshl_add_u64 v[220:221], v[226:227], 0, s[26:27]
	s_mov_b32 m0, s72
	s_nop 0
	global_load_lds_dwordx4 v[220:221], off
	s_waitcnt vmcnt(8)
	s_waitcnt lgkmcnt(0)
	s_barrier
	s_setprio 1
	s_waitcnt lgkmcnt(0)
	v_mfma_f32_16x16x32_bf16 v[60:63], v[128:131], v[180:183], v[60:63]
	v_mfma_f32_16x16x32_bf16 v[60:63], v[132:135], v[192:195], v[60:63]
	v_mfma_f32_16x16x32_bf16 v[56:59], v[136:139], v[180:183], v[56:59]
	v_mfma_f32_16x16x32_bf16 v[56:59], v[140:143], v[192:195], v[56:59]
	v_mfma_f32_16x16x32_bf16 v[44:47], v[128:131], v[196:199], v[44:47]
	v_mfma_f32_16x16x32_bf16 v[44:47], v[132:135], v[200:203], v[44:47]
	v_mfma_f32_16x16x32_bf16 v[40:43], v[136:139], v[196:199], v[40:43]
	v_mfma_f32_16x16x32_bf16 v[40:43], v[140:143], v[200:203], v[40:43]
	v_mfma_f32_16x16x32_bf16 v[28:31], v[128:131], v[204:207], v[28:31]
	v_mfma_f32_16x16x32_bf16 v[28:31], v[132:135], v[208:211], v[28:31]
	v_mfma_f32_16x16x32_bf16 v[24:27], v[136:139], v[204:207], v[24:27]
	v_mfma_f32_16x16x32_bf16 v[24:27], v[140:143], v[208:211], v[24:27]
	v_mfma_f32_16x16x32_bf16 v[12:15], v[128:131], v[212:215], v[12:15]
	v_mfma_f32_16x16x32_bf16 v[12:15], v[132:135], v[216:219], v[12:15]
	v_mfma_f32_16x16x32_bf16 v[8:11], v[136:139], v[212:215], v[8:11]
	v_mfma_f32_16x16x32_bf16 v[8:11], v[140:143], v[216:219], v[8:11]
	s_setprio 0
	s_setprio 1
	v_mfma_f32_16x16x32_bf16 v[52:55], v[144:147], v[180:183], v[52:55]
	v_mfma_f32_16x16x32_bf16 v[52:55], v[148:151], v[192:195], v[52:55]
	v_mfma_f32_16x16x32_bf16 v[48:51], v[172:175], v[180:183], v[48:51]
	v_mfma_f32_16x16x32_bf16 v[48:51], v[176:179], v[192:195], v[48:51]
	v_mfma_f32_16x16x32_bf16 v[36:39], v[144:147], v[196:199], v[36:39]
	v_mfma_f32_16x16x32_bf16 v[36:39], v[148:151], v[200:203], v[36:39]
	v_mfma_f32_16x16x32_bf16 v[32:35], v[172:175], v[196:199], v[32:35]
	v_mfma_f32_16x16x32_bf16 v[32:35], v[176:179], v[200:203], v[32:35]
	v_mfma_f32_16x16x32_bf16 v[20:23], v[144:147], v[204:207], v[20:23]
	v_mfma_f32_16x16x32_bf16 v[20:23], v[148:151], v[208:211], v[20:23]
	v_mfma_f32_16x16x32_bf16 v[16:19], v[172:175], v[204:207], v[16:19]
	v_mfma_f32_16x16x32_bf16 v[16:19], v[176:179], v[208:211], v[16:19]
	v_mfma_f32_16x16x32_bf16 v[4:7], v[144:147], v[212:215], v[4:7]
	v_mfma_f32_16x16x32_bf16 v[4:7], v[148:151], v[216:219], v[4:7]
	v_mfma_f32_16x16x32_bf16 v[0:3], v[172:175], v[212:215], v[0:3]
	v_mfma_f32_16x16x32_bf16 v[0:3], v[176:179], v[216:219], v[0:3]
	s_setprio 0
	s_barrier
	s_add_i32 s80, s80, 2
	s_add_u32 s78, s78, 0x100
	s_addc_u32 s79, s79, 0
	s_add_u32 s58, s58, 0x100
	s_addc_u32 s59, s59, 0
	s_cmp_gt_u32 s80, 13
.LBB0_1011:
	ds_read_b128 v[128:131], v188
	ds_read_b128 v[132:135], v188 offset:1024
	ds_read_b128 v[136:139], v188 offset:2048
	ds_read_b128 v[140:143], v188 offset:3072
	ds_read_b128 v[144:147], v189
	ds_read_b128 v[148:151], v189 offset:1024
	ds_read_b128 v[172:175], v189 offset:2048
	ds_read_b128 v[176:179], v189 offset:3072
	s_add_u32 s60, s58, 0xfffc0080
	s_addc_u32 s61, s59, -1
	s_cmp_eq_u32 s80, 12
	s_cselect_b32 s63, s15, s61
	s_cselect_b32 s62, s51, s60
	s_cselect_b32 s61, s49, s79
	s_cselect_b32 s60, s57, s78
	v_lshl_add_u64 v[220:221], s[58:59], 0, v[166:167]
	s_add_i32 m0, s67, 0xc000
	ds_read_b128 v[180:183], v190
	ds_read_b128 v[192:195], v190 offset:1024
	ds_read_b128 v[196:199], v190 offset:2048
	ds_read_b128 v[200:203], v190 offset:3072
	ds_read_b128 v[204:207], v190 offset:4096
	ds_read_b128 v[208:211], v190 offset:5120
	ds_read_b128 v[212:215], v190 offset:6144
	ds_read_b128 v[216:219], v190 offset:7168
	global_load_lds_dwordx4 v[220:221], off
	v_lshl_add_u64 v[220:221], s[58:59], 0, v[164:165]
	s_add_i32 m0, s67, 0xe000
	s_nop 0
	global_load_lds_dwordx4 v[220:221], off
	s_waitcnt vmcnt(8)
	s_waitcnt lgkmcnt(0)
	s_barrier
	s_setprio 1
	s_waitcnt lgkmcnt(0)
	v_mfma_f32_16x16x32_bf16 v[124:127], v[128:131], v[180:183], v[124:127]
	v_mfma_f32_16x16x32_bf16 v[124:127], v[132:135], v[192:195], v[124:127]
	v_mfma_f32_16x16x32_bf16 v[120:123], v[136:139], v[180:183], v[120:123]
	v_mfma_f32_16x16x32_bf16 v[120:123], v[140:143], v[192:195], v[120:123]
	v_mfma_f32_16x16x32_bf16 v[108:111], v[128:131], v[196:199], v[108:111]
	v_mfma_f32_16x16x32_bf16 v[108:111], v[132:135], v[200:203], v[108:111]
	v_mfma_f32_16x16x32_bf16 v[104:107], v[136:139], v[196:199], v[104:107]
	v_mfma_f32_16x16x32_bf16 v[104:107], v[140:143], v[200:203], v[104:107]
	v_mfma_f32_16x16x32_bf16 v[92:95], v[128:131], v[204:207], v[92:95]
	v_mfma_f32_16x16x32_bf16 v[92:95], v[132:135], v[208:211], v[92:95]
	v_mfma_f32_16x16x32_bf16 v[88:91], v[136:139], v[204:207], v[88:91]
	v_mfma_f32_16x16x32_bf16 v[88:91], v[140:143], v[208:211], v[88:91]
	v_mfma_f32_16x16x32_bf16 v[76:79], v[128:131], v[212:215], v[76:79]
	v_mfma_f32_16x16x32_bf16 v[76:79], v[132:135], v[216:219], v[76:79]
	v_mfma_f32_16x16x32_bf16 v[72:75], v[136:139], v[212:215], v[72:75]
	v_mfma_f32_16x16x32_bf16 v[72:75], v[140:143], v[216:219], v[72:75]
	s_setprio 0
	s_setprio 1
	v_mfma_f32_16x16x32_bf16 v[116:119], v[144:147], v[180:183], v[116:119]
	v_mfma_f32_16x16x32_bf16 v[116:119], v[148:151], v[192:195], v[116:119]
	v_mfma_f32_16x16x32_bf16 v[112:115], v[172:175], v[180:183], v[112:115]
	v_mfma_f32_16x16x32_bf16 v[112:115], v[176:179], v[192:195], v[112:115]
	v_mfma_f32_16x16x32_bf16 v[100:103], v[144:147], v[196:199], v[100:103]
	v_mfma_f32_16x16x32_bf16 v[100:103], v[148:151], v[200:203], v[100:103]
	v_mfma_f32_16x16x32_bf16 v[96:99], v[172:175], v[196:199], v[96:99]
	v_mfma_f32_16x16x32_bf16 v[96:99], v[176:179], v[200:203], v[96:99]
	v_mfma_f32_16x16x32_bf16 v[84:87], v[144:147], v[204:207], v[84:87]
	v_mfma_f32_16x16x32_bf16 v[84:87], v[148:151], v[208:211], v[84:87]
	v_mfma_f32_16x16x32_bf16 v[80:83], v[172:175], v[204:207], v[80:83]
	v_mfma_f32_16x16x32_bf16 v[80:83], v[176:179], v[208:211], v[80:83]
	v_mfma_f32_16x16x32_bf16 v[68:71], v[144:147], v[212:215], v[68:71]
	v_mfma_f32_16x16x32_bf16 v[68:71], v[148:151], v[216:219], v[68:71]
	v_mfma_f32_16x16x32_bf16 v[64:67], v[172:175], v[212:215], v[64:67]
	v_mfma_f32_16x16x32_bf16 v[64:67], v[176:179], v[216:219], v[64:67]
	s_setprio 0
	s_barrier
	s_add_i32 s81, s76, s66
	v_lshl_add_u64 v[220:221], s[60:61], 0, v[154:155]
	s_mov_b32 m0, s81
	ds_read_b128 v[180:183], v190 offset:16384
	ds_read_b128 v[192:195], v190 offset:17408
	ds_read_b128 v[196:199], v190 offset:18432
	ds_read_b128 v[200:203], v190 offset:19456
	ds_read_b128 v[204:207], v190 offset:20480
	ds_read_b128 v[208:211], v190 offset:21504
	ds_read_b128 v[212:215], v190 offset:22528
	ds_read_b128 v[216:219], v190 offset:23552
	global_load_lds_dwordx4 v[220:221], off
	s_add_i32 m0, s81, 0x2000
	s_add_u32 s82, s60, 0x40000
	v_lshl_add_u64 v[222:223], s[60:61], 0, v[162:163]
	s_addc_u32 s83, s61, 0
	s_add_i32 s81, s77, s66
	global_load_lds_dwordx4 v[222:223], off
	v_lshl_add_u64 v[224:225], s[82:83], 0, v[154:155]
	s_mov_b32 m0, s81
	v_lshl_add_u64 v[226:227], s[62:63], 0, v[160:161]
	global_load_lds_dwordx4 v[224:225], off
	v_lshl_add_u64 v[224:225], s[82:83], 0, v[162:163]
	s_add_i32 m0, s81, 0x2000
	s_nop 0
	global_load_lds_dwordx4 v[224:225], off
	v_lshl_add_u64 v[224:225], s[62:63], 0, v[152:153]
	s_mov_b32 m0, s67
	s_nop 0
	global_load_lds_dwordx4 v[224:225], off
	s_mov_b32 m0, s68
	s_nop 0
	global_load_lds_dwordx4 v[226:227], off
	s_waitcnt vmcnt(8)
	s_waitcnt lgkmcnt(0)
	s_barrier
	s_setprio 1
	s_waitcnt lgkmcnt(0)
	v_mfma_f32_16x16x32_bf16 v[60:63], v[128:131], v[180:183], v[60:63]
	v_mfma_f32_16x16x32_bf16 v[60:63], v[132:135], v[192:195], v[60:63]
	v_mfma_f32_16x16x32_bf16 v[56:59], v[136:139], v[180:183], v[56:59]
	v_mfma_f32_16x16x32_bf16 v[56:59], v[140:143], v[192:195], v[56:59]
	v_mfma_f32_16x16x32_bf16 v[44:47], v[128:131], v[196:199], v[44:47]
	v_mfma_f32_16x16x32_bf16 v[44:47], v[132:135], v[200:203], v[44:47]
	v_mfma_f32_16x16x32_bf16 v[40:43], v[136:139], v[196:199], v[40:43]
	v_mfma_f32_16x16x32_bf16 v[40:43], v[140:143], v[200:203], v[40:43]
	v_mfma_f32_16x16x32_bf16 v[28:31], v[128:131], v[204:207], v[28:31]
	v_mfma_f32_16x16x32_bf16 v[28:31], v[132:135], v[208:211], v[28:31]
	v_mfma_f32_16x16x32_bf16 v[24:27], v[136:139], v[204:207], v[24:27]
	v_mfma_f32_16x16x32_bf16 v[24:27], v[140:143], v[208:211], v[24:27]
	v_mfma_f32_16x16x32_bf16 v[12:15], v[128:131], v[212:215], v[12:15]
	v_mfma_f32_16x16x32_bf16 v[12:15], v[132:135], v[216:219], v[12:15]
	v_mfma_f32_16x16x32_bf16 v[8:11], v[136:139], v[212:215], v[8:11]
	v_mfma_f32_16x16x32_bf16 v[8:11], v[140:143], v[216:219], v[8:11]
	s_setprio 0
	s_setprio 1
	v_mfma_f32_16x16x32_bf16 v[52:55], v[144:147], v[180:183], v[52:55]
	v_mfma_f32_16x16x32_bf16 v[52:55], v[148:151], v[192:195], v[52:55]
	v_mfma_f32_16x16x32_bf16 v[48:51], v[172:175], v[180:183], v[48:51]
	v_mfma_f32_16x16x32_bf16 v[48:51], v[176:179], v[192:195], v[48:51]
	v_mfma_f32_16x16x32_bf16 v[36:39], v[144:147], v[196:199], v[36:39]
	v_mfma_f32_16x16x32_bf16 v[36:39], v[148:151], v[200:203], v[36:39]
	v_mfma_f32_16x16x32_bf16 v[32:35], v[172:175], v[196:199], v[32:35]
	v_mfma_f32_16x16x32_bf16 v[32:35], v[176:179], v[200:203], v[32:35]
	v_mfma_f32_16x16x32_bf16 v[20:23], v[144:147], v[204:207], v[20:23]
	v_mfma_f32_16x16x32_bf16 v[20:23], v[148:151], v[208:211], v[20:23]
	v_mfma_f32_16x16x32_bf16 v[16:19], v[172:175], v[204:207], v[16:19]
	v_mfma_f32_16x16x32_bf16 v[16:19], v[176:179], v[208:211], v[16:19]
	v_mfma_f32_16x16x32_bf16 v[4:7], v[144:147], v[212:215], v[4:7]
	v_mfma_f32_16x16x32_bf16 v[4:7], v[148:151], v[216:219], v[4:7]
	v_mfma_f32_16x16x32_bf16 v[0:3], v[172:175], v[212:215], v[0:3]
	v_mfma_f32_16x16x32_bf16 v[0:3], v[176:179], v[216:219], v[0:3]
	s_setprio 0
	s_barrier
	s_add_i32 s81, 0, 0x18000
	s_add_i32 s82, 0, 0x1c000
	v_add_u32_e32 v140, s81, v185
	v_add_u32_e32 v176, s82, v185
	ds_read_b128 v[128:131], v140
	ds_read_b128 v[132:135], v140 offset:1024
	ds_read_b128 v[136:139], v140 offset:2048
	ds_read_b128 v[140:143], v140 offset:3072
	ds_read_b128 v[144:147], v176
	ds_read_b128 v[148:151], v176 offset:1024
	ds_read_b128 v[172:175], v176 offset:2048
	ds_read_b128 v[176:179], v176 offset:3072
	s_add_u32 s62, s62, 0x40000
	s_addc_u32 s63, s63, 0
	s_mov_b32 m0, s69
	v_lshl_add_u64 v[228:229], s[62:63], 0, v[152:153]
	ds_read_b128 v[180:183], v190 offset:32768
	ds_read_b128 v[192:195], v190 offset:33792
	ds_read_b128 v[196:199], v190 offset:34816
	ds_read_b128 v[200:203], v190 offset:35840
	ds_read_b128 v[204:207], v190 offset:36864
	ds_read_b128 v[208:211], v190 offset:37888
	ds_read_b128 v[212:215], v190 offset:38912
	ds_read_b128 v[216:219], v190 offset:39936
	global_load_lds_dwordx4 v[228:229], off
	v_lshl_add_u64 v[228:229], s[62:63], 0, v[160:161]
	s_mov_b32 m0, s70
	s_nop 0
	global_load_lds_dwordx4 v[228:229], off
	s_waitcnt vmcnt(8)
	s_waitcnt lgkmcnt(0)
	s_barrier
	s_setprio 1
	s_waitcnt lgkmcnt(0)
	v_mfma_f32_16x16x32_bf16 v[124:127], v[128:131], v[180:183], v[124:127]
	v_mfma_f32_16x16x32_bf16 v[124:127], v[132:135], v[192:195], v[124:127]
	v_mfma_f32_16x16x32_bf16 v[120:123], v[136:139], v[180:183], v[120:123]
	v_mfma_f32_16x16x32_bf16 v[120:123], v[140:143], v[192:195], v[120:123]
	v_mfma_f32_16x16x32_bf16 v[108:111], v[128:131], v[196:199], v[108:111]
	v_mfma_f32_16x16x32_bf16 v[108:111], v[132:135], v[200:203], v[108:111]
	v_mfma_f32_16x16x32_bf16 v[104:107], v[136:139], v[196:199], v[104:107]
	v_mfma_f32_16x16x32_bf16 v[104:107], v[140:143], v[200:203], v[104:107]
	v_mfma_f32_16x16x32_bf16 v[92:95], v[128:131], v[204:207], v[92:95]
	v_mfma_f32_16x16x32_bf16 v[92:95], v[132:135], v[208:211], v[92:95]
	v_mfma_f32_16x16x32_bf16 v[88:91], v[136:139], v[204:207], v[88:91]
	v_mfma_f32_16x16x32_bf16 v[88:91], v[140:143], v[208:211], v[88:91]
	v_mfma_f32_16x16x32_bf16 v[76:79], v[128:131], v[212:215], v[76:79]
	v_mfma_f32_16x16x32_bf16 v[76:79], v[132:135], v[216:219], v[76:79]
	v_mfma_f32_16x16x32_bf16 v[72:75], v[136:139], v[212:215], v[72:75]
	v_mfma_f32_16x16x32_bf16 v[72:75], v[140:143], v[216:219], v[72:75]
	s_setprio 0
	s_setprio 1
	v_mfma_f32_16x16x32_bf16 v[116:119], v[144:147], v[180:183], v[116:119]
	v_mfma_f32_16x16x32_bf16 v[116:119], v[148:151], v[192:195], v[116:119]
	v_mfma_f32_16x16x32_bf16 v[112:115], v[172:175], v[180:183], v[112:115]
	v_mfma_f32_16x16x32_bf16 v[112:115], v[176:179], v[192:195], v[112:115]
	v_mfma_f32_16x16x32_bf16 v[100:103], v[144:147], v[196:199], v[100:103]
	v_mfma_f32_16x16x32_bf16 v[100:103], v[148:151], v[200:203], v[100:103]
	v_mfma_f32_16x16x32_bf16 v[96:99], v[172:175], v[196:199], v[96:99]
	v_mfma_f32_16x16x32_bf16 v[96:99], v[176:179], v[200:203], v[96:99]
	v_mfma_f32_16x16x32_bf16 v[84:87], v[144:147], v[204:207], v[84:87]
	v_mfma_f32_16x16x32_bf16 v[84:87], v[148:151], v[208:211], v[84:87]
	v_mfma_f32_16x16x32_bf16 v[80:83], v[172:175], v[204:207], v[80:83]
	v_mfma_f32_16x16x32_bf16 v[80:83], v[176:179], v[208:211], v[80:83]
	v_mfma_f32_16x16x32_bf16 v[68:71], v[144:147], v[212:215], v[68:71]
	v_mfma_f32_16x16x32_bf16 v[68:71], v[148:151], v[216:219], v[68:71]
	v_mfma_f32_16x16x32_bf16 v[64:67], v[172:175], v[212:215], v[64:67]
	v_mfma_f32_16x16x32_bf16 v[64:67], v[176:179], v[216:219], v[64:67]
	s_setprio 0
	s_barrier
	s_add_i32 s62, s81, s66
	v_lshl_add_u64 v[220:221], v[220:221], 0, s[26:27]
	s_mov_b32 m0, s62
	ds_read_b128 v[180:183], v190 offset:49152
	ds_read_b128 v[192:195], v190 offset:50176
	ds_read_b128 v[196:199], v190 offset:51200
	ds_read_b128 v[200:203], v190 offset:52224
	ds_read_b128 v[204:207], v190 offset:53248
	ds_read_b128 v[208:211], v190 offset:54272
	ds_read_b128 v[212:215], v190 offset:55296
	ds_read_b128 v[216:219], v190 offset:56320
	global_load_lds_dwordx4 v[220:221], off
	s_add_i32 m0, s62, 0x2000
	s_add_u32 s60, s60, 0x40080
	v_lshl_add_u64 v[220:221], v[222:223], 0, s[26:27]
	s_addc_u32 s61, s61, 0
	s_add_i32 s62, s82, s66
	global_load_lds_dwordx4 v[220:221], off
	v_lshl_add_u64 v[220:221], s[60:61], 0, v[154:155]
	s_mov_b32 m0, s62
	s_nop 0
	global_load_lds_dwordx4 v[220:221], off
	v_lshl_add_u64 v[220:221], s[60:61], 0, v[162:163]
	s_add_i32 m0, s62, 0x2000
	s_nop 0
	global_load_lds_dwordx4 v[220:221], off
	v_lshl_add_u64 v[220:221], v[224:225], 0, s[26:27]
	s_mov_b32 m0, s3
	s_nop 0
	global_load_lds_dwordx4 v[220:221], off
	v_lshl_add_u64 v[220:221], v[226:227], 0, s[26:27]
	s_mov_b32 m0, s72
	s_nop 0
	global_load_lds_dwordx4 v[220:221], off
	s_waitcnt vmcnt(8)
	s_waitcnt lgkmcnt(0)
	s_barrier
	s_setprio 1
	s_waitcnt lgkmcnt(0)
	v_mfma_f32_16x16x32_bf16 v[60:63], v[128:131], v[180:183], v[60:63]
	v_mfma_f32_16x16x32_bf16 v[60:63], v[132:135], v[192:195], v[60:63]
	v_mfma_f32_16x16x32_bf16 v[56:59], v[136:139], v[180:183], v[56:59]
	v_mfma_f32_16x16x32_bf16 v[56:59], v[140:143], v[192:195], v[56:59]
	v_mfma_f32_16x16x32_bf16 v[44:47], v[128:131], v[196:199], v[44:47]
	v_mfma_f32_16x16x32_bf16 v[44:47], v[132:135], v[200:203], v[44:47]
	v_mfma_f32_16x16x32_bf16 v[40:43], v[136:139], v[196:199], v[40:43]
	v_mfma_f32_16x16x32_bf16 v[40:43], v[140:143], v[200:203], v[40:43]
	v_mfma_f32_16x16x32_bf16 v[28:31], v[128:131], v[204:207], v[28:31]
	v_mfma_f32_16x16x32_bf16 v[28:31], v[132:135], v[208:211], v[28:31]
	v_mfma_f32_16x16x32_bf16 v[24:27], v[136:139], v[204:207], v[24:27]
	v_mfma_f32_16x16x32_bf16 v[24:27], v[140:143], v[208:211], v[24:27]
	v_mfma_f32_16x16x32_bf16 v[12:15], v[128:131], v[212:215], v[12:15]
	v_mfma_f32_16x16x32_bf16 v[12:15], v[132:135], v[216:219], v[12:15]
	v_mfma_f32_16x16x32_bf16 v[8:11], v[136:139], v[212:215], v[8:11]
	v_mfma_f32_16x16x32_bf16 v[8:11], v[140:143], v[216:219], v[8:11]
	s_setprio 0
	s_setprio 1
	v_mfma_f32_16x16x32_bf16 v[52:55], v[144:147], v[180:183], v[52:55]
	v_mfma_f32_16x16x32_bf16 v[52:55], v[148:151], v[192:195], v[52:55]
	v_mfma_f32_16x16x32_bf16 v[48:51], v[172:175], v[180:183], v[48:51]
	v_mfma_f32_16x16x32_bf16 v[48:51], v[176:179], v[192:195], v[48:51]
	v_mfma_f32_16x16x32_bf16 v[36:39], v[144:147], v[196:199], v[36:39]
	v_mfma_f32_16x16x32_bf16 v[36:39], v[148:151], v[200:203], v[36:39]
	v_mfma_f32_16x16x32_bf16 v[32:35], v[172:175], v[196:199], v[32:35]
	v_mfma_f32_16x16x32_bf16 v[32:35], v[176:179], v[200:203], v[32:35]
	v_mfma_f32_16x16x32_bf16 v[20:23], v[144:147], v[204:207], v[20:23]
	v_mfma_f32_16x16x32_bf16 v[20:23], v[148:151], v[208:211], v[20:23]
	v_mfma_f32_16x16x32_bf16 v[16:19], v[172:175], v[204:207], v[16:19]
	v_mfma_f32_16x16x32_bf16 v[16:19], v[176:179], v[208:211], v[16:19]
	v_mfma_f32_16x16x32_bf16 v[4:7], v[144:147], v[212:215], v[4:7]
	v_mfma_f32_16x16x32_bf16 v[4:7], v[148:151], v[216:219], v[4:7]
	v_mfma_f32_16x16x32_bf16 v[0:3], v[172:175], v[212:215], v[0:3]
	v_mfma_f32_16x16x32_bf16 v[0:3], v[176:179], v[216:219], v[0:3]
	s_setprio 0
	s_barrier
	s_add_i32 s80, s80, 2
	s_add_u32 s78, s78, 0x100
	s_addc_u32 s79, s79, 0
	s_add_u32 s58, s58, 0x100
	s_addc_u32 s59, s59, 0
	s_cmp_gt_u32 s80, 13
	s_cbranch_scc0 .LBB0_1011
	s_and_b64 vcc, exec, s[28:29]
	s_cbranch_vccz .LBB0_1014
	s_barrier

.LBB0_1096:
	s_ashr_i32 s25, s24, 31
	s_lshl_b64 s[26:27], s[24:25], 19
	s_add_u32 s26, s3, s26
	s_addc_u32 s27, s33, s27
	s_and_b64 s[28:29], s[6:7], exec
	s_cselect_b32 s25, s27, s47
	s_cselect_b32 s65, s26, s46
	s_ashr_i32 s23, s22, 31
	s_lshl_b64 s[28:29], s[22:23], 19
	s_add_u32 s28, s35, s28
	s_addc_u32 s29, s48, s29
	s_and_b64 s[66:67], s[6:7], exec
	s_cselect_b32 s66, s29, s45
	s_cselect_b32 s67, s28, s44
	s_lshl_b32 s23, s30, 8
	v_add_u32_e32 v0, s23, v148
	s_add_u32 s68, s44, 0x100
	v_ashrrev_i32_e32 v1, 31, v0
	s_addc_u32 s69, s45, 0
	v_lshl_add_u64 v[144:145], v[0:1], 4, s[12:13]
	s_add_u32 s30, s46, 0x40080
	s_addc_u32 s31, s47, 0
	s_mov_b32 s70, -2
	s_mov_b64 s[44:45], 0
	s_cmp_eq_u32 s56, 1
	s_cbranch_scc1 .Lfa_10
	v_add_u32_e32 v153, s61, v147
	ds_read_b128 v[160:163], v153
	ds_read_b128 v[164:167], v153 offset:1024
	ds_read_b128 v[168:171], v153 offset:2048
	ds_read_b128 v[172:175], v153 offset:3072
	v_add_u32_e32 v153, s62, v147
	ds_read_b128 v[176:179], v153
	ds_read_b128 v[180:183], v153 offset:1024
	ds_read_b128 v[184:187], v153 offset:2048
	ds_read_b128 v[188:191], v153 offset:3072
	s_add_u32 s46, s30, 0xfffc0080
	s_addc_u32 s47, s31, -1
	s_and_b64 s[44:45], s[44:45], exec
	s_cselect_b32 s47, s25, s47
	s_cselect_b32 s46, s65, s46
	s_cselect_b32 s45, s66, s69
	s_cselect_b32 s44, s67, s68
	v_lshl_add_u64 v[154:155], s[30:31], 0, v[138:139]
	s_add_i32 m0, s52, 0xc000
	ds_read_b128 v[192:195], v150
	ds_read_b128 v[196:199], v150 offset:1024
	ds_read_b128 v[200:203], v150 offset:2048
	ds_read_b128 v[204:207], v150 offset:3072
	ds_read_b128 v[208:211], v150 offset:4096
	ds_read_b128 v[212:215], v150 offset:5120
	ds_read_b128 v[216:219], v150 offset:6144
	ds_read_b128 v[220:223], v150 offset:7168
	global_load_lds_dwordx4 v[154:155], off
	v_lshl_add_u64 v[154:155], s[30:31], 0, v[136:137]
	s_add_i32 m0, s52, 0xe000
	s_nop 0
	global_load_lds_dwordx4 v[154:155], off
	s_waitcnt vmcnt(16)
	s_waitcnt lgkmcnt(0)
	s_barrier
	s_setprio 1
	s_waitcnt lgkmcnt(0)
	v_mfma_f32_16x16x32_bf16 v[124:127], v[160:163], v[192:195], 0
	v_mfma_f32_16x16x32_bf16 v[116:119], v[168:171], v[192:195], 0
	v_mfma_f32_16x16x32_bf16 v[108:111], v[160:163], v[200:203], 0
	v_mfma_f32_16x16x32_bf16 v[100:103], v[168:171], v[200:203], 0
	v_mfma_f32_16x16x32_bf16 v[92:95], v[160:163], v[208:211], 0
	v_mfma_f32_16x16x32_bf16 v[84:87], v[168:171], v[208:211], 0
	v_mfma_f32_16x16x32_bf16 v[76:79], v[160:163], v[216:219], 0
	v_mfma_f32_16x16x32_bf16 v[68:71], v[168:171], v[216:219], 0
	v_mfma_f32_16x16x32_bf16 v[124:127], v[164:167], v[196:199], v[124:127]
	v_mfma_f32_16x16x32_bf16 v[116:119], v[172:175], v[196:199], v[116:119]
	v_mfma_f32_16x16x32_bf16 v[108:111], v[164:167], v[204:207], v[108:111]
	v_mfma_f32_16x16x32_bf16 v[100:103], v[172:175], v[204:207], v[100:103]
	v_mfma_f32_16x16x32_bf16 v[92:95], v[164:167], v[212:215], v[92:95]
	v_mfma_f32_16x16x32_bf16 v[84:87], v[172:175], v[212:215], v[84:87]
	v_mfma_f32_16x16x32_bf16 v[76:79], v[164:167], v[220:223], v[76:79]
	v_mfma_f32_16x16x32_bf16 v[68:71], v[172:175], v[220:223], v[68:71]
	s_setprio 0
	s_setprio 1
	v_mfma_f32_16x16x32_bf16 v[120:123], v[176:179], v[192:195], 0
	v_mfma_f32_16x16x32_bf16 v[112:115], v[184:187], v[192:195], 0
	v_mfma_f32_16x16x32_bf16 v[104:107], v[176:179], v[200:203], 0
	v_mfma_f32_16x16x32_bf16 v[96:99], v[184:187], v[200:203], 0
	v_mfma_f32_16x16x32_bf16 v[88:91], v[176:179], v[208:211], 0
	v_mfma_f32_16x16x32_bf16 v[80:83], v[184:187], v[208:211], 0
	v_mfma_f32_16x16x32_bf16 v[72:75], v[176:179], v[216:219], 0
	v_mfma_f32_16x16x32_bf16 v[64:67], v[184:187], v[216:219], 0
	v_mfma_f32_16x16x32_bf16 v[120:123], v[180:183], v[196:199], v[120:123]
	v_mfma_f32_16x16x32_bf16 v[112:115], v[188:191], v[196:199], v[112:115]
	v_mfma_f32_16x16x32_bf16 v[104:107], v[180:183], v[204:207], v[104:107]
	v_mfma_f32_16x16x32_bf16 v[96:99], v[188:191], v[204:207], v[96:99]
	v_mfma_f32_16x16x32_bf16 v[88:91], v[180:183], v[212:215], v[88:91]
	v_mfma_f32_16x16x32_bf16 v[80:83], v[188:191], v[212:215], v[80:83]
	v_mfma_f32_16x16x32_bf16 v[72:75], v[180:183], v[220:223], v[72:75]
	v_mfma_f32_16x16x32_bf16 v[64:67], v[188:191], v[220:223], v[64:67]
	s_setprio 0
	s_barrier
	s_add_i32 s71, s61, s49
	v_lshl_add_u64 v[154:155], s[44:45], 0, v[132:133]
	s_mov_b32 m0, s71
	ds_read_b128 v[192:195], v150 offset:16384
	ds_read_b128 v[196:199], v150 offset:17408
	ds_read_b128 v[200:203], v150 offset:18432
	ds_read_b128 v[204:207], v150 offset:19456
	ds_read_b128 v[208:211], v150 offset:20480
	ds_read_b128 v[212:215], v150 offset:21504
	ds_read_b128 v[216:219], v150 offset:22528
	ds_read_b128 v[220:223], v150 offset:23552
	global_load_lds_dwordx4 v[154:155], off
	s_add_i32 m0, s71, 0x2000
	s_add_u32 s72, s44, 0x40000
	v_lshl_add_u64 v[224:225], s[44:45], 0, v[128:129]
	s_addc_u32 s73, s45, 0
	s_add_i32 s71, s62, s49
	global_load_lds_dwordx4 v[224:225], off
	v_lshl_add_u64 v[226:227], s[72:73], 0, v[132:133]
	s_mov_b32 m0, s71
	v_lshl_add_u64 v[228:229], s[46:47], 0, v[130:131]
	global_load_lds_dwordx4 v[226:227], off
	v_lshl_add_u64 v[226:227], s[72:73], 0, v[128:129]
	s_add_i32 m0, s71, 0x2000
	s_nop 0
	global_load_lds_dwordx4 v[226:227], off
	v_lshl_add_u64 v[226:227], s[46:47], 0, v[134:135]
	s_mov_b32 m0, s52
	s_nop 0
	global_load_lds_dwordx4 v[226:227], off
	s_mov_b32 m0, s53
	s_nop 0
	global_load_lds_dwordx4 v[228:229], off
	s_waitcnt vmcnt(16)
	s_waitcnt lgkmcnt(0)
	s_barrier
	s_setprio 1
	s_waitcnt lgkmcnt(0)
	v_mfma_f32_16x16x32_bf16 v[60:63], v[160:163], v[192:195], 0
	v_mfma_f32_16x16x32_bf16 v[52:55], v[168:171], v[192:195], 0
	v_mfma_f32_16x16x32_bf16 v[44:47], v[160:163], v[200:203], 0
	v_mfma_f32_16x16x32_bf16 v[36:39], v[168:171], v[200:203], 0
	v_mfma_f32_16x16x32_bf16 v[28:31], v[160:163], v[208:211], 0
	v_mfma_f32_16x16x32_bf16 v[20:23], v[168:171], v[208:211], 0
	v_mfma_f32_16x16x32_bf16 v[12:15], v[160:163], v[216:219], 0
	v_mfma_f32_16x16x32_bf16 v[4:7], v[168:171], v[216:219], 0
	v_mfma_f32_16x16x32_bf16 v[60:63], v[164:167], v[196:199], v[60:63]
	v_mfma_f32_16x16x32_bf16 v[52:55], v[172:175], v[196:199], v[52:55]
	v_mfma_f32_16x16x32_bf16 v[44:47], v[164:167], v[204:207], v[44:47]
	v_mfma_f32_16x16x32_bf16 v[36:39], v[172:175], v[204:207], v[36:39]
	v_mfma_f32_16x16x32_bf16 v[28:31], v[164:167], v[212:215], v[28:31]
	v_mfma_f32_16x16x32_bf16 v[20:23], v[172:175], v[212:215], v[20:23]
	v_mfma_f32_16x16x32_bf16 v[12:15], v[164:167], v[220:223], v[12:15]
	v_mfma_f32_16x16x32_bf16 v[4:7], v[172:175], v[220:223], v[4:7]
	s_setprio 0
	s_setprio 1
	v_mfma_f32_16x16x32_bf16 v[56:59], v[176:179], v[192:195], 0
	v_mfma_f32_16x16x32_bf16 v[48:51], v[184:187], v[192:195], 0
	v_mfma_f32_16x16x32_bf16 v[40:43], v[176:179], v[200:203], 0
	v_mfma_f32_16x16x32_bf16 v[32:35], v[184:187], v[200:203], 0
	v_mfma_f32_16x16x32_bf16 v[24:27], v[176:179], v[208:211], 0
	v_mfma_f32_16x16x32_bf16 v[16:19], v[184:187], v[208:211], 0
	v_mfma_f32_16x16x32_bf16 v[8:11], v[176:179], v[216:219], 0
	v_mfma_f32_16x16x32_bf16 v[0:3], v[184:187], v[216:219], 0
	v_mfma_f32_16x16x32_bf16 v[56:59], v[180:183], v[196:199], v[56:59]
	v_mfma_f32_16x16x32_bf16 v[48:51], v[188:191], v[196:199], v[48:51]
	v_mfma_f32_16x16x32_bf16 v[40:43], v[180:183], v[204:207], v[40:43]
	v_mfma_f32_16x16x32_bf16 v[32:35], v[188:191], v[204:207], v[32:35]
	v_mfma_f32_16x16x32_bf16 v[24:27], v[180:183], v[212:215], v[24:27]
	v_mfma_f32_16x16x32_bf16 v[16:19], v[188:191], v[212:215], v[16:19]
	v_mfma_f32_16x16x32_bf16 v[8:11], v[180:183], v[220:223], v[8:11]
	v_mfma_f32_16x16x32_bf16 v[0:3], v[188:191], v[220:223], v[0:3]
	s_setprio 0
	s_barrier
	s_add_i32 s71, 0, 0x18000
	v_add_u32_e32 v153, s71, v147
	s_add_i32 s72, 0, 0x1c000
	ds_read_b128 v[160:163], v153
	ds_read_b128 v[164:167], v153 offset:1024
	ds_read_b128 v[168:171], v153 offset:2048
	ds_read_b128 v[172:175], v153 offset:3072
	v_add_u32_e32 v153, s72, v147
	ds_read_b128 v[176:179], v153
	ds_read_b128 v[180:183], v153 offset:1024
	ds_read_b128 v[184:187], v153 offset:2048
	ds_read_b128 v[188:191], v153 offset:3072
	s_add_u32 s46, s46, 0x40000
	s_addc_u32 s47, s47, 0
	s_mov_b32 m0, s54
	v_lshl_add_u64 v[230:231], s[46:47], 0, v[134:135]
	ds_read_b128 v[192:195], v150 offset:32768
	ds_read_b128 v[196:199], v150 offset:33792
	ds_read_b128 v[200:203], v150 offset:34816
	ds_read_b128 v[204:207], v150 offset:35840
	ds_read_b128 v[208:211], v150 offset:36864
	ds_read_b128 v[212:215], v150 offset:37888
	ds_read_b128 v[216:219], v150 offset:38912
	ds_read_b128 v[220:223], v150 offset:39936
	global_load_lds_dwordx4 v[230:231], off
	v_lshl_add_u64 v[230:231], s[46:47], 0, v[130:131]
	s_mov_b32 m0, s55
	s_nop 0
	global_load_lds_dwordx4 v[230:231], off
	s_waitcnt vmcnt(8)
	s_waitcnt lgkmcnt(0)
	s_barrier
	s_setprio 1
	s_waitcnt lgkmcnt(0)
	v_mfma_f32_16x16x32_bf16 v[124:127], v[160:163], v[192:195], v[124:127]
	v_mfma_f32_16x16x32_bf16 v[124:127], v[164:167], v[196:199], v[124:127]
	v_mfma_f32_16x16x32_bf16 v[116:119], v[168:171], v[192:195], v[116:119]
	v_mfma_f32_16x16x32_bf16 v[116:119], v[172:175], v[196:199], v[116:119]
	v_mfma_f32_16x16x32_bf16 v[108:111], v[160:163], v[200:203], v[108:111]
	v_mfma_f32_16x16x32_bf16 v[108:111], v[164:167], v[204:207], v[108:111]
	v_mfma_f32_16x16x32_bf16 v[100:103], v[168:171], v[200:203], v[100:103]
	v_mfma_f32_16x16x32_bf16 v[100:103], v[172:175], v[204:207], v[100:103]
	v_mfma_f32_16x16x32_bf16 v[92:95], v[160:163], v[208:211], v[92:95]
	v_mfma_f32_16x16x32_bf16 v[92:95], v[164:167], v[212:215], v[92:95]
	v_mfma_f32_16x16x32_bf16 v[84:87], v[168:171], v[208:211], v[84:87]
	v_mfma_f32_16x16x32_bf16 v[84:87], v[172:175], v[212:215], v[84:87]
	v_mfma_f32_16x16x32_bf16 v[76:79], v[160:163], v[216:219], v[76:79]
	v_mfma_f32_16x16x32_bf16 v[76:79], v[164:167], v[220:223], v[76:79]
	v_mfma_f32_16x16x32_bf16 v[68:71], v[168:171], v[216:219], v[68:71]
	v_mfma_f32_16x16x32_bf16 v[68:71], v[172:175], v[220:223], v[68:71]
	s_setprio 0
	s_setprio 1
	v_mfma_f32_16x16x32_bf16 v[120:123], v[176:179], v[192:195], v[120:123]
	v_mfma_f32_16x16x32_bf16 v[120:123], v[180:183], v[196:199], v[120:123]
	v_mfma_f32_16x16x32_bf16 v[112:115], v[184:187], v[192:195], v[112:115]
	v_mfma_f32_16x16x32_bf16 v[112:115], v[188:191], v[196:199], v[112:115]
	v_mfma_f32_16x16x32_bf16 v[104:107], v[176:179], v[200:203], v[104:107]
	v_mfma_f32_16x16x32_bf16 v[104:107], v[180:183], v[204:207], v[104:107]
	v_mfma_f32_16x16x32_bf16 v[96:99], v[184:187], v[200:203], v[96:99]
	v_mfma_f32_16x16x32_bf16 v[96:99], v[188:191], v[204:207], v[96:99]
	v_mfma_f32_16x16x32_bf16 v[88:91], v[176:179], v[208:211], v[88:91]
	v_mfma_f32_16x16x32_bf16 v[88:91], v[180:183], v[212:215], v[88:91]
	v_mfma_f32_16x16x32_bf16 v[80:83], v[184:187], v[208:211], v[80:83]
	v_mfma_f32_16x16x32_bf16 v[80:83], v[188:191], v[212:215], v[80:83]
	v_mfma_f32_16x16x32_bf16 v[72:75], v[176:179], v[216:219], v[72:75]
	v_mfma_f32_16x16x32_bf16 v[72:75], v[180:183], v[220:223], v[72:75]
	v_mfma_f32_16x16x32_bf16 v[64:67], v[184:187], v[216:219], v[64:67]
	v_mfma_f32_16x16x32_bf16 v[64:67], v[188:191], v[220:223], v[64:67]
	s_setprio 0
	s_barrier
	s_add_i32 s46, s71, s49
	v_lshl_add_u64 v[154:155], v[154:155], 0, s[14:15]
	s_mov_b32 m0, s46
	ds_read_b128 v[192:195], v150 offset:49152
	ds_read_b128 v[196:199], v150 offset:50176
	ds_read_b128 v[200:203], v150 offset:51200
	ds_read_b128 v[204:207], v150 offset:52224
	ds_read_b128 v[208:211], v150 offset:53248
	ds_read_b128 v[212:215], v150 offset:54272
	ds_read_b128 v[216:219], v150 offset:55296
	ds_read_b128 v[220:223], v150 offset:56320
	global_load_lds_dwordx4 v[154:155], off
	s_add_i32 m0, s46, 0x2000
	s_add_u32 s44, s44, 0x40080
	v_lshl_add_u64 v[154:155], v[224:225], 0, s[14:15]
	s_addc_u32 s45, s45, 0
	s_add_i32 s46, s72, s49
	global_load_lds_dwordx4 v[154:155], off
	v_lshl_add_u64 v[154:155], s[44:45], 0, v[132:133]
	s_mov_b32 m0, s46
	s_nop 0
	global_load_lds_dwordx4 v[154:155], off
	v_lshl_add_u64 v[154:155], s[44:45], 0, v[128:129]
	s_add_i32 m0, s46, 0x2000
	s_nop 0
	global_load_lds_dwordx4 v[154:155], off
	v_lshl_add_u64 v[154:155], v[226:227], 0, s[14:15]
	s_mov_b32 m0, s57
	s_nop 0
	global_load_lds_dwordx4 v[154:155], off
	v_lshl_add_u64 v[154:155], v[228:229], 0, s[14:15]
	s_mov_b32 m0, s58
	s_nop 0
	global_load_lds_dwordx4 v[154:155], off
	s_waitcnt vmcnt(8)
	s_waitcnt lgkmcnt(0)
	s_barrier
	s_setprio 1
	s_waitcnt lgkmcnt(0)
	v_mfma_f32_16x16x32_bf16 v[60:63], v[160:163], v[192:195], v[60:63]
	v_mfma_f32_16x16x32_bf16 v[60:63], v[164:167], v[196:199], v[60:63]
	v_mfma_f32_16x16x32_bf16 v[52:55], v[168:171], v[192:195], v[52:55]
	v_mfma_f32_16x16x32_bf16 v[52:55], v[172:175], v[196:199], v[52:55]
	v_mfma_f32_16x16x32_bf16 v[44:47], v[160:163], v[200:203], v[44:47]
	v_mfma_f32_16x16x32_bf16 v[44:47], v[164:167], v[204:207], v[44:47]
	v_mfma_f32_16x16x32_bf16 v[36:39], v[168:171], v[200:203], v[36:39]
	v_mfma_f32_16x16x32_bf16 v[36:39], v[172:175], v[204:207], v[36:39]
	v_mfma_f32_16x16x32_bf16 v[28:31], v[160:163], v[208:211], v[28:31]
	v_mfma_f32_16x16x32_bf16 v[28:31], v[164:167], v[212:215], v[28:31]
	v_mfma_f32_16x16x32_bf16 v[20:23], v[168:171], v[208:211], v[20:23]
	v_mfma_f32_16x16x32_bf16 v[20:23], v[172:175], v[212:215], v[20:23]
	v_mfma_f32_16x16x32_bf16 v[12:15], v[160:163], v[216:219], v[12:15]
	v_mfma_f32_16x16x32_bf16 v[12:15], v[164:167], v[220:223], v[12:15]
	v_mfma_f32_16x16x32_bf16 v[4:7], v[168:171], v[216:219], v[4:7]
	v_mfma_f32_16x16x32_bf16 v[4:7], v[172:175], v[220:223], v[4:7]
	s_setprio 0
	s_setprio 1
	v_mfma_f32_16x16x32_bf16 v[56:59], v[176:179], v[192:195], v[56:59]
	v_mfma_f32_16x16x32_bf16 v[56:59], v[180:183], v[196:199], v[56:59]
	v_mfma_f32_16x16x32_bf16 v[48:51], v[184:187], v[192:195], v[48:51]
	v_mfma_f32_16x16x32_bf16 v[48:51], v[188:191], v[196:199], v[48:51]
	v_mfma_f32_16x16x32_bf16 v[40:43], v[176:179], v[200:203], v[40:43]
	v_mfma_f32_16x16x32_bf16 v[40:43], v[180:183], v[204:207], v[40:43]
	v_mfma_f32_16x16x32_bf16 v[32:35], v[184:187], v[200:203], v[32:35]
	v_mfma_f32_16x16x32_bf16 v[32:35], v[188:191], v[204:207], v[32:35]
	v_mfma_f32_16x16x32_bf16 v[24:27], v[176:179], v[208:211], v[24:27]
	v_mfma_f32_16x16x32_bf16 v[24:27], v[180:183], v[212:215], v[24:27]
	v_mfma_f32_16x16x32_bf16 v[16:19], v[184:187], v[208:211], v[16:19]
	v_mfma_f32_16x16x32_bf16 v[16:19], v[188:191], v[212:215], v[16:19]
	v_mfma_f32_16x16x32_bf16 v[8:11], v[176:179], v[216:219], v[8:11]
	v_mfma_f32_16x16x32_bf16 v[8:11], v[180:183], v[220:223], v[8:11]
	v_mfma_f32_16x16x32_bf16 v[0:3], v[184:187], v[216:219], v[0:3]
	v_mfma_f32_16x16x32_bf16 v[0:3], v[188:191], v[220:223], v[0:3]
	s_setprio 0
	s_barrier
	s_add_i32 s70, s70, 2
	s_add_u32 s68, s68, 0x100
	s_addc_u32 s69, s69, 0
	s_add_u32 s30, s30, 0x100
	s_addc_u32 s31, s31, 0
	s_branch .LBB0_1098
.Lfa_10:
	v_add_u32_e32 v153, s61, v147
	ds_read_b128 v[160:163], v153
	ds_read_b128 v[164:167], v153 offset:1024
	ds_read_b128 v[168:171], v153 offset:2048
	ds_read_b128 v[172:175], v153 offset:3072
	v_add_u32_e32 v153, s62, v147
	ds_read_b128 v[176:179], v153
	ds_read_b128 v[180:183], v153 offset:1024
	ds_read_b128 v[184:187], v153 offset:2048
	ds_read_b128 v[188:191], v153 offset:3072
	s_add_u32 s46, s30, 0xfffc0080
	s_addc_u32 s47, s31, -1
	s_and_b64 s[44:45], s[44:45], exec
	s_cselect_b32 s47, s25, s47
	s_cselect_b32 s46, s65, s46
	s_cselect_b32 s45, s66, s69
	s_cselect_b32 s44, s67, s68
	v_lshl_add_u64 v[154:155], s[30:31], 0, v[138:139]
	s_add_i32 m0, s52, 0xc000
	ds_read_b128 v[192:195], v150
	ds_read_b128 v[196:199], v150 offset:1024
	ds_read_b128 v[200:203], v150 offset:2048
	ds_read_b128 v[204:207], v150 offset:3072
	ds_read_b128 v[208:211], v150 offset:4096
	ds_read_b128 v[212:215], v150 offset:5120
	ds_read_b128 v[216:219], v150 offset:6144
	ds_read_b128 v[220:223], v150 offset:7168
	global_load_lds_dwordx4 v[154:155], off
	v_lshl_add_u64 v[154:155], s[30:31], 0, v[136:137]
	s_add_i32 m0, s52, 0xe000
	s_nop 0
	global_load_lds_dwordx4 v[154:155], off
	s_waitcnt vmcnt(8)
	s_waitcnt lgkmcnt(0)
	s_barrier
	s_setprio 1
	s_waitcnt lgkmcnt(0)
	v_mfma_f32_16x16x32_bf16 v[124:127], v[160:163], v[192:195], 0
	v_mfma_f32_16x16x32_bf16 v[116:119], v[168:171], v[192:195], 0
	v_mfma_f32_16x16x32_bf16 v[108:111], v[160:163], v[200:203], 0
	v_mfma_f32_16x16x32_bf16 v[100:103], v[168:171], v[200:203], 0
	v_mfma_f32_16x16x32_bf16 v[92:95], v[160:163], v[208:211], 0
	v_mfma_f32_16x16x32_bf16 v[84:87], v[168:171], v[208:211], 0
	v_mfma_f32_16x16x32_bf16 v[76:79], v[160:163], v[216:219], 0
	v_mfma_f32_16x16x32_bf16 v[68:71], v[168:171], v[216:219], 0
	v_mfma_f32_16x16x32_bf16 v[124:127], v[164:167], v[196:199], v[124:127]
	v_mfma_f32_16x16x32_bf16 v[116:119], v[172:175], v[196:199], v[116:119]
	v_mfma_f32_16x16x32_bf16 v[108:111], v[164:167], v[204:207], v[108:111]
	v_mfma_f32_16x16x32_bf16 v[100:103], v[172:175], v[204:207], v[100:103]
	v_mfma_f32_16x16x32_bf16 v[92:95], v[164:167], v[212:215], v[92:95]
	v_mfma_f32_16x16x32_bf16 v[84:87], v[172:175], v[212:215], v[84:87]
	v_mfma_f32_16x16x32_bf16 v[76:79], v[164:167], v[220:223], v[76:79]
	v_mfma_f32_16x16x32_bf16 v[68:71], v[172:175], v[220:223], v[68:71]
	s_setprio 0
	s_setprio 1
	v_mfma_f32_16x16x32_bf16 v[120:123], v[176:179], v[192:195], 0
	v_mfma_f32_16x16x32_bf16 v[112:115], v[184:187], v[192:195], 0
	v_mfma_f32_16x16x32_bf16 v[104:107], v[176:179], v[200:203], 0
	v_mfma_f32_16x16x32_bf16 v[96:99], v[184:187], v[200:203], 0
	v_mfma_f32_16x16x32_bf16 v[88:91], v[176:179], v[208:211], 0
	v_mfma_f32_16x16x32_bf16 v[80:83], v[184:187], v[208:211], 0
	v_mfma_f32_16x16x32_bf16 v[72:75], v[176:179], v[216:219], 0
	v_mfma_f32_16x16x32_bf16 v[64:67], v[184:187], v[216:219], 0
	v_mfma_f32_16x16x32_bf16 v[120:123], v[180:183], v[196:199], v[120:123]
	v_mfma_f32_16x16x32_bf16 v[112:115], v[188:191], v[196:199], v[112:115]
	v_mfma_f32_16x16x32_bf16 v[104:107], v[180:183], v[204:207], v[104:107]
	v_mfma_f32_16x16x32_bf16 v[96:99], v[188:191], v[204:207], v[96:99]
	v_mfma_f32_16x16x32_bf16 v[88:91], v[180:183], v[212:215], v[88:91]
	v_mfma_f32_16x16x32_bf16 v[80:83], v[188:191], v[212:215], v[80:83]
	v_mfma_f32_16x16x32_bf16 v[72:75], v[180:183], v[220:223], v[72:75]
	v_mfma_f32_16x16x32_bf16 v[64:67], v[188:191], v[220:223], v[64:67]
	s_setprio 0
	s_barrier
	s_add_i32 s71, s61, s49
	v_lshl_add_u64 v[154:155], s[44:45], 0, v[132:133]
	s_mov_b32 m0, s71
	ds_read_b128 v[192:195], v150 offset:16384
	ds_read_b128 v[196:199], v150 offset:17408
	ds_read_b128 v[200:203], v150 offset:18432
	ds_read_b128 v[204:207], v150 offset:19456
	ds_read_b128 v[208:211], v150 offset:20480
	ds_read_b128 v[212:215], v150 offset:21504
	ds_read_b128 v[216:219], v150 offset:22528
	ds_read_b128 v[220:223], v150 offset:23552
	global_load_lds_dwordx4 v[154:155], off
	s_add_i32 m0, s71, 0x2000
	s_add_u32 s72, s44, 0x40000
	v_lshl_add_u64 v[224:225], s[44:45], 0, v[128:129]
	s_addc_u32 s73, s45, 0
	s_add_i32 s71, s62, s49
	global_load_lds_dwordx4 v[224:225], off
	v_lshl_add_u64 v[226:227], s[72:73], 0, v[132:133]
	s_mov_b32 m0, s71
	v_lshl_add_u64 v[228:229], s[46:47], 0, v[130:131]
	global_load_lds_dwordx4 v[226:227], off
	v_lshl_add_u64 v[226:227], s[72:73], 0, v[128:129]
	s_add_i32 m0, s71, 0x2000
	s_nop 0
	global_load_lds_dwordx4 v[226:227], off
	v_lshl_add_u64 v[226:227], s[46:47], 0, v[134:135]
	s_mov_b32 m0, s52
	s_nop 0
	global_load_lds_dwordx4 v[226:227], off
	s_mov_b32 m0, s53
	s_nop 0
	global_load_lds_dwordx4 v[228:229], off
	s_waitcnt vmcnt(8)
	s_waitcnt lgkmcnt(0)
	s_barrier
	s_setprio 1
	s_waitcnt lgkmcnt(0)
	v_mfma_f32_16x16x32_bf16 v[60:63], v[160:163], v[192:195], 0
	v_mfma_f32_16x16x32_bf16 v[52:55], v[168:171], v[192:195], 0
	v_mfma_f32_16x16x32_bf16 v[44:47], v[160:163], v[200:203], 0
	v_mfma_f32_16x16x32_bf16 v[36:39], v[168:171], v[200:203], 0
	v_mfma_f32_16x16x32_bf16 v[28:31], v[160:163], v[208:211], 0
	v_mfma_f32_16x16x32_bf16 v[20:23], v[168:171], v[208:211], 0
	v_mfma_f32_16x16x32_bf16 v[12:15], v[160:163], v[216:219], 0
	v_mfma_f32_16x16x32_bf16 v[4:7], v[168:171], v[216:219], 0
	v_mfma_f32_16x16x32_bf16 v[60:63], v[164:167], v[196:199], v[60:63]
	v_mfma_f32_16x16x32_bf16 v[52:55], v[172:175], v[196:199], v[52:55]
	v_mfma_f32_16x16x32_bf16 v[44:47], v[164:167], v[204:207], v[44:47]
	v_mfma_f32_16x16x32_bf16 v[36:39], v[172:175], v[204:207], v[36:39]
	v_mfma_f32_16x16x32_bf16 v[28:31], v[164:167], v[212:215], v[28:31]
	v_mfma_f32_16x16x32_bf16 v[20:23], v[172:175], v[212:215], v[20:23]
	v_mfma_f32_16x16x32_bf16 v[12:15], v[164:167], v[220:223], v[12:15]
	v_mfma_f32_16x16x32_bf16 v[4:7], v[172:175], v[220:223], v[4:7]
	s_setprio 0
	s_setprio 1
	v_mfma_f32_16x16x32_bf16 v[56:59], v[176:179], v[192:195], 0
	v_mfma_f32_16x16x32_bf16 v[48:51], v[184:187], v[192:195], 0
	v_mfma_f32_16x16x32_bf16 v[40:43], v[176:179], v[200:203], 0
	v_mfma_f32_16x16x32_bf16 v[32:35], v[184:187], v[200:203], 0
	v_mfma_f32_16x16x32_bf16 v[24:27], v[176:179], v[208:211], 0
	v_mfma_f32_16x16x32_bf16 v[16:19], v[184:187], v[208:211], 0
	v_mfma_f32_16x16x32_bf16 v[8:11], v[176:179], v[216:219], 0
	v_mfma_f32_16x16x32_bf16 v[0:3], v[184:187], v[216:219], 0
	v_mfma_f32_16x16x32_bf16 v[56:59], v[180:183], v[196:199], v[56:59]
	v_mfma_f32_16x16x32_bf16 v[48:51], v[188:191], v[196:199], v[48:51]
	v_mfma_f32_16x16x32_bf16 v[40:43], v[180:183], v[204:207], v[40:43]
	v_mfma_f32_16x16x32_bf16 v[32:35], v[188:191], v[204:207], v[32:35]
	v_mfma_f32_16x16x32_bf16 v[24:27], v[180:183], v[212:215], v[24:27]
	v_mfma_f32_16x16x32_bf16 v[16:19], v[188:191], v[212:215], v[16:19]
	v_mfma_f32_16x16x32_bf16 v[8:11], v[180:183], v[220:223], v[8:11]
	v_mfma_f32_16x16x32_bf16 v[0:3], v[188:191], v[220:223], v[0:3]
	s_setprio 0
	s_barrier
	s_add_i32 s71, 0, 0x18000
	v_add_u32_e32 v153, s71, v147
	s_add_i32 s72, 0, 0x1c000
	ds_read_b128 v[160:163], v153
	ds_read_b128 v[164:167], v153 offset:1024
	ds_read_b128 v[168:171], v153 offset:2048
	ds_read_b128 v[172:175], v153 offset:3072
	v_add_u32_e32 v153, s72, v147
	ds_read_b128 v[176:179], v153
	ds_read_b128 v[180:183], v153 offset:1024
	ds_read_b128 v[184:187], v153 offset:2048
	ds_read_b128 v[188:191], v153 offset:3072
	s_add_u32 s46, s46, 0x40000
	s_addc_u32 s47, s47, 0
	s_mov_b32 m0, s54
	v_lshl_add_u64 v[230:231], s[46:47], 0, v[134:135]
	ds_read_b128 v[192:195], v150 offset:32768
	ds_read_b128 v[196:199], v150 offset:33792
	ds_read_b128 v[200:203], v150 offset:34816
	ds_read_b128 v[204:207], v150 offset:35840
	ds_read_b128 v[208:211], v150 offset:36864
	ds_read_b128 v[212:215], v150 offset:37888
	ds_read_b128 v[216:219], v150 offset:38912
	ds_read_b128 v[220:223], v150 offset:39936
	global_load_lds_dwordx4 v[230:231], off
	v_lshl_add_u64 v[230:231], s[46:47], 0, v[130:131]
	s_mov_b32 m0, s55
	s_nop 0
	global_load_lds_dwordx4 v[230:231], off
	s_waitcnt vmcnt(8)
	s_waitcnt lgkmcnt(0)
	s_barrier
	s_setprio 1
	s_waitcnt lgkmcnt(0)
	v_mfma_f32_16x16x32_bf16 v[124:127], v[160:163], v[192:195], v[124:127]
	v_mfma_f32_16x16x32_bf16 v[124:127], v[164:167], v[196:199], v[124:127]
	v_mfma_f32_16x16x32_bf16 v[116:119], v[168:171], v[192:195], v[116:119]
	v_mfma_f32_16x16x32_bf16 v[116:119], v[172:175], v[196:199], v[116:119]
	v_mfma_f32_16x16x32_bf16 v[108:111], v[160:163], v[200:203], v[108:111]
	v_mfma_f32_16x16x32_bf16 v[108:111], v[164:167], v[204:207], v[108:111]
	v_mfma_f32_16x16x32_bf16 v[100:103], v[168:171], v[200:203], v[100:103]
	v_mfma_f32_16x16x32_bf16 v[100:103], v[172:175], v[204:207], v[100:103]
	v_mfma_f32_16x16x32_bf16 v[92:95], v[160:163], v[208:211], v[92:95]
	v_mfma_f32_16x16x32_bf16 v[92:95], v[164:167], v[212:215], v[92:95]
	v_mfma_f32_16x16x32_bf16 v[84:87], v[168:171], v[208:211], v[84:87]
	v_mfma_f32_16x16x32_bf16 v[84:87], v[172:175], v[212:215], v[84:87]
	v_mfma_f32_16x16x32_bf16 v[76:79], v[160:163], v[216:219], v[76:79]
	v_mfma_f32_16x16x32_bf16 v[76:79], v[164:167], v[220:223], v[76:79]
	v_mfma_f32_16x16x32_bf16 v[68:71], v[168:171], v[216:219], v[68:71]
	v_mfma_f32_16x16x32_bf16 v[68:71], v[172:175], v[220:223], v[68:71]
	s_setprio 0
	s_setprio 1
	v_mfma_f32_16x16x32_bf16 v[120:123], v[176:179], v[192:195], v[120:123]
	v_mfma_f32_16x16x32_bf16 v[120:123], v[180:183], v[196:199], v[120:123]
	v_mfma_f32_16x16x32_bf16 v[112:115], v[184:187], v[192:195], v[112:115]
	v_mfma_f32_16x16x32_bf16 v[112:115], v[188:191], v[196:199], v[112:115]
	v_mfma_f32_16x16x32_bf16 v[104:107], v[176:179], v[200:203], v[104:107]
	v_mfma_f32_16x16x32_bf16 v[104:107], v[180:183], v[204:207], v[104:107]
	v_mfma_f32_16x16x32_bf16 v[96:99], v[184:187], v[200:203], v[96:99]
	v_mfma_f32_16x16x32_bf16 v[96:99], v[188:191], v[204:207], v[96:99]
	v_mfma_f32_16x16x32_bf16 v[88:91], v[176:179], v[208:211], v[88:91]
	v_mfma_f32_16x16x32_bf16 v[88:91], v[180:183], v[212:215], v[88:91]
	v_mfma_f32_16x16x32_bf16 v[80:83], v[184:187], v[208:211], v[80:83]
	v_mfma_f32_16x16x32_bf16 v[80:83], v[188:191], v[212:215], v[80:83]
	v_mfma_f32_16x16x32_bf16 v[72:75], v[176:179], v[216:219], v[72:75]
	v_mfma_f32_16x16x32_bf16 v[72:75], v[180:183], v[220:223], v[72:75]
	v_mfma_f32_16x16x32_bf16 v[64:67], v[184:187], v[216:219], v[64:67]
	v_mfma_f32_16x16x32_bf16 v[64:67], v[188:191], v[220:223], v[64:67]
	s_setprio 0
	s_barrier
	s_add_i32 s46, s71, s49
	v_lshl_add_u64 v[154:155], v[154:155], 0, s[14:15]
	s_mov_b32 m0, s46
	ds_read_b128 v[192:195], v150 offset:49152
	ds_read_b128 v[196:199], v150 offset:50176
	ds_read_b128 v[200:203], v150 offset:51200
	ds_read_b128 v[204:207], v150 offset:52224
	ds_read_b128 v[208:211], v150 offset:53248
	ds_read_b128 v[212:215], v150 offset:54272
	ds_read_b128 v[216:219], v150 offset:55296
	ds_read_b128 v[220:223], v150 offset:56320
	global_load_lds_dwordx4 v[154:155], off
	s_add_i32 m0, s46, 0x2000
	s_add_u32 s44, s44, 0x40080
	v_lshl_add_u64 v[154:155], v[224:225], 0, s[14:15]
	s_addc_u32 s45, s45, 0
	s_add_i32 s46, s72, s49
	global_load_lds_dwordx4 v[154:155], off
	v_lshl_add_u64 v[154:155], s[44:45], 0, v[132:133]
	s_mov_b32 m0, s46
	s_nop 0
	global_load_lds_dwordx4 v[154:155], off
	v_lshl_add_u64 v[154:155], s[44:45], 0, v[128:129]
	s_add_i32 m0, s46, 0x2000
	s_nop 0
	global_load_lds_dwordx4 v[154:155], off
	v_lshl_add_u64 v[154:155], v[226:227], 0, s[14:15]
	s_mov_b32 m0, s57
	s_nop 0
	global_load_lds_dwordx4 v[154:155], off
	v_lshl_add_u64 v[154:155], v[228:229], 0, s[14:15]
	s_mov_b32 m0, s58
	s_nop 0
	global_load_lds_dwordx4 v[154:155], off
	s_waitcnt vmcnt(8)
	s_waitcnt lgkmcnt(0)
	s_barrier
	s_setprio 1
	s_waitcnt lgkmcnt(0)
	v_mfma_f32_16x16x32_bf16 v[60:63], v[160:163], v[192:195], v[60:63]
	v_mfma_f32_16x16x32_bf16 v[60:63], v[164:167], v[196:199], v[60:63]
	v_mfma_f32_16x16x32_bf16 v[52:55], v[168:171], v[192:195], v[52:55]
	v_mfma_f32_16x16x32_bf16 v[52:55], v[172:175], v[196:199], v[52:55]
	v_mfma_f32_16x16x32_bf16 v[44:47], v[160:163], v[200:203], v[44:47]
	v_mfma_f32_16x16x32_bf16 v[44:47], v[164:167], v[204:207], v[44:47]
	v_mfma_f32_16x16x32_bf16 v[36:39], v[168:171], v[200:203], v[36:39]
	v_mfma_f32_16x16x32_bf16 v[36:39], v[172:175], v[204:207], v[36:39]
	v_mfma_f32_16x16x32_bf16 v[28:31], v[160:163], v[208:211], v[28:31]
	v_mfma_f32_16x16x32_bf16 v[28:31], v[164:167], v[212:215], v[28:31]
	v_mfma_f32_16x16x32_bf16 v[20:23], v[168:171], v[208:211], v[20:23]
	v_mfma_f32_16x16x32_bf16 v[20:23], v[172:175], v[212:215], v[20:23]
	v_mfma_f32_16x16x32_bf16 v[12:15], v[160:163], v[216:219], v[12:15]
	v_mfma_f32_16x16x32_bf16 v[12:15], v[164:167], v[220:223], v[12:15]
	v_mfma_f32_16x16x32_bf16 v[4:7], v[168:171], v[216:219], v[4:7]
	v_mfma_f32_16x16x32_bf16 v[4:7], v[172:175], v[220:223], v[4:7]
	s_setprio 0
	s_setprio 1
	v_mfma_f32_16x16x32_bf16 v[56:59], v[176:179], v[192:195], v[56:59]
	v_mfma_f32_16x16x32_bf16 v[56:59], v[180:183], v[196:199], v[56:59]
	v_mfma_f32_16x16x32_bf16 v[48:51], v[184:187], v[192:195], v[48:51]
	v_mfma_f32_16x16x32_bf16 v[48:51], v[188:191], v[196:199], v[48:51]
	v_mfma_f32_16x16x32_bf16 v[40:43], v[176:179], v[200:203], v[40:43]
	v_mfma_f32_16x16x32_bf16 v[40:43], v[180:183], v[204:207], v[40:43]
	v_mfma_f32_16x16x32_bf16 v[32:35], v[184:187], v[200:203], v[32:35]
	v_mfma_f32_16x16x32_bf16 v[32:35], v[188:191], v[204:207], v[32:35]
	v_mfma_f32_16x16x32_bf16 v[24:27], v[176:179], v[208:211], v[24:27]
	v_mfma_f32_16x16x32_bf16 v[24:27], v[180:183], v[212:215], v[24:27]
	v_mfma_f32_16x16x32_bf16 v[16:19], v[184:187], v[208:211], v[16:19]
	v_mfma_f32_16x16x32_bf16 v[16:19], v[188:191], v[212:215], v[16:19]
	v_mfma_f32_16x16x32_bf16 v[8:11], v[176:179], v[216:219], v[8:11]
	v_mfma_f32_16x16x32_bf16 v[8:11], v[180:183], v[220:223], v[8:11]
	v_mfma_f32_16x16x32_bf16 v[0:3], v[184:187], v[216:219], v[0:3]
	v_mfma_f32_16x16x32_bf16 v[0:3], v[188:191], v[220:223], v[0:3]
	s_setprio 0
	s_barrier
	s_add_i32 s70, s70, 2
	s_add_u32 s68, s68, 0x100
	s_addc_u32 s69, s69, 0
	s_add_u32 s30, s30, 0x100
	s_addc_u32 s31, s31, 0
	s_branch .LBB0_1098
.LBB0_1097:
	v_add_u32_e32 v153, s61, v147
	ds_read_b128 v[160:163], v153
	ds_read_b128 v[164:167], v153 offset:1024
	ds_read_b128 v[168:171], v153 offset:2048
	ds_read_b128 v[172:175], v153 offset:3072
	v_add_u32_e32 v153, s62, v147
	ds_read_b128 v[176:179], v153
	ds_read_b128 v[180:183], v153 offset:1024
	ds_read_b128 v[184:187], v153 offset:2048
	ds_read_b128 v[188:191], v153 offset:3072
	s_add_u32 s46, s30, 0xfffc0080
	s_addc_u32 s47, s31, -1
	s_and_b64 s[44:45], s[44:45], exec
	s_cselect_b32 s47, s25, s47
	s_cselect_b32 s46, s65, s46
	s_cselect_b32 s45, s66, s69
	s_cselect_b32 s44, s67, s68
	v_lshl_add_u64 v[154:155], s[30:31], 0, v[138:139]
	s_add_i32 m0, s52, 0xc000
	ds_read_b128 v[192:195], v150
	ds_read_b128 v[196:199], v150 offset:1024
	ds_read_b128 v[200:203], v150 offset:2048
	ds_read_b128 v[204:207], v150 offset:3072
	ds_read_b128 v[208:211], v150 offset:4096
	ds_read_b128 v[212:215], v150 offset:5120
	ds_read_b128 v[216:219], v150 offset:6144
	ds_read_b128 v[220:223], v150 offset:7168
	global_load_lds_dwordx4 v[154:155], off
	v_lshl_add_u64 v[154:155], s[30:31], 0, v[136:137]
	s_add_i32 m0, s52, 0xe000
	s_nop 0
	global_load_lds_dwordx4 v[154:155], off
	s_waitcnt vmcnt(8)
	s_waitcnt lgkmcnt(0)
	s_barrier
	s_setprio 1
	s_waitcnt lgkmcnt(0)
	v_mfma_f32_16x16x32_bf16 v[124:127], v[160:163], v[192:195], v[124:127]
	v_mfma_f32_16x16x32_bf16 v[124:127], v[164:167], v[196:199], v[124:127]
	v_mfma_f32_16x16x32_bf16 v[116:119], v[168:171], v[192:195], v[116:119]
	v_mfma_f32_16x16x32_bf16 v[116:119], v[172:175], v[196:199], v[116:119]
	v_mfma_f32_16x16x32_bf16 v[108:111], v[160:163], v[200:203], v[108:111]
	v_mfma_f32_16x16x32_bf16 v[108:111], v[164:167], v[204:207], v[108:111]
	v_mfma_f32_16x16x32_bf16 v[100:103], v[168:171], v[200:203], v[100:103]
	v_mfma_f32_16x16x32_bf16 v[100:103], v[172:175], v[204:207], v[100:103]
	v_mfma_f32_16x16x32_bf16 v[92:95], v[160:163], v[208:211], v[92:95]
	v_mfma_f32_16x16x32_bf16 v[92:95], v[164:167], v[212:215], v[92:95]
	v_mfma_f32_16x16x32_bf16 v[84:87], v[168:171], v[208:211], v[84:87]
	v_mfma_f32_16x16x32_bf16 v[84:87], v[172:175], v[212:215], v[84:87]
	v_mfma_f32_16x16x32_bf16 v[76:79], v[160:163], v[216:219], v[76:79]
	v_mfma_f32_16x16x32_bf16 v[76:79], v[164:167], v[220:223], v[76:79]
	v_mfma_f32_16x16x32_bf16 v[68:71], v[168:171], v[216:219], v[68:71]
	v_mfma_f32_16x16x32_bf16 v[68:71], v[172:175], v[220:223], v[68:71]
	s_setprio 0
	s_setprio 1
	v_mfma_f32_16x16x32_bf16 v[120:123], v[176:179], v[192:195], v[120:123]
	v_mfma_f32_16x16x32_bf16 v[120:123], v[180:183], v[196:199], v[120:123]
	v_mfma_f32_16x16x32_bf16 v[112:115], v[184:187], v[192:195], v[112:115]
	v_mfma_f32_16x16x32_bf16 v[112:115], v[188:191], v[196:199], v[112:115]
	v_mfma_f32_16x16x32_bf16 v[104:107], v[176:179], v[200:203], v[104:107]
	v_mfma_f32_16x16x32_bf16 v[104:107], v[180:183], v[204:207], v[104:107]
	v_mfma_f32_16x16x32_bf16 v[96:99], v[184:187], v[200:203], v[96:99]
	v_mfma_f32_16x16x32_bf16 v[96:99], v[188:191], v[204:207], v[96:99]
	v_mfma_f32_16x16x32_bf16 v[88:91], v[176:179], v[208:211], v[88:91]
	v_mfma_f32_16x16x32_bf16 v[88:91], v[180:183], v[212:215], v[88:91]
	v_mfma_f32_16x16x32_bf16 v[80:83], v[184:187], v[208:211], v[80:83]
	v_mfma_f32_16x16x32_bf16 v[80:83], v[188:191], v[212:215], v[80:83]
	v_mfma_f32_16x16x32_bf16 v[72:75], v[176:179], v[216:219], v[72:75]
	v_mfma_f32_16x16x32_bf16 v[72:75], v[180:183], v[220:223], v[72:75]
	v_mfma_f32_16x16x32_bf16 v[64:67], v[184:187], v[216:219], v[64:67]
	v_mfma_f32_16x16x32_bf16 v[64:67], v[188:191], v[220:223], v[64:67]
	s_setprio 0
	s_barrier
	s_add_i32 s71, s61, s49
	v_lshl_add_u64 v[154:155], s[44:45], 0, v[132:133]
	s_mov_b32 m0, s71
	ds_read_b128 v[192:195], v150 offset:16384
	ds_read_b128 v[196:199], v150 offset:17408
	ds_read_b128 v[200:203], v150 offset:18432
	ds_read_b128 v[204:207], v150 offset:19456
	ds_read_b128 v[208:211], v150 offset:20480
	ds_read_b128 v[212:215], v150 offset:21504
	ds_read_b128 v[216:219], v150 offset:22528
	ds_read_b128 v[220:223], v150 offset:23552
	global_load_lds_dwordx4 v[154:155], off
	s_add_i32 m0, s71, 0x2000
	s_add_u32 s72, s44, 0x40000
	v_lshl_add_u64 v[224:225], s[44:45], 0, v[128:129]
	s_addc_u32 s73, s45, 0
	s_add_i32 s71, s62, s49
	global_load_lds_dwordx4 v[224:225], off
	v_lshl_add_u64 v[226:227], s[72:73], 0, v[132:133]
	s_mov_b32 m0, s71
	v_lshl_add_u64 v[228:229], s[46:47], 0, v[130:131]
	global_load_lds_dwordx4 v[226:227], off
	v_lshl_add_u64 v[226:227], s[72:73], 0, v[128:129]
	s_add_i32 m0, s71, 0x2000
	s_nop 0
	global_load_lds_dwordx4 v[226:227], off
	v_lshl_add_u64 v[226:227], s[46:47], 0, v[134:135]
	s_mov_b32 m0, s52
	s_nop 0
	global_load_lds_dwordx4 v[226:227], off
	s_mov_b32 m0, s53
	s_nop 0
	global_load_lds_dwordx4 v[228:229], off
	s_waitcnt vmcnt(8)
	s_waitcnt lgkmcnt(0)
	s_barrier
	s_setprio 1
	s_waitcnt lgkmcnt(0)
	v_mfma_f32_16x16x32_bf16 v[60:63], v[160:163], v[192:195], v[60:63]
	v_mfma_f32_16x16x32_bf16 v[60:63], v[164:167], v[196:199], v[60:63]
	v_mfma_f32_16x16x32_bf16 v[52:55], v[168:171], v[192:195], v[52:55]
	v_mfma_f32_16x16x32_bf16 v[52:55], v[172:175], v[196:199], v[52:55]
	v_mfma_f32_16x16x32_bf16 v[44:47], v[160:163], v[200:203], v[44:47]
	v_mfma_f32_16x16x32_bf16 v[44:47], v[164:167], v[204:207], v[44:47]
	v_mfma_f32_16x16x32_bf16 v[36:39], v[168:171], v[200:203], v[36:39]
	v_mfma_f32_16x16x32_bf16 v[36:39], v[172:175], v[204:207], v[36:39]
	v_mfma_f32_16x16x32_bf16 v[28:31], v[160:163], v[208:211], v[28:31]
	v_mfma_f32_16x16x32_bf16 v[28:31], v[164:167], v[212:215], v[28:31]
	v_mfma_f32_16x16x32_bf16 v[20:23], v[168:171], v[208:211], v[20:23]
	v_mfma_f32_16x16x32_bf16 v[20:23], v[172:175], v[212:215], v[20:23]
	v_mfma_f32_16x16x32_bf16 v[12:15], v[160:163], v[216:219], v[12:15]
	v_mfma_f32_16x16x32_bf16 v[12:15], v[164:167], v[220:223], v[12:15]
	v_mfma_f32_16x16x32_bf16 v[4:7], v[168:171], v[216:219], v[4:7]
	v_mfma_f32_16x16x32_bf16 v[4:7], v[172:175], v[220:223], v[4:7]
	s_setprio 0
	s_setprio 1
	v_mfma_f32_16x16x32_bf16 v[56:59], v[176:179], v[192:195], v[56:59]
	v_mfma_f32_16x16x32_bf16 v[56:59], v[180:183], v[196:199], v[56:59]
	v_mfma_f32_16x16x32_bf16 v[48:51], v[184:187], v[192:195], v[48:51]
	v_mfma_f32_16x16x32_bf16 v[48:51], v[188:191], v[196:199], v[48:51]
	v_mfma_f32_16x16x32_bf16 v[40:43], v[176:179], v[200:203], v[40:43]
	v_mfma_f32_16x16x32_bf16 v[40:43], v[180:183], v[204:207], v[40:43]
	v_mfma_f32_16x16x32_bf16 v[32:35], v[184:187], v[200:203], v[32:35]
	v_mfma_f32_16x16x32_bf16 v[32:35], v[188:191], v[204:207], v[32:35]
	v_mfma_f32_16x16x32_bf16 v[24:27], v[176:179], v[208:211], v[24:27]
	v_mfma_f32_16x16x32_bf16 v[24:27], v[180:183], v[212:215], v[24:27]
	v_mfma_f32_16x16x32_bf16 v[16:19], v[184:187], v[208:211], v[16:19]
	v_mfma_f32_16x16x32_bf16 v[16:19], v[188:191], v[212:215], v[16:19]
	v_mfma_f32_16x16x32_bf16 v[8:11], v[176:179], v[216:219], v[8:11]
	v_mfma_f32_16x16x32_bf16 v[8:11], v[180:183], v[220:223], v[8:11]
	v_mfma_f32_16x16x32_bf16 v[0:3], v[184:187], v[216:219], v[0:3]
	v_mfma_f32_16x16x32_bf16 v[0:3], v[188:191], v[220:223], v[0:3]
	s_setprio 0
	s_barrier
	s_add_i32 s71, 0, 0x18000
	v_add_u32_e32 v153, s71, v147
	s_add_i32 s72, 0, 0x1c000
	ds_read_b128 v[160:163], v153
	ds_read_b128 v[164:167], v153 offset:1024
	ds_read_b128 v[168:171], v153 offset:2048
	ds_read_b128 v[172:175], v153 offset:3072
	v_add_u32_e32 v153, s72, v147
	ds_read_b128 v[176:179], v153
	ds_read_b128 v[180:183], v153 offset:1024
	ds_read_b128 v[184:187], v153 offset:2048
	ds_read_b128 v[188:191], v153 offset:3072
	s_add_u32 s46, s46, 0x40000
	s_addc_u32 s47, s47, 0
	s_mov_b32 m0, s54
	v_lshl_add_u64 v[230:231], s[46:47], 0, v[134:135]
	ds_read_b128 v[192:195], v150 offset:32768
	ds_read_b128 v[196:199], v150 offset:33792
	ds_read_b128 v[200:203], v150 offset:34816
	ds_read_b128 v[204:207], v150 offset:35840
	ds_read_b128 v[208:211], v150 offset:36864
	ds_read_b128 v[212:215], v150 offset:37888
	ds_read_b128 v[216:219], v150 offset:38912
	ds_read_b128 v[220:223], v150 offset:39936
	global_load_lds_dwordx4 v[230:231], off
	v_lshl_add_u64 v[230:231], s[46:47], 0, v[130:131]
	s_mov_b32 m0, s55
	s_nop 0
	global_load_lds_dwordx4 v[230:231], off
	s_waitcnt vmcnt(8)
	s_waitcnt lgkmcnt(0)
	s_barrier
	s_setprio 1
	s_waitcnt lgkmcnt(0)
	v_mfma_f32_16x16x32_bf16 v[124:127], v[160:163], v[192:195], v[124:127]
	v_mfma_f32_16x16x32_bf16 v[124:127], v[164:167], v[196:199], v[124:127]
	v_mfma_f32_16x16x32_bf16 v[116:119], v[168:171], v[192:195], v[116:119]
	v_mfma_f32_16x16x32_bf16 v[116:119], v[172:175], v[196:199], v[116:119]
	v_mfma_f32_16x16x32_bf16 v[108:111], v[160:163], v[200:203], v[108:111]
	v_mfma_f32_16x16x32_bf16 v[108:111], v[164:167], v[204:207], v[108:111]
	v_mfma_f32_16x16x32_bf16 v[100:103], v[168:171], v[200:203], v[100:103]
	v_mfma_f32_16x16x32_bf16 v[100:103], v[172:175], v[204:207], v[100:103]
	v_mfma_f32_16x16x32_bf16 v[92:95], v[160:163], v[208:211], v[92:95]
	v_mfma_f32_16x16x32_bf16 v[92:95], v[164:167], v[212:215], v[92:95]
	v_mfma_f32_16x16x32_bf16 v[84:87], v[168:171], v[208:211], v[84:87]
	v_mfma_f32_16x16x32_bf16 v[84:87], v[172:175], v[212:215], v[84:87]
	v_mfma_f32_16x16x32_bf16 v[76:79], v[160:163], v[216:219], v[76:79]
	v_mfma_f32_16x16x32_bf16 v[76:79], v[164:167], v[220:223], v[76:79]
	v_mfma_f32_16x16x32_bf16 v[68:71], v[168:171], v[216:219], v[68:71]
	v_mfma_f32_16x16x32_bf16 v[68:71], v[172:175], v[220:223], v[68:71]
	s_setprio 0
	s_setprio 1
	v_mfma_f32_16x16x32_bf16 v[120:123], v[176:179], v[192:195], v[120:123]
	v_mfma_f32_16x16x32_bf16 v[120:123], v[180:183], v[196:199], v[120:123]
	v_mfma_f32_16x16x32_bf16 v[112:115], v[184:187], v[192:195], v[112:115]
	v_mfma_f32_16x16x32_bf16 v[112:115], v[188:191], v[196:199], v[112:115]
	v_mfma_f32_16x16x32_bf16 v[104:107], v[176:179], v[200:203], v[104:107]
	v_mfma_f32_16x16x32_bf16 v[104:107], v[180:183], v[204:207], v[104:107]
	v_mfma_f32_16x16x32_bf16 v[96:99], v[184:187], v[200:203], v[96:99]
	v_mfma_f32_16x16x32_bf16 v[96:99], v[188:191], v[204:207], v[96:99]
	v_mfma_f32_16x16x32_bf16 v[88:91], v[176:179], v[208:211], v[88:91]
	v_mfma_f32_16x16x32_bf16 v[88:91], v[180:183], v[212:215], v[88:91]
	v_mfma_f32_16x16x32_bf16 v[80:83], v[184:187], v[208:211], v[80:83]
	v_mfma_f32_16x16x32_bf16 v[80:83], v[188:191], v[212:215], v[80:83]
	v_mfma_f32_16x16x32_bf16 v[72:75], v[176:179], v[216:219], v[72:75]
	v_mfma_f32_16x16x32_bf16 v[72:75], v[180:183], v[220:223], v[72:75]
	v_mfma_f32_16x16x32_bf16 v[64:67], v[184:187], v[216:219], v[64:67]
	v_mfma_f32_16x16x32_bf16 v[64:67], v[188:191], v[220:223], v[64:67]
	s_setprio 0
	s_barrier
	s_add_i32 s46, s71, s49
	v_lshl_add_u64 v[154:155], v[154:155], 0, s[14:15]
	s_mov_b32 m0, s46
	ds_read_b128 v[192:195], v150 offset:49152
	ds_read_b128 v[196:199], v150 offset:50176
	ds_read_b128 v[200:203], v150 offset:51200
	ds_read_b128 v[204:207], v150 offset:52224
	ds_read_b128 v[208:211], v150 offset:53248
	ds_read_b128 v[212:215], v150 offset:54272
	ds_read_b128 v[216:219], v150 offset:55296
	ds_read_b128 v[220:223], v150 offset:56320
	global_load_lds_dwordx4 v[154:155], off
	s_add_i32 m0, s46, 0x2000
	s_add_u32 s44, s44, 0x40080
	v_lshl_add_u64 v[154:155], v[224:225], 0, s[14:15]
	s_addc_u32 s45, s45, 0
	s_add_i32 s46, s72, s49
	global_load_lds_dwordx4 v[154:155], off
	v_lshl_add_u64 v[154:155], s[44:45], 0, v[132:133]
	s_mov_b32 m0, s46
	s_nop 0
	global_load_lds_dwordx4 v[154:155], off
	v_lshl_add_u64 v[154:155], s[44:45], 0, v[128:129]
	s_add_i32 m0, s46, 0x2000
	s_nop 0
	global_load_lds_dwordx4 v[154:155], off
	v_lshl_add_u64 v[154:155], v[226:227], 0, s[14:15]
	s_mov_b32 m0, s57
	s_nop 0
	global_load_lds_dwordx4 v[154:155], off
	v_lshl_add_u64 v[154:155], v[228:229], 0, s[14:15]
	s_mov_b32 m0, s58
	s_nop 0
	global_load_lds_dwordx4 v[154:155], off
	s_waitcnt vmcnt(8)
	s_waitcnt lgkmcnt(0)
	s_barrier
	s_setprio 1
	s_waitcnt lgkmcnt(0)
	v_mfma_f32_16x16x32_bf16 v[60:63], v[160:163], v[192:195], v[60:63]
	v_mfma_f32_16x16x32_bf16 v[60:63], v[164:167], v[196:199], v[60:63]
	v_mfma_f32_16x16x32_bf16 v[52:55], v[168:171], v[192:195], v[52:55]
	v_mfma_f32_16x16x32_bf16 v[52:55], v[172:175], v[196:199], v[52:55]
	v_mfma_f32_16x16x32_bf16 v[44:47], v[160:163], v[200:203], v[44:47]
	v_mfma_f32_16x16x32_bf16 v[44:47], v[164:167], v[204:207], v[44:47]
	v_mfma_f32_16x16x32_bf16 v[36:39], v[168:171], v[200:203], v[36:39]
	v_mfma_f32_16x16x32_bf16 v[36:39], v[172:175], v[204:207], v[36:39]
	v_mfma_f32_16x16x32_bf16 v[28:31], v[160:163], v[208:211], v[28:31]
	v_mfma_f32_16x16x32_bf16 v[28:31], v[164:167], v[212:215], v[28:31]
	v_mfma_f32_16x16x32_bf16 v[20:23], v[168:171], v[208:211], v[20:23]
	v_mfma_f32_16x16x32_bf16 v[20:23], v[172:175], v[212:215], v[20:23]
	v_mfma_f32_16x16x32_bf16 v[12:15], v[160:163], v[216:219], v[12:15]
	v_mfma_f32_16x16x32_bf16 v[12:15], v[164:167], v[220:223], v[12:15]
	v_mfma_f32_16x16x32_bf16 v[4:7], v[168:171], v[216:219], v[4:7]
	v_mfma_f32_16x16x32_bf16 v[4:7], v[172:175], v[220:223], v[4:7]
	s_setprio 0
	s_setprio 1
	v_mfma_f32_16x16x32_bf16 v[56:59], v[176:179], v[192:195], v[56:59]
	v_mfma_f32_16x16x32_bf16 v[56:59], v[180:183], v[196:199], v[56:59]
	v_mfma_f32_16x16x32_bf16 v[48:51], v[184:187], v[192:195], v[48:51]
	v_mfma_f32_16x16x32_bf16 v[48:51], v[188:191], v[196:199], v[48:51]
	v_mfma_f32_16x16x32_bf16 v[40:43], v[176:179], v[200:203], v[40:43]
	v_mfma_f32_16x16x32_bf16 v[40:43], v[180:183], v[204:207], v[40:43]
	v_mfma_f32_16x16x32_bf16 v[32:35], v[184:187], v[200:203], v[32:35]
	v_mfma_f32_16x16x32_bf16 v[32:35], v[188:191], v[204:207], v[32:35]
	v_mfma_f32_16x16x32_bf16 v[24:27], v[176:179], v[208:211], v[24:27]
	v_mfma_f32_16x16x32_bf16 v[24:27], v[180:183], v[212:215], v[24:27]
	v_mfma_f32_16x16x32_bf16 v[16:19], v[184:187], v[208:211], v[16:19]
	v_mfma_f32_16x16x32_bf16 v[16:19], v[188:191], v[212:215], v[16:19]
	v_mfma_f32_16x16x32_bf16 v[8:11], v[176:179], v[216:219], v[8:11]
	v_mfma_f32_16x16x32_bf16 v[8:11], v[180:183], v[220:223], v[8:11]
	v_mfma_f32_16x16x32_bf16 v[0:3], v[184:187], v[216:219], v[0:3]
	v_mfma_f32_16x16x32_bf16 v[0:3], v[188:191], v[220:223], v[0:3]
	s_setprio 0
	s_barrier
	s_add_i32 s70, s70, 2
	s_add_u32 s68, s68, 0x100
	s_addc_u32 s69, s69, 0
	s_add_u32 s30, s30, 0x100
	s_addc_u32 s31, s31, 0
	s_cmp_gt_u32 s70, 13
	s_cbranch_scc1 .LBB0_1100

.Llast_10:
	v_add_u32_e32 v153, s61, v147
	ds_read_b128 v[160:163], v153
	ds_read_b128 v[164:167], v153 offset:1024
	ds_read_b128 v[168:171], v153 offset:2048
	ds_read_b128 v[172:175], v153 offset:3072
	v_add_u32_e32 v153, s62, v147
	ds_read_b128 v[176:179], v153
	ds_read_b128 v[180:183], v153 offset:1024
	ds_read_b128 v[184:187], v153 offset:2048
	ds_read_b128 v[188:191], v153 offset:3072
	s_add_u32 s46, s30, 0xfffc0080
	s_addc_u32 s47, s31, -1
	s_and_b64 s[44:45], s[44:45], exec
	s_cselect_b32 s47, s25, s47
	s_cselect_b32 s46, s65, s46
	s_cselect_b32 s45, s66, s69
	s_cselect_b32 s44, s67, s68
	v_lshl_add_u64 v[154:155], s[30:31], 0, v[138:139]
	s_add_i32 m0, s52, 0xc000
	ds_read_b128 v[192:195], v150
	ds_read_b128 v[196:199], v150 offset:1024
	ds_read_b128 v[200:203], v150 offset:2048
	ds_read_b128 v[204:207], v150 offset:3072
	ds_read_b128 v[208:211], v150 offset:4096
	ds_read_b128 v[212:215], v150 offset:5120
	ds_read_b128 v[216:219], v150 offset:6144
	ds_read_b128 v[220:223], v150 offset:7168
	global_load_lds_dwordx4 v[154:155], off
	v_lshl_add_u64 v[154:155], s[30:31], 0, v[136:137]
	s_add_i32 m0, s52, 0xe000
	s_nop 0
	global_load_lds_dwordx4 v[154:155], off
	s_waitcnt vmcnt(8)
	s_waitcnt lgkmcnt(0)
	s_barrier
	s_setprio 1
	s_waitcnt lgkmcnt(0)
	v_mfma_f32_16x16x32_bf16 v[124:127], v[160:163], v[192:195], v[124:127]
	v_mfma_f32_16x16x32_bf16 v[124:127], v[164:167], v[196:199], v[124:127]
	v_mfma_f32_16x16x32_bf16 v[116:119], v[168:171], v[192:195], v[116:119]
	v_mfma_f32_16x16x32_bf16 v[116:119], v[172:175], v[196:199], v[116:119]
	v_mfma_f32_16x16x32_bf16 v[108:111], v[160:163], v[200:203], v[108:111]
	v_mfma_f32_16x16x32_bf16 v[108:111], v[164:167], v[204:207], v[108:111]
	v_mfma_f32_16x16x32_bf16 v[100:103], v[168:171], v[200:203], v[100:103]
	v_mfma_f32_16x16x32_bf16 v[100:103], v[172:175], v[204:207], v[100:103]
	v_mfma_f32_16x16x32_bf16 v[92:95], v[160:163], v[208:211], v[92:95]
	v_mfma_f32_16x16x32_bf16 v[92:95], v[164:167], v[212:215], v[92:95]
	v_mfma_f32_16x16x32_bf16 v[84:87], v[168:171], v[208:211], v[84:87]
	v_mfma_f32_16x16x32_bf16 v[84:87], v[172:175], v[212:215], v[84:87]
	v_mfma_f32_16x16x32_bf16 v[76:79], v[160:163], v[216:219], v[76:79]
	v_mfma_f32_16x16x32_bf16 v[76:79], v[164:167], v[220:223], v[76:79]
	v_mfma_f32_16x16x32_bf16 v[68:71], v[168:171], v[216:219], v[68:71]
	v_mfma_f32_16x16x32_bf16 v[68:71], v[172:175], v[220:223], v[68:71]
	s_setprio 0
	s_setprio 1
	v_mfma_f32_16x16x32_bf16 v[120:123], v[176:179], v[192:195], v[120:123]
	v_mfma_f32_16x16x32_bf16 v[120:123], v[180:183], v[196:199], v[120:123]
	v_mfma_f32_16x16x32_bf16 v[112:115], v[184:187], v[192:195], v[112:115]
	v_mfma_f32_16x16x32_bf16 v[112:115], v[188:191], v[196:199], v[112:115]
	v_mfma_f32_16x16x32_bf16 v[104:107], v[176:179], v[200:203], v[104:107]
	v_mfma_f32_16x16x32_bf16 v[104:107], v[180:183], v[204:207], v[104:107]
	v_mfma_f32_16x16x32_bf16 v[96:99], v[184:187], v[200:203], v[96:99]
	v_mfma_f32_16x16x32_bf16 v[96:99], v[188:191], v[204:207], v[96:99]
	v_mfma_f32_16x16x32_bf16 v[88:91], v[176:179], v[208:211], v[88:91]
	v_mfma_f32_16x16x32_bf16 v[88:91], v[180:183], v[212:215], v[88:91]
	v_mfma_f32_16x16x32_bf16 v[80:83], v[184:187], v[208:211], v[80:83]
	v_mfma_f32_16x16x32_bf16 v[80:83], v[188:191], v[212:215], v[80:83]
	v_mfma_f32_16x16x32_bf16 v[72:75], v[176:179], v[216:219], v[72:75]
	v_mfma_f32_16x16x32_bf16 v[72:75], v[180:183], v[220:223], v[72:75]
	v_mfma_f32_16x16x32_bf16 v[64:67], v[184:187], v[216:219], v[64:67]
	v_mfma_f32_16x16x32_bf16 v[64:67], v[188:191], v[220:223], v[64:67]
	s_setprio 0
	s_barrier
	s_add_i32 s71, s61, s49
	v_lshl_add_u64 v[154:155], s[44:45], 0, v[132:133]
	s_mov_b32 m0, s71
	ds_read_b128 v[192:195], v150 offset:16384
	ds_read_b128 v[196:199], v150 offset:17408
	ds_read_b128 v[200:203], v150 offset:18432
	ds_read_b128 v[204:207], v150 offset:19456
	ds_read_b128 v[208:211], v150 offset:20480
	ds_read_b128 v[212:215], v150 offset:21504
	ds_read_b128 v[216:219], v150 offset:22528
	ds_read_b128 v[220:223], v150 offset:23552
	global_load_lds_dwordx4 v[154:155], off
	s_add_i32 m0, s71, 0x2000
	s_add_u32 s72, s44, 0x40000
	v_lshl_add_u64 v[224:225], s[44:45], 0, v[128:129]
	s_addc_u32 s73, s45, 0
	s_add_i32 s71, s62, s49
	global_load_lds_dwordx4 v[224:225], off
	v_lshl_add_u64 v[226:227], s[72:73], 0, v[132:133]
	s_mov_b32 m0, s71
	v_lshl_add_u64 v[228:229], s[46:47], 0, v[130:131]
	global_load_lds_dwordx4 v[226:227], off
	v_lshl_add_u64 v[226:227], s[72:73], 0, v[128:129]
	s_add_i32 m0, s71, 0x2000
	s_nop 0
	global_load_lds_dwordx4 v[226:227], off
	v_lshl_add_u64 v[226:227], s[46:47], 0, v[134:135]
	s_mov_b32 m0, s52
	s_nop 0
	global_load_lds_dwordx4 v[226:227], off
	s_mov_b32 m0, s53
	s_nop 0
	global_load_lds_dwordx4 v[228:229], off
	s_waitcnt vmcnt(8)
	s_waitcnt lgkmcnt(0)
	s_barrier
	s_setprio 1
	s_waitcnt lgkmcnt(0)
	v_mfma_f32_16x16x32_bf16 v[60:63], v[160:163], v[192:195], v[60:63]
	v_mfma_f32_16x16x32_bf16 v[60:63], v[164:167], v[196:199], v[60:63]
	v_mfma_f32_16x16x32_bf16 v[52:55], v[168:171], v[192:195], v[52:55]
	v_mfma_f32_16x16x32_bf16 v[52:55], v[172:175], v[196:199], v[52:55]
	v_mfma_f32_16x16x32_bf16 v[44:47], v[160:163], v[200:203], v[44:47]
	v_mfma_f32_16x16x32_bf16 v[44:47], v[164:167], v[204:207], v[44:47]
	v_mfma_f32_16x16x32_bf16 v[36:39], v[168:171], v[200:203], v[36:39]
	v_mfma_f32_16x16x32_bf16 v[36:39], v[172:175], v[204:207], v[36:39]
	v_mfma_f32_16x16x32_bf16 v[28:31], v[160:163], v[208:211], v[28:31]
	v_mfma_f32_16x16x32_bf16 v[28:31], v[164:167], v[212:215], v[28:31]
	v_mfma_f32_16x16x32_bf16 v[20:23], v[168:171], v[208:211], v[20:23]
	v_mfma_f32_16x16x32_bf16 v[20:23], v[172:175], v[212:215], v[20:23]
	v_mfma_f32_16x16x32_bf16 v[12:15], v[160:163], v[216:219], v[12:15]
	v_mfma_f32_16x16x32_bf16 v[12:15], v[164:167], v[220:223], v[12:15]
	v_mfma_f32_16x16x32_bf16 v[4:7], v[168:171], v[216:219], v[4:7]
	v_mfma_f32_16x16x32_bf16 v[4:7], v[172:175], v[220:223], v[4:7]
	s_setprio 0
	s_setprio 1
	v_mfma_f32_16x16x32_bf16 v[56:59], v[176:179], v[192:195], v[56:59]
	v_mfma_f32_16x16x32_bf16 v[56:59], v[180:183], v[196:199], v[56:59]
	v_mfma_f32_16x16x32_bf16 v[48:51], v[184:187], v[192:195], v[48:51]
	v_mfma_f32_16x16x32_bf16 v[48:51], v[188:191], v[196:199], v[48:51]
	v_mfma_f32_16x16x32_bf16 v[40:43], v[176:179], v[200:203], v[40:43]
	v_mfma_f32_16x16x32_bf16 v[40:43], v[180:183], v[204:207], v[40:43]
	v_mfma_f32_16x16x32_bf16 v[32:35], v[184:187], v[200:203], v[32:35]
	v_mfma_f32_16x16x32_bf16 v[32:35], v[188:191], v[204:207], v[32:35]
	v_mfma_f32_16x16x32_bf16 v[24:27], v[176:179], v[208:211], v[24:27]
	v_mfma_f32_16x16x32_bf16 v[24:27], v[180:183], v[212:215], v[24:27]
	v_mfma_f32_16x16x32_bf16 v[16:19], v[184:187], v[208:211], v[16:19]
	v_mfma_f32_16x16x32_bf16 v[16:19], v[188:191], v[212:215], v[16:19]
	v_mfma_f32_16x16x32_bf16 v[8:11], v[176:179], v[216:219], v[8:11]
	v_mfma_f32_16x16x32_bf16 v[8:11], v[180:183], v[220:223], v[8:11]
	v_mfma_f32_16x16x32_bf16 v[0:3], v[184:187], v[216:219], v[0:3]
	v_mfma_f32_16x16x32_bf16 v[0:3], v[188:191], v[220:223], v[0:3]
	s_setprio 0
	s_barrier
	s_add_i32 s71, 0, 0x18000
	v_add_u32_e32 v153, s71, v147
	s_add_i32 s72, 0, 0x1c000
	ds_read_b128 v[160:163], v153
	ds_read_b128 v[164:167], v153 offset:1024
	ds_read_b128 v[168:171], v153 offset:2048
	ds_read_b128 v[172:175], v153 offset:3072
	v_add_u32_e32 v153, s72, v147
	ds_read_b128 v[176:179], v153
	ds_read_b128 v[180:183], v153 offset:1024
	ds_read_b128 v[184:187], v153 offset:2048
	ds_read_b128 v[188:191], v153 offset:3072
	s_add_u32 s46, s46, 0x40000
	s_addc_u32 s47, s47, 0
	s_mov_b32 m0, s54
	v_lshl_add_u64 v[230:231], s[46:47], 0, v[134:135]
	ds_read_b128 v[192:195], v150 offset:32768
	ds_read_b128 v[196:199], v150 offset:33792
	ds_read_b128 v[200:203], v150 offset:34816
	ds_read_b128 v[204:207], v150 offset:35840
	ds_read_b128 v[208:211], v150 offset:36864
	ds_read_b128 v[212:215], v150 offset:37888
	ds_read_b128 v[216:219], v150 offset:38912
	ds_read_b128 v[220:223], v150 offset:39936
	global_load_lds_dwordx4 v[230:231], off
	v_lshl_add_u64 v[230:231], s[46:47], 0, v[130:131]
	s_mov_b32 m0, s55
	s_nop 0
	global_load_lds_dwordx4 v[230:231], off
	s_waitcnt vmcnt(8)
	s_waitcnt lgkmcnt(0)
	s_barrier
	s_setprio 1
	s_waitcnt lgkmcnt(0)
	v_mfma_f32_16x16x32_bf16 v[124:127], v[160:163], v[192:195], v[124:127]
	v_mfma_f32_16x16x32_bf16 v[124:127], v[164:167], v[196:199], v[124:127]
	v_mfma_f32_16x16x32_bf16 v[116:119], v[168:171], v[192:195], v[116:119]
	v_mfma_f32_16x16x32_bf16 v[116:119], v[172:175], v[196:199], v[116:119]
	v_mfma_f32_16x16x32_bf16 v[108:111], v[160:163], v[200:203], v[108:111]
	v_mfma_f32_16x16x32_bf16 v[108:111], v[164:167], v[204:207], v[108:111]
	v_mfma_f32_16x16x32_bf16 v[100:103], v[168:171], v[200:203], v[100:103]
	v_mfma_f32_16x16x32_bf16 v[100:103], v[172:175], v[204:207], v[100:103]
	v_mfma_f32_16x16x32_bf16 v[92:95], v[160:163], v[208:211], v[92:95]
	v_mfma_f32_16x16x32_bf16 v[92:95], v[164:167], v[212:215], v[92:95]
	v_mfma_f32_16x16x32_bf16 v[84:87], v[168:171], v[208:211], v[84:87]
	v_mfma_f32_16x16x32_bf16 v[84:87], v[172:175], v[212:215], v[84:87]
	v_mfma_f32_16x16x32_bf16 v[76:79], v[160:163], v[216:219], v[76:79]
	v_mfma_f32_16x16x32_bf16 v[76:79], v[164:167], v[220:223], v[76:79]
	v_mfma_f32_16x16x32_bf16 v[68:71], v[168:171], v[216:219], v[68:71]
	v_mfma_f32_16x16x32_bf16 v[68:71], v[172:175], v[220:223], v[68:71]
	s_setprio 0
	s_setprio 1
	v_mfma_f32_16x16x32_bf16 v[120:123], v[176:179], v[192:195], v[120:123]
	v_mfma_f32_16x16x32_bf16 v[120:123], v[180:183], v[196:199], v[120:123]
	v_mfma_f32_16x16x32_bf16 v[112:115], v[184:187], v[192:195], v[112:115]
	v_mfma_f32_16x16x32_bf16 v[112:115], v[188:191], v[196:199], v[112:115]
	v_mfma_f32_16x16x32_bf16 v[104:107], v[176:179], v[200:203], v[104:107]
	v_mfma_f32_16x16x32_bf16 v[104:107], v[180:183], v[204:207], v[104:107]
	v_mfma_f32_16x16x32_bf16 v[96:99], v[184:187], v[200:203], v[96:99]
	v_mfma_f32_16x16x32_bf16 v[96:99], v[188:191], v[204:207], v[96:99]
	v_mfma_f32_16x16x32_bf16 v[88:91], v[176:179], v[208:211], v[88:91]
	v_mfma_f32_16x16x32_bf16 v[88:91], v[180:183], v[212:215], v[88:91]
	v_mfma_f32_16x16x32_bf16 v[80:83], v[184:187], v[208:211], v[80:83]
	v_mfma_f32_16x16x32_bf16 v[80:83], v[188:191], v[212:215], v[80:83]
	v_mfma_f32_16x16x32_bf16 v[72:75], v[176:179], v[216:219], v[72:75]
	v_mfma_f32_16x16x32_bf16 v[72:75], v[180:183], v[220:223], v[72:75]
	v_mfma_f32_16x16x32_bf16 v[64:67], v[184:187], v[216:219], v[64:67]
	v_mfma_f32_16x16x32_bf16 v[64:67], v[188:191], v[220:223], v[64:67]
	s_setprio 0
	s_barrier
	v_add_u32_e32 v234, 0x21000, v151
	ds_read_b128 v[236:239], v234
	ds_read_b128 v[240:243], v234 offset:256
	ds_read_b128 v[244:247], v234 offset:512
	ds_read_b128 v[248:251], v234 offset:768
	v_add_u32_e32 v235, s23, v146
	v_mul_u32_u24_e32 v235, 0x1600, v235
	v_lshl_or_b32 v234, s64, 7, v149
	v_lshl_add_u32 v235, v234, 1, v235
	s_add_i32 s46, s71, s49
	v_lshl_add_u64 v[154:155], v[154:155], 0, s[14:15]
	s_mov_b32 m0, s46
	ds_read_b128 v[192:195], v150 offset:49152
	ds_read_b128 v[196:199], v150 offset:50176
	ds_read_b128 v[200:203], v150 offset:51200
	ds_read_b128 v[204:207], v150 offset:52224
	ds_read_b128 v[208:211], v150 offset:53248
	ds_read_b128 v[212:215], v150 offset:54272
	ds_read_b128 v[216:219], v150 offset:55296
	ds_read_b128 v[220:223], v150 offset:56320
	global_load_lds_dwordx4 v[154:155], off
	s_add_i32 m0, s46, 0x2000
	s_add_u32 s44, s44, 0x40080
	v_lshl_add_u64 v[154:155], v[224:225], 0, s[14:15]
	s_addc_u32 s45, s45, 0
	s_add_i32 s46, s72, s49
	global_load_lds_dwordx4 v[154:155], off
	v_lshl_add_u64 v[154:155], s[44:45], 0, v[132:133]
	s_mov_b32 m0, s46
	s_nop 0
	global_load_lds_dwordx4 v[154:155], off
	v_lshl_add_u64 v[154:155], s[44:45], 0, v[128:129]
	s_add_i32 m0, s46, 0x2000
	s_nop 0
	global_load_lds_dwordx4 v[154:155], off
	v_lshl_add_u64 v[154:155], v[226:227], 0, s[14:15]
	s_mov_b32 m0, s57
	s_nop 0
	global_load_lds_dwordx4 v[154:155], off
	v_lshl_add_u64 v[154:155], v[228:229], 0, s[14:15]
	s_mov_b32 m0, s58
	s_nop 0
	global_load_lds_dwordx4 v[154:155], off
	s_waitcnt lgkmcnt(8)
	v_add_f32_e32 v236, v236, v237
	v_add_f32_e32 v238, v238, v239
	v_add_f32_e32 v240, v240, v241
	v_add_f32_e32 v242, v242, v243
	v_add_f32_e32 v244, v244, v245
	v_add_f32_e32 v246, v246, v247
	v_add_f32_e32 v248, v248, v249
	v_add_f32_e32 v250, v250, v251
	v_add_f32_e32 v236, v236, v238
	v_add_f32_e32 v240, v240, v242
	v_add_f32_e32 v244, v244, v246
	v_add_f32_e32 v248, v248, v250
	v_fmamk_f32 v236, v236, 0x3a800000, v152
	v_fmamk_f32 v240, v240, 0x3a800000, v152
	v_fmamk_f32 v244, v244, 0x3a800000, v152
	v_fmamk_f32 v248, v248, 0x3a800000, v152
	v_rsq_f32_e32 v236, v236
	v_rsq_f32_e32 v240, v240
	v_rsq_f32_e32 v244, v244
	v_rsq_f32_e32 v248, v248
	v_mul_f32_e32 v252, 0xbfb8aa3b, v236
	v_mul_f32_e32 v254, v236, v236
	v_pk_mul_f32 v[120:121], v[124:125], v[120:121]
	v_pk_mul_f32 v[122:123], v[126:127], v[122:123]
	v_pk_mul_f32 v[112:113], v[116:117], v[112:113]
	v_pk_mul_f32 v[114:115], v[118:119], v[114:115]
	v_pk_mul_f32 v[124:125], v[124:125], v[252:253] op_sel_hi:[1,0]
	v_pk_mul_f32 v[126:127], v[126:127], v[252:253] op_sel_hi:[1,0]
	v_pk_mul_f32 v[116:117], v[116:117], v[252:253] op_sel_hi:[1,0]
	v_pk_mul_f32 v[118:119], v[118:119], v[252:253] op_sel_hi:[1,0]
	v_exp_f32_e32 v124, v124
	v_exp_f32_e32 v125, v125
	v_exp_f32_e32 v126, v126
	v_exp_f32_e32 v127, v127
	v_exp_f32_e32 v116, v116
	v_exp_f32_e32 v117, v117
	v_exp_f32_e32 v118, v118
	v_exp_f32_e32 v119, v119
	v_pk_add_f32 v[124:125], v[124:125], 1.0 op_sel_hi:[1,0]
	v_pk_add_f32 v[126:127], v[126:127], 1.0 op_sel_hi:[1,0]
	v_pk_add_f32 v[116:117], v[116:117], 1.0 op_sel_hi:[1,0]
	v_pk_add_f32 v[118:119], v[118:119], 1.0 op_sel_hi:[1,0]
	v_rcp_f32_e32 v124, v124
	v_rcp_f32_e32 v125, v125
	v_rcp_f32_e32 v126, v126
	v_rcp_f32_e32 v127, v127
	v_rcp_f32_e32 v116, v116
	v_rcp_f32_e32 v117, v117
	v_rcp_f32_e32 v118, v118
	v_rcp_f32_e32 v119, v119
	v_pk_mul_f32 v[120:121], v[120:121], v[254:255] op_sel_hi:[1,0]
	v_pk_mul_f32 v[122:123], v[122:123], v[254:255] op_sel_hi:[1,0]
	v_pk_mul_f32 v[112:113], v[112:113], v[254:255] op_sel_hi:[1,0]
	v_pk_mul_f32 v[114:115], v[114:115], v[254:255] op_sel_hi:[1,0]
	v_pk_mul_f32 v[120:121], v[120:121], v[124:125]
	v_pk_mul_f32 v[122:123], v[122:123], v[126:127]
	v_pk_mul_f32 v[112:113], v[112:113], v[116:117]
	v_pk_mul_f32 v[114:115], v[114:115], v[118:119]
	v_cvt_pk_bf16_f32 v120, v120, v121
	v_cvt_pk_bf16_f32 v121, v122, v123
	v_cvt_pk_bf16_f32 v122, v112, v113
	v_cvt_pk_bf16_f32 v123, v114, v115
	global_store_dwordx4 v235, v[120:123], s[10:11]
	v_add_u32_e32 v234, 0x16000, v235
	v_mul_f32_e32 v252, 0xbfb8aa3b, v240
	v_mul_f32_e32 v254, v240, v240
	v_pk_mul_f32 v[104:105], v[108:109], v[104:105]
	v_pk_mul_f32 v[106:107], v[110:111], v[106:107]
	v_pk_mul_f32 v[96:97], v[100:101], v[96:97]
	v_pk_mul_f32 v[98:99], v[102:103], v[98:99]
	v_pk_mul_f32 v[108:109], v[108:109], v[252:253] op_sel_hi:[1,0]
	v_pk_mul_f32 v[110:111], v[110:111], v[252:253] op_sel_hi:[1,0]
	v_pk_mul_f32 v[100:101], v[100:101], v[252:253] op_sel_hi:[1,0]
	v_pk_mul_f32 v[102:103], v[102:103], v[252:253] op_sel_hi:[1,0]
	v_exp_f32_e32 v108, v108
	v_exp_f32_e32 v109, v109
	v_exp_f32_e32 v110, v110
	v_exp_f32_e32 v111, v111
	v_exp_f32_e32 v100, v100
	v_exp_f32_e32 v101, v101
	v_exp_f32_e32 v102, v102
	v_exp_f32_e32 v103, v103
	v_pk_add_f32 v[108:109], v[108:109], 1.0 op_sel_hi:[1,0]
	v_pk_add_f32 v[110:111], v[110:111], 1.0 op_sel_hi:[1,0]
	v_pk_add_f32 v[100:101], v[100:101], 1.0 op_sel_hi:[1,0]
	v_pk_add_f32 v[102:103], v[102:103], 1.0 op_sel_hi:[1,0]
	v_rcp_f32_e32 v108, v108
	v_rcp_f32_e32 v109, v109
	v_rcp_f32_e32 v110, v110
	v_rcp_f32_e32 v111, v111
	v_rcp_f32_e32 v100, v100
	v_rcp_f32_e32 v101, v101
	v_rcp_f32_e32 v102, v102
	v_rcp_f32_e32 v103, v103
	v_pk_mul_f32 v[104:105], v[104:105], v[254:255] op_sel_hi:[1,0]
	v_pk_mul_f32 v[106:107], v[106:107], v[254:255] op_sel_hi:[1,0]
	v_pk_mul_f32 v[96:97], v[96:97], v[254:255] op_sel_hi:[1,0]
	v_pk_mul_f32 v[98:99], v[98:99], v[254:255] op_sel_hi:[1,0]
	v_pk_mul_f32 v[104:105], v[104:105], v[108:109]
	v_pk_mul_f32 v[106:107], v[106:107], v[110:111]
	v_pk_mul_f32 v[96:97], v[96:97], v[100:101]
	v_pk_mul_f32 v[98:99], v[98:99], v[102:103]
	v_cvt_pk_bf16_f32 v104, v104, v105
	v_cvt_pk_bf16_f32 v105, v106, v107
	v_cvt_pk_bf16_f32 v106, v96, v97
	v_cvt_pk_bf16_f32 v107, v98, v99
	global_store_dwordx4 v234, v[104:107], s[10:11]
	v_add_u32_e32 v235, 0x16000, v234
	v_mul_f32_e32 v252, 0xbfb8aa3b, v244
	v_mul_f32_e32 v254, v244, v244
	v_pk_mul_f32 v[88:89], v[92:93], v[88:89]
	v_pk_mul_f32 v[90:91], v[94:95], v[90:91]
	v_pk_mul_f32 v[80:81], v[84:85], v[80:81]
	v_pk_mul_f32 v[82:83], v[86:87], v[82:83]
	v_pk_mul_f32 v[92:93], v[92:93], v[252:253] op_sel_hi:[1,0]
	v_pk_mul_f32 v[94:95], v[94:95], v[252:253] op_sel_hi:[1,0]
	v_pk_mul_f32 v[84:85], v[84:85], v[252:253] op_sel_hi:[1,0]
	v_pk_mul_f32 v[86:87], v[86:87], v[252:253] op_sel_hi:[1,0]
	v_exp_f32_e32 v92, v92
	v_exp_f32_e32 v93, v93
	v_exp_f32_e32 v94, v94
	v_exp_f32_e32 v95, v95
	v_exp_f32_e32 v84, v84
	v_exp_f32_e32 v85, v85
	v_exp_f32_e32 v86, v86
	v_exp_f32_e32 v87, v87
	v_pk_add_f32 v[92:93], v[92:93], 1.0 op_sel_hi:[1,0]
	v_pk_add_f32 v[94:95], v[94:95], 1.0 op_sel_hi:[1,0]
	v_pk_add_f32 v[84:85], v[84:85], 1.0 op_sel_hi:[1,0]
	v_pk_add_f32 v[86:87], v[86:87], 1.0 op_sel_hi:[1,0]
	v_rcp_f32_e32 v92, v92
	v_rcp_f32_e32 v93, v93
	v_rcp_f32_e32 v94, v94
	v_rcp_f32_e32 v95, v95
	v_rcp_f32_e32 v84, v84
	v_rcp_f32_e32 v85, v85
	v_rcp_f32_e32 v86, v86
	v_rcp_f32_e32 v87, v87
	v_pk_mul_f32 v[88:89], v[88:89], v[254:255] op_sel_hi:[1,0]
	v_pk_mul_f32 v[90:91], v[90:91], v[254:255] op_sel_hi:[1,0]
	v_pk_mul_f32 v[80:81], v[80:81], v[254:255] op_sel_hi:[1,0]
	v_pk_mul_f32 v[82:83], v[82:83], v[254:255] op_sel_hi:[1,0]
	v_pk_mul_f32 v[88:89], v[88:89], v[92:93]
	v_pk_mul_f32 v[90:91], v[90:91], v[94:95]
	v_pk_mul_f32 v[80:81], v[80:81], v[84:85]
	v_pk_mul_f32 v[82:83], v[82:83], v[86:87]
	v_cvt_pk_bf16_f32 v88, v88, v89
	v_cvt_pk_bf16_f32 v89, v90, v91
	v_cvt_pk_bf16_f32 v90, v80, v81
	v_cvt_pk_bf16_f32 v91, v82, v83
	global_store_dwordx4 v235, v[88:91], s[10:11]
	v_add_u32_e32 v234, 0x16000, v235
	v_mul_f32_e32 v252, 0xbfb8aa3b, v248
	v_mul_f32_e32 v254, v248, v248
	v_pk_mul_f32 v[72:73], v[76:77], v[72:73]
	v_pk_mul_f32 v[74:75], v[78:79], v[74:75]
	v_pk_mul_f32 v[64:65], v[68:69], v[64:65]
	v_pk_mul_f32 v[66:67], v[70:71], v[66:67]
	v_pk_mul_f32 v[76:77], v[76:77], v[252:253] op_sel_hi:[1,0]
	v_pk_mul_f32 v[78:79], v[78:79], v[252:253] op_sel_hi:[1,0]
	v_pk_mul_f32 v[68:69], v[68:69], v[252:253] op_sel_hi:[1,0]
	v_pk_mul_f32 v[70:71], v[70:71], v[252:253] op_sel_hi:[1,0]
	v_exp_f32_e32 v76, v76
	v_exp_f32_e32 v77, v77
	v_exp_f32_e32 v78, v78
	v_exp_f32_e32 v79, v79
	v_exp_f32_e32 v68, v68
	v_exp_f32_e32 v69, v69
	v_exp_f32_e32 v70, v70
	v_exp_f32_e32 v71, v71
	v_pk_add_f32 v[76:77], v[76:77], 1.0 op_sel_hi:[1,0]
	v_pk_add_f32 v[78:79], v[78:79], 1.0 op_sel_hi:[1,0]
	v_pk_add_f32 v[68:69], v[68:69], 1.0 op_sel_hi:[1,0]
	v_pk_add_f32 v[70:71], v[70:71], 1.0 op_sel_hi:[1,0]
	v_rcp_f32_e32 v76, v76
	v_rcp_f32_e32 v77, v77
	v_rcp_f32_e32 v78, v78
	v_rcp_f32_e32 v79, v79
	v_rcp_f32_e32 v68, v68
	v_rcp_f32_e32 v69, v69
	v_rcp_f32_e32 v70, v70
	v_rcp_f32_e32 v71, v71
	v_pk_mul_f32 v[72:73], v[72:73], v[254:255] op_sel_hi:[1,0]
	v_pk_mul_f32 v[74:75], v[74:75], v[254:255] op_sel_hi:[1,0]
	v_pk_mul_f32 v[64:65], v[64:65], v[254:255] op_sel_hi:[1,0]
	v_pk_mul_f32 v[66:67], v[66:67], v[254:255] op_sel_hi:[1,0]
	v_pk_mul_f32 v[72:73], v[72:73], v[76:77]
	v_pk_mul_f32 v[74:75], v[74:75], v[78:79]
	v_pk_mul_f32 v[64:65], v[64:65], v[68:69]
	v_pk_mul_f32 v[66:67], v[66:67], v[70:71]
	v_cvt_pk_bf16_f32 v72, v72, v73
	v_cvt_pk_bf16_f32 v73, v74, v75
	v_cvt_pk_bf16_f32 v74, v64, v65
	v_cvt_pk_bf16_f32 v75, v66, v67
	global_store_dwordx4 v234, v[72:75], s[10:11]
	s_waitcnt vmcnt(12)
	s_waitcnt lgkmcnt(0)
	s_barrier
	s_setprio 1
	s_waitcnt lgkmcnt(0)
	v_mfma_f32_16x16x32_bf16 v[60:63], v[160:163], v[192:195], v[60:63]
	v_mfma_f32_16x16x32_bf16 v[60:63], v[164:167], v[196:199], v[60:63]
	v_mfma_f32_16x16x32_bf16 v[52:55], v[168:171], v[192:195], v[52:55]
	v_mfma_f32_16x16x32_bf16 v[52:55], v[172:175], v[196:199], v[52:55]
	v_mfma_f32_16x16x32_bf16 v[44:47], v[160:163], v[200:203], v[44:47]
	v_mfma_f32_16x16x32_bf16 v[44:47], v[164:167], v[204:207], v[44:47]
	v_mfma_f32_16x16x32_bf16 v[36:39], v[168:171], v[200:203], v[36:39]
	v_mfma_f32_16x16x32_bf16 v[36:39], v[172:175], v[204:207], v[36:39]
	v_mfma_f32_16x16x32_bf16 v[28:31], v[160:163], v[208:211], v[28:31]
	v_mfma_f32_16x16x32_bf16 v[28:31], v[164:167], v[212:215], v[28:31]
	v_mfma_f32_16x16x32_bf16 v[20:23], v[168:171], v[208:211], v[20:23]
	v_mfma_f32_16x16x32_bf16 v[20:23], v[172:175], v[212:215], v[20:23]
	v_mfma_f32_16x16x32_bf16 v[12:15], v[160:163], v[216:219], v[12:15]
	v_mfma_f32_16x16x32_bf16 v[12:15], v[164:167], v[220:223], v[12:15]
	v_mfma_f32_16x16x32_bf16 v[4:7], v[168:171], v[216:219], v[4:7]
	v_mfma_f32_16x16x32_bf16 v[4:7], v[172:175], v[220:223], v[4:7]
	s_setprio 0
	s_setprio 1
	v_mfma_f32_16x16x32_bf16 v[56:59], v[176:179], v[192:195], v[56:59]
	v_mfma_f32_16x16x32_bf16 v[56:59], v[180:183], v[196:199], v[56:59]
	v_mfma_f32_16x16x32_bf16 v[48:51], v[184:187], v[192:195], v[48:51]
	v_mfma_f32_16x16x32_bf16 v[48:51], v[188:191], v[196:199], v[48:51]
	v_mfma_f32_16x16x32_bf16 v[40:43], v[176:179], v[200:203], v[40:43]
	v_mfma_f32_16x16x32_bf16 v[40:43], v[180:183], v[204:207], v[40:43]
	v_mfma_f32_16x16x32_bf16 v[32:35], v[184:187], v[200:203], v[32:35]
	v_mfma_f32_16x16x32_bf16 v[32:35], v[188:191], v[204:207], v[32:35]
	v_mfma_f32_16x16x32_bf16 v[24:27], v[176:179], v[208:211], v[24:27]
	v_mfma_f32_16x16x32_bf16 v[24:27], v[180:183], v[212:215], v[24:27]
	v_mfma_f32_16x16x32_bf16 v[16:19], v[184:187], v[208:211], v[16:19]
	v_mfma_f32_16x16x32_bf16 v[16:19], v[188:191], v[212:215], v[16:19]
	v_mfma_f32_16x16x32_bf16 v[8:11], v[176:179], v[216:219], v[8:11]
	v_mfma_f32_16x16x32_bf16 v[8:11], v[180:183], v[220:223], v[8:11]
	v_mfma_f32_16x16x32_bf16 v[0:3], v[184:187], v[216:219], v[0:3]
	v_mfma_f32_16x16x32_bf16 v[0:3], v[188:191], v[220:223], v[0:3]
	s_setprio 0
	s_barrier
	s_add_i32 s70, s70, 2
	s_add_u32 s68, s68, 0x100
	s_addc_u32 s69, s69, 0
	s_add_u32 s30, s30, 0x100
	s_addc_u32 s31, s31, 0

.LBB0_1180:
	s_add_u32 s72, s50, 0x100
	s_addc_u32 s73, s51, 0
	s_mov_b32 s74, -2
	s_waitcnt lgkmcnt(0)
	s_cmp_eq_u32 s63, 1
	s_cbranch_scc1 .Lfa_11
	ds_read_b128 v[128:131], v188
	ds_read_b128 v[132:135], v188 offset:1024
	ds_read_b128 v[136:139], v188 offset:2048
	ds_read_b128 v[140:143], v188 offset:3072
	ds_read_b128 v[144:147], v189
	ds_read_b128 v[148:151], v189 offset:1024
	ds_read_b128 v[172:175], v189 offset:2048
	ds_read_b128 v[176:179], v189 offset:3072
	s_add_u32 s50, s48, 0x100
	s_addc_u32 s51, s49, 0
	s_cmp_eq_u32 s74, 40
	s_cselect_b32 s55, s11, s51
	s_cselect_b32 s54, s10, s50
	s_cselect_b32 s53, s47, s73
	s_cselect_b32 s52, s46, s72
	v_lshl_add_u64 v[220:221], s[48:49], 0, v[166:167]
	s_add_i32 m0, s59, 0xc000
	ds_read_b128 v[180:183], v190
	ds_read_b128 v[192:195], v190 offset:1024
	ds_read_b128 v[196:199], v190 offset:2048
	ds_read_b128 v[200:203], v190 offset:3072
	ds_read_b128 v[204:207], v190 offset:4096
	ds_read_b128 v[208:211], v190 offset:5120
	ds_read_b128 v[212:215], v190 offset:6144
	ds_read_b128 v[216:219], v190 offset:7168
	global_load_lds_dwordx4 v[220:221], off
	v_lshl_add_u64 v[220:221], s[48:49], 0, v[164:165]
	s_add_i32 m0, s59, 0xe000
	s_nop 0
	global_load_lds_dwordx4 v[220:221], off
	s_waitcnt vmcnt(24)
	s_waitcnt lgkmcnt(0)
	s_barrier
	s_setprio 1
	s_waitcnt lgkmcnt(0)
	v_mfma_f32_16x16x32_bf16 v[124:127], v[128:131], v[180:183], 0
	v_mfma_f32_16x16x32_bf16 v[120:123], v[136:139], v[180:183], 0
	v_mfma_f32_16x16x32_bf16 v[108:111], v[128:131], v[196:199], 0
	v_mfma_f32_16x16x32_bf16 v[104:107], v[136:139], v[196:199], 0
	v_mfma_f32_16x16x32_bf16 v[92:95], v[128:131], v[204:207], 0
	v_mfma_f32_16x16x32_bf16 v[88:91], v[136:139], v[204:207], 0
	v_mfma_f32_16x16x32_bf16 v[76:79], v[128:131], v[212:215], 0
	v_mfma_f32_16x16x32_bf16 v[72:75], v[136:139], v[212:215], 0
	v_mfma_f32_16x16x32_bf16 v[124:127], v[132:135], v[192:195], v[124:127]
	v_mfma_f32_16x16x32_bf16 v[120:123], v[140:143], v[192:195], v[120:123]
	v_mfma_f32_16x16x32_bf16 v[108:111], v[132:135], v[200:203], v[108:111]
	v_mfma_f32_16x16x32_bf16 v[104:107], v[140:143], v[200:203], v[104:107]
	v_mfma_f32_16x16x32_bf16 v[92:95], v[132:135], v[208:211], v[92:95]
	v_mfma_f32_16x16x32_bf16 v[88:91], v[140:143], v[208:211], v[88:91]
	v_mfma_f32_16x16x32_bf16 v[76:79], v[132:135], v[216:219], v[76:79]
	v_mfma_f32_16x16x32_bf16 v[72:75], v[140:143], v[216:219], v[72:75]
	s_setprio 0
	s_setprio 1
	v_mfma_f32_16x16x32_bf16 v[116:119], v[144:147], v[180:183], 0
	v_mfma_f32_16x16x32_bf16 v[112:115], v[172:175], v[180:183], 0
	v_mfma_f32_16x16x32_bf16 v[100:103], v[144:147], v[196:199], 0
	v_mfma_f32_16x16x32_bf16 v[96:99], v[172:175], v[196:199], 0
	v_mfma_f32_16x16x32_bf16 v[84:87], v[144:147], v[204:207], 0
	v_mfma_f32_16x16x32_bf16 v[80:83], v[172:175], v[204:207], 0
	v_mfma_f32_16x16x32_bf16 v[68:71], v[144:147], v[212:215], 0
	v_mfma_f32_16x16x32_bf16 v[64:67], v[172:175], v[212:215], 0
	v_mfma_f32_16x16x32_bf16 v[116:119], v[148:151], v[192:195], v[116:119]
	v_mfma_f32_16x16x32_bf16 v[112:115], v[176:179], v[192:195], v[112:115]
	v_mfma_f32_16x16x32_bf16 v[100:103], v[148:151], v[200:203], v[100:103]
	v_mfma_f32_16x16x32_bf16 v[96:99], v[176:179], v[200:203], v[96:99]
	v_mfma_f32_16x16x32_bf16 v[84:87], v[148:151], v[208:211], v[84:87]
	v_mfma_f32_16x16x32_bf16 v[80:83], v[176:179], v[208:211], v[80:83]
	v_mfma_f32_16x16x32_bf16 v[68:71], v[148:151], v[216:219], v[68:71]
	v_mfma_f32_16x16x32_bf16 v[64:67], v[176:179], v[216:219], v[64:67]
	s_setprio 0
	s_barrier
	s_add_i32 s48, s68, s58
	v_lshl_add_u64 v[220:221], s[52:53], 0, v[154:155]
	s_mov_b32 m0, s48
	ds_read_b128 v[180:183], v190 offset:16384
	ds_read_b128 v[192:195], v190 offset:17408
	ds_read_b128 v[196:199], v190 offset:18432
	ds_read_b128 v[200:203], v190 offset:19456
	ds_read_b128 v[204:207], v190 offset:20480
	ds_read_b128 v[208:211], v190 offset:21504
	ds_read_b128 v[212:215], v190 offset:22528
	ds_read_b128 v[216:219], v190 offset:23552
	global_load_lds_dwordx4 v[220:221], off
	s_add_i32 m0, s48, 0x2000
	s_add_u32 s48, s52, 0xb0000
	v_lshl_add_u64 v[222:223], s[52:53], 0, v[162:163]
	s_addc_u32 s49, s53, 0
	s_add_i32 s75, s69, s58
	global_load_lds_dwordx4 v[222:223], off
	v_lshl_add_u64 v[224:225], s[48:49], 0, v[154:155]
	s_mov_b32 m0, s75
	v_lshl_add_u64 v[226:227], s[54:55], 0, v[160:161]
	global_load_lds_dwordx4 v[224:225], off
	v_lshl_add_u64 v[224:225], s[48:49], 0, v[162:163]
	s_add_i32 m0, s75, 0x2000
	s_nop 0
	global_load_lds_dwordx4 v[224:225], off
	v_lshl_add_u64 v[224:225], s[54:55], 0, v[152:153]
	s_mov_b32 m0, s59
	s_nop 0
	global_load_lds_dwordx4 v[224:225], off
	s_mov_b32 m0, s60
	s_nop 0
	global_load_lds_dwordx4 v[226:227], off
	s_waitcnt vmcnt(24)
	s_waitcnt lgkmcnt(0)
	s_barrier
	s_setprio 1
	s_waitcnt lgkmcnt(0)
	v_mfma_f32_16x16x32_bf16 v[60:63], v[128:131], v[180:183], 0
	v_mfma_f32_16x16x32_bf16 v[56:59], v[136:139], v[180:183], 0
	v_mfma_f32_16x16x32_bf16 v[44:47], v[128:131], v[196:199], 0
	v_mfma_f32_16x16x32_bf16 v[40:43], v[136:139], v[196:199], 0
	v_mfma_f32_16x16x32_bf16 v[28:31], v[128:131], v[204:207], 0
	v_mfma_f32_16x16x32_bf16 v[24:27], v[136:139], v[204:207], 0
	v_mfma_f32_16x16x32_bf16 v[12:15], v[128:131], v[212:215], 0
	v_mfma_f32_16x16x32_bf16 v[8:11], v[136:139], v[212:215], 0
	v_mfma_f32_16x16x32_bf16 v[60:63], v[132:135], v[192:195], v[60:63]
	v_mfma_f32_16x16x32_bf16 v[56:59], v[140:143], v[192:195], v[56:59]
	v_mfma_f32_16x16x32_bf16 v[44:47], v[132:135], v[200:203], v[44:47]
	v_mfma_f32_16x16x32_bf16 v[40:43], v[140:143], v[200:203], v[40:43]
	v_mfma_f32_16x16x32_bf16 v[28:31], v[132:135], v[208:211], v[28:31]
	v_mfma_f32_16x16x32_bf16 v[24:27], v[140:143], v[208:211], v[24:27]
	v_mfma_f32_16x16x32_bf16 v[12:15], v[132:135], v[216:219], v[12:15]
	v_mfma_f32_16x16x32_bf16 v[8:11], v[140:143], v[216:219], v[8:11]
	s_setprio 0
	s_setprio 1
	v_mfma_f32_16x16x32_bf16 v[52:55], v[144:147], v[180:183], 0
	v_mfma_f32_16x16x32_bf16 v[48:51], v[172:175], v[180:183], 0
	v_mfma_f32_16x16x32_bf16 v[36:39], v[144:147], v[196:199], 0
	v_mfma_f32_16x16x32_bf16 v[32:35], v[172:175], v[196:199], 0
	v_mfma_f32_16x16x32_bf16 v[20:23], v[144:147], v[204:207], 0
	v_mfma_f32_16x16x32_bf16 v[16:19], v[172:175], v[204:207], 0
	v_mfma_f32_16x16x32_bf16 v[4:7], v[144:147], v[212:215], 0
	v_mfma_f32_16x16x32_bf16 v[0:3], v[172:175], v[212:215], 0
	v_mfma_f32_16x16x32_bf16 v[52:55], v[148:151], v[192:195], v[52:55]
	v_mfma_f32_16x16x32_bf16 v[48:51], v[176:179], v[192:195], v[48:51]
	v_mfma_f32_16x16x32_bf16 v[36:39], v[148:151], v[200:203], v[36:39]
	v_mfma_f32_16x16x32_bf16 v[32:35], v[176:179], v[200:203], v[32:35]
	v_mfma_f32_16x16x32_bf16 v[20:23], v[148:151], v[208:211], v[20:23]
	v_mfma_f32_16x16x32_bf16 v[16:19], v[176:179], v[208:211], v[16:19]
	v_mfma_f32_16x16x32_bf16 v[4:7], v[148:151], v[216:219], v[4:7]
	v_mfma_f32_16x16x32_bf16 v[0:3], v[176:179], v[216:219], v[0:3]
	s_setprio 0
	s_barrier
	s_add_i32 s75, 0, 0x18000
	s_add_i32 s76, 0, 0x1c000
	v_add_u32_e32 v140, s75, v185
	v_add_u32_e32 v176, s76, v185
	ds_read_b128 v[128:131], v140
	ds_read_b128 v[132:135], v140 offset:1024
	ds_read_b128 v[136:139], v140 offset:2048
	ds_read_b128 v[140:143], v140 offset:3072
	ds_read_b128 v[144:147], v176
	ds_read_b128 v[148:151], v176 offset:1024
	ds_read_b128 v[172:175], v176 offset:2048
	ds_read_b128 v[176:179], v176 offset:3072
	s_add_u32 s48, s54, 0xb0000
	s_addc_u32 s49, s55, 0
	s_mov_b32 m0, s61
	v_lshl_add_u64 v[228:229], s[48:49], 0, v[152:153]
	ds_read_b128 v[180:183], v190 offset:32768
	ds_read_b128 v[192:195], v190 offset:33792
	ds_read_b128 v[196:199], v190 offset:34816
	ds_read_b128 v[200:203], v190 offset:35840
	ds_read_b128 v[204:207], v190 offset:36864
	ds_read_b128 v[208:211], v190 offset:37888
	ds_read_b128 v[212:215], v190 offset:38912
	ds_read_b128 v[216:219], v190 offset:39936
	global_load_lds_dwordx4 v[228:229], off
	v_lshl_add_u64 v[228:229], s[48:49], 0, v[160:161]
	s_mov_b32 m0, s62
	s_nop 0
	global_load_lds_dwordx4 v[228:229], off
	s_waitcnt vmcnt(8)
	s_waitcnt lgkmcnt(0)
	s_barrier
	s_setprio 1
	s_waitcnt lgkmcnt(0)
	v_mfma_f32_16x16x32_bf16 v[124:127], v[128:131], v[180:183], v[124:127]
	v_mfma_f32_16x16x32_bf16 v[124:127], v[132:135], v[192:195], v[124:127]
	v_mfma_f32_16x16x32_bf16 v[120:123], v[136:139], v[180:183], v[120:123]
	v_mfma_f32_16x16x32_bf16 v[120:123], v[140:143], v[192:195], v[120:123]
	v_mfma_f32_16x16x32_bf16 v[108:111], v[128:131], v[196:199], v[108:111]
	v_mfma_f32_16x16x32_bf16 v[108:111], v[132:135], v[200:203], v[108:111]
	v_mfma_f32_16x16x32_bf16 v[104:107], v[136:139], v[196:199], v[104:107]
	v_mfma_f32_16x16x32_bf16 v[104:107], v[140:143], v[200:203], v[104:107]
	v_mfma_f32_16x16x32_bf16 v[92:95], v[128:131], v[204:207], v[92:95]
	v_mfma_f32_16x16x32_bf16 v[92:95], v[132:135], v[208:211], v[92:95]
	v_mfma_f32_16x16x32_bf16 v[88:91], v[136:139], v[204:207], v[88:91]
	v_mfma_f32_16x16x32_bf16 v[88:91], v[140:143], v[208:211], v[88:91]
	v_mfma_f32_16x16x32_bf16 v[76:79], v[128:131], v[212:215], v[76:79]
	v_mfma_f32_16x16x32_bf16 v[76:79], v[132:135], v[216:219], v[76:79]
	v_mfma_f32_16x16x32_bf16 v[72:75], v[136:139], v[212:215], v[72:75]
	v_mfma_f32_16x16x32_bf16 v[72:75], v[140:143], v[216:219], v[72:75]
	s_setprio 0
	s_setprio 1
	v_mfma_f32_16x16x32_bf16 v[116:119], v[144:147], v[180:183], v[116:119]
	v_mfma_f32_16x16x32_bf16 v[116:119], v[148:151], v[192:195], v[116:119]
	v_mfma_f32_16x16x32_bf16 v[112:115], v[172:175], v[180:183], v[112:115]
	v_mfma_f32_16x16x32_bf16 v[112:115], v[176:179], v[192:195], v[112:115]
	v_mfma_f32_16x16x32_bf16 v[100:103], v[144:147], v[196:199], v[100:103]
	v_mfma_f32_16x16x32_bf16 v[100:103], v[148:151], v[200:203], v[100:103]
	v_mfma_f32_16x16x32_bf16 v[96:99], v[172:175], v[196:199], v[96:99]
	v_mfma_f32_16x16x32_bf16 v[96:99], v[176:179], v[200:203], v[96:99]
	v_mfma_f32_16x16x32_bf16 v[84:87], v[144:147], v[204:207], v[84:87]
	v_mfma_f32_16x16x32_bf16 v[84:87], v[148:151], v[208:211], v[84:87]
	v_mfma_f32_16x16x32_bf16 v[80:83], v[172:175], v[204:207], v[80:83]
	v_mfma_f32_16x16x32_bf16 v[80:83], v[176:179], v[208:211], v[80:83]
	v_mfma_f32_16x16x32_bf16 v[68:71], v[144:147], v[212:215], v[68:71]
	v_mfma_f32_16x16x32_bf16 v[68:71], v[148:151], v[216:219], v[68:71]
	v_mfma_f32_16x16x32_bf16 v[64:67], v[172:175], v[212:215], v[64:67]
	v_mfma_f32_16x16x32_bf16 v[64:67], v[176:179], v[216:219], v[64:67]
	s_setprio 0
	s_barrier
	s_add_i32 s48, s75, s58
	v_lshl_add_u64 v[220:221], v[220:221], 0, s[22:23]
	s_mov_b32 m0, s48
	ds_read_b128 v[180:183], v190 offset:49152
	ds_read_b128 v[192:195], v190 offset:50176
	ds_read_b128 v[196:199], v190 offset:51200
	ds_read_b128 v[200:203], v190 offset:52224
	ds_read_b128 v[204:207], v190 offset:53248
	ds_read_b128 v[208:211], v190 offset:54272
	ds_read_b128 v[212:215], v190 offset:55296
	ds_read_b128 v[216:219], v190 offset:56320
	global_load_lds_dwordx4 v[220:221], off
	s_add_i32 m0, s48, 0x2000
	s_add_u32 s48, s52, 0xb0080
	v_lshl_add_u64 v[220:221], v[222:223], 0, s[22:23]
	s_addc_u32 s49, s53, 0
	s_add_i32 s52, s76, s58
	global_load_lds_dwordx4 v[220:221], off
	v_lshl_add_u64 v[220:221], s[48:49], 0, v[154:155]
	s_mov_b32 m0, s52
	s_nop 0
	global_load_lds_dwordx4 v[220:221], off
	v_lshl_add_u64 v[220:221], s[48:49], 0, v[162:163]
	s_add_i32 m0, s52, 0x2000
	s_nop 0
	global_load_lds_dwordx4 v[220:221], off
	v_lshl_add_u64 v[220:221], v[224:225], 0, s[22:23]
	s_mov_b32 m0, s3
	s_nop 0
	global_load_lds_dwordx4 v[220:221], off
	v_lshl_add_u64 v[220:221], v[226:227], 0, s[22:23]
	s_mov_b32 m0, s64
	s_nop 0
	global_load_lds_dwordx4 v[220:221], off
	s_waitcnt vmcnt(8)
	s_waitcnt lgkmcnt(0)
	s_barrier
	s_setprio 1
	s_waitcnt lgkmcnt(0)
	v_mfma_f32_16x16x32_bf16 v[60:63], v[128:131], v[180:183], v[60:63]
	v_mfma_f32_16x16x32_bf16 v[60:63], v[132:135], v[192:195], v[60:63]
	v_mfma_f32_16x16x32_bf16 v[56:59], v[136:139], v[180:183], v[56:59]
	v_mfma_f32_16x16x32_bf16 v[56:59], v[140:143], v[192:195], v[56:59]
	v_mfma_f32_16x16x32_bf16 v[44:47], v[128:131], v[196:199], v[44:47]
	v_mfma_f32_16x16x32_bf16 v[44:47], v[132:135], v[200:203], v[44:47]
	v_mfma_f32_16x16x32_bf16 v[40:43], v[136:139], v[196:199], v[40:43]
	v_mfma_f32_16x16x32_bf16 v[40:43], v[140:143], v[200:203], v[40:43]
	v_mfma_f32_16x16x32_bf16 v[28:31], v[128:131], v[204:207], v[28:31]
	v_mfma_f32_16x16x32_bf16 v[28:31], v[132:135], v[208:211], v[28:31]
	v_mfma_f32_16x16x32_bf16 v[24:27], v[136:139], v[204:207], v[24:27]
	v_mfma_f32_16x16x32_bf16 v[24:27], v[140:143], v[208:211], v[24:27]
	v_mfma_f32_16x16x32_bf16 v[12:15], v[128:131], v[212:215], v[12:15]
	v_mfma_f32_16x16x32_bf16 v[12:15], v[132:135], v[216:219], v[12:15]
	v_mfma_f32_16x16x32_bf16 v[8:11], v[136:139], v[212:215], v[8:11]
	v_mfma_f32_16x16x32_bf16 v[8:11], v[140:143], v[216:219], v[8:11]
	s_setprio 0
	s_setprio 1
	v_mfma_f32_16x16x32_bf16 v[52:55], v[144:147], v[180:183], v[52:55]
	v_mfma_f32_16x16x32_bf16 v[52:55], v[148:151], v[192:195], v[52:55]
	v_mfma_f32_16x16x32_bf16 v[48:51], v[172:175], v[180:183], v[48:51]
	v_mfma_f32_16x16x32_bf16 v[48:51], v[176:179], v[192:195], v[48:51]
	v_mfma_f32_16x16x32_bf16 v[36:39], v[144:147], v[196:199], v[36:39]
	v_mfma_f32_16x16x32_bf16 v[36:39], v[148:151], v[200:203], v[36:39]
	v_mfma_f32_16x16x32_bf16 v[32:35], v[172:175], v[196:199], v[32:35]
	v_mfma_f32_16x16x32_bf16 v[32:35], v[176:179], v[200:203], v[32:35]
	v_mfma_f32_16x16x32_bf16 v[20:23], v[144:147], v[204:207], v[20:23]
	v_mfma_f32_16x16x32_bf16 v[20:23], v[148:151], v[208:211], v[20:23]
	v_mfma_f32_16x16x32_bf16 v[16:19], v[172:175], v[204:207], v[16:19]
	v_mfma_f32_16x16x32_bf16 v[16:19], v[176:179], v[208:211], v[16:19]
	v_mfma_f32_16x16x32_bf16 v[4:7], v[144:147], v[212:215], v[4:7]
	v_mfma_f32_16x16x32_bf16 v[4:7], v[148:151], v[216:219], v[4:7]
	v_mfma_f32_16x16x32_bf16 v[0:3], v[172:175], v[212:215], v[0:3]
	v_mfma_f32_16x16x32_bf16 v[0:3], v[176:179], v[216:219], v[0:3]
	s_setprio 0
	s_barrier
	s_add_i32 s74, s74, 2
	s_add_u32 s72, s72, 0x100
	s_addc_u32 s73, s73, 0
	s_cmp_gt_u32 s74, 41
	s_mov_b64 s[48:49], s[50:51]
	s_branch .LBB0_1181
.Lfa_11:
	ds_read_b128 v[128:131], v188
	ds_read_b128 v[132:135], v188 offset:1024
	ds_read_b128 v[136:139], v188 offset:2048
	ds_read_b128 v[140:143], v188 offset:3072
	ds_read_b128 v[144:147], v189
	ds_read_b128 v[148:151], v189 offset:1024
	ds_read_b128 v[172:175], v189 offset:2048
	ds_read_b128 v[176:179], v189 offset:3072
	s_add_u32 s50, s48, 0x100
	s_addc_u32 s51, s49, 0
	s_cmp_eq_u32 s74, 40
	s_cselect_b32 s55, s11, s51
	s_cselect_b32 s54, s10, s50
	s_cselect_b32 s53, s47, s73
	s_cselect_b32 s52, s46, s72
	v_lshl_add_u64 v[220:221], s[48:49], 0, v[166:167]
	s_add_i32 m0, s59, 0xc000
	ds_read_b128 v[180:183], v190
	ds_read_b128 v[192:195], v190 offset:1024
	ds_read_b128 v[196:199], v190 offset:2048
	ds_read_b128 v[200:203], v190 offset:3072
	ds_read_b128 v[204:207], v190 offset:4096
	ds_read_b128 v[208:211], v190 offset:5120
	ds_read_b128 v[212:215], v190 offset:6144
	ds_read_b128 v[216:219], v190 offset:7168
	global_load_lds_dwordx4 v[220:221], off
	v_lshl_add_u64 v[220:221], s[48:49], 0, v[164:165]
	s_add_i32 m0, s59, 0xe000
	s_nop 0
	global_load_lds_dwordx4 v[220:221], off
	s_waitcnt vmcnt(8)
	s_waitcnt lgkmcnt(0)
	s_barrier
	s_setprio 1
	s_waitcnt lgkmcnt(0)
	v_mfma_f32_16x16x32_bf16 v[124:127], v[128:131], v[180:183], 0
	v_mfma_f32_16x16x32_bf16 v[120:123], v[136:139], v[180:183], 0
	v_mfma_f32_16x16x32_bf16 v[108:111], v[128:131], v[196:199], 0
	v_mfma_f32_16x16x32_bf16 v[104:107], v[136:139], v[196:199], 0
	v_mfma_f32_16x16x32_bf16 v[92:95], v[128:131], v[204:207], 0
	v_mfma_f32_16x16x32_bf16 v[88:91], v[136:139], v[204:207], 0
	v_mfma_f32_16x16x32_bf16 v[76:79], v[128:131], v[212:215], 0
	v_mfma_f32_16x16x32_bf16 v[72:75], v[136:139], v[212:215], 0
	v_mfma_f32_16x16x32_bf16 v[124:127], v[132:135], v[192:195], v[124:127]
	v_mfma_f32_16x16x32_bf16 v[120:123], v[140:143], v[192:195], v[120:123]
	v_mfma_f32_16x16x32_bf16 v[108:111], v[132:135], v[200:203], v[108:111]
	v_mfma_f32_16x16x32_bf16 v[104:107], v[140:143], v[200:203], v[104:107]
	v_mfma_f32_16x16x32_bf16 v[92:95], v[132:135], v[208:211], v[92:95]
	v_mfma_f32_16x16x32_bf16 v[88:91], v[140:143], v[208:211], v[88:91]
	v_mfma_f32_16x16x32_bf16 v[76:79], v[132:135], v[216:219], v[76:79]
	v_mfma_f32_16x16x32_bf16 v[72:75], v[140:143], v[216:219], v[72:75]
	s_setprio 0
	s_setprio 1
	v_mfma_f32_16x16x32_bf16 v[116:119], v[144:147], v[180:183], 0
	v_mfma_f32_16x16x32_bf16 v[112:115], v[172:175], v[180:183], 0
	v_mfma_f32_16x16x32_bf16 v[100:103], v[144:147], v[196:199], 0
	v_mfma_f32_16x16x32_bf16 v[96:99], v[172:175], v[196:199], 0
	v_mfma_f32_16x16x32_bf16 v[84:87], v[144:147], v[204:207], 0
	v_mfma_f32_16x16x32_bf16 v[80:83], v[172:175], v[204:207], 0
	v_mfma_f32_16x16x32_bf16 v[68:71], v[144:147], v[212:215], 0
	v_mfma_f32_16x16x32_bf16 v[64:67], v[172:175], v[212:215], 0
	v_mfma_f32_16x16x32_bf16 v[116:119], v[148:151], v[192:195], v[116:119]
	v_mfma_f32_16x16x32_bf16 v[112:115], v[176:179], v[192:195], v[112:115]
	v_mfma_f32_16x16x32_bf16 v[100:103], v[148:151], v[200:203], v[100:103]
	v_mfma_f32_16x16x32_bf16 v[96:99], v[176:179], v[200:203], v[96:99]
	v_mfma_f32_16x16x32_bf16 v[84:87], v[148:151], v[208:211], v[84:87]
	v_mfma_f32_16x16x32_bf16 v[80:83], v[176:179], v[208:211], v[80:83]
	v_mfma_f32_16x16x32_bf16 v[68:71], v[148:151], v[216:219], v[68:71]
	v_mfma_f32_16x16x32_bf16 v[64:67], v[176:179], v[216:219], v[64:67]
	s_setprio 0
	s_barrier
	s_add_i32 s48, s68, s58
	v_lshl_add_u64 v[220:221], s[52:53], 0, v[154:155]
	s_mov_b32 m0, s48
	ds_read_b128 v[180:183], v190 offset:16384
	ds_read_b128 v[192:195], v190 offset:17408
	ds_read_b128 v[196:199], v190 offset:18432
	ds_read_b128 v[200:203], v190 offset:19456
	ds_read_b128 v[204:207], v190 offset:20480
	ds_read_b128 v[208:211], v190 offset:21504
	ds_read_b128 v[212:215], v190 offset:22528
	ds_read_b128 v[216:219], v190 offset:23552
	global_load_lds_dwordx4 v[220:221], off
	s_add_i32 m0, s48, 0x2000
	s_add_u32 s48, s52, 0xb0000
	v_lshl_add_u64 v[222:223], s[52:53], 0, v[162:163]
	s_addc_u32 s49, s53, 0
	s_add_i32 s75, s69, s58
	global_load_lds_dwordx4 v[222:223], off
	v_lshl_add_u64 v[224:225], s[48:49], 0, v[154:155]
	s_mov_b32 m0, s75
	v_lshl_add_u64 v[226:227], s[54:55], 0, v[160:161]
	global_load_lds_dwordx4 v[224:225], off
	v_lshl_add_u64 v[224:225], s[48:49], 0, v[162:163]
	s_add_i32 m0, s75, 0x2000
	s_nop 0
	global_load_lds_dwordx4 v[224:225], off
	v_lshl_add_u64 v[224:225], s[54:55], 0, v[152:153]
	s_mov_b32 m0, s59
	s_nop 0
	global_load_lds_dwordx4 v[224:225], off
	s_mov_b32 m0, s60
	s_nop 0
	global_load_lds_dwordx4 v[226:227], off
	s_waitcnt vmcnt(8)
	s_waitcnt lgkmcnt(0)
	s_barrier
	s_setprio 1
	s_waitcnt lgkmcnt(0)
	v_mfma_f32_16x16x32_bf16 v[60:63], v[128:131], v[180:183], 0
	v_mfma_f32_16x16x32_bf16 v[56:59], v[136:139], v[180:183], 0
	v_mfma_f32_16x16x32_bf16 v[44:47], v[128:131], v[196:199], 0
	v_mfma_f32_16x16x32_bf16 v[40:43], v[136:139], v[196:199], 0
	v_mfma_f32_16x16x32_bf16 v[28:31], v[128:131], v[204:207], 0
	v_mfma_f32_16x16x32_bf16 v[24:27], v[136:139], v[204:207], 0
	v_mfma_f32_16x16x32_bf16 v[12:15], v[128:131], v[212:215], 0
	v_mfma_f32_16x16x32_bf16 v[8:11], v[136:139], v[212:215], 0
	v_mfma_f32_16x16x32_bf16 v[60:63], v[132:135], v[192:195], v[60:63]
	v_mfma_f32_16x16x32_bf16 v[56:59], v[140:143], v[192:195], v[56:59]
	v_mfma_f32_16x16x32_bf16 v[44:47], v[132:135], v[200:203], v[44:47]
	v_mfma_f32_16x16x32_bf16 v[40:43], v[140:143], v[200:203], v[40:43]
	v_mfma_f32_16x16x32_bf16 v[28:31], v[132:135], v[208:211], v[28:31]
	v_mfma_f32_16x16x32_bf16 v[24:27], v[140:143], v[208:211], v[24:27]
	v_mfma_f32_16x16x32_bf16 v[12:15], v[132:135], v[216:219], v[12:15]
	v_mfma_f32_16x16x32_bf16 v[8:11], v[140:143], v[216:219], v[8:11]
	s_setprio 0
	s_setprio 1
	v_mfma_f32_16x16x32_bf16 v[52:55], v[144:147], v[180:183], 0
	v_mfma_f32_16x16x32_bf16 v[48:51], v[172:175], v[180:183], 0
	v_mfma_f32_16x16x32_bf16 v[36:39], v[144:147], v[196:199], 0
	v_mfma_f32_16x16x32_bf16 v[32:35], v[172:175], v[196:199], 0
	v_mfma_f32_16x16x32_bf16 v[20:23], v[144:147], v[204:207], 0
	v_mfma_f32_16x16x32_bf16 v[16:19], v[172:175], v[204:207], 0
	v_mfma_f32_16x16x32_bf16 v[4:7], v[144:147], v[212:215], 0
	v_mfma_f32_16x16x32_bf16 v[0:3], v[172:175], v[212:215], 0
	v_mfma_f32_16x16x32_bf16 v[52:55], v[148:151], v[192:195], v[52:55]
	v_mfma_f32_16x16x32_bf16 v[48:51], v[176:179], v[192:195], v[48:51]
	v_mfma_f32_16x16x32_bf16 v[36:39], v[148:151], v[200:203], v[36:39]
	v_mfma_f32_16x16x32_bf16 v[32:35], v[176:179], v[200:203], v[32:35]
	v_mfma_f32_16x16x32_bf16 v[20:23], v[148:151], v[208:211], v[20:23]
	v_mfma_f32_16x16x32_bf16 v[16:19], v[176:179], v[208:211], v[16:19]
	v_mfma_f32_16x16x32_bf16 v[4:7], v[148:151], v[216:219], v[4:7]
	v_mfma_f32_16x16x32_bf16 v[0:3], v[176:179], v[216:219], v[0:3]
	s_setprio 0
	s_barrier
	s_add_i32 s75, 0, 0x18000
	s_add_i32 s76, 0, 0x1c000
	v_add_u32_e32 v140, s75, v185
	v_add_u32_e32 v176, s76, v185
	ds_read_b128 v[128:131], v140
	ds_read_b128 v[132:135], v140 offset:1024
	ds_read_b128 v[136:139], v140 offset:2048
	ds_read_b128 v[140:143], v140 offset:3072
	ds_read_b128 v[144:147], v176
	ds_read_b128 v[148:151], v176 offset:1024
	ds_read_b128 v[172:175], v176 offset:2048
	ds_read_b128 v[176:179], v176 offset:3072
	s_add_u32 s48, s54, 0xb0000
	s_addc_u32 s49, s55, 0
	s_mov_b32 m0, s61
	v_lshl_add_u64 v[228:229], s[48:49], 0, v[152:153]
	ds_read_b128 v[180:183], v190 offset:32768
	ds_read_b128 v[192:195], v190 offset:33792
	ds_read_b128 v[196:199], v190 offset:34816
	ds_read_b128 v[200:203], v190 offset:35840
	ds_read_b128 v[204:207], v190 offset:36864
	ds_read_b128 v[208:211], v190 offset:37888
	ds_read_b128 v[212:215], v190 offset:38912
	ds_read_b128 v[216:219], v190 offset:39936
	global_load_lds_dwordx4 v[228:229], off
	v_lshl_add_u64 v[228:229], s[48:49], 0, v[160:161]
	s_mov_b32 m0, s62
	s_nop 0
	global_load_lds_dwordx4 v[228:229], off
	s_waitcnt vmcnt(8)
	s_waitcnt lgkmcnt(0)
	s_barrier
	s_setprio 1
	s_waitcnt lgkmcnt(0)
	v_mfma_f32_16x16x32_bf16 v[124:127], v[128:131], v[180:183], v[124:127]
	v_mfma_f32_16x16x32_bf16 v[124:127], v[132:135], v[192:195], v[124:127]
	v_mfma_f32_16x16x32_bf16 v[120:123], v[136:139], v[180:183], v[120:123]
	v_mfma_f32_16x16x32_bf16 v[120:123], v[140:143], v[192:195], v[120:123]
	v_mfma_f32_16x16x32_bf16 v[108:111], v[128:131], v[196:199], v[108:111]
	v_mfma_f32_16x16x32_bf16 v[108:111], v[132:135], v[200:203], v[108:111]
	v_mfma_f32_16x16x32_bf16 v[104:107], v[136:139], v[196:199], v[104:107]
	v_mfma_f32_16x16x32_bf16 v[104:107], v[140:143], v[200:203], v[104:107]
	v_mfma_f32_16x16x32_bf16 v[92:95], v[128:131], v[204:207], v[92:95]
	v_mfma_f32_16x16x32_bf16 v[92:95], v[132:135], v[208:211], v[92:95]
	v_mfma_f32_16x16x32_bf16 v[88:91], v[136:139], v[204:207], v[88:91]
	v_mfma_f32_16x16x32_bf16 v[88:91], v[140:143], v[208:211], v[88:91]
	v_mfma_f32_16x16x32_bf16 v[76:79], v[128:131], v[212:215], v[76:79]
	v_mfma_f32_16x16x32_bf16 v[76:79], v[132:135], v[216:219], v[76:79]
	v_mfma_f32_16x16x32_bf16 v[72:75], v[136:139], v[212:215], v[72:75]
	v_mfma_f32_16x16x32_bf16 v[72:75], v[140:143], v[216:219], v[72:75]
	s_setprio 0
	s_setprio 1
	v_mfma_f32_16x16x32_bf16 v[116:119], v[144:147], v[180:183], v[116:119]
	v_mfma_f32_16x16x32_bf16 v[116:119], v[148:151], v[192:195], v[116:119]
	v_mfma_f32_16x16x32_bf16 v[112:115], v[172:175], v[180:183], v[112:115]
	v_mfma_f32_16x16x32_bf16 v[112:115], v[176:179], v[192:195], v[112:115]
	v_mfma_f32_16x16x32_bf16 v[100:103], v[144:147], v[196:199], v[100:103]
	v_mfma_f32_16x16x32_bf16 v[100:103], v[148:151], v[200:203], v[100:103]
	v_mfma_f32_16x16x32_bf16 v[96:99], v[172:175], v[196:199], v[96:99]
	v_mfma_f32_16x16x32_bf16 v[96:99], v[176:179], v[200:203], v[96:99]
	v_mfma_f32_16x16x32_bf16 v[84:87], v[144:147], v[204:207], v[84:87]
	v_mfma_f32_16x16x32_bf16 v[84:87], v[148:151], v[208:211], v[84:87]
	v_mfma_f32_16x16x32_bf16 v[80:83], v[172:175], v[204:207], v[80:83]
	v_mfma_f32_16x16x32_bf16 v[80:83], v[176:179], v[208:211], v[80:83]
	v_mfma_f32_16x16x32_bf16 v[68:71], v[144:147], v[212:215], v[68:71]
	v_mfma_f32_16x16x32_bf16 v[68:71], v[148:151], v[216:219], v[68:71]
	v_mfma_f32_16x16x32_bf16 v[64:67], v[172:175], v[212:215], v[64:67]
	v_mfma_f32_16x16x32_bf16 v[64:67], v[176:179], v[216:219], v[64:67]
	s_setprio 0
	s_barrier
	s_add_i32 s48, s75, s58
	v_lshl_add_u64 v[220:221], v[220:221], 0, s[22:23]
	s_mov_b32 m0, s48
	ds_read_b128 v[180:183], v190 offset:49152
	ds_read_b128 v[192:195], v190 offset:50176
	ds_read_b128 v[196:199], v190 offset:51200
	ds_read_b128 v[200:203], v190 offset:52224
	ds_read_b128 v[204:207], v190 offset:53248
	ds_read_b128 v[208:211], v190 offset:54272
	ds_read_b128 v[212:215], v190 offset:55296
	ds_read_b128 v[216:219], v190 offset:56320
	global_load_lds_dwordx4 v[220:221], off
	s_add_i32 m0, s48, 0x2000
	s_add_u32 s48, s52, 0xb0080
	v_lshl_add_u64 v[220:221], v[222:223], 0, s[22:23]
	s_addc_u32 s49, s53, 0
	s_add_i32 s52, s76, s58
	global_load_lds_dwordx4 v[220:221], off
	v_lshl_add_u64 v[220:221], s[48:49], 0, v[154:155]
	s_mov_b32 m0, s52
	s_nop 0
	global_load_lds_dwordx4 v[220:221], off
	v_lshl_add_u64 v[220:221], s[48:49], 0, v[162:163]
	s_add_i32 m0, s52, 0x2000
	s_nop 0
	global_load_lds_dwordx4 v[220:221], off
	v_lshl_add_u64 v[220:221], v[224:225], 0, s[22:23]
	s_mov_b32 m0, s3
	s_nop 0
	global_load_lds_dwordx4 v[220:221], off
	v_lshl_add_u64 v[220:221], v[226:227], 0, s[22:23]
	s_mov_b32 m0, s64
	s_nop 0
	global_load_lds_dwordx4 v[220:221], off
	s_waitcnt vmcnt(8)
	s_waitcnt lgkmcnt(0)
	s_barrier
	s_setprio 1
	s_waitcnt lgkmcnt(0)
	v_mfma_f32_16x16x32_bf16 v[60:63], v[128:131], v[180:183], v[60:63]
	v_mfma_f32_16x16x32_bf16 v[60:63], v[132:135], v[192:195], v[60:63]
	v_mfma_f32_16x16x32_bf16 v[56:59], v[136:139], v[180:183], v[56:59]
	v_mfma_f32_16x16x32_bf16 v[56:59], v[140:143], v[192:195], v[56:59]
	v_mfma_f32_16x16x32_bf16 v[44:47], v[128:131], v[196:199], v[44:47]
	v_mfma_f32_16x16x32_bf16 v[44:47], v[132:135], v[200:203], v[44:47]
	v_mfma_f32_16x16x32_bf16 v[40:43], v[136:139], v[196:199], v[40:43]
	v_mfma_f32_16x16x32_bf16 v[40:43], v[140:143], v[200:203], v[40:43]
	v_mfma_f32_16x16x32_bf16 v[28:31], v[128:131], v[204:207], v[28:31]
	v_mfma_f32_16x16x32_bf16 v[28:31], v[132:135], v[208:211], v[28:31]
	v_mfma_f32_16x16x32_bf16 v[24:27], v[136:139], v[204:207], v[24:27]
	v_mfma_f32_16x16x32_bf16 v[24:27], v[140:143], v[208:211], v[24:27]
	v_mfma_f32_16x16x32_bf16 v[12:15], v[128:131], v[212:215], v[12:15]
	v_mfma_f32_16x16x32_bf16 v[12:15], v[132:135], v[216:219], v[12:15]
	v_mfma_f32_16x16x32_bf16 v[8:11], v[136:139], v[212:215], v[8:11]
	v_mfma_f32_16x16x32_bf16 v[8:11], v[140:143], v[216:219], v[8:11]
	s_setprio 0
	s_setprio 1
	v_mfma_f32_16x16x32_bf16 v[52:55], v[144:147], v[180:183], v[52:55]
	v_mfma_f32_16x16x32_bf16 v[52:55], v[148:151], v[192:195], v[52:55]
	v_mfma_f32_16x16x32_bf16 v[48:51], v[172:175], v[180:183], v[48:51]
	v_mfma_f32_16x16x32_bf16 v[48:51], v[176:179], v[192:195], v[48:51]
	v_mfma_f32_16x16x32_bf16 v[36:39], v[144:147], v[196:199], v[36:39]
	v_mfma_f32_16x16x32_bf16 v[36:39], v[148:151], v[200:203], v[36:39]
	v_mfma_f32_16x16x32_bf16 v[32:35], v[172:175], v[196:199], v[32:35]
	v_mfma_f32_16x16x32_bf16 v[32:35], v[176:179], v[200:203], v[32:35]
	v_mfma_f32_16x16x32_bf16 v[20:23], v[144:147], v[204:207], v[20:23]
	v_mfma_f32_16x16x32_bf16 v[20:23], v[148:151], v[208:211], v[20:23]
	v_mfma_f32_16x16x32_bf16 v[16:19], v[172:175], v[204:207], v[16:19]
	v_mfma_f32_16x16x32_bf16 v[16:19], v[176:179], v[208:211], v[16:19]
	v_mfma_f32_16x16x32_bf16 v[4:7], v[144:147], v[212:215], v[4:7]
	v_mfma_f32_16x16x32_bf16 v[4:7], v[148:151], v[216:219], v[4:7]
	v_mfma_f32_16x16x32_bf16 v[0:3], v[172:175], v[212:215], v[0:3]
	v_mfma_f32_16x16x32_bf16 v[0:3], v[176:179], v[216:219], v[0:3]
	s_setprio 0
	s_barrier
	s_add_i32 s74, s74, 2
	s_add_u32 s72, s72, 0x100
	s_addc_u32 s73, s73, 0
	s_cmp_gt_u32 s74, 41
	s_mov_b64 s[48:49], s[50:51]
.LBB0_1181:
	ds_read_b128 v[128:131], v188
	ds_read_b128 v[132:135], v188 offset:1024
	ds_read_b128 v[136:139], v188 offset:2048
	ds_read_b128 v[140:143], v188 offset:3072
	ds_read_b128 v[144:147], v189
	ds_read_b128 v[148:151], v189 offset:1024
	ds_read_b128 v[172:175], v189 offset:2048
	ds_read_b128 v[176:179], v189 offset:3072
	s_add_u32 s50, s48, 0x100
	s_addc_u32 s51, s49, 0
	s_cmp_eq_u32 s74, 40
	s_cselect_b32 s55, s11, s51
	s_cselect_b32 s54, s10, s50
	s_cselect_b32 s53, s47, s73
	s_cselect_b32 s52, s46, s72
	v_lshl_add_u64 v[220:221], s[48:49], 0, v[166:167]
	s_add_i32 m0, s59, 0xc000
	ds_read_b128 v[180:183], v190
	ds_read_b128 v[192:195], v190 offset:1024
	ds_read_b128 v[196:199], v190 offset:2048
	ds_read_b128 v[200:203], v190 offset:3072
	ds_read_b128 v[204:207], v190 offset:4096
	ds_read_b128 v[208:211], v190 offset:5120
	ds_read_b128 v[212:215], v190 offset:6144
	ds_read_b128 v[216:219], v190 offset:7168
	global_load_lds_dwordx4 v[220:221], off
	v_lshl_add_u64 v[220:221], s[48:49], 0, v[164:165]
	s_add_i32 m0, s59, 0xe000
	s_nop 0
	global_load_lds_dwordx4 v[220:221], off
	s_waitcnt vmcnt(8)
	s_waitcnt lgkmcnt(0)
	s_barrier
	s_setprio 1
	s_waitcnt lgkmcnt(0)
	v_mfma_f32_16x16x32_bf16 v[124:127], v[128:131], v[180:183], v[124:127]
	v_mfma_f32_16x16x32_bf16 v[124:127], v[132:135], v[192:195], v[124:127]
	v_mfma_f32_16x16x32_bf16 v[120:123], v[136:139], v[180:183], v[120:123]
	v_mfma_f32_16x16x32_bf16 v[120:123], v[140:143], v[192:195], v[120:123]
	v_mfma_f32_16x16x32_bf16 v[108:111], v[128:131], v[196:199], v[108:111]
	v_mfma_f32_16x16x32_bf16 v[108:111], v[132:135], v[200:203], v[108:111]
	v_mfma_f32_16x16x32_bf16 v[104:107], v[136:139], v[196:199], v[104:107]
	v_mfma_f32_16x16x32_bf16 v[104:107], v[140:143], v[200:203], v[104:107]
	v_mfma_f32_16x16x32_bf16 v[92:95], v[128:131], v[204:207], v[92:95]
	v_mfma_f32_16x16x32_bf16 v[92:95], v[132:135], v[208:211], v[92:95]
	v_mfma_f32_16x16x32_bf16 v[88:91], v[136:139], v[204:207], v[88:91]
	v_mfma_f32_16x16x32_bf16 v[88:91], v[140:143], v[208:211], v[88:91]
	v_mfma_f32_16x16x32_bf16 v[76:79], v[128:131], v[212:215], v[76:79]
	v_mfma_f32_16x16x32_bf16 v[76:79], v[132:135], v[216:219], v[76:79]
	v_mfma_f32_16x16x32_bf16 v[72:75], v[136:139], v[212:215], v[72:75]
	v_mfma_f32_16x16x32_bf16 v[72:75], v[140:143], v[216:219], v[72:75]
	s_setprio 0
	s_setprio 1
	v_mfma_f32_16x16x32_bf16 v[116:119], v[144:147], v[180:183], v[116:119]
	v_mfma_f32_16x16x32_bf16 v[116:119], v[148:151], v[192:195], v[116:119]
	v_mfma_f32_16x16x32_bf16 v[112:115], v[172:175], v[180:183], v[112:115]
	v_mfma_f32_16x16x32_bf16 v[112:115], v[176:179], v[192:195], v[112:115]
	v_mfma_f32_16x16x32_bf16 v[100:103], v[144:147], v[196:199], v[100:103]
	v_mfma_f32_16x16x32_bf16 v[100:103], v[148:151], v[200:203], v[100:103]
	v_mfma_f32_16x16x32_bf16 v[96:99], v[172:175], v[196:199], v[96:99]
	v_mfma_f32_16x16x32_bf16 v[96:99], v[176:179], v[200:203], v[96:99]
	v_mfma_f32_16x16x32_bf16 v[84:87], v[144:147], v[204:207], v[84:87]
	v_mfma_f32_16x16x32_bf16 v[84:87], v[148:151], v[208:211], v[84:87]
	v_mfma_f32_16x16x32_bf16 v[80:83], v[172:175], v[204:207], v[80:83]
	v_mfma_f32_16x16x32_bf16 v[80:83], v[176:179], v[208:211], v[80:83]
	v_mfma_f32_16x16x32_bf16 v[68:71], v[144:147], v[212:215], v[68:71]
	v_mfma_f32_16x16x32_bf16 v[68:71], v[148:151], v[216:219], v[68:71]
	v_mfma_f32_16x16x32_bf16 v[64:67], v[172:175], v[212:215], v[64:67]
	v_mfma_f32_16x16x32_bf16 v[64:67], v[176:179], v[216:219], v[64:67]
	s_setprio 0
	s_barrier
	s_add_i32 s48, s68, s58
	v_lshl_add_u64 v[220:221], s[52:53], 0, v[154:155]
	s_mov_b32 m0, s48
	ds_read_b128 v[180:183], v190 offset:16384
	ds_read_b128 v[192:195], v190 offset:17408
	ds_read_b128 v[196:199], v190 offset:18432
	ds_read_b128 v[200:203], v190 offset:19456
	ds_read_b128 v[204:207], v190 offset:20480
	ds_read_b128 v[208:211], v190 offset:21504
	ds_read_b128 v[212:215], v190 offset:22528
	ds_read_b128 v[216:219], v190 offset:23552
	global_load_lds_dwordx4 v[220:221], off
	s_add_i32 m0, s48, 0x2000
	s_add_u32 s48, s52, 0xb0000
	v_lshl_add_u64 v[222:223], s[52:53], 0, v[162:163]
	s_addc_u32 s49, s53, 0
	s_add_i32 s75, s69, s58
	global_load_lds_dwordx4 v[222:223], off
	v_lshl_add_u64 v[224:225], s[48:49], 0, v[154:155]
	s_mov_b32 m0, s75
	v_lshl_add_u64 v[226:227], s[54:55], 0, v[160:161]
	global_load_lds_dwordx4 v[224:225], off
	v_lshl_add_u64 v[224:225], s[48:49], 0, v[162:163]
	s_add_i32 m0, s75, 0x2000
	s_nop 0
	global_load_lds_dwordx4 v[224:225], off
	v_lshl_add_u64 v[224:225], s[54:55], 0, v[152:153]
	s_mov_b32 m0, s59
	s_nop 0
	global_load_lds_dwordx4 v[224:225], off
	s_mov_b32 m0, s60
	s_nop 0
	global_load_lds_dwordx4 v[226:227], off
	s_waitcnt vmcnt(8)
	s_waitcnt lgkmcnt(0)
	s_barrier
	s_setprio 1
	s_waitcnt lgkmcnt(0)
	v_mfma_f32_16x16x32_bf16 v[60:63], v[128:131], v[180:183], v[60:63]
	v_mfma_f32_16x16x32_bf16 v[60:63], v[132:135], v[192:195], v[60:63]
	v_mfma_f32_16x16x32_bf16 v[56:59], v[136:139], v[180:183], v[56:59]
	v_mfma_f32_16x16x32_bf16 v[56:59], v[140:143], v[192:195], v[56:59]
	v_mfma_f32_16x16x32_bf16 v[44:47], v[128:131], v[196:199], v[44:47]
	v_mfma_f32_16x16x32_bf16 v[44:47], v[132:135], v[200:203], v[44:47]
	v_mfma_f32_16x16x32_bf16 v[40:43], v[136:139], v[196:199], v[40:43]
	v_mfma_f32_16x16x32_bf16 v[40:43], v[140:143], v[200:203], v[40:43]
	v_mfma_f32_16x16x32_bf16 v[28:31], v[128:131], v[204:207], v[28:31]
	v_mfma_f32_16x16x32_bf16 v[28:31], v[132:135], v[208:211], v[28:31]
	v_mfma_f32_16x16x32_bf16 v[24:27], v[136:139], v[204:207], v[24:27]
	v_mfma_f32_16x16x32_bf16 v[24:27], v[140:143], v[208:211], v[24:27]
	v_mfma_f32_16x16x32_bf16 v[12:15], v[128:131], v[212:215], v[12:15]
	v_mfma_f32_16x16x32_bf16 v[12:15], v[132:135], v[216:219], v[12:15]
	v_mfma_f32_16x16x32_bf16 v[8:11], v[136:139], v[212:215], v[8:11]
	v_mfma_f32_16x16x32_bf16 v[8:11], v[140:143], v[216:219], v[8:11]
	s_setprio 0
	s_setprio 1
	v_mfma_f32_16x16x32_bf16 v[52:55], v[144:147], v[180:183], v[52:55]
	v_mfma_f32_16x16x32_bf16 v[52:55], v[148:151], v[192:195], v[52:55]
	v_mfma_f32_16x16x32_bf16 v[48:51], v[172:175], v[180:183], v[48:51]
	v_mfma_f32_16x16x32_bf16 v[48:51], v[176:179], v[192:195], v[48:51]
	v_mfma_f32_16x16x32_bf16 v[36:39], v[144:147], v[196:199], v[36:39]
	v_mfma_f32_16x16x32_bf16 v[36:39], v[148:151], v[200:203], v[36:39]
	v_mfma_f32_16x16x32_bf16 v[32:35], v[172:175], v[196:199], v[32:35]
	v_mfma_f32_16x16x32_bf16 v[32:35], v[176:179], v[200:203], v[32:35]
	v_mfma_f32_16x16x32_bf16 v[20:23], v[144:147], v[204:207], v[20:23]
	v_mfma_f32_16x16x32_bf16 v[20:23], v[148:151], v[208:211], v[20:23]
	v_mfma_f32_16x16x32_bf16 v[16:19], v[172:175], v[204:207], v[16:19]
	v_mfma_f32_16x16x32_bf16 v[16:19], v[176:179], v[208:211], v[16:19]
	v_mfma_f32_16x16x32_bf16 v[4:7], v[144:147], v[212:215], v[4:7]
	v_mfma_f32_16x16x32_bf16 v[4:7], v[148:151], v[216:219], v[4:7]
	v_mfma_f32_16x16x32_bf16 v[0:3], v[172:175], v[212:215], v[0:3]
	v_mfma_f32_16x16x32_bf16 v[0:3], v[176:179], v[216:219], v[0:3]
	s_setprio 0
	s_barrier
	s_add_i32 s75, 0, 0x18000
	s_add_i32 s76, 0, 0x1c000
	v_add_u32_e32 v140, s75, v185
	v_add_u32_e32 v176, s76, v185
	ds_read_b128 v[128:131], v140
	ds_read_b128 v[132:135], v140 offset:1024
	ds_read_b128 v[136:139], v140 offset:2048
	ds_read_b128 v[140:143], v140 offset:3072
	ds_read_b128 v[144:147], v176
	ds_read_b128 v[148:151], v176 offset:1024
	ds_read_b128 v[172:175], v176 offset:2048
	ds_read_b128 v[176:179], v176 offset:3072
	s_add_u32 s48, s54, 0xb0000
	s_addc_u32 s49, s55, 0
	s_mov_b32 m0, s61
	v_lshl_add_u64 v[228:229], s[48:49], 0, v[152:153]
	ds_read_b128 v[180:183], v190 offset:32768
	ds_read_b128 v[192:195], v190 offset:33792
	ds_read_b128 v[196:199], v190 offset:34816
	ds_read_b128 v[200:203], v190 offset:35840
	ds_read_b128 v[204:207], v190 offset:36864
	ds_read_b128 v[208:211], v190 offset:37888
	ds_read_b128 v[212:215], v190 offset:38912
	ds_read_b128 v[216:219], v190 offset:39936
	global_load_lds_dwordx4 v[228:229], off
	v_lshl_add_u64 v[228:229], s[48:49], 0, v[160:161]
	s_mov_b32 m0, s62
	s_nop 0
	global_load_lds_dwordx4 v[228:229], off
	s_waitcnt vmcnt(8)
	s_waitcnt lgkmcnt(0)
	s_barrier
	s_setprio 1
	s_waitcnt lgkmcnt(0)
	v_mfma_f32_16x16x32_bf16 v[124:127], v[128:131], v[180:183], v[124:127]
	v_mfma_f32_16x16x32_bf16 v[124:127], v[132:135], v[192:195], v[124:127]
	v_mfma_f32_16x16x32_bf16 v[120:123], v[136:139], v[180:183], v[120:123]
	v_mfma_f32_16x16x32_bf16 v[120:123], v[140:143], v[192:195], v[120:123]
	v_mfma_f32_16x16x32_bf16 v[108:111], v[128:131], v[196:199], v[108:111]
	v_mfma_f32_16x16x32_bf16 v[108:111], v[132:135], v[200:203], v[108:111]
	v_mfma_f32_16x16x32_bf16 v[104:107], v[136:139], v[196:199], v[104:107]
	v_mfma_f32_16x16x32_bf16 v[104:107], v[140:143], v[200:203], v[104:107]
	v_mfma_f32_16x16x32_bf16 v[92:95], v[128:131], v[204:207], v[92:95]
	v_mfma_f32_16x16x32_bf16 v[92:95], v[132:135], v[208:211], v[92:95]
	v_mfma_f32_16x16x32_bf16 v[88:91], v[136:139], v[204:207], v[88:91]
	v_mfma_f32_16x16x32_bf16 v[88:91], v[140:143], v[208:211], v[88:91]
	v_mfma_f32_16x16x32_bf16 v[76:79], v[128:131], v[212:215], v[76:79]
	v_mfma_f32_16x16x32_bf16 v[76:79], v[132:135], v[216:219], v[76:79]
	v_mfma_f32_16x16x32_bf16 v[72:75], v[136:139], v[212:215], v[72:75]
	v_mfma_f32_16x16x32_bf16 v[72:75], v[140:143], v[216:219], v[72:75]
	s_setprio 0
	s_setprio 1
	v_mfma_f32_16x16x32_bf16 v[116:119], v[144:147], v[180:183], v[116:119]
	v_mfma_f32_16x16x32_bf16 v[116:119], v[148:151], v[192:195], v[116:119]
	v_mfma_f32_16x16x32_bf16 v[112:115], v[172:175], v[180:183], v[112:115]
	v_mfma_f32_16x16x32_bf16 v[112:115], v[176:179], v[192:195], v[112:115]
	v_mfma_f32_16x16x32_bf16 v[100:103], v[144:147], v[196:199], v[100:103]
	v_mfma_f32_16x16x32_bf16 v[100:103], v[148:151], v[200:203], v[100:103]
	v_mfma_f32_16x16x32_bf16 v[96:99], v[172:175], v[196:199], v[96:99]
	v_mfma_f32_16x16x32_bf16 v[96:99], v[176:179], v[200:203], v[96:99]
	v_mfma_f32_16x16x32_bf16 v[84:87], v[144:147], v[204:207], v[84:87]
	v_mfma_f32_16x16x32_bf16 v[84:87], v[148:151], v[208:211], v[84:87]
	v_mfma_f32_16x16x32_bf16 v[80:83], v[172:175], v[204:207], v[80:83]
	v_mfma_f32_16x16x32_bf16 v[80:83], v[176:179], v[208:211], v[80:83]
	v_mfma_f32_16x16x32_bf16 v[68:71], v[144:147], v[212:215], v[68:71]
	v_mfma_f32_16x16x32_bf16 v[68:71], v[148:151], v[216:219], v[68:71]
	v_mfma_f32_16x16x32_bf16 v[64:67], v[172:175], v[212:215], v[64:67]
	v_mfma_f32_16x16x32_bf16 v[64:67], v[176:179], v[216:219], v[64:67]
	s_setprio 0
	s_barrier
	s_add_i32 s48, s75, s58
	v_lshl_add_u64 v[220:221], v[220:221], 0, s[22:23]
	s_mov_b32 m0, s48
	ds_read_b128 v[180:183], v190 offset:49152
	ds_read_b128 v[192:195], v190 offset:50176
	ds_read_b128 v[196:199], v190 offset:51200
	ds_read_b128 v[200:203], v190 offset:52224
	ds_read_b128 v[204:207], v190 offset:53248
	ds_read_b128 v[208:211], v190 offset:54272
	ds_read_b128 v[212:215], v190 offset:55296
	ds_read_b128 v[216:219], v190 offset:56320
	global_load_lds_dwordx4 v[220:221], off
	s_add_i32 m0, s48, 0x2000
	s_add_u32 s48, s52, 0xb0080
	v_lshl_add_u64 v[220:221], v[222:223], 0, s[22:23]
	s_addc_u32 s49, s53, 0
	s_add_i32 s52, s76, s58
	global_load_lds_dwordx4 v[220:221], off
	v_lshl_add_u64 v[220:221], s[48:49], 0, v[154:155]
	s_mov_b32 m0, s52
	s_nop 0
	global_load_lds_dwordx4 v[220:221], off
	v_lshl_add_u64 v[220:221], s[48:49], 0, v[162:163]
	s_add_i32 m0, s52, 0x2000
	s_nop 0
	global_load_lds_dwordx4 v[220:221], off
	v_lshl_add_u64 v[220:221], v[224:225], 0, s[22:23]
	s_mov_b32 m0, s3
	s_nop 0
	global_load_lds_dwordx4 v[220:221], off
	v_lshl_add_u64 v[220:221], v[226:227], 0, s[22:23]
	s_mov_b32 m0, s64
	s_nop 0
	global_load_lds_dwordx4 v[220:221], off
	s_waitcnt vmcnt(8)
	s_waitcnt lgkmcnt(0)
	s_barrier
	s_setprio 1
	s_waitcnt lgkmcnt(0)
	v_mfma_f32_16x16x32_bf16 v[60:63], v[128:131], v[180:183], v[60:63]
	v_mfma_f32_16x16x32_bf16 v[60:63], v[132:135], v[192:195], v[60:63]
	v_mfma_f32_16x16x32_bf16 v[56:59], v[136:139], v[180:183], v[56:59]
	v_mfma_f32_16x16x32_bf16 v[56:59], v[140:143], v[192:195], v[56:59]
	v_mfma_f32_16x16x32_bf16 v[44:47], v[128:131], v[196:199], v[44:47]
	v_mfma_f32_16x16x32_bf16 v[44:47], v[132:135], v[200:203], v[44:47]
	v_mfma_f32_16x16x32_bf16 v[40:43], v[136:139], v[196:199], v[40:43]
	v_mfma_f32_16x16x32_bf16 v[40:43], v[140:143], v[200:203], v[40:43]
	v_mfma_f32_16x16x32_bf16 v[28:31], v[128:131], v[204:207], v[28:31]
	v_mfma_f32_16x16x32_bf16 v[28:31], v[132:135], v[208:211], v[28:31]
	v_mfma_f32_16x16x32_bf16 v[24:27], v[136:139], v[204:207], v[24:27]
	v_mfma_f32_16x16x32_bf16 v[24:27], v[140:143], v[208:211], v[24:27]
	v_mfma_f32_16x16x32_bf16 v[12:15], v[128:131], v[212:215], v[12:15]
	v_mfma_f32_16x16x32_bf16 v[12:15], v[132:135], v[216:219], v[12:15]
	v_mfma_f32_16x16x32_bf16 v[8:11], v[136:139], v[212:215], v[8:11]
	v_mfma_f32_16x16x32_bf16 v[8:11], v[140:143], v[216:219], v[8:11]
	s_setprio 0
	s_setprio 1
	v_mfma_f32_16x16x32_bf16 v[52:55], v[144:147], v[180:183], v[52:55]
	v_mfma_f32_16x16x32_bf16 v[52:55], v[148:151], v[192:195], v[52:55]
	v_mfma_f32_16x16x32_bf16 v[48:51], v[172:175], v[180:183], v[48:51]
	v_mfma_f32_16x16x32_bf16 v[48:51], v[176:179], v[192:195], v[48:51]
	v_mfma_f32_16x16x32_bf16 v[36:39], v[144:147], v[196:199], v[36:39]
	v_mfma_f32_16x16x32_bf16 v[36:39], v[148:151], v[200:203], v[36:39]
	v_mfma_f32_16x16x32_bf16 v[32:35], v[172:175], v[196:199], v[32:35]
	v_mfma_f32_16x16x32_bf16 v[32:35], v[176:179], v[200:203], v[32:35]
	v_mfma_f32_16x16x32_bf16 v[20:23], v[144:147], v[204:207], v[20:23]
	v_mfma_f32_16x16x32_bf16 v[20:23], v[148:151], v[208:211], v[20:23]
	v_mfma_f32_16x16x32_bf16 v[16:19], v[172:175], v[204:207], v[16:19]
	v_mfma_f32_16x16x32_bf16 v[16:19], v[176:179], v[208:211], v[16:19]
	v_mfma_f32_16x16x32_bf16 v[4:7], v[144:147], v[212:215], v[4:7]
	v_mfma_f32_16x16x32_bf16 v[4:7], v[148:151], v[216:219], v[4:7]
	v_mfma_f32_16x16x32_bf16 v[0:3], v[172:175], v[212:215], v[0:3]
	v_mfma_f32_16x16x32_bf16 v[0:3], v[176:179], v[216:219], v[0:3]
	s_setprio 0
	s_barrier
	s_add_i32 s74, s74, 2
	s_add_u32 s72, s72, 0x100
	s_addc_u32 s73, s73, 0
	s_cmp_gt_u32 s74, 41
	s_mov_b64 s[48:49], s[50:51]
	s_cbranch_scc0 .LBB0_1181
	s_and_b64 vcc, exec, s[24:25]
	s_cbranch_vccz .LBB0_1184
	s_barrier
